# sc1 write-through on all plain dwordx4/x2 bulk stores (epilogues, norms, weight copies) so grid-barrier wbl2 finds L2 clean
# speedup vs baseline: 1.0099x; 1.0099x over previous
.LBB0_91:
	v_mul_u32_u24_e32 v2, s40, v1
	v_lshlrev_b32_e32 v2, 2, v2
	s_waitcnt vmcnt(62)
	v_lshl_add_u64 v[46:47], s[38:39], 0, v[2:3]
	v_mov_b32_e32 v7, v3
	s_waitcnt vmcnt(57)
	v_lshl_add_u64 v[54:55], v[46:47], 0, v[6:7]
	s_lshl_b64 s[38:39], s[40:41], 3
	s_waitcnt vmcnt(55)
	v_lshl_add_u64 v[56:57], v[54:55], 0, s[38:39]
	s_waitcnt vmcnt(53)
	v_lshl_add_u64 v[58:59], v[56:57], 0, s[38:39]
	s_waitcnt vmcnt(51)
	v_lshl_add_u64 v[60:61], v[58:59], 0, s[38:39]
	s_waitcnt vmcnt(49)
	v_lshl_add_u64 v[62:63], v[60:61], 0, s[38:39]
	s_waitcnt vmcnt(47)
	v_lshl_add_u64 v[64:65], v[62:63], 0, s[38:39]
	s_waitcnt vmcnt(44)
	v_lshl_add_u64 v[68:69], v[64:65], 0, s[38:39]
	s_waitcnt vmcnt(42)
	v_lshl_add_u64 v[70:71], v[68:69], 0, s[38:39]
	global_load_dword v45, v[54:55], off nt
	global_load_dword v46, v[56:57], off nt
	global_load_dword v47, v[58:59], off nt
	global_load_dword v48, v[60:61], off nt
	global_load_dword v49, v[62:63], off nt
	global_load_dword v50, v[64:65], off nt
	global_load_dword v51, v[68:69], off nt
	global_load_dword v52, v[70:71], off nt
	v_lshl_add_u64 v[54:55], v[70:71], 0, s[38:39]
	v_lshl_add_u64 v[56:57], v[54:55], 0, s[38:39]
	global_load_dword v53, v[54:55], off nt
	v_add_u32_e32 v80, 0xc00, v12
	global_load_dword v54, v[56:57], off nt
	v_lshl_add_u64 v[56:57], v[56:57], 0, s[38:39]
	v_lshl_add_u64 v[58:59], v[56:57], 0, s[38:39]
	global_load_dword v55, v[56:57], off nt
	v_add_u32_e32 v81, 0x1000, v12
	global_load_dword v56, v[58:59], off nt
	v_lshl_add_u64 v[58:59], v[58:59], 0, s[38:39]
	v_lshl_add_u64 v[60:61], v[58:59], 0, s[38:39]
	global_load_dword v57, v[58:59], off nt
	v_add_u32_e32 v82, 0x1400, v12
	global_load_dword v58, v[60:61], off nt
	v_lshl_add_u64 v[60:61], v[60:61], 0, s[38:39]
	v_lshl_add_u64 v[62:63], v[60:61], 0, s[38:39]
	global_load_dword v59, v[60:61], off nt
	v_add_u32_e32 v83, 0x1800, v12
	global_load_dword v60, v[62:63], off nt
	v_lshl_add_u64 v[62:63], v[62:63], 0, s[38:39]
	v_lshl_add_u64 v[64:65], v[62:63], 0, s[38:39]
	global_load_dword v61, v[62:63], off nt
	v_add_u32_e32 v84, 0x1c00, v12
	global_load_dword v62, v[64:65], off nt
	v_lshl_add_u64 v[64:65], v[64:65], 0, s[38:39]
	v_lshl_add_u64 v[68:69], v[64:65], 0, s[38:39]
	global_load_dword v63, v[64:65], off nt
	v_lshlrev_b32_e32 v2, 1, v4
	global_load_dword v64, v[68:69], off nt
	v_lshl_add_u64 v[68:69], v[68:69], 0, s[38:39]
	global_load_dword v65, v[68:69], off nt
	v_lshl_add_u64 v[68:69], v[68:69], 0, s[38:39]
	v_lshl_add_u64 v[70:71], v[68:69], 0, s[38:39]
	global_load_dword v67, v[68:69], off nt
	s_add_i32 s19, s44, 2
	global_load_dword v68, v[70:71], off nt
	v_lshl_add_u64 v[70:71], v[70:71], 0, s[38:39]
	s_waitcnt vmcnt(62)
	v_lshl_add_u64 v[72:73], v[70:71], 0, s[38:39]
	global_load_dword v69, v[70:71], off nt
	s_min_i32 s4, s19, s33
	global_load_dword v70, v[72:73], off nt
	v_lshl_add_u64 v[72:73], v[72:73], 0, s[38:39]
	s_waitcnt vmcnt(62)
	v_lshl_add_u64 v[74:75], v[72:73], 0, s[38:39]
	global_load_dword v71, v[72:73], off nt
	s_nop 0
	global_load_dword v72, v[74:75], off nt
	v_lshl_add_u64 v[74:75], v[74:75], 0, s[38:39]
	s_waitcnt vmcnt(62)
	v_lshl_add_u64 v[76:77], v[74:75], 0, s[38:39]
	global_load_dword v73, v[74:75], off nt
	s_nop 0
	global_load_dword v74, v[76:77], off nt
	v_lshl_add_u64 v[76:77], v[76:77], 0, s[38:39]
	v_lshl_add_u64 v[78:79], v[76:77], 0, s[38:39]
	global_load_dword v75, v[76:77], off nt
	s_nop 0
	global_load_dword v76, v[78:79], off nt
	v_lshl_add_u64 v[78:79], v[78:79], 0, s[38:39]
	global_load_dword v77, v[78:79], off nt
	v_add_u32_e32 v78, 0x400, v12
	v_add_u32_e32 v79, 0x800, v12
	s_waitcnt vmcnt(32)
	ds_write2_b32 v12, v37, v36 offset1:66
	ds_write2_b32 v12, v35, v34 offset0:132 offset1:198
	ds_write2_b32 v78, v29, v28 offset0:8 offset1:74
	ds_write2_b32 v78, v23, v22 offset0:140 offset1:206
	ds_write2_b32 v79, v32, v33 offset0:16 offset1:82
	ds_write2_b32 v79, v30, v31 offset0:148 offset1:214
	ds_write2_b32 v80, v26, v27 offset0:24 offset1:90
	ds_write2_b32 v80, v24, v25 offset0:156 offset1:222
	ds_write2_b32 v81, v20, v21 offset0:32 offset1:98
	ds_write2_b32 v81, v18, v19 offset0:164 offset1:230
	ds_write2_b32 v82, v16, v17 offset0:40 offset1:106
	ds_write2_b32 v82, v14, v15 offset0:172 offset1:238
	ds_write2_b32 v83, v13, v38 offset0:48 offset1:114
	ds_write2_b32 v83, v39, v41 offset0:180 offset1:246
	ds_write2_b32 v84, v40, v42 offset0:56 offset1:122
	ds_write2_b32 v84, v43, v44 offset0:188 offset1:254
	s_waitcnt lgkmcnt(0)
	ds_read2_b32 v[14:15], v8 offset1:33
	s_waitcnt lgkmcnt(0)
	v_cvt_pk_bf16_f32 v14, v14, v15
	ds_read2_b32 v[16:17], v8 offset0:66 offset1:99
	s_waitcnt lgkmcnt(0)
	v_cvt_pk_bf16_f32 v15, v16, v17
	ds_read2_b32 v[16:17], v8 offset0:132 offset1:165
	v_lshl_add_u64 v[20:21], s[6:7], 0, v[2:3]
	v_mul_hi_i32_i24_e32 v23, s8, v5
	v_mul_i32_i24_e32 v22, s8, v5
	s_waitcnt lgkmcnt(0)
	v_cvt_pk_bf16_f32 v16, v16, v17
	ds_read2_b32 v[18:19], v8 offset0:198 offset1:231
	s_waitcnt lgkmcnt(0)
	v_cvt_pk_bf16_f32 v17, v18, v19
	v_lshl_add_u64 v[22:23], v[22:23], 1, v[20:21]
	ds_read2_b32 v[18:19], v8 offset0:8 offset1:41
	global_store_dwordx4 v[22:23], v[14:17], off sc1
	v_mul_hi_i32_i24_e32 v23, s8, v9
	v_mul_i32_i24_e32 v22, s8, v9
	s_waitcnt lgkmcnt(0)
	v_cvt_pk_bf16_f32 v14, v18, v19
	ds_read2_b32 v[16:17], v8 offset0:74 offset1:107
	s_waitcnt lgkmcnt(0)
	v_cvt_pk_bf16_f32 v15, v16, v17
	ds_read2_b32 v[16:17], v8 offset0:140 offset1:173
	s_waitcnt lgkmcnt(0)
	v_cvt_pk_bf16_f32 v16, v16, v17
	ds_read2_b32 v[18:19], v8 offset0:206 offset1:239
	s_waitcnt lgkmcnt(0)
	v_cvt_pk_bf16_f32 v17, v18, v19
	v_lshl_add_u64 v[22:23], v[22:23], 1, v[20:21]
	ds_read2_b32 v[18:19], v8 offset0:16 offset1:49
	global_store_dwordx4 v[22:23], v[14:17], off sc1
	v_mul_hi_i32_i24_e32 v23, s8, v10
	v_mul_i32_i24_e32 v22, s8, v10
	s_waitcnt lgkmcnt(0)
	v_cvt_pk_bf16_f32 v14, v18, v19
	ds_read2_b32 v[16:17], v8 offset0:82 offset1:115
	s_waitcnt lgkmcnt(0)
	v_cvt_pk_bf16_f32 v15, v16, v17
	ds_read2_b32 v[16:17], v8 offset0:148 offset1:181
	s_waitcnt lgkmcnt(0)
	v_cvt_pk_bf16_f32 v16, v16, v17
	ds_read2_b32 v[18:19], v8 offset0:214 offset1:247
	s_waitcnt lgkmcnt(0)
	v_cvt_pk_bf16_f32 v17, v18, v19
	v_lshl_add_u64 v[22:23], v[22:23], 1, v[20:21]
	ds_read2_b32 v[18:19], v8 offset0:24 offset1:57
	global_store_dwordx4 v[22:23], v[14:17], off sc1
	s_mov_b64 s[6:7], -1
	s_waitcnt lgkmcnt(0)
	v_cvt_pk_bf16_f32 v14, v18, v19
	ds_read2_b32 v[16:17], v8 offset0:90 offset1:123
	s_waitcnt lgkmcnt(0)
	v_cvt_pk_bf16_f32 v15, v16, v17
	ds_read2_b32 v[16:17], v8 offset0:156 offset1:189
	s_waitcnt lgkmcnt(0)
	v_cvt_pk_bf16_f32 v16, v16, v17
	ds_read2_b32 v[18:19], v8 offset0:222 offset1:255
	s_waitcnt lgkmcnt(0)
	v_cvt_pk_bf16_f32 v17, v18, v19
	v_mul_hi_i32_i24_e32 v19, s8, v11
	v_mul_i32_i24_e32 v18, s8, v11
	v_lshl_add_u64 v[18:19], v[18:19], 1, v[20:21]
	global_store_dwordx4 v[18:19], v[14:17], off sc1
	s_waitcnt lgkmcnt(0)
	s_mul_i32 s8, s4, s82
	s_add_i32 s8, s8, s3
	s_cmpk_lt_i32 s8, 0x1680
	s_cbranch_scc0 .LBB0_97
	s_cmpk_lt_i32 s8, 0x1080
	s_cbranch_scc0 .LBB0_94
	s_add_i32 s4, s8, 0xb00
	s_cmpk_gt_i32 s8, 0xaff
	s_cselect_b32 s47, s4, s8
	s_mov_b64 s[6:7], 0

.LBB0_119:
	v_mul_u32_u24_e32 v7, s40, v1
	v_lshlrev_b32_e32 v14, 2, v7
	v_mov_b32_e32 v15, v3
	v_lshl_add_u64 v[14:15], s[38:39], 0, v[14:15]
	v_mov_b32_e32 v7, v3
	v_lshl_add_u64 v[14:15], v[14:15], 0, v[6:7]
	s_lshl_b64 s[38:39], s[40:41], 3
	v_lshl_add_u64 v[16:17], v[14:15], 0, s[38:39]
	v_lshl_add_u64 v[18:19], v[16:17], 0, s[38:39]
	v_lshl_add_u64 v[20:21], v[18:19], 0, s[38:39]
	v_lshl_add_u64 v[24:25], v[20:21], 0, s[38:39]
	v_lshl_add_u64 v[26:27], v[24:25], 0, s[38:39]
	v_lshl_add_u64 v[30:31], v[26:27], 0, s[38:39]
	v_lshl_add_u64 v[32:33], v[30:31], 0, s[38:39]
	global_load_dword v37, v[14:15], off nt
	global_load_dword v36, v[16:17], off nt
	global_load_dword v35, v[18:19], off nt
	global_load_dword v34, v[20:21], off nt
	global_load_dword v29, v[24:25], off nt
	global_load_dword v28, v[26:27], off nt
	global_load_dword v23, v[30:31], off nt
	global_load_dword v22, v[32:33], off nt
	v_lshl_add_u64 v[14:15], v[32:33], 0, s[38:39]
	global_load_dword v32, v[14:15], off nt
	v_lshl_add_u64 v[14:15], v[14:15], 0, s[38:39]
	global_load_dword v33, v[14:15], off nt
	v_lshl_add_u64 v[14:15], v[14:15], 0, s[38:39]
	global_load_dword v30, v[14:15], off nt
	v_lshl_add_u64 v[14:15], v[14:15], 0, s[38:39]
	global_load_dword v31, v[14:15], off nt
	v_lshl_add_u64 v[14:15], v[14:15], 0, s[38:39]
	global_load_dword v26, v[14:15], off nt
	v_lshl_add_u64 v[14:15], v[14:15], 0, s[38:39]
	global_load_dword v27, v[14:15], off nt
	v_lshl_add_u64 v[14:15], v[14:15], 0, s[38:39]
	global_load_dword v24, v[14:15], off nt
	v_lshl_add_u64 v[14:15], v[14:15], 0, s[38:39]
	global_load_dword v25, v[14:15], off nt
	v_lshl_add_u64 v[14:15], v[14:15], 0, s[38:39]
	global_load_dword v20, v[14:15], off nt
	v_lshl_add_u64 v[14:15], v[14:15], 0, s[38:39]
	global_load_dword v21, v[14:15], off nt
	v_lshl_add_u64 v[14:15], v[14:15], 0, s[38:39]
	global_load_dword v18, v[14:15], off nt
	v_lshl_add_u64 v[14:15], v[14:15], 0, s[38:39]
	global_load_dword v19, v[14:15], off nt
	v_lshl_add_u64 v[14:15], v[14:15], 0, s[38:39]
	global_load_dword v16, v[14:15], off nt
	v_lshl_add_u64 v[14:15], v[14:15], 0, s[38:39]
	v_lshl_add_u64 v[38:39], v[14:15], 0, s[38:39]
	global_load_dword v17, v[14:15], off nt
	s_cmp_ge_i32 s44, s33
	global_load_dword v14, v[38:39], off nt
	v_lshl_add_u64 v[38:39], v[38:39], 0, s[38:39]
	global_load_dword v15, v[38:39], off nt
	v_lshl_add_u64 v[38:39], v[38:39], 0, s[38:39]
	v_lshl_add_u64 v[40:41], v[38:39], 0, s[38:39]
	global_load_dword v13, v[38:39], off nt
	s_nop 0
	global_load_dword v38, v[40:41], off nt
	v_lshl_add_u64 v[40:41], v[40:41], 0, s[38:39]
	v_lshl_add_u64 v[42:43], v[40:41], 0, s[38:39]
	global_load_dword v39, v[40:41], off nt
	s_nop 0
	global_load_dword v41, v[42:43], off nt
	v_lshl_add_u64 v[42:43], v[42:43], 0, s[38:39]
	v_lshl_add_u64 v[86:87], v[42:43], 0, s[38:39]
	global_load_dword v40, v[42:43], off nt
	s_nop 0
	global_load_dword v42, v[86:87], off nt
	v_lshl_add_u64 v[86:87], v[86:87], 0, s[38:39]
	global_load_dword v43, v[86:87], off nt
	v_lshl_add_u64 v[86:87], v[86:87], 0, s[38:39]
	global_load_dword v44, v[86:87], off nt
	s_cbranch_scc1 .LBB0_62
	s_waitcnt vmcnt(62)
	ds_write2_b32 v12, v45, v46 offset1:66
	ds_write2_b32 v12, v47, v48 offset0:132 offset1:198
	ds_write2_b32 v78, v49, v50 offset0:8 offset1:74
	s_waitcnt vmcnt(60)
	ds_write2_b32 v78, v51, v52 offset0:140 offset1:206
	s_waitcnt vmcnt(58)
	ds_write2_b32 v79, v53, v54 offset0:16 offset1:82
	s_waitcnt vmcnt(56)
	ds_write2_b32 v79, v55, v56 offset0:148 offset1:214
	s_waitcnt vmcnt(54)
	ds_write2_b32 v80, v57, v58 offset0:24 offset1:90
	s_waitcnt vmcnt(52)
	ds_write2_b32 v80, v59, v60 offset0:156 offset1:222
	s_waitcnt vmcnt(50)
	ds_write2_b32 v81, v61, v62 offset0:32 offset1:98
	s_waitcnt vmcnt(48)
	ds_write2_b32 v81, v63, v64 offset0:164 offset1:230
	s_waitcnt vmcnt(46)
	ds_write2_b32 v82, v65, v67 offset0:40 offset1:106
	s_waitcnt vmcnt(44)
	ds_write2_b32 v82, v68, v69 offset0:172 offset1:238
	s_waitcnt vmcnt(42)
	ds_write2_b32 v83, v70, v71 offset0:48 offset1:114
	s_waitcnt vmcnt(40)
	ds_write2_b32 v83, v72, v73 offset0:180 offset1:246
	s_waitcnt vmcnt(38)
	ds_write2_b32 v84, v74, v75 offset0:56 offset1:122
	s_waitcnt vmcnt(36)
	ds_write2_b32 v84, v76, v77 offset0:188 offset1:254
	s_waitcnt lgkmcnt(0)
	ds_read2_b32 v[46:47], v8 offset1:33
	s_waitcnt lgkmcnt(0)
	v_cvt_pk_bf16_f32 v46, v46, v47
	ds_read2_b32 v[48:49], v8 offset0:66 offset1:99
	v_lshl_add_u64 v[52:53], s[16:17], 0, v[2:3]
	v_mul_u32_u24_e32 v2, s18, v5
	s_waitcnt lgkmcnt(0)
	v_cvt_pk_bf16_f32 v47, v48, v49
	ds_read2_b32 v[48:49], v8 offset0:132 offset1:165
	v_lshlrev_b32_e32 v2, 1, v2
	s_waitcnt lgkmcnt(0)
	v_cvt_pk_bf16_f32 v48, v48, v49
	ds_read2_b32 v[50:51], v8 offset0:198 offset1:231
	s_waitcnt lgkmcnt(0)
	v_cvt_pk_bf16_f32 v49, v50, v51
	v_lshl_add_u64 v[54:55], v[52:53], 0, v[2:3]
	ds_read2_b32 v[50:51], v8 offset0:8 offset1:41
	global_store_dwordx4 v[54:55], v[46:49], off sc1
	v_mul_u32_u24_e32 v2, s18, v9
	v_lshlrev_b32_e32 v2, 1, v2
	s_waitcnt lgkmcnt(0)
	v_cvt_pk_bf16_f32 v46, v50, v51
	ds_read2_b32 v[48:49], v8 offset0:74 offset1:107
	s_waitcnt lgkmcnt(0)
	v_cvt_pk_bf16_f32 v47, v48, v49
	ds_read2_b32 v[48:49], v8 offset0:140 offset1:173
	s_waitcnt lgkmcnt(0)
	v_cvt_pk_bf16_f32 v48, v48, v49
	ds_read2_b32 v[50:51], v8 offset0:206 offset1:239
	s_waitcnt lgkmcnt(0)
	v_cvt_pk_bf16_f32 v49, v50, v51
	v_lshl_add_u64 v[54:55], v[52:53], 0, v[2:3]
	ds_read2_b32 v[50:51], v8 offset0:16 offset1:49
	global_store_dwordx4 v[54:55], v[46:49], off sc1
	v_mul_u32_u24_e32 v2, s18, v10
	v_lshlrev_b32_e32 v2, 1, v2
	s_waitcnt lgkmcnt(0)
	v_cvt_pk_bf16_f32 v46, v50, v51
	ds_read2_b32 v[48:49], v8 offset0:82 offset1:115
	s_waitcnt lgkmcnt(0)
	v_cvt_pk_bf16_f32 v47, v48, v49
	ds_read2_b32 v[48:49], v8 offset0:148 offset1:181
	s_waitcnt lgkmcnt(0)
	v_cvt_pk_bf16_f32 v48, v48, v49
	ds_read2_b32 v[50:51], v8 offset0:214 offset1:247
	s_waitcnt lgkmcnt(0)
	v_cvt_pk_bf16_f32 v49, v50, v51
	v_lshl_add_u64 v[54:55], v[52:53], 0, v[2:3]
	ds_read2_b32 v[50:51], v8 offset0:24 offset1:57
	global_store_dwordx4 v[54:55], v[46:49], off sc1
	v_mul_u32_u24_e32 v2, s18, v11
	v_lshlrev_b32_e32 v2, 1, v2
	s_waitcnt lgkmcnt(0)
	v_cvt_pk_bf16_f32 v46, v50, v51
	ds_read2_b32 v[48:49], v8 offset0:90 offset1:123
	s_waitcnt lgkmcnt(0)
	v_cvt_pk_bf16_f32 v47, v48, v49
	ds_read2_b32 v[48:49], v8 offset0:156 offset1:189
	s_waitcnt lgkmcnt(0)
	v_cvt_pk_bf16_f32 v48, v48, v49
	ds_read2_b32 v[50:51], v8 offset0:222 offset1:255
	s_waitcnt lgkmcnt(0)
	v_cvt_pk_bf16_f32 v49, v50, v51
	v_lshl_add_u64 v[50:51], v[52:53], 0, v[2:3]
	global_store_dwordx4 v[50:51], v[46:49], off sc1
	s_waitcnt lgkmcnt(0)
	s_branch .LBB0_62

.LBB0_123:
	s_or_b64 exec, exec, s[8:9]
	v_add_u32_e32 v11, s16, v11
	v_mul_f32_e32 v13, 0x3d000000, v16
	v_mul_f32_e32 v15, 0x3d000000, v15
	v_mul_f32_e32 v14, 0x3d000000, v14
	v_mul_f32_e32 v12, 0x3d000000, v12
	v_cmp_lt_i32_e64 s[4:5], s27, v11
	v_mul_f32_e32 v19, 0x3d000000, v19
	v_mul_f32_e32 v18, 0x3d000000, v18
	v_mul_f32_e32 v17, 0x3d000000, v17
	v_mul_f32_e32 v16, 0x3d000000, v23
	v_cvt_pk_bf16_f32 v12, v12, v14
	v_cvt_pk_bf16_f32 v13, v15, v13
	v_cvt_pk_bf16_f32 v14, v17, v18
	v_cvt_pk_bf16_f32 v15, v19, v16
	global_store_dwordx4 v[4:5], v[12:15], off sc1
	v_lshl_add_u64 v[4:5], v[4:5], 0, s[20:21]
	s_or_b64 s[22:23], s[4:5], s[22:23]
	v_add_u32_e32 v6, s3, v6
	s_andn2_b64 exec, exec, s[22:23]
	s_cbranch_execz .LBB0_156

.LBB0_158:
	s_or_b64 exec, exec, s[8:9]
	v_add_u32_e32 v11, s16, v11
	v_mul_f32_e32 v13, 0x3d800000, v16
	v_mul_f32_e32 v15, 0x3d800000, v15
	v_mul_f32_e32 v14, 0x3d800000, v14
	v_mul_f32_e32 v12, 0x3d800000, v12
	v_cmp_lt_i32_e64 s[4:5], s27, v11
	v_mul_f32_e32 v19, 0x3d800000, v19
	v_mul_f32_e32 v18, 0x3d800000, v18
	v_mul_f32_e32 v17, 0x3d800000, v17
	v_mul_f32_e32 v16, 0x3d800000, v23
	v_cvt_pk_bf16_f32 v12, v12, v14
	v_cvt_pk_bf16_f32 v13, v15, v13
	v_cvt_pk_bf16_f32 v14, v17, v18
	v_cvt_pk_bf16_f32 v15, v19, v16
	global_store_dwordx4 v[4:5], v[12:15], off sc1
	v_lshl_add_u64 v[4:5], v[4:5], 0, s[20:21]
	s_or_b64 s[22:23], s[4:5], s[22:23]
	v_add_u32_e32 v6, s3, v6
	s_andn2_b64 exec, exec, s[22:23]
	s_cbranch_execz .LBB0_191

.LBB0_193:
	global_load_dwordx4 v[10:13], v[4:5], off offset:-16
	global_load_dwordx4 v[14:17], v[4:5], off
	v_add_u32_e32 v8, s16, v8
	v_cmp_lt_i32_e64 s[4:5], s3, v8
	v_lshl_add_u64 v[4:5], v[4:5], 0, s[8:9]
	s_or_b64 s[20:21], s[4:5], s[20:21]
	s_waitcnt vmcnt(1)
	v_cvt_pk_bf16_f32 v10, v10, v11
	v_cvt_pk_bf16_f32 v11, v12, v13
	s_waitcnt vmcnt(0)
	v_cvt_pk_bf16_f32 v12, v14, v15
	v_cvt_pk_bf16_f32 v13, v16, v17
	global_store_dwordx4 v[6:7], v[10:13], off sc1
	v_lshl_add_u64 v[6:7], v[6:7], 0, s[18:19]
	s_andn2_b64 exec, exec, s[20:21]
	s_cbranch_execnz .LBB0_193

.LBB0_196:
	v_lshrrev_b32_e32 v8, 12, v10
	s_waitcnt vmcnt(7)
	v_and_b32_e32 v13, 12, v8
	v_lshrrev_b32_e32 v12, 3, v10
	v_add_u32_sdwa v13, v13, sext(v10) dst_sel:DWORD dst_unused:UNUSED_PAD src0_sel:DWORD src1_sel:WORD_1
	v_and_b32_e32 v8, 0x700, v12
	v_perm_b32 v12, v13, v12, s17
	v_ashrrev_i32_e32 v13, 31, v12
	v_lshlrev_b64 v[12:13], 11, v[12:13]
	v_and_b32_e32 v11, 56, v3
	v_lshl_add_u64 v[12:13], s[12:13], 0, v[12:13]
	v_lshl_add_u64 v[12:13], v[12:13], 0, v[8:9]
	v_lshlrev_b32_e32 v8, 2, v11
	v_lshl_add_u64 v[20:21], v[12:13], 0, v[8:9]
	global_load_dwordx4 v[12:15], v[20:21], off nt
	global_load_dwordx4 v[16:19], v[20:21], off offset:16 nt
	v_add_u32_e32 v10, s16, v10
	v_cmp_lt_i32_e32 vcc, s18, v10
	v_add_u32_e32 v3, s3, v3
	s_or_b64 s[8:9], vcc, s[8:9]
	s_waitcnt vmcnt(1)
	v_cvt_pk_bf16_f32 v12, v12, v13
	v_cvt_pk_bf16_f32 v13, v14, v15
	s_waitcnt vmcnt(0)
	v_cvt_pk_bf16_f32 v14, v16, v17
	v_cvt_pk_bf16_f32 v15, v18, v19
	global_store_dwordx4 v[6:7], v[12:15], off sc1
	v_lshl_add_u64 v[6:7], v[6:7], 0, s[6:7]
	s_andn2_b64 exec, exec, s[8:9]
	s_cbranch_execnz .LBB0_196
	s_or_b64 exec, exec, s[8:9]
	s_mov_b64 s[8:9], 0xb00000
	v_lshl_add_u64 v[4:5], v[4:5], 0, s[8:9]
	s_mov_b64 s[8:9], 0
	v_mov_b32_e32 v7, 0
	s_movk_i32 s12, 0x1000
	s_movk_i32 s13, 0x2000
	s_movk_i32 s17, 0x3000
	s_mov_b32 s18, 0x3ffff
.LBB0_198:
	v_lshrrev_b32_e32 v6, 12, v2
	v_ashrrev_i32_e32 v3, 16, v2
	v_lshrrev_b32_e32 v8, 3, v2
	v_and_b32_e32 v10, 12, v6
	v_and_b32_e32 v9, 24, v1
	v_and_b32_e32 v11, 0xe0, v8
	v_add_lshl_u32 v3, v10, v3, 8
	v_and_b32_e32 v6, 0x700, v8
	v_or3_b32 v8, v3, v11, v9
	v_ashrrev_i32_e32 v9, 31, v8
	v_lshlrev_b64 v[8:9], 11, v[8:9]
	v_lshl_add_u64 v[8:9], s[14:15], 0, v[8:9]
	v_lshl_add_u64 v[8:9], v[8:9], 0, v[6:7]
	v_and_b32_e32 v6, 0xfc, v2
	v_lshl_add_u64 v[8:9], v[8:9], 0, v[6:7]
	v_add_co_u32_e32 v10, vcc, s12, v8
	v_add_u32_e32 v2, s16, v2
	s_nop 0
	v_addc_co_u32_e32 v11, vcc, 0, v9, vcc
	v_add_co_u32_e32 v12, vcc, s13, v8
	v_add_u32_e32 v1, s3, v1
	s_nop 0
	v_addc_co_u32_e32 v13, vcc, 0, v9, vcc
	v_add_co_u32_e32 v14, vcc, s17, v8
	s_nop 1
	v_addc_co_u32_e32 v15, vcc, 0, v9, vcc
	global_load_dword v3, v[8:9], off offset:2048 nt
	global_load_dword v6, v[10:11], off offset:2048 nt
	global_load_dword v16, v[14:15], off nt
	global_load_dword v17, v[8:9], off nt
	global_load_dword v18, v[12:13], off offset:-4096 nt
	global_load_dword v19, v[12:13], off offset:2048 nt
	global_load_dword v20, v[12:13], off nt
	global_load_dword v21, v[14:15], off offset:2048 nt
	v_cmp_lt_i32_e32 vcc, s18, v2
	s_or_b64 s[8:9], vcc, s[8:9]
	s_waitcnt vmcnt(4)
	v_cvt_pk_bf16_f32 v8, v17, v3
	s_waitcnt vmcnt(3)
	v_cvt_pk_bf16_f32 v9, v18, v6
	s_waitcnt vmcnt(1)
	v_cvt_pk_bf16_f32 v10, v20, v19
	s_waitcnt vmcnt(0)
	v_cvt_pk_bf16_f32 v11, v16, v21
	global_store_dwordx4 v[4:5], v[8:11], off sc1
	v_lshl_add_u64 v[4:5], v[4:5], 0, s[6:7]
	s_andn2_b64 exec, exec, s[8:9]
	s_cbranch_execnz .LBB0_198

.LBB0_267:
	s_waitcnt vmcnt(15)
	v_pk_mul_f32 v[136:137], v[14:15], v[14:15]
	v_pk_mul_f32 v[138:139], v[12:13], v[12:13]
	s_waitcnt vmcnt(14)
	v_pk_mul_f32 v[126:127], v[10:11], v[10:11]
	v_pk_mul_f32 v[134:135], v[8:9], v[8:9]
	v_pk_mov_b32 v[140:141], v[138:139], v[136:137] op_sel:[1,0]
	v_mov_b32_e32 v139, v137
	v_pk_add_f32 v[136:137], v[140:141], v[138:139]
	v_pk_mov_b32 v[138:139], v[134:135], v[126:127] op_sel:[1,0]
	v_mov_b32_e32 v135, v127
	v_pk_add_f32 v[126:127], v[138:139], v[134:135]
	v_pk_add_f32 v[136:137], v[136:137], v[136:137] op_sel_hi:[0,1]
	v_pk_add_f32 v[126:127], v[126:127], v[126:127] op_sel_hi:[0,1]
	s_waitcnt vmcnt(13)
	v_mul_f32_e32 v126, v0, v0
	v_pk_fma_f32 v[134:135], v[0:1], v[0:1], v[126:127] op_sel_hi:[1,1,0]
	v_mul_f32_e32 v126, v2, v2
	v_pk_fma_f32 v[138:139], v[2:3], v[2:3], v[126:127] op_sel_hi:[1,1,0]
	s_waitcnt vmcnt(12)
	v_mul_f32_e32 v134, v4, v4
	v_mul_f32_e32 v138, v5, v5
	v_mul_f32_e32 v136, v6, v6
	v_mul_f32_e32 v126, v7, v7
	v_pk_add_f32 v[134:135], v[134:135], v[138:139]
	v_pk_add_f32 v[126:127], v[136:137], v[126:127]
	s_waitcnt vmcnt(3)
	v_pk_add_f32 v[90:91], v[90:91], 1.0 op_sel_hi:[1,0]
	v_pk_add_f32 v[126:127], v[134:135], v[126:127]
	v_pk_add_f32 v[88:89], v[88:89], 1.0 op_sel_hi:[1,0]
	v_add_f32_e32 v126, v126, v127
	ds_bpermute_b32 v127, v99, v126
	v_pk_add_f32 v[78:79], v[78:79], 1.0 op_sel_hi:[1,0]
	v_pk_add_f32 v[76:77], v[76:77], 1.0 op_sel_hi:[1,0]
	v_pk_add_f32 v[66:67], v[66:67], 1.0 op_sel_hi:[1,0]
	v_pk_add_f32 v[64:65], v[64:65], 1.0 op_sel_hi:[1,0]
	s_waitcnt lgkmcnt(0)
	v_add_f32_e32 v126, v126, v127
	ds_bpermute_b32 v127, v128, v126
	s_waitcnt vmcnt(2)
	v_pk_add_f32 v[54:55], v[54:55], 1.0 op_sel_hi:[1,0]
	v_pk_add_f32 v[52:53], v[52:53], 1.0 op_sel_hi:[1,0]
	v_lshl_add_u64 v[96:97], v[96:97], 0, s[82:83]
	s_waitcnt lgkmcnt(0)
	v_add_f32_e32 v126, v126, v127
	ds_bpermute_b32 v127, v129, v126
	s_waitcnt lgkmcnt(0)
	v_add_f32_e32 v126, v126, v127
	ds_bpermute_b32 v127, v130, v126
	s_waitcnt lgkmcnt(0)
	v_add_f32_e32 v126, v126, v127
	ds_bpermute_b32 v127, v131, v126
	s_waitcnt lgkmcnt(0)
	v_add_f32_e32 v126, v126, v127
	ds_bpermute_b32 v127, v132, v126
	s_waitcnt lgkmcnt(0)
	v_add_f32_e32 v126, v126, v127
	v_fmamk_f32 v126, v126, 0x3a800000, v146
	v_cmp_gt_f32_e32 vcc, s72, v126
	v_mul_f32_e32 v127, 0x4b800000, v126
	s_nop 0
	v_cndmask_b32_e32 v126, v126, v127, vcc
	v_rsq_f32_e32 v126, v126
	s_nop 0
	v_mul_f32_e32 v127, 0x45800000, v126
	v_cndmask_b32_e32 v126, v126, v127, vcc
	v_pk_mul_f32 v[134:135], v[14:15], v[126:127] op_sel_hi:[1,0]
	v_pk_mul_f32 v[136:137], v[12:13], v[126:127] op_sel_hi:[1,0]
	v_pk_mul_f32 v[94:95], v[94:95], v[134:135]
	v_pk_mul_f32 v[92:93], v[92:93], v[136:137]
	v_pk_fma_f32 v[86:87], v[90:91], v[94:95], v[86:87]
	v_pk_fma_f32 v[84:85], v[88:89], v[92:93], v[84:85]
	v_pk_mul_f32 v[88:89], v[8:9], v[126:127] op_sel_hi:[1,0]
	v_cvt_pk_bf16_f32 v84, v84, v85
	v_cvt_pk_bf16_f32 v85, v86, v87
	v_pk_mul_f32 v[86:87], v[10:11], v[126:127] op_sel_hi:[1,0]
	v_pk_mul_f32 v[80:81], v[80:81], v[88:89]
	v_pk_mul_f32 v[82:83], v[82:83], v[86:87]
	v_pk_fma_f32 v[72:73], v[76:77], v[80:81], v[72:73]
	v_pk_fma_f32 v[74:75], v[78:79], v[82:83], v[74:75]
	v_cvt_pk_bf16_f32 v72, v72, v73
	v_pk_mul_f32 v[76:77], v[0:1], v[126:127] op_sel_hi:[1,0]
	v_cvt_pk_bf16_f32 v73, v74, v75
	v_pk_mul_f32 v[74:75], v[2:3], v[126:127] op_sel_hi:[1,0]
	s_waitcnt vmcnt(1)
	v_pk_mul_f32 v[68:69], v[68:69], v[76:77]
	v_pk_mul_f32 v[70:71], v[70:71], v[74:75]
	v_pk_fma_f32 v[60:61], v[64:65], v[68:69], v[60:61]
	v_pk_fma_f32 v[62:63], v[66:67], v[70:71], v[62:63]
	v_cvt_pk_bf16_f32 v60, v60, v61
	v_pk_mul_f32 v[64:65], v[4:5], v[126:127] op_sel_hi:[1,0]
	v_cvt_pk_bf16_f32 v61, v62, v63
	v_pk_mul_f32 v[62:63], v[6:7], v[126:127] op_sel_hi:[1,0]
	s_waitcnt vmcnt(0)
	v_pk_mul_f32 v[56:57], v[56:57], v[64:65]
	v_pk_mul_f32 v[58:59], v[58:59], v[62:63]
	v_pk_fma_f32 v[48:49], v[52:53], v[56:57], v[48:49]
	v_pk_fma_f32 v[50:51], v[54:55], v[58:59], v[50:51]
	v_cvt_pk_bf16_f32 v48, v48, v49
	v_mov_b64_e32 v[54:55], v[38:39]
	v_cvt_pk_bf16_f32 v49, v50, v51
	v_lshl_add_u64 v[50:51], s[8:9], 0, v[108:109]
	global_store_dwordx4 v[50:51], v[12:15], off sc1
	global_store_dwordx4 v[50:51], v[8:11], off offset:1024 sc1
	global_store_dwordx4 v[50:51], v[0:3], off offset:2048 sc1
	global_store_dwordx4 v[50:51], v[4:7], off offset:3072 sc1
	v_mov_b64_e32 v[58:59], v[30:31]
	v_add_co_u32_e32 v0, vcc, s74, v106
	v_mov_b64_e32 v[66:67], v[42:43]
	s_nop 0
	v_addc_co_u32_e32 v1, vcc, -1, v107, vcc
	global_store_dwordx2 v[0:1], v[84:85], off offset:-1536 sc1
	global_store_dwordx2 v[0:1], v[72:73], off offset:-1024 sc1
	global_store_dwordx2 v[0:1], v[60:61], off offset:-512 sc1
	global_store_dwordx2 v[0:1], v[48:49], off sc1
	v_cmp_lt_i32_e32 vcc, s75, v96
	v_mov_b64_e32 v[50:51], v[46:47]
	v_mov_b64_e32 v[62:63], v[18:19]
	v_mov_b64_e32 v[70:71], v[34:35]
	v_mov_b64_e32 v[74:75], v[26:27]
	v_mov_b64_e32 v[78:79], v[22:23]
	v_lshl_add_u64 v[106:107], v[106:107], 0, s[84:85]
	v_lshl_add_u64 v[108:109], v[108:109], 0, s[34:35]
	s_or_b64 s[10:11], vcc, s[10:11]
	v_mov_b64_e32 v[48:49], v[44:45]
	v_mov_b64_e32 v[52:53], v[36:37]
	v_mov_b64_e32 v[56:57], v[28:29]
	v_mov_b64_e32 v[60:61], v[16:17]
	v_mov_b64_e32 v[64:65], v[40:41]
	v_mov_b64_e32 v[68:69], v[32:33]
	v_mov_b64_e32 v[72:73], v[24:25]
	v_mov_b64_e32 v[76:77], v[20:21]
	v_mov_b64_e32 v[80:81], v[122:123]
	v_mov_b64_e32 v[82:83], v[116:117]
	v_mov_b64_e32 v[84:85], v[112:113]
	v_mov_b64_e32 v[86:87], v[110:111]
	v_mov_b64_e32 v[88:89], v[124:125]
	v_mov_b64_e32 v[90:91], v[120:121]
	v_mov_b64_e32 v[92:93], v[118:119]
	v_mov_b64_e32 v[94:95], v[114:115]
	s_andn2_b64 exec, exec, s[10:11]
	s_cbranch_execz .LBB0_280

.LBB0_348:
	v_mul_f32_e32 v155, 0xbfb8aa3b, v124
	v_exp_f32_e32 v155, v155
	v_lshl_or_b32 v138, s25, 7, v142
	v_ashrrev_i32_e32 v139, 31, v138
	v_lshl_add_u32 v154, s24, 8, v140
	v_add_f32_e32 v155, 1.0, v155
	v_rcp_f32_e32 v155, v155
	v_lshl_add_u64 v[138:139], v[138:139], 1, s[12:13]
	s_andn2_b64 vcc, exec, s[0:1]
	v_mul_f32_e32 v124, v124, v155
	v_mul_f32_e32 v120, v124, v120
	v_mul_f32_e32 v124, 0xbfb8aa3b, v125
	v_exp_f32_e32 v124, v124
	s_nop 0
	v_add_f32_e32 v124, 1.0, v124
	v_rcp_f32_e32 v124, v124
	s_nop 0
	v_mul_f32_e32 v124, v125, v124
	v_mul_f32_e32 v121, v124, v121
	v_cvt_pk_bf16_f32 v120, v120, v121
	v_mul_f32_e32 v121, 0xbfb8aa3b, v126
	v_exp_f32_e32 v121, v121
	s_nop 0
	v_add_f32_e32 v121, 1.0, v121
	v_rcp_f32_e32 v121, v121
	s_nop 0
	v_mul_f32_e32 v121, v126, v121
	v_mul_f32_e32 v121, v121, v122
	v_mul_f32_e32 v122, 0xbfb8aa3b, v127
	v_exp_f32_e32 v122, v122
	s_nop 0
	v_add_f32_e32 v122, 1.0, v122
	v_rcp_f32_e32 v122, v122
	s_nop 0
	v_mul_f32_e32 v122, v127, v122
	v_mul_f32_e32 v122, v122, v123
	v_cvt_pk_bf16_f32 v121, v121, v122
	v_mul_f32_e32 v122, 0xbfb8aa3b, v116
	v_exp_f32_e32 v122, v122
	s_nop 0
	v_add_f32_e32 v122, 1.0, v122
	v_rcp_f32_e32 v122, v122
	s_nop 0
	v_mul_f32_e32 v116, v116, v122
	v_mul_f32_e32 v112, v116, v112
	v_mul_f32_e32 v116, 0xbfb8aa3b, v117
	v_exp_f32_e32 v116, v116
	s_nop 0
	v_add_f32_e32 v116, 1.0, v116
	v_rcp_f32_e32 v116, v116
	s_nop 0
	v_mul_f32_e32 v116, v117, v116
	v_mul_f32_e32 v113, v116, v113
	v_cvt_pk_bf16_f32 v122, v112, v113
	v_mul_f32_e32 v112, 0xbfb8aa3b, v118
	v_mul_f32_e32 v113, 0xbfb8aa3b, v119
	v_exp_f32_e32 v112, v112
	v_exp_f32_e32 v113, v113
	v_add_f32_e32 v112, 1.0, v112
	v_add_f32_e32 v113, 1.0, v113
	v_rcp_f32_e32 v112, v112
	v_rcp_f32_e32 v113, v113
	v_mul_f32_e32 v112, v118, v112
	v_mul_f32_e32 v113, v119, v113
	v_mul_f32_e32 v112, v112, v114
	v_mul_f32_e32 v113, v113, v115
	v_cvt_pk_bf16_f32 v123, v112, v113
	v_mad_i64_i32 v[112:113], s[24:25], v154, s68, v[138:139]
	global_store_dwordx4 v[112:113], v[120:123], off sc1
	v_mul_f32_e32 v112, 0xbfb8aa3b, v108
	v_exp_f32_e32 v112, v112
	s_nop 0
	v_add_f32_e32 v112, 1.0, v112
	v_rcp_f32_e32 v112, v112
	s_nop 0
	v_mul_f32_e32 v108, v108, v112
	v_mul_f32_e32 v104, v108, v104
	v_mul_f32_e32 v108, 0xbfb8aa3b, v109
	v_exp_f32_e32 v108, v108
	s_nop 0
	v_add_f32_e32 v108, 1.0, v108
	v_rcp_f32_e32 v108, v108
	s_nop 0
	v_mul_f32_e32 v108, v109, v108
	v_mul_f32_e32 v105, v108, v105
	v_cvt_pk_bf16_f32 v104, v104, v105
	v_mul_f32_e32 v105, 0xbfb8aa3b, v110
	v_exp_f32_e32 v105, v105
	s_nop 0
	v_add_f32_e32 v105, 1.0, v105
	v_rcp_f32_e32 v105, v105
	s_nop 0
	v_mul_f32_e32 v105, v110, v105
	v_mul_f32_e32 v105, v105, v106
	v_mul_f32_e32 v106, 0xbfb8aa3b, v111
	v_exp_f32_e32 v106, v106
	s_nop 0
	v_add_f32_e32 v106, 1.0, v106
	v_rcp_f32_e32 v106, v106
	s_nop 0
	v_mul_f32_e32 v106, v111, v106
	v_mul_f32_e32 v106, v106, v107
	v_cvt_pk_bf16_f32 v105, v105, v106
	v_mul_f32_e32 v106, 0xbfb8aa3b, v100
	v_exp_f32_e32 v106, v106
	s_nop 0
	v_add_f32_e32 v106, 1.0, v106
	v_rcp_f32_e32 v106, v106
	s_nop 0
	v_mul_f32_e32 v100, v100, v106
	v_mul_f32_e32 v96, v100, v96
	v_mul_f32_e32 v100, 0xbfb8aa3b, v101
	v_exp_f32_e32 v100, v100
	s_nop 0
	v_add_f32_e32 v100, 1.0, v100
	v_rcp_f32_e32 v100, v100
	s_nop 0
	v_mul_f32_e32 v100, v101, v100
	v_mul_f32_e32 v97, v100, v97
	v_cvt_pk_bf16_f32 v106, v96, v97
	v_mul_f32_e32 v96, 0xbfb8aa3b, v102
	v_exp_f32_e32 v96, v96
	v_mul_f32_e32 v97, 0xbfb8aa3b, v103
	v_exp_f32_e32 v97, v97
	v_add_f32_e32 v96, 1.0, v96
	v_rcp_f32_e32 v96, v96
	v_add_f32_e32 v97, 1.0, v97
	v_rcp_f32_e32 v97, v97
	v_mul_f32_e32 v96, v102, v96
	v_mul_f32_e32 v96, v96, v98
	v_mul_f32_e32 v97, v103, v97
	v_mul_f32_e32 v97, v97, v99
	v_cvt_pk_bf16_f32 v107, v96, v97
	v_or_b32_e32 v96, 16, v154
	v_mad_i64_i32 v[96:97], s[24:25], v96, s68, v[138:139]
	global_store_dwordx4 v[96:97], v[104:107], off sc1
	v_mul_f32_e32 v96, 0xbfb8aa3b, v92
	v_exp_f32_e32 v96, v96
	s_nop 0
	v_add_f32_e32 v96, 1.0, v96
	v_rcp_f32_e32 v96, v96
	s_nop 0
	v_mul_f32_e32 v92, v92, v96
	v_mul_f32_e32 v88, v92, v88
	v_mul_f32_e32 v92, 0xbfb8aa3b, v93
	v_exp_f32_e32 v92, v92
	s_nop 0
	v_add_f32_e32 v92, 1.0, v92
	v_rcp_f32_e32 v92, v92
	s_nop 0
	v_mul_f32_e32 v92, v93, v92
	v_mul_f32_e32 v89, v92, v89
	v_cvt_pk_bf16_f32 v88, v88, v89
	v_mul_f32_e32 v89, 0xbfb8aa3b, v94
	v_exp_f32_e32 v89, v89
	s_nop 0
	v_add_f32_e32 v89, 1.0, v89
	v_rcp_f32_e32 v89, v89
	s_nop 0
	v_mul_f32_e32 v89, v94, v89
	v_mul_f32_e32 v89, v89, v90
	v_mul_f32_e32 v90, 0xbfb8aa3b, v95
	v_exp_f32_e32 v90, v90
	s_nop 0
	v_add_f32_e32 v90, 1.0, v90
	v_rcp_f32_e32 v90, v90
	s_nop 0
	v_mul_f32_e32 v90, v95, v90
	v_mul_f32_e32 v90, v90, v91
	v_cvt_pk_bf16_f32 v89, v89, v90
	v_mul_f32_e32 v90, 0xbfb8aa3b, v84
	v_exp_f32_e32 v90, v90
	s_nop 0
	v_add_f32_e32 v90, 1.0, v90
	v_rcp_f32_e32 v90, v90
	s_nop 0
	v_mul_f32_e32 v84, v84, v90
	v_mul_f32_e32 v80, v84, v80
	v_mul_f32_e32 v84, 0xbfb8aa3b, v85
	v_exp_f32_e32 v84, v84
	s_nop 0
	v_add_f32_e32 v84, 1.0, v84
	v_rcp_f32_e32 v84, v84
	s_nop 0
	v_mul_f32_e32 v84, v85, v84
	v_mul_f32_e32 v81, v84, v81
	v_cvt_pk_bf16_f32 v90, v80, v81
	v_mul_f32_e32 v80, 0xbfb8aa3b, v86
	v_exp_f32_e32 v80, v80
	v_mul_f32_e32 v81, 0xbfb8aa3b, v87
	v_exp_f32_e32 v81, v81
	v_add_f32_e32 v80, 1.0, v80
	v_rcp_f32_e32 v80, v80
	v_add_f32_e32 v81, 1.0, v81
	v_rcp_f32_e32 v81, v81
	v_mul_f32_e32 v80, v86, v80
	v_mul_f32_e32 v80, v80, v82
	v_mul_f32_e32 v81, v87, v81
	v_mul_f32_e32 v81, v81, v83
	v_cvt_pk_bf16_f32 v91, v80, v81
	v_or_b32_e32 v80, 32, v154
	v_mad_i64_i32 v[80:81], s[24:25], v80, s68, v[138:139]
	global_store_dwordx4 v[80:81], v[88:91], off sc1
	v_mul_f32_e32 v80, 0xbfb8aa3b, v76
	v_exp_f32_e32 v80, v80
	s_nop 0
	v_add_f32_e32 v80, 1.0, v80
	v_rcp_f32_e32 v80, v80
	s_nop 0
	v_mul_f32_e32 v76, v76, v80
	v_mul_f32_e32 v72, v76, v72
	v_mul_f32_e32 v76, 0xbfb8aa3b, v77
	v_exp_f32_e32 v76, v76
	s_nop 0
	v_add_f32_e32 v76, 1.0, v76
	v_rcp_f32_e32 v76, v76
	s_nop 0
	v_mul_f32_e32 v76, v77, v76
	v_mul_f32_e32 v73, v76, v73
	v_cvt_pk_bf16_f32 v72, v72, v73
	v_mul_f32_e32 v73, 0xbfb8aa3b, v78
	v_exp_f32_e32 v73, v73
	s_nop 0
	v_add_f32_e32 v73, 1.0, v73
	v_rcp_f32_e32 v73, v73
	s_nop 0
	v_mul_f32_e32 v73, v78, v73
	v_mul_f32_e32 v73, v73, v74
	v_mul_f32_e32 v74, 0xbfb8aa3b, v79
	v_exp_f32_e32 v74, v74
	s_nop 0
	v_add_f32_e32 v74, 1.0, v74
	v_rcp_f32_e32 v74, v74
	s_nop 0
	v_mul_f32_e32 v74, v79, v74
	v_mul_f32_e32 v74, v74, v75
	v_cvt_pk_bf16_f32 v73, v73, v74
	v_mul_f32_e32 v74, 0xbfb8aa3b, v68
	v_exp_f32_e32 v74, v74
	s_nop 0
	v_add_f32_e32 v74, 1.0, v74
	v_rcp_f32_e32 v74, v74
	s_nop 0
	v_mul_f32_e32 v68, v68, v74
	v_mul_f32_e32 v64, v68, v64
	v_mul_f32_e32 v68, 0xbfb8aa3b, v69
	v_exp_f32_e32 v68, v68
	s_nop 0
	v_add_f32_e32 v68, 1.0, v68
	v_rcp_f32_e32 v68, v68
	s_nop 0
	v_mul_f32_e32 v68, v69, v68
	v_mul_f32_e32 v65, v68, v65
	v_cvt_pk_bf16_f32 v74, v64, v65
	v_mul_f32_e32 v64, 0xbfb8aa3b, v70
	v_exp_f32_e32 v64, v64
	v_mul_f32_e32 v65, 0xbfb8aa3b, v71
	v_exp_f32_e32 v65, v65
	v_add_f32_e32 v64, 1.0, v64
	v_rcp_f32_e32 v64, v64
	v_add_f32_e32 v65, 1.0, v65
	v_rcp_f32_e32 v65, v65
	v_mul_f32_e32 v64, v70, v64
	v_mul_f32_e32 v64, v64, v66
	v_mul_f32_e32 v65, v71, v65
	v_mul_f32_e32 v65, v65, v67
	v_cvt_pk_bf16_f32 v75, v64, v65
	v_or_b32_e32 v64, 48, v154
	v_mad_i64_i32 v[64:65], s[24:25], v64, s68, v[138:139]
	global_store_dwordx4 v[64:65], v[72:75], off sc1
	v_mul_f32_e32 v65, 0xbfb8aa3b, v60
	v_exp_f32_e32 v65, v65
	v_add_u32_e32 v64, 0x80, v154
	v_add_f32_e32 v65, 1.0, v65
	v_rcp_f32_e32 v65, v65
	s_nop 0
	v_mul_f32_e32 v60, v60, v65
	v_mul_f32_e32 v56, v60, v56
	v_mul_f32_e32 v60, 0xbfb8aa3b, v61
	v_exp_f32_e32 v60, v60
	s_nop 0
	v_add_f32_e32 v60, 1.0, v60
	v_rcp_f32_e32 v60, v60
	s_nop 0
	v_mul_f32_e32 v60, v61, v60
	v_mul_f32_e32 v57, v60, v57
	v_cvt_pk_bf16_f32 v56, v56, v57
	v_mul_f32_e32 v57, 0xbfb8aa3b, v62
	v_exp_f32_e32 v57, v57
	s_nop 0
	v_add_f32_e32 v57, 1.0, v57
	v_rcp_f32_e32 v57, v57
	s_nop 0
	v_mul_f32_e32 v57, v62, v57
	v_mul_f32_e32 v57, v57, v58
	v_mul_f32_e32 v58, 0xbfb8aa3b, v63
	v_exp_f32_e32 v58, v58
	s_nop 0
	v_add_f32_e32 v58, 1.0, v58
	v_rcp_f32_e32 v58, v58
	s_nop 0
	v_mul_f32_e32 v58, v63, v58
	v_mul_f32_e32 v58, v58, v59
	v_cvt_pk_bf16_f32 v57, v57, v58
	v_mul_f32_e32 v58, 0xbfb8aa3b, v52
	v_exp_f32_e32 v58, v58
	s_nop 0
	v_add_f32_e32 v58, 1.0, v58
	v_rcp_f32_e32 v58, v58
	s_nop 0
	v_mul_f32_e32 v52, v52, v58
	v_mul_f32_e32 v48, v52, v48
	v_mul_f32_e32 v52, 0xbfb8aa3b, v53
	v_exp_f32_e32 v52, v52
	s_nop 0
	v_add_f32_e32 v52, 1.0, v52
	v_rcp_f32_e32 v52, v52
	s_nop 0
	v_mul_f32_e32 v52, v53, v52
	v_mul_f32_e32 v49, v52, v49
	v_cvt_pk_bf16_f32 v58, v48, v49
	v_mul_f32_e32 v48, 0xbfb8aa3b, v54
	v_mul_f32_e32 v49, 0xbfb8aa3b, v55
	v_exp_f32_e32 v48, v48
	v_exp_f32_e32 v49, v49
	v_add_f32_e32 v48, 1.0, v48
	v_add_f32_e32 v49, 1.0, v49
	v_rcp_f32_e32 v48, v48
	v_rcp_f32_e32 v49, v49
	v_mul_f32_e32 v48, v54, v48
	v_mul_f32_e32 v49, v55, v49
	v_mul_f32_e32 v48, v48, v50
	v_mul_f32_e32 v49, v49, v51
	v_cvt_pk_bf16_f32 v59, v48, v49
	v_mad_i64_i32 v[48:49], s[24:25], v64, s68, v[138:139]
	global_store_dwordx4 v[48:49], v[56:59], off sc1
	v_mul_f32_e32 v48, 0xbfb8aa3b, v44
	v_exp_f32_e32 v48, v48
	s_nop 0
	v_add_f32_e32 v48, 1.0, v48
	v_rcp_f32_e32 v48, v48
	s_nop 0
	v_mul_f32_e32 v44, v44, v48
	v_mul_f32_e32 v40, v44, v40
	v_mul_f32_e32 v44, 0xbfb8aa3b, v45
	v_exp_f32_e32 v44, v44
	s_nop 0
	v_add_f32_e32 v44, 1.0, v44
	v_rcp_f32_e32 v44, v44
	s_nop 0
	v_mul_f32_e32 v44, v45, v44
	v_mul_f32_e32 v41, v44, v41
	v_cvt_pk_bf16_f32 v40, v40, v41
	v_mul_f32_e32 v41, 0xbfb8aa3b, v46
	v_exp_f32_e32 v41, v41
	s_nop 0
	v_add_f32_e32 v41, 1.0, v41
	v_rcp_f32_e32 v41, v41
	s_nop 0
	v_mul_f32_e32 v41, v46, v41
	v_mul_f32_e32 v41, v41, v42
	v_mul_f32_e32 v42, 0xbfb8aa3b, v47
	v_exp_f32_e32 v42, v42
	s_nop 0
	v_add_f32_e32 v42, 1.0, v42
	v_rcp_f32_e32 v42, v42
	s_nop 0
	v_mul_f32_e32 v42, v47, v42
	v_mul_f32_e32 v42, v42, v43
	v_cvt_pk_bf16_f32 v41, v41, v42
	v_mul_f32_e32 v42, 0xbfb8aa3b, v36
	v_exp_f32_e32 v42, v42
	s_nop 0
	v_add_f32_e32 v42, 1.0, v42
	v_rcp_f32_e32 v42, v42
	s_nop 0
	v_mul_f32_e32 v36, v36, v42
	v_mul_f32_e32 v32, v36, v32
	v_mul_f32_e32 v36, 0xbfb8aa3b, v37
	v_exp_f32_e32 v36, v36
	s_nop 0
	v_add_f32_e32 v36, 1.0, v36
	v_rcp_f32_e32 v36, v36
	s_nop 0
	v_mul_f32_e32 v36, v37, v36
	v_mul_f32_e32 v33, v36, v33
	v_cvt_pk_bf16_f32 v42, v32, v33
	v_mul_f32_e32 v32, 0xbfb8aa3b, v38
	v_exp_f32_e32 v32, v32
	v_mul_f32_e32 v33, 0xbfb8aa3b, v39
	v_exp_f32_e32 v33, v33
	v_add_f32_e32 v32, 1.0, v32
	v_rcp_f32_e32 v32, v32
	v_add_f32_e32 v33, 1.0, v33
	v_rcp_f32_e32 v33, v33
	v_mul_f32_e32 v32, v38, v32
	v_mul_f32_e32 v32, v32, v34
	v_mul_f32_e32 v33, v39, v33
	v_mul_f32_e32 v33, v33, v35
	v_cvt_pk_bf16_f32 v43, v32, v33
	v_add_u32_e32 v32, 0x90, v154
	v_mad_i64_i32 v[32:33], s[24:25], v32, s68, v[138:139]
	global_store_dwordx4 v[32:33], v[40:43], off sc1
	v_mul_f32_e32 v32, 0xbfb8aa3b, v28
	v_exp_f32_e32 v32, v32
	s_nop 0
	v_add_f32_e32 v32, 1.0, v32
	v_rcp_f32_e32 v32, v32
	s_nop 0
	v_mul_f32_e32 v28, v28, v32
	v_mul_f32_e32 v24, v28, v24
	v_mul_f32_e32 v28, 0xbfb8aa3b, v29
	v_exp_f32_e32 v28, v28
	s_nop 0
	v_add_f32_e32 v28, 1.0, v28
	v_rcp_f32_e32 v28, v28
	s_nop 0
	v_mul_f32_e32 v28, v29, v28
	v_mul_f32_e32 v25, v28, v25
	v_cvt_pk_bf16_f32 v24, v24, v25
	v_mul_f32_e32 v25, 0xbfb8aa3b, v30
	v_exp_f32_e32 v25, v25
	s_nop 0
	v_add_f32_e32 v25, 1.0, v25
	v_rcp_f32_e32 v25, v25
	s_nop 0
	v_mul_f32_e32 v25, v30, v25
	v_mul_f32_e32 v25, v25, v26
	v_mul_f32_e32 v26, 0xbfb8aa3b, v31
	v_exp_f32_e32 v26, v26
	s_nop 0
	v_add_f32_e32 v26, 1.0, v26
	v_rcp_f32_e32 v26, v26
	s_nop 0
	v_mul_f32_e32 v26, v31, v26
	v_mul_f32_e32 v26, v26, v27
	v_cvt_pk_bf16_f32 v25, v25, v26
	v_mul_f32_e32 v26, 0xbfb8aa3b, v20
	v_exp_f32_e32 v26, v26
	s_nop 0
	v_add_f32_e32 v26, 1.0, v26
	v_rcp_f32_e32 v26, v26
	s_nop 0
	v_mul_f32_e32 v20, v20, v26
	v_mul_f32_e32 v16, v20, v16
	v_mul_f32_e32 v20, 0xbfb8aa3b, v21
	v_exp_f32_e32 v20, v20
	s_nop 0
	v_add_f32_e32 v20, 1.0, v20
	v_rcp_f32_e32 v20, v20
	s_nop 0
	v_mul_f32_e32 v20, v21, v20
	v_mul_f32_e32 v17, v20, v17
	v_cvt_pk_bf16_f32 v26, v16, v17
	v_mul_f32_e32 v16, 0xbfb8aa3b, v22
	v_exp_f32_e32 v16, v16
	v_mul_f32_e32 v17, 0xbfb8aa3b, v23
	v_exp_f32_e32 v17, v17
	v_add_f32_e32 v16, 1.0, v16
	v_rcp_f32_e32 v16, v16
	v_add_f32_e32 v17, 1.0, v17
	v_rcp_f32_e32 v17, v17
	v_mul_f32_e32 v16, v22, v16
	v_mul_f32_e32 v16, v16, v18
	v_mul_f32_e32 v17, v23, v17
	v_mul_f32_e32 v17, v17, v19
	v_cvt_pk_bf16_f32 v27, v16, v17
	v_add_u32_e32 v16, 0xa0, v154
	v_mad_i64_i32 v[16:17], s[24:25], v16, s68, v[138:139]
	global_store_dwordx4 v[16:17], v[24:27], off sc1
	v_mul_f32_e32 v16, 0xbfb8aa3b, v12
	v_exp_f32_e32 v16, v16
	s_nop 0
	v_add_f32_e32 v16, 1.0, v16
	v_rcp_f32_e32 v16, v16
	s_nop 0
	v_mul_f32_e32 v12, v12, v16
	v_mul_f32_e32 v8, v12, v8
	v_mul_f32_e32 v12, 0xbfb8aa3b, v13
	v_exp_f32_e32 v12, v12
	s_nop 0
	v_add_f32_e32 v12, 1.0, v12
	v_rcp_f32_e32 v12, v12
	s_nop 0
	v_mul_f32_e32 v12, v13, v12
	v_mul_f32_e32 v9, v12, v9
	v_cvt_pk_bf16_f32 v8, v8, v9
	v_mul_f32_e32 v9, 0xbfb8aa3b, v14
	v_exp_f32_e32 v9, v9
	s_nop 0
	v_add_f32_e32 v9, 1.0, v9
	v_rcp_f32_e32 v9, v9
	s_nop 0
	v_mul_f32_e32 v9, v14, v9
	v_mul_f32_e32 v9, v9, v10
	v_mul_f32_e32 v10, 0xbfb8aa3b, v15
	v_exp_f32_e32 v10, v10
	s_nop 0
	v_add_f32_e32 v10, 1.0, v10
	v_rcp_f32_e32 v10, v10
	s_nop 0
	v_mul_f32_e32 v10, v15, v10
	v_mul_f32_e32 v10, v10, v11
	v_cvt_pk_bf16_f32 v9, v9, v10
	v_mul_f32_e32 v10, 0xbfb8aa3b, v4
	v_exp_f32_e32 v10, v10
	s_nop 0
	v_add_f32_e32 v10, 1.0, v10
	v_rcp_f32_e32 v10, v10
	s_nop 0
	v_mul_f32_e32 v4, v4, v10
	v_mul_f32_e32 v0, v4, v0
	v_mul_f32_e32 v4, 0xbfb8aa3b, v5
	v_exp_f32_e32 v4, v4
	s_nop 0
	v_add_f32_e32 v4, 1.0, v4
	v_rcp_f32_e32 v4, v4
	s_nop 0
	v_mul_f32_e32 v4, v5, v4
	v_mul_f32_e32 v1, v4, v1
	v_cvt_pk_bf16_f32 v10, v0, v1
	v_mul_f32_e32 v0, 0xbfb8aa3b, v6
	v_exp_f32_e32 v0, v0
	v_mul_f32_e32 v1, 0xbfb8aa3b, v7
	v_exp_f32_e32 v1, v1
	v_add_f32_e32 v0, 1.0, v0
	v_rcp_f32_e32 v0, v0
	v_add_f32_e32 v1, 1.0, v1
	v_rcp_f32_e32 v1, v1
	v_mul_f32_e32 v0, v6, v0
	v_mul_f32_e32 v0, v0, v2
	v_mul_f32_e32 v1, v7, v1
	v_mul_f32_e32 v1, v1, v3
	v_cvt_pk_bf16_f32 v11, v0, v1
	v_add_u32_e32 v0, 0xb0, v154
	v_mad_i64_i32 v[0:1], s[24:25], v0, s68, v[138:139]
	s_mov_b64 s[24:25], -1
	global_store_dwordx4 v[0:1], v[8:11], off sc1
	s_cbranch_vccnz .LBB0_341
	s_andn2_b64 vcc, exec, s[4:5]
	s_cbranch_vccnz .LBB0_340
	s_barrier
	s_branch .LBB0_340

.LBB0_374:
	v_lshl_add_u64 v[8:9], v[0:1], 2, v[8:9]
	s_lshl_b32 s38, s12, 3
	global_load_dword v48, v[8:9], off nt
	v_lshl_add_u64 v[8:9], v[8:9], 0, s[38:39]
	global_load_dword v49, v[8:9], off nt
	v_lshl_add_u64 v[8:9], v[8:9], 0, s[38:39]
	global_load_dword v50, v[8:9], off nt
	v_lshl_add_u64 v[8:9], v[8:9], 0, s[38:39]
	global_load_dword v51, v[8:9], off nt
	v_lshl_add_u64 v[8:9], v[8:9], 0, s[38:39]
	global_load_dword v52, v[8:9], off nt
	v_lshl_add_u64 v[8:9], v[8:9], 0, s[38:39]
	global_load_dword v53, v[8:9], off nt
	v_lshl_add_u64 v[8:9], v[8:9], 0, s[38:39]
	global_load_dword v54, v[8:9], off nt
	v_lshl_add_u64 v[8:9], v[8:9], 0, s[38:39]
	global_load_dword v55, v[8:9], off nt
	v_lshl_add_u64 v[8:9], v[8:9], 0, s[38:39]
	global_load_dword v56, v[8:9], off nt
	v_lshl_add_u64 v[8:9], v[8:9], 0, s[38:39]
	global_load_dword v57, v[8:9], off nt
	v_lshl_add_u64 v[8:9], v[8:9], 0, s[38:39]
	global_load_dword v58, v[8:9], off nt
	v_lshl_add_u64 v[8:9], v[8:9], 0, s[38:39]
	global_load_dword v59, v[8:9], off nt
	v_lshl_add_u64 v[8:9], v[8:9], 0, s[38:39]
	global_load_dword v60, v[8:9], off nt
	v_lshl_add_u64 v[8:9], v[8:9], 0, s[38:39]
	global_load_dword v61, v[8:9], off nt
	v_lshl_add_u64 v[8:9], v[8:9], 0, s[38:39]
	global_load_dword v62, v[8:9], off nt
	v_lshl_add_u64 v[8:9], v[8:9], 0, s[38:39]
	global_load_dword v63, v[8:9], off nt
	v_lshl_add_u64 v[8:9], v[8:9], 0, s[38:39]
	global_load_dword v64, v[8:9], off nt
	v_lshl_add_u64 v[8:9], v[8:9], 0, s[38:39]
	global_load_dword v65, v[8:9], off nt
	v_lshl_add_u64 v[8:9], v[8:9], 0, s[38:39]
	global_load_dword v66, v[8:9], off nt
	v_lshl_add_u64 v[8:9], v[8:9], 0, s[38:39]
	global_load_dword v67, v[8:9], off nt
	v_lshl_add_u64 v[8:9], v[8:9], 0, s[38:39]
	global_load_dword v68, v[8:9], off nt
	v_lshl_add_u64 v[8:9], v[8:9], 0, s[38:39]
	global_load_dword v69, v[8:9], off nt
	v_lshl_add_u64 v[8:9], v[8:9], 0, s[38:39]
	global_load_dword v70, v[8:9], off nt
	v_lshl_add_u64 v[8:9], v[8:9], 0, s[38:39]
	global_load_dword v71, v[8:9], off nt
	v_lshl_add_u64 v[8:9], v[8:9], 0, s[38:39]
	global_load_dword v72, v[8:9], off nt
	v_lshl_add_u64 v[8:9], v[8:9], 0, s[38:39]
	global_load_dword v73, v[8:9], off nt
	v_lshl_add_u64 v[8:9], v[8:9], 0, s[38:39]
	global_load_dword v74, v[8:9], off nt
	v_lshl_add_u64 v[8:9], v[8:9], 0, s[38:39]
	global_load_dword v75, v[8:9], off nt
	v_lshl_add_u64 v[8:9], v[8:9], 0, s[38:39]
	global_load_dword v76, v[8:9], off nt
	v_lshl_add_u64 v[8:9], v[8:9], 0, s[38:39]
	global_load_dword v77, v[8:9], off nt
	v_lshl_add_u64 v[8:9], v[8:9], 0, s[38:39]
	global_load_dword v78, v[8:9], off nt
	v_lshl_add_u64 v[8:9], v[8:9], 0, s[38:39]
	global_load_dword v79, v[8:9], off nt
	v_add_u32_e32 v80, 0x400, v15
	v_add_u32_e32 v81, 0x800, v15
	v_add_u32_e32 v82, 0xc00, v15
	v_add_u32_e32 v83, 0x1000, v15
	v_add_u32_e32 v84, 0x1400, v15
	v_add_u32_e32 v85, 0x1800, v15
	v_add_u32_e32 v86, 0x1c00, v15
	s_waitcnt vmcnt(62)
	ds_write2_b32 v15, v16, v17 offset1:66
	s_waitcnt vmcnt(60)
	ds_write2_b32 v15, v18, v19 offset0:132 offset1:198
	s_waitcnt vmcnt(58)
	ds_write2_b32 v80, v20, v21 offset0:8 offset1:74
	s_waitcnt vmcnt(56)
	ds_write2_b32 v80, v22, v23 offset0:140 offset1:206
	s_waitcnt vmcnt(54)
	ds_write2_b32 v81, v24, v25 offset0:16 offset1:82
	s_waitcnt vmcnt(52)
	ds_write2_b32 v81, v26, v27 offset0:148 offset1:214
	s_waitcnt vmcnt(50)
	ds_write2_b32 v82, v28, v29 offset0:24 offset1:90
	s_waitcnt vmcnt(48)
	ds_write2_b32 v82, v30, v31 offset0:156 offset1:222
	s_waitcnt vmcnt(46)
	ds_write2_b32 v83, v32, v33 offset0:32 offset1:98
	s_waitcnt vmcnt(44)
	ds_write2_b32 v83, v34, v35 offset0:164 offset1:230
	s_waitcnt vmcnt(42)
	ds_write2_b32 v84, v36, v37 offset0:40 offset1:106
	s_waitcnt vmcnt(40)
	ds_write2_b32 v84, v38, v39 offset0:172 offset1:238
	s_waitcnt vmcnt(38)
	ds_write2_b32 v85, v40, v41 offset0:48 offset1:114
	s_waitcnt vmcnt(36)
	ds_write2_b32 v85, v42, v43 offset0:180 offset1:246
	s_waitcnt vmcnt(34)
	ds_write2_b32 v86, v44, v45 offset0:56 offset1:122
	s_waitcnt vmcnt(32)
	ds_write2_b32 v86, v46, v47 offset0:188 offset1:254
	s_waitcnt lgkmcnt(0)
	ds_read2_b32 v[8:9], v11 offset1:33
	s_waitcnt lgkmcnt(0)
	v_cvt_pk_bf16_f32 v16, v8, v9
	ds_read2_b32 v[8:9], v11 offset0:66 offset1:99
	s_waitcnt lgkmcnt(0)
	v_cvt_pk_bf16_f32 v17, v8, v9
	ds_read2_b32 v[8:9], v11 offset0:132 offset1:165
	v_lshlrev_b32_e32 v144, 1, v2
	s_waitcnt lgkmcnt(0)
	v_cvt_pk_bf16_f32 v18, v8, v9
	ds_read2_b32 v[8:9], v11 offset0:198 offset1:231
	v_lshl_add_u64 v[4:5], v[4:5], 0, v[144:145]
	s_waitcnt lgkmcnt(0)
	v_cvt_pk_bf16_f32 v19, v8, v9
	v_mul_hi_i32_i24_e32 v9, s0, v3
	v_mul_i32_i24_e32 v8, s0, v3
	v_lshl_add_u64 v[8:9], v[8:9], 1, v[4:5]
	global_store_dwordx4 v[8:9], v[16:19], off sc1
	ds_read2_b32 v[8:9], v11 offset0:8 offset1:41
	s_add_i32 s11, s22, 2
	s_waitcnt lgkmcnt(0)
	v_cvt_pk_bf16_f32 v16, v8, v9
	ds_read2_b32 v[8:9], v11 offset0:74 offset1:107
	s_waitcnt lgkmcnt(0)
	v_cvt_pk_bf16_f32 v17, v8, v9
	ds_read2_b32 v[8:9], v11 offset0:140 offset1:173
	s_waitcnt lgkmcnt(0)
	v_cvt_pk_bf16_f32 v18, v8, v9
	ds_read2_b32 v[8:9], v11 offset0:206 offset1:239
	s_waitcnt lgkmcnt(0)
	v_cvt_pk_bf16_f32 v19, v8, v9
	v_mul_hi_i32_i24_e32 v9, s0, v12
	v_mul_i32_i24_e32 v8, s0, v12
	v_lshl_add_u64 v[8:9], v[8:9], 1, v[4:5]
	global_store_dwordx4 v[8:9], v[16:19], off sc1
	ds_read2_b32 v[8:9], v11 offset0:16 offset1:49
	s_waitcnt lgkmcnt(0)
	v_cvt_pk_bf16_f32 v16, v8, v9
	ds_read2_b32 v[8:9], v11 offset0:82 offset1:115
	s_waitcnt lgkmcnt(0)
	v_cvt_pk_bf16_f32 v17, v8, v9
	ds_read2_b32 v[8:9], v11 offset0:148 offset1:181
	s_waitcnt lgkmcnt(0)
	v_cvt_pk_bf16_f32 v18, v8, v9
	ds_read2_b32 v[8:9], v11 offset0:214 offset1:247
	s_waitcnt lgkmcnt(0)
	v_cvt_pk_bf16_f32 v19, v8, v9
	v_mul_hi_i32_i24_e32 v9, s0, v13
	v_mul_i32_i24_e32 v8, s0, v13
	v_lshl_add_u64 v[8:9], v[8:9], 1, v[4:5]
	global_store_dwordx4 v[8:9], v[16:19], off sc1
	ds_read2_b32 v[8:9], v11 offset0:24 offset1:57
	s_waitcnt lgkmcnt(0)
	v_cvt_pk_bf16_f32 v16, v8, v9
	ds_read2_b32 v[8:9], v11 offset0:90 offset1:123
	s_waitcnt lgkmcnt(0)
	v_cvt_pk_bf16_f32 v17, v8, v9
	ds_read2_b32 v[8:9], v11 offset0:156 offset1:189
	s_waitcnt lgkmcnt(0)
	v_cvt_pk_bf16_f32 v18, v8, v9
	ds_read2_b32 v[8:9], v11 offset0:222 offset1:255
	s_waitcnt lgkmcnt(0)
	v_cvt_pk_bf16_f32 v19, v8, v9
	v_mul_hi_i32_i24_e32 v9, s0, v14
	v_mul_i32_i24_e32 v8, s0, v14
	v_lshl_add_u64 v[4:5], v[8:9], 1, v[4:5]
	global_store_dwordx4 v[4:5], v[16:19], off sc1
	s_waitcnt lgkmcnt(0)
	s_min_i32 s0, s11, s17
	s_lshl_b32 s12, s0, 9
	s_add_i32 s12, s12, s16
	s_mov_b64 s[0:1], -1
	s_cmpk_gt_i32 s12, 0xaff
	s_cbranch_scc0 .LBB0_376
	s_lshl_b32 s0, s12, 1
	s_andn2_b32 s0, s0, 63
	s_add_i32 s38, s0, 0xffffea00
	s_lshl_b64 s[0:1], s[38:39], 1
	v_or_b32_e32 v4, s38, v10
	v_mov_b32_e32 v5, v145
	s_add_u32 s14, s18, s0
	v_lshlrev_b64 v[4:5], 12, v[4:5]
	s_addc_u32 s15, s19, s1
	v_lshl_add_u64 v[8:9], s[6:7], 0, v[4:5]
	s_mov_b64 s[0:1], 0
	v_mov_b64_e32 v[4:5], s[14:15]

.LBB0_383:
	v_lshl_add_u64 v[8:9], v[0:1], 2, v[8:9]
	s_lshl_b32 s38, s12, 3
	global_load_dword v16, v[8:9], off nt
	v_lshl_add_u64 v[8:9], v[8:9], 0, s[38:39]
	global_load_dword v17, v[8:9], off nt
	v_lshl_add_u64 v[8:9], v[8:9], 0, s[38:39]
	global_load_dword v18, v[8:9], off nt
	v_lshl_add_u64 v[8:9], v[8:9], 0, s[38:39]
	global_load_dword v19, v[8:9], off nt
	v_lshl_add_u64 v[8:9], v[8:9], 0, s[38:39]
	global_load_dword v20, v[8:9], off nt
	v_lshl_add_u64 v[8:9], v[8:9], 0, s[38:39]
	global_load_dword v21, v[8:9], off nt
	v_lshl_add_u64 v[8:9], v[8:9], 0, s[38:39]
	global_load_dword v22, v[8:9], off nt
	v_lshl_add_u64 v[8:9], v[8:9], 0, s[38:39]
	global_load_dword v23, v[8:9], off nt
	v_lshl_add_u64 v[8:9], v[8:9], 0, s[38:39]
	global_load_dword v24, v[8:9], off nt
	v_lshl_add_u64 v[8:9], v[8:9], 0, s[38:39]
	global_load_dword v25, v[8:9], off nt
	v_lshl_add_u64 v[8:9], v[8:9], 0, s[38:39]
	global_load_dword v26, v[8:9], off nt
	v_lshl_add_u64 v[8:9], v[8:9], 0, s[38:39]
	global_load_dword v27, v[8:9], off nt
	v_lshl_add_u64 v[8:9], v[8:9], 0, s[38:39]
	global_load_dword v28, v[8:9], off nt
	v_lshl_add_u64 v[8:9], v[8:9], 0, s[38:39]
	global_load_dword v29, v[8:9], off nt
	v_lshl_add_u64 v[8:9], v[8:9], 0, s[38:39]
	global_load_dword v30, v[8:9], off nt
	v_lshl_add_u64 v[8:9], v[8:9], 0, s[38:39]
	global_load_dword v31, v[8:9], off nt
	v_lshl_add_u64 v[8:9], v[8:9], 0, s[38:39]
	global_load_dword v32, v[8:9], off nt
	v_lshl_add_u64 v[8:9], v[8:9], 0, s[38:39]
	global_load_dword v33, v[8:9], off nt
	v_lshl_add_u64 v[8:9], v[8:9], 0, s[38:39]
	global_load_dword v34, v[8:9], off nt
	v_lshl_add_u64 v[8:9], v[8:9], 0, s[38:39]
	global_load_dword v35, v[8:9], off nt
	v_lshl_add_u64 v[8:9], v[8:9], 0, s[38:39]
	global_load_dword v36, v[8:9], off nt
	v_lshl_add_u64 v[8:9], v[8:9], 0, s[38:39]
	global_load_dword v37, v[8:9], off nt
	v_lshl_add_u64 v[8:9], v[8:9], 0, s[38:39]
	global_load_dword v38, v[8:9], off nt
	v_lshl_add_u64 v[8:9], v[8:9], 0, s[38:39]
	global_load_dword v39, v[8:9], off nt
	v_lshl_add_u64 v[8:9], v[8:9], 0, s[38:39]
	global_load_dword v40, v[8:9], off nt
	v_lshl_add_u64 v[8:9], v[8:9], 0, s[38:39]
	global_load_dword v41, v[8:9], off nt
	v_lshl_add_u64 v[8:9], v[8:9], 0, s[38:39]
	global_load_dword v42, v[8:9], off nt
	v_lshl_add_u64 v[8:9], v[8:9], 0, s[38:39]
	global_load_dword v43, v[8:9], off nt
	v_lshl_add_u64 v[8:9], v[8:9], 0, s[38:39]
	global_load_dword v44, v[8:9], off nt
	v_lshl_add_u64 v[8:9], v[8:9], 0, s[38:39]
	global_load_dword v45, v[8:9], off nt
	v_lshl_add_u64 v[8:9], v[8:9], 0, s[38:39]
	global_load_dword v46, v[8:9], off nt
	v_lshl_add_u64 v[8:9], v[8:9], 0, s[38:39]
	global_load_dword v47, v[8:9], off nt
	s_cmp_ge_u32 s22, s17
	s_cbranch_scc1 .LBB0_364
	s_waitcnt vmcnt(62)
	ds_write2_b32 v15, v48, v49 offset1:66
	ds_write2_b32 v15, v50, v51 offset0:132 offset1:198
	ds_write2_b32 v80, v52, v53 offset0:8 offset1:74
	s_waitcnt vmcnt(60)
	ds_write2_b32 v80, v54, v55 offset0:140 offset1:206
	s_waitcnt vmcnt(58)
	ds_write2_b32 v81, v56, v57 offset0:16 offset1:82
	s_waitcnt vmcnt(56)
	ds_write2_b32 v81, v58, v59 offset0:148 offset1:214
	s_waitcnt vmcnt(54)
	ds_write2_b32 v82, v60, v61 offset0:24 offset1:90
	s_waitcnt vmcnt(52)
	ds_write2_b32 v82, v62, v63 offset0:156 offset1:222
	s_waitcnt vmcnt(50)
	ds_write2_b32 v83, v64, v65 offset0:32 offset1:98
	s_waitcnt vmcnt(48)
	ds_write2_b32 v83, v66, v67 offset0:164 offset1:230
	s_waitcnt vmcnt(46)
	ds_write2_b32 v84, v68, v69 offset0:40 offset1:106
	s_waitcnt vmcnt(44)
	ds_write2_b32 v84, v70, v71 offset0:172 offset1:238
	s_waitcnt vmcnt(42)
	ds_write2_b32 v85, v72, v73 offset0:48 offset1:114
	s_waitcnt vmcnt(40)
	ds_write2_b32 v85, v74, v75 offset0:180 offset1:246
	s_waitcnt vmcnt(38)
	ds_write2_b32 v86, v76, v77 offset0:56 offset1:122
	s_waitcnt vmcnt(36)
	ds_write2_b32 v86, v78, v79 offset0:188 offset1:254
	s_waitcnt lgkmcnt(0)
	v_lshl_add_u64 v[48:49], v[6:7], 0, v[144:145]
	ds_read2_b32 v[6:7], v11 offset1:33
	s_waitcnt lgkmcnt(0)
	v_cvt_pk_bf16_f32 v6, v6, v7
	ds_read2_b32 v[8:9], v11 offset0:66 offset1:99
	s_waitcnt lgkmcnt(0)
	v_cvt_pk_bf16_f32 v7, v8, v9
	ds_read2_b32 v[8:9], v11 offset0:132 offset1:165
	s_waitcnt lgkmcnt(0)
	v_cvt_pk_bf16_f32 v8, v8, v9
	ds_read2_b32 v[50:51], v11 offset0:198 offset1:231
	s_waitcnt lgkmcnt(0)
	v_cvt_pk_bf16_f32 v9, v50, v51
	v_mul_u32_u24_e32 v50, s10, v3
	v_lshlrev_b32_e32 v144, 1, v50
	v_lshl_add_u64 v[50:51], v[48:49], 0, v[144:145]
	global_store_dwordx4 v[50:51], v[6:9], off sc1
	ds_read2_b32 v[6:7], v11 offset0:8 offset1:41
	s_waitcnt lgkmcnt(0)
	v_cvt_pk_bf16_f32 v6, v6, v7
	ds_read2_b32 v[8:9], v11 offset0:74 offset1:107
	s_waitcnt lgkmcnt(0)
	v_cvt_pk_bf16_f32 v7, v8, v9
	ds_read2_b32 v[8:9], v11 offset0:140 offset1:173
	s_waitcnt lgkmcnt(0)
	v_cvt_pk_bf16_f32 v8, v8, v9
	ds_read2_b32 v[50:51], v11 offset0:206 offset1:239
	s_waitcnt lgkmcnt(0)
	v_cvt_pk_bf16_f32 v9, v50, v51
	v_mul_u32_u24_e32 v50, s10, v12
	v_lshlrev_b32_e32 v144, 1, v50
	v_lshl_add_u64 v[50:51], v[48:49], 0, v[144:145]
	global_store_dwordx4 v[50:51], v[6:9], off sc1
	ds_read2_b32 v[6:7], v11 offset0:16 offset1:49
	s_waitcnt lgkmcnt(0)
	v_cvt_pk_bf16_f32 v6, v6, v7
	ds_read2_b32 v[8:9], v11 offset0:82 offset1:115
	s_waitcnt lgkmcnt(0)
	v_cvt_pk_bf16_f32 v7, v8, v9
	ds_read2_b32 v[8:9], v11 offset0:148 offset1:181
	s_waitcnt lgkmcnt(0)
	v_cvt_pk_bf16_f32 v8, v8, v9
	ds_read2_b32 v[50:51], v11 offset0:214 offset1:247
	s_waitcnt lgkmcnt(0)
	v_cvt_pk_bf16_f32 v9, v50, v51
	v_mul_u32_u24_e32 v50, s10, v13
	v_lshlrev_b32_e32 v144, 1, v50
	v_lshl_add_u64 v[50:51], v[48:49], 0, v[144:145]
	global_store_dwordx4 v[50:51], v[6:9], off sc1
	ds_read2_b32 v[6:7], v11 offset0:24 offset1:57
	s_waitcnt lgkmcnt(0)
	v_cvt_pk_bf16_f32 v6, v6, v7
	ds_read2_b32 v[8:9], v11 offset0:90 offset1:123
	s_waitcnt lgkmcnt(0)
	v_cvt_pk_bf16_f32 v7, v8, v9
	ds_read2_b32 v[8:9], v11 offset0:156 offset1:189
	s_waitcnt lgkmcnt(0)
	v_cvt_pk_bf16_f32 v8, v8, v9
	ds_read2_b32 v[50:51], v11 offset0:222 offset1:255
	s_waitcnt lgkmcnt(0)
	v_cvt_pk_bf16_f32 v9, v50, v51
	v_mul_u32_u24_e32 v50, s10, v14
	v_lshlrev_b32_e32 v144, 1, v50
	v_lshl_add_u64 v[48:49], v[48:49], 0, v[144:145]
	global_store_dwordx4 v[48:49], v[6:9], off sc1
	s_waitcnt lgkmcnt(0)
	s_branch .LBB0_364

.LBB0_462:
	s_ashr_i32 s17, s16, 31
	s_lshl_b64 s[16:17], s[16:17], 24
	v_lshl_add_u32 v140, s54, 8, v142
	s_add_u32 s16, s45, s16
	v_ashrrev_i32_e32 v141, 31, v140
	s_addc_u32 s17, s46, s17
	v_lshlrev_b64 v[140:141], 11, v[140:141]
	v_lshl_add_u64 v[140:141], s[16:17], 0, v[140:141]
	s_lshl_b32 s16, s55, 8
	s_ashr_i32 s17, s16, 31
	v_lshl_add_u64 v[140:141], s[16:17], 1, v[140:141]
	v_lshl_add_u64 v[140:141], v[140:141], 0, s[38:39]
	v_lshl_add_u64 v[140:141], v[140:141], 0, v[144:145]
	v_cvt_pk_bf16_f32 v124, v124, v125
	v_cvt_pk_bf16_f32 v125, v126, v127
	v_cvt_pk_bf16_f32 v126, v120, v121
	v_cvt_pk_bf16_f32 v127, v122, v123
	global_store_dwordx4 v[140:141], v[124:127], off sc1
	v_cvt_pk_bf16_f32 v112, v112, v113
	v_cvt_pk_bf16_f32 v113, v114, v115
	v_cvt_pk_bf16_f32 v114, v104, v105
	v_cvt_pk_bf16_f32 v115, v106, v107
	global_store_dwordx4 v[140:141], v[112:115], off offset:256 sc1
	v_cvt_pk_bf16_f32 v104, v116, v117
	v_cvt_pk_bf16_f32 v105, v118, v119
	v_cvt_pk_bf16_f32 v106, v108, v109
	v_add_co_u32_e32 v108, vcc, s86, v140
	v_cvt_pk_bf16_f32 v107, v110, v111
	s_nop 1
	v_addc_co_u32_e32 v109, vcc, 0, v141, vcc
	global_store_dwordx4 v[108:109], v[104:107], off sc1
	v_cvt_pk_bf16_f32 v96, v96, v97
	v_cvt_pk_bf16_f32 v97, v98, v99
	v_cvt_pk_bf16_f32 v98, v88, v89
	v_cvt_pk_bf16_f32 v99, v90, v91
	global_store_dwordx4 v[108:109], v[96:99], off offset:256 sc1
	v_cvt_pk_bf16_f32 v88, v100, v101
	v_cvt_pk_bf16_f32 v89, v102, v103
	v_cvt_pk_bf16_f32 v90, v92, v93
	v_add_co_u32_e32 v92, vcc, s76, v140
	v_cvt_pk_bf16_f32 v91, v94, v95
	s_nop 1
	v_addc_co_u32_e32 v93, vcc, 0, v141, vcc
	global_store_dwordx4 v[92:93], v[88:91], off sc1
	v_cvt_pk_bf16_f32 v80, v80, v81
	v_cvt_pk_bf16_f32 v81, v82, v83
	v_cvt_pk_bf16_f32 v82, v72, v73
	v_cvt_pk_bf16_f32 v83, v74, v75
	global_store_dwordx4 v[92:93], v[80:83], off offset:256 sc1
	v_cvt_pk_bf16_f32 v72, v84, v85
	v_cvt_pk_bf16_f32 v73, v86, v87
	v_cvt_pk_bf16_f32 v74, v76, v77
	v_add_co_u32_e32 v76, vcc, s77, v140
	v_cvt_pk_bf16_f32 v75, v78, v79
	s_nop 1
	v_addc_co_u32_e32 v77, vcc, 0, v141, vcc
	global_store_dwordx4 v[76:77], v[72:75], off sc1
	v_cvt_pk_bf16_f32 v68, v68, v69
	v_cvt_pk_bf16_f32 v69, v70, v71
	v_cvt_pk_bf16_f32 v70, v64, v65
	v_cvt_pk_bf16_f32 v71, v66, v67
	global_store_dwordx4 v[76:77], v[68:71], off offset:256 sc1
	v_cvt_pk_bf16_f32 v60, v60, v61
	v_cvt_pk_bf16_f32 v61, v62, v63
	v_cvt_pk_bf16_f32 v62, v56, v57
	v_add_co_u32_e32 v56, vcc, s87, v140
	v_cvt_pk_bf16_f32 v63, v58, v59
	s_nop 1
	v_addc_co_u32_e32 v57, vcc, 0, v141, vcc
	global_store_dwordx4 v[56:57], v[60:63], off sc1
	v_cvt_pk_bf16_f32 v48, v48, v49
	v_cvt_pk_bf16_f32 v49, v50, v51
	v_cvt_pk_bf16_f32 v50, v40, v41
	v_cvt_pk_bf16_f32 v51, v42, v43
	global_store_dwordx4 v[56:57], v[48:51], off offset:256 sc1
	v_cvt_pk_bf16_f32 v40, v52, v53
	v_cvt_pk_bf16_f32 v41, v54, v55
	v_cvt_pk_bf16_f32 v42, v44, v45
	v_add_co_u32_e32 v44, vcc, s90, v140
	v_cvt_pk_bf16_f32 v43, v46, v47
	s_nop 1
	v_addc_co_u32_e32 v45, vcc, 0, v141, vcc
	global_store_dwordx4 v[44:45], v[40:43], off sc1
	v_cvt_pk_bf16_f32 v32, v32, v33
	v_cvt_pk_bf16_f32 v33, v34, v35
	v_cvt_pk_bf16_f32 v34, v24, v25
	v_cvt_pk_bf16_f32 v35, v26, v27
	global_store_dwordx4 v[44:45], v[32:35], off offset:256 sc1
	v_cvt_pk_bf16_f32 v24, v36, v37
	v_cvt_pk_bf16_f32 v25, v38, v39
	v_cvt_pk_bf16_f32 v26, v28, v29
	v_add_co_u32_e32 v28, vcc, s78, v140
	v_cvt_pk_bf16_f32 v27, v30, v31
	s_nop 1
	v_addc_co_u32_e32 v29, vcc, 0, v141, vcc
	global_store_dwordx4 v[28:29], v[24:27], off sc1
	v_cvt_pk_bf16_f32 v16, v16, v17
	v_cvt_pk_bf16_f32 v17, v18, v19
	v_cvt_pk_bf16_f32 v18, v8, v9
	v_cvt_pk_bf16_f32 v19, v10, v11
	global_store_dwordx4 v[28:29], v[16:19], off offset:256 sc1
	v_cvt_pk_bf16_f32 v8, v20, v21
	v_cvt_pk_bf16_f32 v9, v22, v23
	v_cvt_pk_bf16_f32 v10, v12, v13
	v_add_co_u32_e32 v12, vcc, s79, v140
	v_cvt_pk_bf16_f32 v11, v14, v15
	s_nop 1
	v_addc_co_u32_e32 v13, vcc, 0, v141, vcc
	s_and_b64 vcc, exec, s[6:7]
	s_mov_b64 s[6:7], -1
	global_store_dwordx4 v[12:13], v[8:11], off sc1
	v_cvt_pk_bf16_f32 v4, v4, v5
	v_cvt_pk_bf16_f32 v5, v6, v7
	v_cvt_pk_bf16_f32 v6, v0, v1
	v_cvt_pk_bf16_f32 v7, v2, v3
	global_store_dwordx4 v[12:13], v[4:7], off offset:256 sc1
	s_cbranch_vccnz .LBB0_447
	s_andn2_b64 vcc, exec, s[8:9]
	s_cbranch_vccnz .LBB0_446
	s_barrier
	s_branch .LBB0_446

.LBB0_522:
	v_add_u32_e32 v0, 0xfffff000, v16
	v_ashrrev_i32_e32 v0, 10, v0
	v_add_u32_e32 v0, 1, v0
	v_cmp_lt_i32_e32 vcc, s69, v16
	v_add_u32_e32 v16, s82, v16
	s_nop 0
	v_cndmask_b32_e32 v17, 0, v0, vcc
	v_mul_hi_i32_i24_e32 v67, 0x9000, v17
	v_mul_i32_i24_e32 v66, 0x9000, v17
	v_add_co_u32_e32 v60, vcc, s73, v24
	v_lshl_add_u64 v[58:59], v[18:19], 0, v[66:67]
	s_nop 0
	v_addc_co_u32_e32 v61, vcc, -1, v25, vcc
	global_load_dwordx4 v[12:15], v[26:27], off
	global_load_dwordx4 v[8:11], v[26:27], off offset:1024
	global_load_dwordx4 v[4:7], v[26:27], off offset:2048
	global_load_dwordx4 v[0:3], v[26:27], off offset:3072
	global_load_dwordx2 v[114:115], v[60:61], off offset:-1536
	global_load_dwordx2 v[116:117], v[24:25], off offset:-1536
	global_load_dwordx4 v[34:37], v[58:59], off
	global_load_dwordx4 v[38:41], v[20:21], off
	global_load_dwordx2 v[118:119], v[60:61], off offset:-1024
	global_load_dwordx2 v[120:121], v[24:25], off offset:-1024
	global_load_dwordx4 v[42:45], v[58:59], off offset:1024
	global_load_dwordx4 v[46:49], v[20:21], off offset:1024
	global_load_dwordx2 v[122:123], v[60:61], off offset:-512
	global_load_dwordx2 v[124:125], v[24:25], off offset:-512
	global_load_dwordx4 v[50:53], v[58:59], off offset:2048
	global_load_dwordx4 v[54:57], v[20:21], off offset:2048
	global_load_dwordx2 v[126:127], v[60:61], off
	global_load_dwordx2 v[128:129], v[24:25], off
	s_nop 0
	global_load_dwordx4 v[58:61], v[58:59], off offset:3072
	s_nop 0
	global_load_dwordx4 v[62:65], v[20:21], off offset:3072
	v_lshl_add_u64 v[66:67], s[10:11], 0, v[66:67]
	v_lshl_add_u64 v[102:103], v[66:67], 0, v[144:145]
	global_load_dwordx4 v[66:69], v[102:103], off
	v_add_co_u32_e32 v70, vcc, s67, v102
	v_lshl_add_u64 v[106:107], v[102:103], 0, s[94:95]
	s_nop 0
	v_addc_co_u32_e32 v71, vcc, 0, v103, vcc
	global_load_dwordx4 v[70:73], v[70:71], off
	s_nop 0
	global_load_dwordx4 v[74:77], v[22:23], off
	global_load_dwordx4 v[78:81], v[102:103], off offset:1024
	global_load_dwordx4 v[82:85], v[106:107], off offset:1024
	global_load_dwordx4 v[86:89], v[22:23], off offset:1024
	global_load_dwordx4 v[90:93], v[102:103], off offset:2048
	global_load_dwordx4 v[94:97], v[106:107], off offset:2048
	global_load_dwordx4 v[98:101], v[22:23], off offset:2048
	s_nop 0
	global_load_dwordx4 v[102:105], v[102:103], off offset:3072
	s_nop 0
	global_load_dwordx4 v[106:109], v[106:107], off offset:3072
	s_nop 0
	global_load_dwordx4 v[110:113], v[22:23], off offset:3072
	s_waitcnt vmcnt(27)
	v_lshlrev_b32_e32 v130, 16, v114
	v_and_b32_e32 v131, 0xffff0000, v114
	s_waitcnt vmcnt(26)
	v_lshlrev_b32_e32 v132, 16, v116
	v_and_b32_e32 v133, 0xffff0000, v116
	v_lshlrev_b32_e32 v114, 16, v115
	v_and_b32_e32 v115, 0xffff0000, v115
	v_lshlrev_b32_e32 v116, 16, v117
	v_and_b32_e32 v117, 0xffff0000, v117
	v_pk_add_f32 v[130:131], v[130:131], v[132:133]
	v_pk_add_f32 v[114:115], v[114:115], v[116:117]
	v_mov_b32_e32 v132, v130
	v_pk_mov_b32 v[116:117], v[130:131], v[114:115] op_sel:[1,0]
	v_mov_b32_e32 v133, v115
	v_pk_mul_f32 v[116:117], v[116:117], v[116:117]
	s_waitcnt vmcnt(22)
	v_lshlrev_b32_e32 v134, 16, v120
	v_pk_fma_f32 v[116:117], v[132:133], v[132:133], v[116:117]
	v_lshlrev_b32_e32 v132, 16, v118
	v_and_b32_e32 v133, 0xffff0000, v118
	v_and_b32_e32 v135, 0xffff0000, v120
	v_lshlrev_b32_e32 v118, 16, v119
	v_and_b32_e32 v119, 0xffff0000, v119
	v_lshlrev_b32_e32 v120, 16, v121
	v_and_b32_e32 v121, 0xffff0000, v121
	v_pk_add_f32 v[132:133], v[132:133], v[134:135]
	v_pk_add_f32 v[118:119], v[118:119], v[120:121]
	v_mov_b32_e32 v134, v132
	v_pk_mov_b32 v[120:121], v[132:133], v[118:119] op_sel:[1,0]
	v_mov_b32_e32 v135, v119
	v_pk_mul_f32 v[120:121], v[120:121], v[120:121]
	s_waitcnt vmcnt(18)
	v_lshlrev_b32_e32 v136, 16, v124
	v_pk_fma_f32 v[120:121], v[134:135], v[134:135], v[120:121]
	v_lshlrev_b32_e32 v134, 16, v122
	v_and_b32_e32 v135, 0xffff0000, v122
	v_and_b32_e32 v137, 0xffff0000, v124
	v_lshlrev_b32_e32 v122, 16, v123
	v_and_b32_e32 v123, 0xffff0000, v123
	v_lshlrev_b32_e32 v124, 16, v125
	v_and_b32_e32 v125, 0xffff0000, v125
	v_pk_add_f32 v[134:135], v[134:135], v[136:137]
	v_pk_add_f32 v[122:123], v[122:123], v[124:125]
	s_waitcnt vmcnt(15)
	v_lshlrev_b32_e32 v138, 16, v126
	v_and_b32_e32 v139, 0xffff0000, v126
	s_waitcnt vmcnt(14)
	v_lshlrev_b32_e32 v140, 16, v128
	v_and_b32_e32 v141, 0xffff0000, v128
	v_lshlrev_b32_e32 v126, 16, v127
	v_and_b32_e32 v127, 0xffff0000, v127
	v_lshlrev_b32_e32 v128, 16, v129
	v_and_b32_e32 v129, 0xffff0000, v129
	v_mul_f32_e32 v124, v135, v135
	v_mul_f32_e32 v136, v123, v123
	v_pk_add_f32 v[138:139], v[138:139], v[140:141]
	v_pk_add_f32 v[126:127], v[126:127], v[128:129]
	v_pk_add_f32 v[116:117], v[116:117], v[116:117] op_sel:[0,1] op_sel_hi:[1,0]
	v_pk_add_f32 v[120:121], v[120:121], v[120:121] op_sel:[0,1] op_sel_hi:[1,0]
	v_pk_fma_f32 v[124:125], v[134:135], v[134:135], v[124:125] op_sel_hi:[1,1,0]
	v_pk_fma_f32 v[136:137], v[122:123], v[122:123], v[136:137] op_sel_hi:[1,1,0]
	v_pk_mul_f32 v[128:129], v[138:139], v[138:139]
	v_pk_mul_f32 v[140:141], v[126:127], v[126:127]
	v_mov_b32_e32 v117, v128
	v_mov_b32_e32 v121, v129
	v_mov_b32_e32 v125, v141
	v_mov_b32_e32 v137, v140
	v_pk_add_f32 v[116:117], v[116:117], v[120:121]
	v_pk_add_f32 v[120:121], v[124:125], v[136:137]
	s_nop 0
	v_pk_add_f32 v[116:117], v[116:117], v[120:121]
	s_nop 0
	v_add_f32_e32 v17, v116, v117
	ds_bpermute_b32 v116, v28, v17
	s_waitcnt lgkmcnt(0)
	v_add_f32_e32 v17, v17, v116
	ds_bpermute_b32 v116, v29, v17
	s_waitcnt lgkmcnt(0)
	v_add_f32_e32 v17, v17, v116
	ds_bpermute_b32 v116, v30, v17
	s_waitcnt lgkmcnt(0)
	v_add_f32_e32 v17, v17, v116
	ds_bpermute_b32 v116, v31, v17
	s_waitcnt lgkmcnt(0)
	v_add_f32_e32 v17, v17, v116
	ds_bpermute_b32 v116, v32, v17
	s_waitcnt lgkmcnt(0)
	v_add_f32_e32 v17, v17, v116
	ds_bpermute_b32 v116, v33, v17
	s_waitcnt lgkmcnt(0)
	v_add_f32_e32 v17, v17, v116
	v_fmamk_f32 v17, v17, 0x3a800000, v146
	v_cmp_gt_f32_e32 vcc, s72, v17
	v_mul_f32_e32 v116, 0x4b800000, v17
	s_nop 0
	v_cndmask_b32_e32 v17, v17, v116, vcc
	v_rsq_f32_e32 v17, v17
	s_nop 0
	v_mul_f32_e32 v116, 0x45800000, v17
	v_cndmask_b32_e32 v17, v17, v116, vcc
	v_mul_f32_e32 v116, 0.5, v17
	v_pk_mul_f32 v[114:115], v[114:115], v[116:117] op_sel_hi:[1,0]
	v_pk_mul_f32 v[120:121], v[130:131], v[116:117] op_sel_hi:[1,0]
	v_pk_mul_f32 v[40:41], v[40:41], v[114:115]
	v_pk_mul_f32 v[38:39], v[38:39], v[120:121]
	v_pk_fma_f32 v[14:15], v[36:37], v[40:41], v[14:15]
	v_pk_fma_f32 v[12:13], v[34:35], v[38:39], v[12:13]
	v_pk_mul_f32 v[34:35], v[118:119], v[116:117] op_sel_hi:[1,0]
	v_pk_mul_f32 v[36:37], v[132:133], v[116:117] op_sel_hi:[1,0]
	v_pk_mul_f32 v[34:35], v[48:49], v[34:35]
	v_pk_mul_f32 v[36:37], v[46:47], v[36:37]
	v_pk_fma_f32 v[10:11], v[44:45], v[34:35], v[10:11]
	v_pk_fma_f32 v[8:9], v[42:43], v[36:37], v[8:9]
	v_pk_mul_f32 v[34:35], v[122:123], v[116:117] op_sel_hi:[1,0]
	v_pk_mul_f32 v[36:37], v[134:135], v[116:117] op_sel_hi:[1,0]
	v_pk_mul_f32 v[34:35], v[56:57], v[34:35]
	v_pk_mul_f32 v[38:39], v[54:55], v[36:37]
	v_pk_fma_f32 v[36:37], v[52:53], v[34:35], v[6:7]
	v_pk_fma_f32 v[34:35], v[50:51], v[38:39], v[4:5]
	v_pk_mul_f32 v[4:5], v[126:127], v[116:117] op_sel_hi:[1,0]
	v_pk_mul_f32 v[6:7], v[138:139], v[116:117] op_sel_hi:[1,0]
	s_waitcnt vmcnt(12)
	v_pk_mul_f32 v[4:5], v[64:65], v[4:5]
	v_pk_mul_f32 v[6:7], v[62:63], v[6:7]
	v_pk_fma_f32 v[40:41], v[60:61], v[4:5], v[2:3]
	v_pk_fma_f32 v[38:39], v[58:59], v[6:7], v[0:1]
	v_pk_mul_f32 v[0:1], v[14:15], v[14:15]
	v_pk_mul_f32 v[2:3], v[12:13], v[12:13]
	s_waitcnt vmcnt(10)
	v_pk_add_f32 v[42:43], v[70:71], 1.0 op_sel_hi:[1,0]
	v_pk_mov_b32 v[4:5], v[2:3], v[0:1] op_sel:[1,0]
	v_mov_b32_e32 v3, v1
	v_pk_add_f32 v[0:1], v[4:5], v[2:3]
	v_pk_mul_f32 v[2:3], v[10:11], v[10:11]
	v_pk_add_f32 v[0:1], v[0:1], v[0:1] op_sel_hi:[0,1]
	v_pk_mul_f32 v[4:5], v[8:9], v[8:9]
	v_mul_f32_e32 v0, v34, v34
	v_pk_mov_b32 v[6:7], v[4:5], v[2:3] op_sel:[1,0]
	v_mov_b32_e32 v5, v3
	v_pk_add_f32 v[2:3], v[6:7], v[4:5]
	v_pk_fma_f32 v[4:5], v[34:35], v[34:35], v[0:1] op_sel_hi:[1,1,0]
	v_mul_f32_e32 v0, v36, v36
	v_pk_add_f32 v[2:3], v[2:3], v[2:3] op_sel_hi:[0,1]
	v_pk_fma_f32 v[6:7], v[36:37], v[36:37], v[0:1] op_sel_hi:[1,1,0]
	v_mul_f32_e32 v4, v38, v38
	v_mul_f32_e32 v6, v39, v39
	v_mul_f32_e32 v0, v40, v40
	v_mul_f32_e32 v2, v41, v41
	v_pk_add_f32 v[4:5], v[4:5], v[6:7]
	v_pk_add_f32 v[0:1], v[0:1], v[2:3]
	s_waitcnt vmcnt(7)
	v_pk_add_f32 v[44:45], v[82:83], 1.0 op_sel_hi:[1,0]
	v_pk_add_f32 v[0:1], v[4:5], v[0:1]
	v_pk_add_f32 v[4:5], v[72:73], 1.0 op_sel_hi:[1,0]
	v_add_f32_e32 v0, v0, v1
	ds_bpermute_b32 v1, v28, v0
	s_waitcnt vmcnt(4)
	v_pk_add_f32 v[46:47], v[94:95], 1.0 op_sel_hi:[1,0]
	s_waitcnt lgkmcnt(0)
	v_add_f32_e32 v0, v0, v1
	ds_bpermute_b32 v1, v29, v0
	s_waitcnt lgkmcnt(0)
	v_add_f32_e32 v0, v0, v1
	ds_bpermute_b32 v1, v30, v0
	s_waitcnt lgkmcnt(0)
	v_add_f32_e32 v0, v0, v1
	ds_bpermute_b32 v1, v31, v0
	s_waitcnt lgkmcnt(0)
	v_add_f32_e32 v0, v0, v1
	ds_bpermute_b32 v1, v32, v0
	s_waitcnt lgkmcnt(0)
	v_add_f32_e32 v0, v0, v1
	ds_bpermute_b32 v1, v33, v0
	s_waitcnt lgkmcnt(0)
	v_add_f32_e32 v0, v0, v1
	v_fmamk_f32 v0, v0, 0x3a800000, v146
	v_cmp_gt_f32_e32 vcc, s72, v0
	v_mul_f32_e32 v1, 0x4b800000, v0
	s_nop 0
	v_cndmask_b32_e32 v0, v0, v1, vcc
	v_rsq_f32_e32 v0, v0
	s_nop 0
	v_mul_f32_e32 v1, 0x45800000, v0
	v_cndmask_b32_e32 v6, v0, v1, vcc
	v_pk_mul_f32 v[0:1], v[14:15], v[6:7] op_sel_hi:[1,0]
	v_pk_mul_f32 v[2:3], v[12:13], v[6:7] op_sel_hi:[1,0]
	v_pk_mul_f32 v[0:1], v[76:77], v[0:1]
	v_pk_mul_f32 v[2:3], v[74:75], v[2:3]
	v_pk_fma_f32 v[4:5], v[4:5], v[0:1], v[68:69]
	v_pk_fma_f32 v[0:1], v[42:43], v[2:3], v[66:67]
	v_pk_mul_f32 v[2:3], v[10:11], v[6:7] op_sel_hi:[1,0]
	v_cvt_pk_bf16_f32 v0, v0, v1
	v_cvt_pk_bf16_f32 v1, v4, v5
	v_pk_mul_f32 v[4:5], v[8:9], v[6:7] op_sel_hi:[1,0]
	v_pk_mul_f32 v[2:3], v[88:89], v[2:3]
	v_pk_mul_f32 v[4:5], v[86:87], v[4:5]
	v_pk_add_f32 v[42:43], v[84:85], 1.0 op_sel_hi:[1,0]
	s_nop 0
	v_pk_fma_f32 v[42:43], v[42:43], v[2:3], v[80:81]
	v_pk_fma_f32 v[2:3], v[44:45], v[4:5], v[78:79]
	v_pk_mul_f32 v[4:5], v[36:37], v[6:7] op_sel_hi:[1,0]
	v_cvt_pk_bf16_f32 v2, v2, v3
	v_cvt_pk_bf16_f32 v3, v42, v43
	v_pk_mul_f32 v[42:43], v[34:35], v[6:7] op_sel_hi:[1,0]
	s_waitcnt vmcnt(3)
	v_pk_mul_f32 v[4:5], v[100:101], v[4:5]
	v_pk_mul_f32 v[42:43], v[98:99], v[42:43]
	v_pk_add_f32 v[44:45], v[96:97], 1.0 op_sel_hi:[1,0]
	s_nop 0
	v_pk_fma_f32 v[44:45], v[44:45], v[4:5], v[92:93]
	v_pk_fma_f32 v[4:5], v[46:47], v[42:43], v[90:91]
	v_pk_mul_f32 v[42:43], v[40:41], v[6:7] op_sel_hi:[1,0]
	v_pk_mul_f32 v[6:7], v[38:39], v[6:7] op_sel_hi:[1,0]
	s_waitcnt vmcnt(1)
	v_pk_add_f32 v[46:47], v[106:107], 1.0 op_sel_hi:[1,0]
	s_waitcnt vmcnt(0)
	v_pk_mul_f32 v[6:7], v[110:111], v[6:7]
	v_cvt_pk_bf16_f32 v4, v4, v5
	v_cvt_pk_bf16_f32 v5, v44, v45
	v_pk_mul_f32 v[42:43], v[112:113], v[42:43]
	v_pk_add_f32 v[44:45], v[108:109], 1.0 op_sel_hi:[1,0]
	v_pk_fma_f32 v[6:7], v[46:47], v[6:7], v[102:103]
	v_pk_fma_f32 v[42:43], v[44:45], v[42:43], v[104:105]
	v_cvt_pk_bf16_f32 v6, v6, v7
	s_nop 0
	v_cvt_pk_bf16_f32 v7, v42, v43
	global_store_dwordx4 v[26:27], v[12:15], off sc1
	global_store_dwordx4 v[26:27], v[8:11], off offset:1024 sc1
	global_store_dwordx4 v[26:27], v[34:37], off offset:2048 sc1
	global_store_dwordx4 v[26:27], v[38:41], off offset:3072 sc1
	v_add_co_u32_e32 v8, vcc, s74, v24
	v_lshl_add_u64 v[26:27], v[26:27], 0, s[34:35]
	s_nop 0
	v_addc_co_u32_e32 v9, vcc, -1, v25, vcc
	v_cmp_lt_i32_e32 vcc, s75, v16
	v_lshl_add_u64 v[24:25], v[24:25], 0, s[84:85]
	s_or_b64 s[4:5], vcc, s[4:5]
	global_store_dwordx2 v[8:9], v[0:1], off offset:-1536 sc1
	global_store_dwordx2 v[8:9], v[2:3], off offset:-1024 sc1
	global_store_dwordx2 v[8:9], v[4:5], off offset:-512 sc1
	global_store_dwordx2 v[8:9], v[6:7], off sc1
	s_andn2_b64 exec, exec, s[4:5]
	s_cbranch_execnz .LBB0_522

.LBB0_597:
	s_cmp_lt_i32 s6, 16
	s_cselect_b64 s[4:5], -1, 0
	s_cmp_gt_i32 s8, 1
	s_cselect_b64 s[42:43], -1, 0
	s_cmp_gt_u32 s8, 3
	v_sub_co_u32_e64 v128, s[26:27], s8, 6
	s_cselect_b64 s[54:55], -1, 0
	s_xor_b64 s[60:61], s[26:27], -1
	s_cmp_gt_u32 s8, 7
	s_cselect_b64 s[58:59], -1, 0
	s_lshl_b32 s8, s8, 8
	s_add_i32 s38, s8, 0xfffff800
	s_lshl_b64 s[26:27], s[38:39], 1
	s_add_u32 s64, s41, s26
	s_addc_u32 s65, s33, s27
	s_ashr_i32 s9, s8, 31
	s_add_i32 s93, s8, 0xfffffc00
	s_add_i32 s91, s8, 0xfffffe00
	s_lshl_b64 s[8:9], s[8:9], 1
	s_add_u32 s62, s85, s8
	s_addc_u32 s63, s53, s9
	s_lshl_b32 s95, s6, 8
	v_lshlrev_b32_e32 v144, 11, v128
	s_add_i32 s95, s95, s75
	v_lshl_add_u64 v[168:169], s[88:89], 0, v[144:145]
	v_lshlrev_b32_e32 v144, 9, v128
	v_or_b32_e32 v128, s95, v140
	s_add_i32 s7, s95, 0xfffff000
	v_bitop3_b32 v131, s95, v195, v140 bitop3:0xc8
	v_lshl_add_u64 v[166:167], s[22:23], 0, v[144:145]
	s_ashr_i32 s7, s7, 10
	v_bitop3_b32 v130, s95, v194, v140 bitop3:0xc8
	v_ashrrev_i32_e32 v129, 31, v128
	v_lshlrev_b32_e32 v144, 1, v131
	s_ashr_i32 s6, s95, 8
	v_lshlrev_b64 v[180:181], 10, v[128:129]
	v_lshl_add_u64 v[174:175], v[168:169], 0, v[144:145]
	v_lshlrev_b32_e32 v144, 1, v130
	s_lshl_b32 s31, s7, 7
	v_bfe_u32 v128, v128, 6, 4
	v_lshl_add_u64 v[176:177], v[166:167], 0, v[144:145]
	v_lshlrev_b32_e32 v144, 11, v130
	v_or_b32_e32 v161, s31, v128
	s_lshl_b32 s36, s6, 6
	v_lshrrev_b32_e32 v128, 5, v130
	s_lshl_b32 s37, s7, 13
	s_lshl_b32 s26, s6, 11
	s_mov_b64 s[44:45], -1
	v_lshl_add_u64 v[178:179], s[64:65], 0, v[180:181]
	s_lshl_b32 s40, s7, 8
	s_and_b32 s30, s95, 0xffffff00
	s_lshl_b32 s73, s6, 2
	v_lshl_add_u64 v[172:173], s[12:13], 0, v[144:145]
	v_or_b32_e32 v203, s36, v128
	v_or_b32_e32 v157, s37, v131
	v_or_b32_e32 v159, s26, v130
	v_lshl_add_u64 v[170:171], s[24:25], 0, v[144:145]
	s_and_b64 vcc, exec, s[42:43]
	s_cbranch_vccz .LBB0_615
	s_mov_b64 s[6:7], -1
	s_and_b64 vcc, exec, s[54:55]
	s_cbranch_vccz .LBB0_611
	s_and_b64 vcc, exec, s[60:61]
	s_cbranch_vccz .LBB0_605
	s_and_b64 vcc, exec, s[58:59]
	s_cbranch_vccz .LBB0_602
	v_mul_f32_e32 v128, 0x3d372713, v124
	v_mul_f32_e32 v128, v124, v128
	v_fma_f32 v128, v124, v128, v124
	v_mul_f32_e32 v128, 0x3f4c422a, v128
	v_add_f32_e32 v128, v128, v128
	v_mul_f32_e32 v128, 0x3fb8aa3b, v128
	v_exp_f32_e32 v128, v128
	v_mul_f32_e32 v129, 0.5, v124
	v_mul_f32_e32 v130, 0.5, v125
	v_mul_f32_e32 v131, 0.5, v127
	v_add_f32_e32 v128, 1.0, v128
	v_rcp_f32_e32 v128, v128
	v_mul_f32_e32 v144, 0.5, v121
	v_mul_f32_e32 v190, 0.5, v123
	s_mov_b64 s[6:7], 0
	v_fma_f32 v128, v128, -2.0, 1.0
	v_add_f32_e32 v128, 1.0, v128
	v_mul_f32_e32 v128, v129, v128
	v_mul_f32_e32 v129, 0x3d372713, v125
	v_mul_f32_e32 v129, v125, v129
	v_fma_f32 v129, v125, v129, v125
	v_mul_f32_e32 v129, 0x3f4c422a, v129
	v_add_f32_e32 v129, v129, v129
	v_mul_f32_e32 v129, 0x3fb8aa3b, v129
	v_exp_f32_e32 v129, v129
	s_nop 0
	v_add_f32_e32 v129, 1.0, v129
	v_rcp_f32_e32 v129, v129
	s_nop 0
	v_fma_f32 v129, v129, -2.0, 1.0
	v_add_f32_e32 v129, 1.0, v129
	v_mul_f32_e32 v129, v130, v129
	v_cvt_pk_bf16_f32 v128, v128, v129
	v_mul_f32_e32 v129, 0x3d372713, v126
	v_mul_f32_e32 v129, v126, v129
	v_fma_f32 v129, v126, v129, v126
	v_mul_f32_e32 v129, 0x3f4c422a, v129
	v_add_f32_e32 v129, v129, v129
	v_mul_f32_e32 v129, 0x3fb8aa3b, v129
	v_exp_f32_e32 v129, v129
	v_mul_f32_e32 v130, 0.5, v126
	v_add_f32_e32 v129, 1.0, v129
	v_rcp_f32_e32 v129, v129
	s_nop 0
	v_fma_f32 v129, v129, -2.0, 1.0
	v_add_f32_e32 v129, 1.0, v129
	v_mul_f32_e32 v129, v130, v129
	v_mul_f32_e32 v130, 0x3d372713, v127
	v_mul_f32_e32 v130, v127, v130
	v_fma_f32 v130, v127, v130, v127
	v_mul_f32_e32 v130, 0x3f4c422a, v130
	v_add_f32_e32 v130, v130, v130
	v_mul_f32_e32 v130, 0x3fb8aa3b, v130
	v_exp_f32_e32 v130, v130
	s_nop 0
	v_add_f32_e32 v130, 1.0, v130
	v_rcp_f32_e32 v130, v130
	s_nop 0
	v_fma_f32 v130, v130, -2.0, 1.0
	v_add_f32_e32 v130, 1.0, v130
	v_mul_f32_e32 v130, v131, v130
	v_cvt_pk_bf16_f32 v129, v129, v130
	v_mul_f32_e32 v130, 0x3d372713, v120
	v_mul_f32_e32 v130, v120, v130
	v_fma_f32 v130, v120, v130, v120
	v_mul_f32_e32 v130, 0x3f4c422a, v130
	v_add_f32_e32 v130, v130, v130
	v_mul_f32_e32 v130, 0x3fb8aa3b, v130
	v_exp_f32_e32 v130, v130
	v_mul_f32_e32 v131, 0.5, v120
	v_add_f32_e32 v130, 1.0, v130
	v_rcp_f32_e32 v130, v130
	s_nop 0
	v_fma_f32 v130, v130, -2.0, 1.0
	v_add_f32_e32 v130, 1.0, v130
	v_mul_f32_e32 v130, v131, v130
	v_mul_f32_e32 v131, 0x3d372713, v121
	v_mul_f32_e32 v131, v121, v131
	v_fma_f32 v131, v121, v131, v121
	v_mul_f32_e32 v131, 0x3f4c422a, v131
	v_add_f32_e32 v131, v131, v131
	v_mul_f32_e32 v131, 0x3fb8aa3b, v131
	v_exp_f32_e32 v131, v131
	s_nop 0
	v_add_f32_e32 v131, 1.0, v131
	v_rcp_f32_e32 v131, v131
	s_nop 0
	v_fma_f32 v131, v131, -2.0, 1.0
	v_add_f32_e32 v131, 1.0, v131
	v_mul_f32_e32 v131, v144, v131
	v_cvt_pk_bf16_f32 v130, v130, v131
	v_mul_f32_e32 v131, 0x3d372713, v122
	v_mul_f32_e32 v131, v122, v131
	v_fma_f32 v131, v122, v131, v122
	v_mul_f32_e32 v131, 0x3f4c422a, v131
	v_add_f32_e32 v131, v131, v131
	v_mul_f32_e32 v131, 0x3fb8aa3b, v131
	v_exp_f32_e32 v131, v131
	v_mul_f32_e32 v144, 0.5, v122
	v_add_f32_e32 v131, 1.0, v131
	v_rcp_f32_e32 v131, v131
	s_nop 0
	v_fma_f32 v131, v131, -2.0, 1.0
	v_add_f32_e32 v131, 1.0, v131
	v_mul_f32_e32 v131, v144, v131
	v_mul_f32_e32 v144, 0x3d372713, v123
	v_mul_f32_e32 v144, v123, v144
	v_fma_f32 v144, v123, v144, v123
	v_mul_f32_e32 v144, 0x3f4c422a, v144
	v_add_f32_e32 v144, v144, v144
	v_mul_f32_e32 v144, 0x3fb8aa3b, v144
	v_exp_f32_e32 v144, v144
	s_nop 0
	v_add_f32_e32 v144, 1.0, v144
	v_rcp_f32_e32 v144, v144
	s_nop 0
	v_fma_f32 v144, v144, -2.0, 1.0
	v_add_f32_e32 v144, 1.0, v144
	v_mul_f32_e32 v144, v190, v144
	v_cvt_pk_bf16_f32 v131, v131, v144
	v_lshlrev_b32_e32 v144, 1, v142
	v_lshl_add_u64 v[190:191], v[178:179], 0, v[144:145]
	global_store_dwordx4 v[190:191], v[128:131], off sc1

.LBB0_611:
	s_andn2_b64 vcc, exec, s[6:7]
	s_cbranch_vccnz .LBB0_614
	v_or_b32_e32 v128, s91, v142
	s_and_b64 s[6:7], s[4:5], exec
	v_lshrrev_b32_e32 v129, 6, v128
	s_cselect_b32 s8, 8, 10
	v_cndmask_b32_e64 v130, v157, v159, s[4:5]
	v_lshl_add_u32 v130, v129, s8, v130
	v_ashrrev_i32_e32 v131, 31, v130
	s_cselect_b32 s7, s47, s69
	s_cselect_b32 s6, s46, s2
	v_lshlrev_b64 v[130:131], 7, v[130:131]
	v_lshl_add_u64 v[130:131], s[6:7], 0, v[130:131]
	v_lshlrev_b32_e32 v144, 1, v154
	v_lshl_add_u64 v[130:131], v[130:131], 0, v[144:145]
	s_andn2_b64 vcc, exec, s[4:5]
	v_cvt_pk_bf16_f32 v204, v124, v125
	v_cvt_pk_bf16_f32 v205, v126, v127
	v_cvt_pk_bf16_f32 v206, v120, v121
	v_cvt_pk_bf16_f32 v207, v122, v123
	global_store_dwordx4 v[130:131], v[204:207], off sc1
	s_cbranch_vccnz .LBB0_614
	s_or_b32 s6, s73, s70
	s_ashr_i32 s7, s6, 31
	s_lshl_b64 s[6:7], s[6:7], 19
	v_lshl_add_u64 v[130:131], v[170:171], 0, s[6:7]
	v_mov_b32_e32 v129, v145
	v_lshl_add_u64 v[128:129], v[128:129], 2, v[130:131]
	global_store_dwordx4 v[128:129], v[124:127], off nt
	global_store_dwordx4 v[128:129], v[120:123], off offset:16 nt

.LBB0_615:
	v_lshl_add_u64 v[130:131], s[62:63], 0, v[180:181]
	s_andn2_b64 vcc, exec, s[44:45]
	v_lshlrev_b32_e32 v128, 1, v142
	s_cbranch_vccnz .LBB0_617
	v_pk_mul_f32 v[124:125], v[124:125], s[52:53] op_sel_hi:[1,0]
	v_mov_b32_e32 v129, v145
	v_pk_mul_f32 v[180:181], v[122:123], s[52:53] op_sel_hi:[1,0]
	v_pk_mul_f32 v[122:123], v[120:121], s[52:53] op_sel_hi:[1,0]
	v_cvt_pk_bf16_f32 v120, v124, v125
	v_lshl_add_u64 v[124:125], v[130:131], 0, v[128:129]
	v_pk_mul_f32 v[126:127], v[126:127], s[52:53] op_sel_hi:[1,0]
	s_nop 0
	v_cvt_pk_bf16_f32 v121, v126, v127
	v_cvt_pk_bf16_f32 v122, v122, v123
	v_cvt_pk_bf16_f32 v123, v180, v181
	global_store_dwordx4 v[124:125], v[120:123], off sc1
.LBB0_617:
	s_nop 1
	v_cndmask_b32_e64 v120, 0, 1, s[42:43]
	v_cmp_ne_u32_e64 s[8:9], 1, v120
	v_cndmask_b32_e64 v120, 0, 1, s[54:55]
	s_mov_b64 s[44:45], -1
	s_andn2_b64 vcc, exec, s[42:43]
	v_cmp_ne_u32_e64 s[6:7], 1, v120
	s_cbranch_vccnz .LBB0_635
	s_and_b64 vcc, exec, s[6:7]
	s_mov_b64 s[42:43], -1
	s_cbranch_vccnz .LBB0_631
	s_andn2_b64 vcc, exec, s[60:61]
	s_cbranch_vccnz .LBB0_625
	s_andn2_b64 vcc, exec, s[58:59]
	s_cbranch_vccnz .LBB0_622
	v_mul_f32_e32 v120, 0x3d372713, v116
	v_mul_f32_e32 v120, v116, v120
	v_fma_f32 v120, v116, v120, v116
	v_mul_f32_e32 v120, 0x3f4c422a, v120
	v_add_f32_e32 v120, v120, v120
	v_mul_f32_e32 v120, 0x3fb8aa3b, v120
	v_exp_f32_e32 v120, v120
	v_mul_f32_e32 v121, 0.5, v116
	v_mul_f32_e32 v122, 0.5, v117
	v_mul_f32_e32 v123, 0.5, v119
	v_add_f32_e32 v120, 1.0, v120
	v_rcp_f32_e32 v120, v120
	v_mul_f32_e32 v124, 0.5, v113
	v_mul_f32_e32 v125, 0.5, v115
	v_mov_b32_e32 v129, v145
	v_fma_f32 v120, v120, -2.0, 1.0
	v_add_f32_e32 v120, 1.0, v120
	v_mul_f32_e32 v120, v121, v120
	v_mul_f32_e32 v121, 0x3d372713, v117
	v_mul_f32_e32 v121, v117, v121
	v_fma_f32 v121, v117, v121, v117
	v_mul_f32_e32 v121, 0x3f4c422a, v121
	v_add_f32_e32 v121, v121, v121
	v_mul_f32_e32 v121, 0x3fb8aa3b, v121
	v_exp_f32_e32 v121, v121
	s_mov_b64 s[42:43], 0
	v_add_f32_e32 v121, 1.0, v121
	v_rcp_f32_e32 v121, v121
	s_nop 0
	v_fma_f32 v121, v121, -2.0, 1.0
	v_add_f32_e32 v121, 1.0, v121
	v_mul_f32_e32 v121, v122, v121
	v_cvt_pk_bf16_f32 v120, v120, v121
	v_mul_f32_e32 v121, 0x3d372713, v118
	v_mul_f32_e32 v121, v118, v121
	v_fma_f32 v121, v118, v121, v118
	v_mul_f32_e32 v121, 0x3f4c422a, v121
	v_add_f32_e32 v121, v121, v121
	v_mul_f32_e32 v121, 0x3fb8aa3b, v121
	v_exp_f32_e32 v121, v121
	v_mul_f32_e32 v122, 0.5, v118
	v_add_f32_e32 v121, 1.0, v121
	v_rcp_f32_e32 v121, v121
	s_nop 0
	v_fma_f32 v121, v121, -2.0, 1.0
	v_add_f32_e32 v121, 1.0, v121
	v_mul_f32_e32 v121, v122, v121
	v_mul_f32_e32 v122, 0x3d372713, v119
	v_mul_f32_e32 v122, v119, v122
	v_fma_f32 v122, v119, v122, v119
	v_mul_f32_e32 v122, 0x3f4c422a, v122
	v_add_f32_e32 v122, v122, v122
	v_mul_f32_e32 v122, 0x3fb8aa3b, v122
	v_exp_f32_e32 v122, v122
	s_nop 0
	v_add_f32_e32 v122, 1.0, v122
	v_rcp_f32_e32 v122, v122
	s_nop 0
	v_fma_f32 v122, v122, -2.0, 1.0
	v_add_f32_e32 v122, 1.0, v122
	v_mul_f32_e32 v122, v123, v122
	v_cvt_pk_bf16_f32 v121, v121, v122
	v_mul_f32_e32 v122, 0x3d372713, v112
	v_mul_f32_e32 v122, v112, v122
	v_fma_f32 v122, v112, v122, v112
	v_mul_f32_e32 v122, 0x3f4c422a, v122
	v_add_f32_e32 v122, v122, v122
	v_mul_f32_e32 v122, 0x3fb8aa3b, v122
	v_exp_f32_e32 v122, v122
	v_mul_f32_e32 v123, 0.5, v112
	v_add_f32_e32 v122, 1.0, v122
	v_rcp_f32_e32 v122, v122
	s_nop 0
	v_fma_f32 v122, v122, -2.0, 1.0
	v_add_f32_e32 v122, 1.0, v122
	v_mul_f32_e32 v122, v123, v122
	v_mul_f32_e32 v123, 0x3d372713, v113
	v_mul_f32_e32 v123, v113, v123
	v_fma_f32 v123, v113, v123, v113
	v_mul_f32_e32 v123, 0x3f4c422a, v123
	v_add_f32_e32 v123, v123, v123
	v_mul_f32_e32 v123, 0x3fb8aa3b, v123
	v_exp_f32_e32 v123, v123
	s_nop 0
	v_add_f32_e32 v123, 1.0, v123
	v_rcp_f32_e32 v123, v123
	s_nop 0
	v_fma_f32 v123, v123, -2.0, 1.0
	v_add_f32_e32 v123, 1.0, v123
	v_mul_f32_e32 v123, v124, v123
	v_cvt_pk_bf16_f32 v122, v122, v123
	v_mul_f32_e32 v123, 0x3d372713, v114
	v_mul_f32_e32 v123, v114, v123
	v_fma_f32 v123, v114, v123, v114
	v_mul_f32_e32 v123, 0x3f4c422a, v123
	v_add_f32_e32 v123, v123, v123
	v_mul_f32_e32 v123, 0x3fb8aa3b, v123
	v_exp_f32_e32 v123, v123
	v_mul_f32_e32 v124, 0.5, v114
	v_add_f32_e32 v123, 1.0, v123
	v_rcp_f32_e32 v123, v123
	s_nop 0
	v_fma_f32 v123, v123, -2.0, 1.0
	v_add_f32_e32 v123, 1.0, v123
	v_mul_f32_e32 v123, v124, v123
	v_mul_f32_e32 v124, 0x3d372713, v115
	v_mul_f32_e32 v124, v115, v124
	v_fma_f32 v124, v115, v124, v115
	v_mul_f32_e32 v124, 0x3f4c422a, v124
	v_add_f32_e32 v124, v124, v124
	v_mul_f32_e32 v124, 0x3fb8aa3b, v124
	v_exp_f32_e32 v124, v124
	s_nop 0
	v_add_f32_e32 v124, 1.0, v124
	v_rcp_f32_e32 v124, v124
	s_nop 0
	v_fma_f32 v124, v124, -2.0, 1.0
	v_add_f32_e32 v124, 1.0, v124
	v_mul_f32_e32 v124, v125, v124
	v_cvt_pk_bf16_f32 v123, v123, v124
	v_lshl_add_u64 v[124:125], v[178:179], 0, v[128:129]
	global_store_dwordx4 v[124:125], v[120:123], off offset:256 sc1

.LBB0_631:
	s_andn2_b64 vcc, exec, s[42:43]
	s_cbranch_vccnz .LBB0_634
	v_or_b32_e32 v124, s91, v143
	s_and_b64 s[42:43], s[4:5], exec
	v_lshrrev_b32_e32 v124, 6, v124
	s_cselect_b32 s27, 8, 10
	v_cndmask_b32_e64 v125, v157, v159, s[4:5]
	v_lshl_add_u32 v124, v124, s27, v125
	v_ashrrev_i32_e32 v125, 31, v124
	s_cselect_b32 s43, s47, s69
	s_cselect_b32 s42, s46, s2
	v_lshlrev_b64 v[124:125], 7, v[124:125]
	v_lshl_add_u64 v[124:125], s[42:43], 0, v[124:125]
	v_lshlrev_b32_e32 v144, 1, v154
	v_lshl_add_u64 v[124:125], v[124:125], 0, v[144:145]
	s_andn2_b64 vcc, exec, s[4:5]
	v_cvt_pk_bf16_f32 v120, v116, v117
	v_cvt_pk_bf16_f32 v121, v118, v119
	v_cvt_pk_bf16_f32 v122, v112, v113
	v_cvt_pk_bf16_f32 v123, v114, v115
	global_store_dwordx4 v[124:125], v[120:123], off sc1
	s_cbranch_vccnz .LBB0_634
	s_or_b32 s42, s73, s70
	s_ashr_i32 s43, s42, 31
	s_lshl_b64 s[42:43], s[42:43], 19
	v_lshl_add_u64 v[120:121], v[170:171], 0, s[42:43]
	v_add_u32_e32 v144, s91, v142
	v_lshl_add_u64 v[120:121], v[144:145], 2, v[120:121]
	global_store_dwordx4 v[120:121], v[116:119], off offset:512 nt
	global_store_dwordx4 v[120:121], v[112:115], off offset:528 nt

.LBB0_635:
	s_andn2_b64 vcc, exec, s[44:45]
	s_cbranch_vccnz .LBB0_637
	v_pk_mul_f32 v[116:117], v[116:117], s[52:53] op_sel_hi:[1,0]
	v_mov_b32_e32 v129, v145
	v_pk_mul_f32 v[120:121], v[114:115], s[52:53] op_sel_hi:[1,0]
	v_pk_mul_f32 v[114:115], v[112:113], s[52:53] op_sel_hi:[1,0]
	v_cvt_pk_bf16_f32 v112, v116, v117
	v_lshl_add_u64 v[116:117], v[130:131], 0, v[128:129]
	v_pk_mul_f32 v[118:119], v[118:119], s[52:53] op_sel_hi:[1,0]
	s_nop 0
	v_cvt_pk_bf16_f32 v113, v118, v119
	v_cvt_pk_bf16_f32 v114, v114, v115
	v_cvt_pk_bf16_f32 v115, v120, v121
	global_store_dwordx4 v[116:117], v[112:115], off offset:256 sc1
.LBB0_637:
	s_nop 1
	v_or_b32_e32 v112, s95, v156
	v_bitop3_b32 v115, s95, v197, v156 bitop3:0xc8
	v_bitop3_b32 v114, s95, v196, v156 bitop3:0xc8
	v_ashrrev_i32_e32 v113, 31, v112
	v_lshlrev_b32_e32 v144, 1, v115
	v_lshlrev_b64 v[126:127], 10, v[112:113]
	v_lshl_add_u64 v[120:121], v[168:169], 0, v[144:145]
	v_lshlrev_b32_e32 v144, 1, v114
	v_bfe_u32 v112, v112, 6, 4
	v_lshl_add_u64 v[122:123], v[166:167], 0, v[144:145]
	v_lshlrev_b32_e32 v144, 11, v114
	v_or_b32_e32 v157, s31, v112
	v_lshrrev_b32_e32 v112, 5, v114
	v_lshl_add_u64 v[124:125], s[64:65], 0, v[126:127]
	v_lshl_add_u64 v[118:119], s[12:13], 0, v[144:145]
	v_or_b32_e32 v159, s36, v112
	v_or_b32_e32 v130, s37, v115
	v_or_b32_e32 v131, s26, v114
	v_lshl_add_u64 v[116:117], s[24:25], 0, v[144:145]
	s_and_b64 vcc, exec, s[8:9]
	s_mov_b64 s[42:43], -1
	s_cbranch_vccnz .LBB0_648
	s_and_b64 vcc, exec, s[6:7]
	s_cbranch_vccnz .LBB0_745
	s_andn2_b64 vcc, exec, s[60:61]
	s_cbranch_vccnz .LBB0_645
	s_andn2_b64 vcc, exec, s[58:59]
	s_cbranch_vccnz .LBB0_642
	v_mul_f32_e32 v112, 0x3d372713, v108
	v_mul_f32_e32 v112, v108, v112
	v_fma_f32 v112, v108, v112, v108
	v_mul_f32_e32 v112, 0x3f4c422a, v112
	v_add_f32_e32 v112, v112, v112
	v_mul_f32_e32 v112, 0x3fb8aa3b, v112
	v_exp_f32_e32 v112, v112
	v_mul_f32_e32 v113, 0.5, v108
	v_mul_f32_e32 v114, 0.5, v109
	v_mul_f32_e32 v115, 0.5, v111
	v_add_f32_e32 v112, 1.0, v112
	v_rcp_f32_e32 v112, v112
	v_mul_f32_e32 v129, 0.5, v105
	v_mul_f32_e32 v144, 0.5, v107
	s_mov_b64 s[42:43], 0
	v_fma_f32 v112, v112, -2.0, 1.0
	v_add_f32_e32 v112, 1.0, v112
	v_mul_f32_e32 v112, v113, v112
	v_mul_f32_e32 v113, 0x3d372713, v109
	v_mul_f32_e32 v113, v109, v113
	v_fma_f32 v113, v109, v113, v109
	v_mul_f32_e32 v113, 0x3f4c422a, v113
	v_add_f32_e32 v113, v113, v113
	v_mul_f32_e32 v113, 0x3fb8aa3b, v113
	v_exp_f32_e32 v113, v113
	s_nop 0
	v_add_f32_e32 v113, 1.0, v113
	v_rcp_f32_e32 v113, v113
	s_nop 0
	v_fma_f32 v113, v113, -2.0, 1.0
	v_add_f32_e32 v113, 1.0, v113
	v_mul_f32_e32 v113, v114, v113
	v_cvt_pk_bf16_f32 v112, v112, v113
	v_mul_f32_e32 v113, 0x3d372713, v110
	v_mul_f32_e32 v113, v110, v113
	v_fma_f32 v113, v110, v113, v110
	v_mul_f32_e32 v113, 0x3f4c422a, v113
	v_add_f32_e32 v113, v113, v113
	v_mul_f32_e32 v113, 0x3fb8aa3b, v113
	v_exp_f32_e32 v113, v113
	v_mul_f32_e32 v114, 0.5, v110
	v_add_f32_e32 v113, 1.0, v113
	v_rcp_f32_e32 v113, v113
	s_nop 0
	v_fma_f32 v113, v113, -2.0, 1.0
	v_add_f32_e32 v113, 1.0, v113
	v_mul_f32_e32 v113, v114, v113
	v_mul_f32_e32 v114, 0x3d372713, v111
	v_mul_f32_e32 v114, v111, v114
	v_fma_f32 v114, v111, v114, v111
	v_mul_f32_e32 v114, 0x3f4c422a, v114
	v_add_f32_e32 v114, v114, v114
	v_mul_f32_e32 v114, 0x3fb8aa3b, v114
	v_exp_f32_e32 v114, v114
	s_nop 0
	v_add_f32_e32 v114, 1.0, v114
	v_rcp_f32_e32 v114, v114
	s_nop 0
	v_fma_f32 v114, v114, -2.0, 1.0
	v_add_f32_e32 v114, 1.0, v114
	v_mul_f32_e32 v114, v115, v114
	v_cvt_pk_bf16_f32 v113, v113, v114
	v_mul_f32_e32 v114, 0x3d372713, v104
	v_mul_f32_e32 v114, v104, v114
	v_fma_f32 v114, v104, v114, v104
	v_mul_f32_e32 v114, 0x3f4c422a, v114
	v_add_f32_e32 v114, v114, v114
	v_mul_f32_e32 v114, 0x3fb8aa3b, v114
	v_exp_f32_e32 v114, v114
	v_mul_f32_e32 v115, 0.5, v104
	v_add_f32_e32 v114, 1.0, v114
	v_rcp_f32_e32 v114, v114
	s_nop 0
	v_fma_f32 v114, v114, -2.0, 1.0
	v_add_f32_e32 v114, 1.0, v114
	v_mul_f32_e32 v114, v115, v114
	v_mul_f32_e32 v115, 0x3d372713, v105
	v_mul_f32_e32 v115, v105, v115
	v_fma_f32 v115, v105, v115, v105
	v_mul_f32_e32 v115, 0x3f4c422a, v115
	v_add_f32_e32 v115, v115, v115
	v_mul_f32_e32 v115, 0x3fb8aa3b, v115
	v_exp_f32_e32 v115, v115
	s_nop 0
	v_add_f32_e32 v115, 1.0, v115
	v_rcp_f32_e32 v115, v115
	s_nop 0
	v_fma_f32 v115, v115, -2.0, 1.0
	v_add_f32_e32 v115, 1.0, v115
	v_mul_f32_e32 v115, v129, v115
	v_cvt_pk_bf16_f32 v114, v114, v115
	v_mul_f32_e32 v115, 0x3d372713, v106
	v_mul_f32_e32 v115, v106, v115
	v_fma_f32 v115, v106, v115, v106
	v_mul_f32_e32 v115, 0x3f4c422a, v115
	v_add_f32_e32 v115, v115, v115
	v_mul_f32_e32 v115, 0x3fb8aa3b, v115
	v_exp_f32_e32 v115, v115
	v_mul_f32_e32 v129, 0.5, v106
	v_add_f32_e32 v115, 1.0, v115
	v_rcp_f32_e32 v115, v115
	s_nop 0
	v_fma_f32 v115, v115, -2.0, 1.0
	v_add_f32_e32 v115, 1.0, v115
	v_mul_f32_e32 v115, v129, v115
	v_mul_f32_e32 v129, 0x3d372713, v107
	v_mul_f32_e32 v129, v107, v129
	v_fma_f32 v129, v107, v129, v107
	v_mul_f32_e32 v129, 0x3f4c422a, v129
	v_add_f32_e32 v129, v129, v129
	v_mul_f32_e32 v129, 0x3fb8aa3b, v129
	v_exp_f32_e32 v129, v129
	s_nop 0
	v_add_f32_e32 v129, 1.0, v129
	v_rcp_f32_e32 v129, v129
	s_nop 0
	v_fma_f32 v129, v129, -2.0, 1.0
	v_add_f32_e32 v129, 1.0, v129
	v_mul_f32_e32 v129, v144, v129
	v_cvt_pk_bf16_f32 v115, v115, v129
	v_mov_b32_e32 v129, v145
	v_lshl_add_u64 v[170:171], v[124:125], 0, v[128:129]
	global_store_dwordx4 v[170:171], v[112:115], off sc1

.LBB0_649:
	v_pk_mul_f32 v[108:109], v[108:109], s[52:53] op_sel_hi:[1,0]
	v_mov_b32_e32 v129, v145
	v_pk_mul_f32 v[114:115], v[106:107], s[52:53] op_sel_hi:[1,0]
	v_pk_mul_f32 v[106:107], v[104:105], s[52:53] op_sel_hi:[1,0]
	v_cvt_pk_bf16_f32 v104, v108, v109
	v_lshl_add_u64 v[108:109], v[112:113], 0, v[128:129]
	v_pk_mul_f32 v[110:111], v[110:111], s[52:53] op_sel_hi:[1,0]
	s_nop 0
	v_cvt_pk_bf16_f32 v105, v110, v111
	v_cvt_pk_bf16_f32 v106, v106, v107
	v_cvt_pk_bf16_f32 v107, v114, v115
	global_store_dwordx4 v[108:109], v[104:107], off sc1
	s_and_b64 vcc, exec, s[8:9]
	s_mov_b64 s[42:43], -1
	s_cbranch_vccz .LBB0_750

.LBB0_651:
	v_pk_mul_f32 v[100:101], v[100:101], s[52:53] op_sel_hi:[1,0]
	v_mov_b32_e32 v129, v145
	v_pk_mul_f32 v[104:105], v[98:99], s[52:53] op_sel_hi:[1,0]
	v_pk_mul_f32 v[98:99], v[96:97], s[52:53] op_sel_hi:[1,0]
	v_cvt_pk_bf16_f32 v96, v100, v101
	v_lshl_add_u64 v[100:101], v[112:113], 0, v[128:129]
	v_pk_mul_f32 v[102:103], v[102:103], s[52:53] op_sel_hi:[1,0]
	s_nop 0
	v_cvt_pk_bf16_f32 v97, v102, v103
	v_cvt_pk_bf16_f32 v98, v98, v99
	v_cvt_pk_bf16_f32 v99, v104, v105
	global_store_dwordx4 v[100:101], v[96:99], off offset:256 sc1
.LBB0_652:
	s_nop 1
	v_bitop3_b32 v99, s95, v199, v158 bitop3:0xc8
	v_or_b32_e32 v96, s95, v158
	v_bitop3_b32 v98, s95, v198, v158 bitop3:0xc8
	v_lshlrev_b32_e32 v144, 1, v99
	v_ashrrev_i32_e32 v97, 31, v96
	v_lshl_add_u64 v[104:105], v[168:169], 0, v[144:145]
	v_lshlrev_b32_e32 v144, 1, v98
	v_lshlrev_b64 v[110:111], 10, v[96:97]
	v_lshl_add_u64 v[106:107], v[166:167], 0, v[144:145]
	v_lshlrev_b32_e32 v144, 11, v98
	v_bfe_u32 v97, v96, 6, 4
	v_bfe_u32 v96, v96, 5, 3
	v_lshl_add_u64 v[108:109], s[64:65], 0, v[110:111]
	v_lshl_add_u64 v[102:103], s[12:13], 0, v[144:145]
	v_or_b32_e32 v114, s31, v97
	v_or_b32_e32 v115, s36, v96
	v_or_b32_e32 v112, s37, v99
	v_or_b32_e32 v113, s26, v98
	v_lshl_add_u64 v[100:101], s[24:25], 0, v[144:145]
	s_and_b64 vcc, exec, s[8:9]
	s_mov_b64 s[42:43], -1
	s_cbranch_vccnz .LBB0_663
	s_and_b64 vcc, exec, s[6:7]
	s_cbranch_vccnz .LBB0_763
	s_andn2_b64 vcc, exec, s[60:61]
	s_cbranch_vccnz .LBB0_660
	s_andn2_b64 vcc, exec, s[58:59]
	s_cbranch_vccnz .LBB0_657
	v_mul_f32_e32 v96, 0x3d372713, v92
	v_mul_f32_e32 v96, v92, v96
	v_fma_f32 v96, v92, v96, v92
	v_mul_f32_e32 v96, 0x3f4c422a, v96
	v_add_f32_e32 v96, v96, v96
	v_mul_f32_e32 v96, 0x3fb8aa3b, v96
	v_exp_f32_e32 v96, v96
	v_mul_f32_e32 v97, 0.5, v92
	v_mul_f32_e32 v98, 0.5, v93
	v_mul_f32_e32 v99, 0.5, v95
	v_add_f32_e32 v96, 1.0, v96
	v_rcp_f32_e32 v96, v96
	v_mul_f32_e32 v116, 0.5, v89
	v_mul_f32_e32 v117, 0.5, v91
	v_mov_b32_e32 v129, v145
	v_fma_f32 v96, v96, -2.0, 1.0
	v_add_f32_e32 v96, 1.0, v96
	v_mul_f32_e32 v96, v97, v96
	v_mul_f32_e32 v97, 0x3d372713, v93
	v_mul_f32_e32 v97, v93, v97
	v_fma_f32 v97, v93, v97, v93
	v_mul_f32_e32 v97, 0x3f4c422a, v97
	v_add_f32_e32 v97, v97, v97
	v_mul_f32_e32 v97, 0x3fb8aa3b, v97
	v_exp_f32_e32 v97, v97
	s_mov_b64 s[42:43], 0
	v_add_f32_e32 v97, 1.0, v97
	v_rcp_f32_e32 v97, v97
	s_nop 0
	v_fma_f32 v97, v97, -2.0, 1.0
	v_add_f32_e32 v97, 1.0, v97
	v_mul_f32_e32 v97, v98, v97
	v_cvt_pk_bf16_f32 v96, v96, v97
	v_mul_f32_e32 v97, 0x3d372713, v94
	v_mul_f32_e32 v97, v94, v97
	v_fma_f32 v97, v94, v97, v94
	v_mul_f32_e32 v97, 0x3f4c422a, v97
	v_add_f32_e32 v97, v97, v97
	v_mul_f32_e32 v97, 0x3fb8aa3b, v97
	v_exp_f32_e32 v97, v97
	v_mul_f32_e32 v98, 0.5, v94
	v_add_f32_e32 v97, 1.0, v97
	v_rcp_f32_e32 v97, v97
	s_nop 0
	v_fma_f32 v97, v97, -2.0, 1.0
	v_add_f32_e32 v97, 1.0, v97
	v_mul_f32_e32 v97, v98, v97
	v_mul_f32_e32 v98, 0x3d372713, v95
	v_mul_f32_e32 v98, v95, v98
	v_fma_f32 v98, v95, v98, v95
	v_mul_f32_e32 v98, 0x3f4c422a, v98
	v_add_f32_e32 v98, v98, v98
	v_mul_f32_e32 v98, 0x3fb8aa3b, v98
	v_exp_f32_e32 v98, v98
	s_nop 0
	v_add_f32_e32 v98, 1.0, v98
	v_rcp_f32_e32 v98, v98
	s_nop 0
	v_fma_f32 v98, v98, -2.0, 1.0
	v_add_f32_e32 v98, 1.0, v98
	v_mul_f32_e32 v98, v99, v98
	v_cvt_pk_bf16_f32 v97, v97, v98
	v_mul_f32_e32 v98, 0x3d372713, v88
	v_mul_f32_e32 v98, v88, v98
	v_fma_f32 v98, v88, v98, v88
	v_mul_f32_e32 v98, 0x3f4c422a, v98
	v_add_f32_e32 v98, v98, v98
	v_mul_f32_e32 v98, 0x3fb8aa3b, v98
	v_exp_f32_e32 v98, v98
	v_mul_f32_e32 v99, 0.5, v88
	v_add_f32_e32 v98, 1.0, v98
	v_rcp_f32_e32 v98, v98
	s_nop 0
	v_fma_f32 v98, v98, -2.0, 1.0
	v_add_f32_e32 v98, 1.0, v98
	v_mul_f32_e32 v98, v99, v98
	v_mul_f32_e32 v99, 0x3d372713, v89
	v_mul_f32_e32 v99, v89, v99
	v_fma_f32 v99, v89, v99, v89
	v_mul_f32_e32 v99, 0x3f4c422a, v99
	v_add_f32_e32 v99, v99, v99
	v_mul_f32_e32 v99, 0x3fb8aa3b, v99
	v_exp_f32_e32 v99, v99
	s_nop 0
	v_add_f32_e32 v99, 1.0, v99
	v_rcp_f32_e32 v99, v99
	s_nop 0
	v_fma_f32 v99, v99, -2.0, 1.0
	v_add_f32_e32 v99, 1.0, v99
	v_mul_f32_e32 v99, v116, v99
	v_cvt_pk_bf16_f32 v98, v98, v99
	v_mul_f32_e32 v99, 0x3d372713, v90
	v_mul_f32_e32 v99, v90, v99
	v_fma_f32 v99, v90, v99, v90
	v_mul_f32_e32 v99, 0x3f4c422a, v99
	v_add_f32_e32 v99, v99, v99
	v_mul_f32_e32 v99, 0x3fb8aa3b, v99
	v_exp_f32_e32 v99, v99
	v_mul_f32_e32 v116, 0.5, v90
	v_add_f32_e32 v99, 1.0, v99
	v_rcp_f32_e32 v99, v99
	s_nop 0
	v_fma_f32 v99, v99, -2.0, 1.0
	v_add_f32_e32 v99, 1.0, v99
	v_mul_f32_e32 v99, v116, v99
	v_mul_f32_e32 v116, 0x3d372713, v91
	v_mul_f32_e32 v116, v91, v116
	v_fma_f32 v116, v91, v116, v91
	v_mul_f32_e32 v116, 0x3f4c422a, v116
	v_add_f32_e32 v116, v116, v116
	v_mul_f32_e32 v116, 0x3fb8aa3b, v116
	v_exp_f32_e32 v116, v116
	s_nop 0
	v_add_f32_e32 v116, 1.0, v116
	v_rcp_f32_e32 v116, v116
	s_nop 0
	v_fma_f32 v116, v116, -2.0, 1.0
	v_add_f32_e32 v116, 1.0, v116
	v_mul_f32_e32 v116, v117, v116
	v_cvt_pk_bf16_f32 v99, v99, v116
	v_lshl_add_u64 v[116:117], v[108:109], 0, v[128:129]
	global_store_dwordx4 v[116:117], v[96:99], off sc1

.LBB0_664:
	v_pk_mul_f32 v[92:93], v[92:93], s[52:53] op_sel_hi:[1,0]
	v_mov_b32_e32 v129, v145
	v_pk_mul_f32 v[98:99], v[90:91], s[52:53] op_sel_hi:[1,0]
	v_pk_mul_f32 v[90:91], v[88:89], s[52:53] op_sel_hi:[1,0]
	v_cvt_pk_bf16_f32 v88, v92, v93
	v_lshl_add_u64 v[92:93], v[96:97], 0, v[128:129]
	v_pk_mul_f32 v[94:95], v[94:95], s[52:53] op_sel_hi:[1,0]
	s_nop 0
	v_cvt_pk_bf16_f32 v89, v94, v95
	v_cvt_pk_bf16_f32 v90, v90, v91
	v_cvt_pk_bf16_f32 v91, v98, v99
	global_store_dwordx4 v[92:93], v[88:91], off sc1
	s_and_b64 vcc, exec, s[8:9]
	s_mov_b64 s[42:43], -1
	s_cbranch_vccz .LBB0_768

.LBB0_666:
	v_pk_mul_f32 v[84:85], v[84:85], s[52:53] op_sel_hi:[1,0]
	v_mov_b32_e32 v129, v145
	v_pk_mul_f32 v[88:89], v[82:83], s[52:53] op_sel_hi:[1,0]
	v_pk_mul_f32 v[82:83], v[80:81], s[52:53] op_sel_hi:[1,0]
	v_cvt_pk_bf16_f32 v80, v84, v85
	v_lshl_add_u64 v[84:85], v[96:97], 0, v[128:129]
	v_pk_mul_f32 v[86:87], v[86:87], s[52:53] op_sel_hi:[1,0]
	s_nop 0
	v_cvt_pk_bf16_f32 v81, v86, v87
	v_cvt_pk_bf16_f32 v82, v82, v83
	v_cvt_pk_bf16_f32 v83, v88, v89
	global_store_dwordx4 v[84:85], v[80:83], off offset:256 sc1
.LBB0_667:
	s_nop 1
	v_bitop3_b32 v83, s95, v201, v160 bitop3:0xc8
	v_or_b32_e32 v80, s95, v160
	v_bitop3_b32 v82, s95, v200, v160 bitop3:0xc8
	v_lshlrev_b32_e32 v144, 1, v83
	v_ashrrev_i32_e32 v81, 31, v80
	v_lshl_add_u64 v[88:89], v[168:169], 0, v[144:145]
	v_lshlrev_b32_e32 v144, 1, v82
	v_lshlrev_b64 v[94:95], 10, v[80:81]
	v_lshl_add_u64 v[90:91], v[166:167], 0, v[144:145]
	v_lshlrev_b32_e32 v144, 11, v82
	v_bfe_u32 v81, v80, 6, 4
	v_bfe_u32 v80, v80, 5, 3
	v_lshl_add_u64 v[92:93], s[64:65], 0, v[94:95]
	v_lshl_add_u64 v[86:87], s[12:13], 0, v[144:145]
	v_or_b32_e32 v98, s31, v81
	v_or_b32_e32 v99, s36, v80
	v_or_b32_e32 v96, s37, v83
	v_or_b32_e32 v97, s26, v82
	v_lshl_add_u64 v[84:85], s[24:25], 0, v[144:145]
	s_and_b64 vcc, exec, s[8:9]
	s_mov_b64 s[42:43], -1
	s_cbranch_vccnz .LBB0_678
	s_and_b64 vcc, exec, s[6:7]
	s_cbranch_vccnz .LBB0_781
	s_andn2_b64 vcc, exec, s[60:61]
	s_cbranch_vccnz .LBB0_675
	s_andn2_b64 vcc, exec, s[58:59]
	s_cbranch_vccnz .LBB0_672
	v_mul_f32_e32 v80, 0x3d372713, v76
	v_mul_f32_e32 v80, v76, v80
	v_fma_f32 v80, v76, v80, v76
	v_mul_f32_e32 v80, 0x3f4c422a, v80
	v_add_f32_e32 v80, v80, v80
	v_mul_f32_e32 v80, 0x3fb8aa3b, v80
	v_exp_f32_e32 v80, v80
	v_mul_f32_e32 v81, 0.5, v76
	v_mul_f32_e32 v82, 0.5, v77
	v_mul_f32_e32 v83, 0.5, v79
	v_add_f32_e32 v80, 1.0, v80
	v_rcp_f32_e32 v80, v80
	v_mul_f32_e32 v100, 0.5, v73
	v_mul_f32_e32 v101, 0.5, v75
	v_mov_b32_e32 v129, v145
	v_fma_f32 v80, v80, -2.0, 1.0
	v_add_f32_e32 v80, 1.0, v80
	v_mul_f32_e32 v80, v81, v80
	v_mul_f32_e32 v81, 0x3d372713, v77
	v_mul_f32_e32 v81, v77, v81
	v_fma_f32 v81, v77, v81, v77
	v_mul_f32_e32 v81, 0x3f4c422a, v81
	v_add_f32_e32 v81, v81, v81
	v_mul_f32_e32 v81, 0x3fb8aa3b, v81
	v_exp_f32_e32 v81, v81
	s_mov_b64 s[42:43], 0
	v_add_f32_e32 v81, 1.0, v81
	v_rcp_f32_e32 v81, v81
	s_nop 0
	v_fma_f32 v81, v81, -2.0, 1.0
	v_add_f32_e32 v81, 1.0, v81
	v_mul_f32_e32 v81, v82, v81
	v_cvt_pk_bf16_f32 v80, v80, v81
	v_mul_f32_e32 v81, 0x3d372713, v78
	v_mul_f32_e32 v81, v78, v81
	v_fma_f32 v81, v78, v81, v78
	v_mul_f32_e32 v81, 0x3f4c422a, v81
	v_add_f32_e32 v81, v81, v81
	v_mul_f32_e32 v81, 0x3fb8aa3b, v81
	v_exp_f32_e32 v81, v81
	v_mul_f32_e32 v82, 0.5, v78
	v_add_f32_e32 v81, 1.0, v81
	v_rcp_f32_e32 v81, v81
	s_nop 0
	v_fma_f32 v81, v81, -2.0, 1.0
	v_add_f32_e32 v81, 1.0, v81
	v_mul_f32_e32 v81, v82, v81
	v_mul_f32_e32 v82, 0x3d372713, v79
	v_mul_f32_e32 v82, v79, v82
	v_fma_f32 v82, v79, v82, v79
	v_mul_f32_e32 v82, 0x3f4c422a, v82
	v_add_f32_e32 v82, v82, v82
	v_mul_f32_e32 v82, 0x3fb8aa3b, v82
	v_exp_f32_e32 v82, v82
	s_nop 0
	v_add_f32_e32 v82, 1.0, v82
	v_rcp_f32_e32 v82, v82
	s_nop 0
	v_fma_f32 v82, v82, -2.0, 1.0
	v_add_f32_e32 v82, 1.0, v82
	v_mul_f32_e32 v82, v83, v82
	v_cvt_pk_bf16_f32 v81, v81, v82
	v_mul_f32_e32 v82, 0x3d372713, v72
	v_mul_f32_e32 v82, v72, v82
	v_fma_f32 v82, v72, v82, v72
	v_mul_f32_e32 v82, 0x3f4c422a, v82
	v_add_f32_e32 v82, v82, v82
	v_mul_f32_e32 v82, 0x3fb8aa3b, v82
	v_exp_f32_e32 v82, v82
	v_mul_f32_e32 v83, 0.5, v72
	v_add_f32_e32 v82, 1.0, v82
	v_rcp_f32_e32 v82, v82
	s_nop 0
	v_fma_f32 v82, v82, -2.0, 1.0
	v_add_f32_e32 v82, 1.0, v82
	v_mul_f32_e32 v82, v83, v82
	v_mul_f32_e32 v83, 0x3d372713, v73
	v_mul_f32_e32 v83, v73, v83
	v_fma_f32 v83, v73, v83, v73
	v_mul_f32_e32 v83, 0x3f4c422a, v83
	v_add_f32_e32 v83, v83, v83
	v_mul_f32_e32 v83, 0x3fb8aa3b, v83
	v_exp_f32_e32 v83, v83
	s_nop 0
	v_add_f32_e32 v83, 1.0, v83
	v_rcp_f32_e32 v83, v83
	s_nop 0
	v_fma_f32 v83, v83, -2.0, 1.0
	v_add_f32_e32 v83, 1.0, v83
	v_mul_f32_e32 v83, v100, v83
	v_cvt_pk_bf16_f32 v82, v82, v83
	v_mul_f32_e32 v83, 0x3d372713, v74
	v_mul_f32_e32 v83, v74, v83
	v_fma_f32 v83, v74, v83, v74
	v_mul_f32_e32 v83, 0x3f4c422a, v83
	v_add_f32_e32 v83, v83, v83
	v_mul_f32_e32 v83, 0x3fb8aa3b, v83
	v_exp_f32_e32 v83, v83
	v_mul_f32_e32 v100, 0.5, v74
	v_add_f32_e32 v83, 1.0, v83
	v_rcp_f32_e32 v83, v83
	s_nop 0
	v_fma_f32 v83, v83, -2.0, 1.0
	v_add_f32_e32 v83, 1.0, v83
	v_mul_f32_e32 v83, v100, v83
	v_mul_f32_e32 v100, 0x3d372713, v75
	v_mul_f32_e32 v100, v75, v100
	v_fma_f32 v100, v75, v100, v75
	v_mul_f32_e32 v100, 0x3f4c422a, v100
	v_add_f32_e32 v100, v100, v100
	v_mul_f32_e32 v100, 0x3fb8aa3b, v100
	v_exp_f32_e32 v100, v100
	s_nop 0
	v_add_f32_e32 v100, 1.0, v100
	v_rcp_f32_e32 v100, v100
	s_nop 0
	v_fma_f32 v100, v100, -2.0, 1.0
	v_add_f32_e32 v100, 1.0, v100
	v_mul_f32_e32 v100, v101, v100
	v_cvt_pk_bf16_f32 v83, v83, v100
	v_lshl_add_u64 v[100:101], v[92:93], 0, v[128:129]
	global_store_dwordx4 v[100:101], v[80:83], off sc1

.LBB0_679:
	v_pk_mul_f32 v[76:77], v[76:77], s[52:53] op_sel_hi:[1,0]
	v_mov_b32_e32 v129, v145
	v_pk_mul_f32 v[82:83], v[74:75], s[52:53] op_sel_hi:[1,0]
	v_pk_mul_f32 v[74:75], v[72:73], s[52:53] op_sel_hi:[1,0]
	v_cvt_pk_bf16_f32 v72, v76, v77
	v_lshl_add_u64 v[76:77], v[80:81], 0, v[128:129]
	v_pk_mul_f32 v[78:79], v[78:79], s[52:53] op_sel_hi:[1,0]
	s_nop 0
	v_cvt_pk_bf16_f32 v73, v78, v79
	v_cvt_pk_bf16_f32 v74, v74, v75
	v_cvt_pk_bf16_f32 v75, v82, v83
	global_store_dwordx4 v[76:77], v[72:75], off sc1
	s_and_b64 vcc, exec, s[8:9]
	s_mov_b64 s[42:43], -1
	s_cbranch_vccz .LBB0_786

.LBB0_681:
	v_pk_mul_f32 v[68:69], v[68:69], s[52:53] op_sel_hi:[1,0]
	v_mov_b32_e32 v129, v145
	v_pk_mul_f32 v[72:73], v[66:67], s[52:53] op_sel_hi:[1,0]
	v_pk_mul_f32 v[66:67], v[64:65], s[52:53] op_sel_hi:[1,0]
	v_cvt_pk_bf16_f32 v64, v68, v69
	v_lshl_add_u64 v[68:69], v[80:81], 0, v[128:129]
	v_pk_mul_f32 v[70:71], v[70:71], s[52:53] op_sel_hi:[1,0]
	s_nop 0
	v_cvt_pk_bf16_f32 v65, v70, v71
	v_cvt_pk_bf16_f32 v66, v66, v67
	v_cvt_pk_bf16_f32 v67, v72, v73
	global_store_dwordx4 v[68:69], v[64:67], off offset:256 sc1
.LBB0_682:
	s_add_i32 s31, s95, 0x80
	s_nop 0
	v_or_b32_e32 v64, s31, v140
	s_addk_i32 s95, 0xf080
	v_bitop3_b32 v67, s31, v195, v140 bitop3:0xc8
	s_ashr_i32 s26, s95, 10
	v_bitop3_b32 v66, s31, v194, v140 bitop3:0xc8
	v_ashrrev_i32_e32 v65, 31, v64
	v_lshlrev_b32_e32 v144, 1, v67
	s_ashr_i32 s27, s31, 8
	v_lshlrev_b64 v[78:79], 10, v[64:65]
	v_lshl_add_u64 v[72:73], v[168:169], 0, v[144:145]
	v_lshlrev_b32_e32 v144, 1, v66
	s_lshl_b32 s36, s26, 7
	v_bfe_u32 v64, v64, 6, 4
	s_lshl_b32 s40, s26, 8
	v_lshl_add_u64 v[74:75], v[166:167], 0, v[144:145]
	s_lshl_b32 s73, s27, 2
	v_lshlrev_b32_e32 v144, 11, v66
	v_or_b32_e32 v82, s36, v64
	s_lshl_b32 s37, s27, 6
	v_lshrrev_b32_e32 v64, 5, v66
	s_lshl_b32 s26, s26, 13
	s_lshl_b32 s27, s27, 11
	v_lshl_add_u64 v[76:77], s[64:65], 0, v[78:79]
	s_and_b32 s30, s31, 0xffffff00
	v_lshl_add_u64 v[70:71], s[12:13], 0, v[144:145]
	v_or_b32_e32 v83, s37, v64
	v_or_b32_e32 v80, s26, v67
	v_or_b32_e32 v81, s27, v66
	v_lshl_add_u64 v[68:69], s[24:25], 0, v[144:145]
	s_and_b64 vcc, exec, s[8:9]
	s_mov_b64 s[42:43], -1
	s_cbranch_vccnz .LBB0_693
	s_and_b64 vcc, exec, s[6:7]
	s_cbranch_vccnz .LBB0_799
	s_andn2_b64 vcc, exec, s[60:61]
	s_cbranch_vccnz .LBB0_690
	s_andn2_b64 vcc, exec, s[58:59]
	s_cbranch_vccnz .LBB0_687
	v_mul_f32_e32 v64, 0x3d372713, v60
	v_mul_f32_e32 v64, v60, v64
	v_fma_f32 v64, v60, v64, v60
	v_mul_f32_e32 v64, 0x3f4c422a, v64
	v_add_f32_e32 v64, v64, v64
	v_mul_f32_e32 v64, 0x3fb8aa3b, v64
	v_exp_f32_e32 v64, v64
	v_mul_f32_e32 v65, 0.5, v60
	v_mul_f32_e32 v66, 0.5, v61
	v_mul_f32_e32 v67, 0.5, v63
	v_add_f32_e32 v64, 1.0, v64
	v_rcp_f32_e32 v64, v64
	v_mul_f32_e32 v84, 0.5, v57
	v_mul_f32_e32 v85, 0.5, v59
	v_mov_b32_e32 v129, v145
	v_fma_f32 v64, v64, -2.0, 1.0
	v_add_f32_e32 v64, 1.0, v64
	v_mul_f32_e32 v64, v65, v64
	v_mul_f32_e32 v65, 0x3d372713, v61
	v_mul_f32_e32 v65, v61, v65
	v_fma_f32 v65, v61, v65, v61
	v_mul_f32_e32 v65, 0x3f4c422a, v65
	v_add_f32_e32 v65, v65, v65
	v_mul_f32_e32 v65, 0x3fb8aa3b, v65
	v_exp_f32_e32 v65, v65
	s_mov_b64 s[42:43], 0
	v_add_f32_e32 v65, 1.0, v65
	v_rcp_f32_e32 v65, v65
	s_nop 0
	v_fma_f32 v65, v65, -2.0, 1.0
	v_add_f32_e32 v65, 1.0, v65
	v_mul_f32_e32 v65, v66, v65
	v_cvt_pk_bf16_f32 v64, v64, v65
	v_mul_f32_e32 v65, 0x3d372713, v62
	v_mul_f32_e32 v65, v62, v65
	v_fma_f32 v65, v62, v65, v62
	v_mul_f32_e32 v65, 0x3f4c422a, v65
	v_add_f32_e32 v65, v65, v65
	v_mul_f32_e32 v65, 0x3fb8aa3b, v65
	v_exp_f32_e32 v65, v65
	v_mul_f32_e32 v66, 0.5, v62
	v_add_f32_e32 v65, 1.0, v65
	v_rcp_f32_e32 v65, v65
	s_nop 0
	v_fma_f32 v65, v65, -2.0, 1.0
	v_add_f32_e32 v65, 1.0, v65
	v_mul_f32_e32 v65, v66, v65
	v_mul_f32_e32 v66, 0x3d372713, v63
	v_mul_f32_e32 v66, v63, v66
	v_fma_f32 v66, v63, v66, v63
	v_mul_f32_e32 v66, 0x3f4c422a, v66
	v_add_f32_e32 v66, v66, v66
	v_mul_f32_e32 v66, 0x3fb8aa3b, v66
	v_exp_f32_e32 v66, v66
	s_nop 0
	v_add_f32_e32 v66, 1.0, v66
	v_rcp_f32_e32 v66, v66
	s_nop 0
	v_fma_f32 v66, v66, -2.0, 1.0
	v_add_f32_e32 v66, 1.0, v66
	v_mul_f32_e32 v66, v67, v66
	v_cvt_pk_bf16_f32 v65, v65, v66
	v_mul_f32_e32 v66, 0x3d372713, v56
	v_mul_f32_e32 v66, v56, v66
	v_fma_f32 v66, v56, v66, v56
	v_mul_f32_e32 v66, 0x3f4c422a, v66
	v_add_f32_e32 v66, v66, v66
	v_mul_f32_e32 v66, 0x3fb8aa3b, v66
	v_exp_f32_e32 v66, v66
	v_mul_f32_e32 v67, 0.5, v56
	v_add_f32_e32 v66, 1.0, v66
	v_rcp_f32_e32 v66, v66
	s_nop 0
	v_fma_f32 v66, v66, -2.0, 1.0
	v_add_f32_e32 v66, 1.0, v66
	v_mul_f32_e32 v66, v67, v66
	v_mul_f32_e32 v67, 0x3d372713, v57
	v_mul_f32_e32 v67, v57, v67
	v_fma_f32 v67, v57, v67, v57
	v_mul_f32_e32 v67, 0x3f4c422a, v67
	v_add_f32_e32 v67, v67, v67
	v_mul_f32_e32 v67, 0x3fb8aa3b, v67
	v_exp_f32_e32 v67, v67
	s_nop 0
	v_add_f32_e32 v67, 1.0, v67
	v_rcp_f32_e32 v67, v67
	s_nop 0
	v_fma_f32 v67, v67, -2.0, 1.0
	v_add_f32_e32 v67, 1.0, v67
	v_mul_f32_e32 v67, v84, v67
	v_cvt_pk_bf16_f32 v66, v66, v67
	v_mul_f32_e32 v67, 0x3d372713, v58
	v_mul_f32_e32 v67, v58, v67
	v_fma_f32 v67, v58, v67, v58
	v_mul_f32_e32 v67, 0x3f4c422a, v67
	v_add_f32_e32 v67, v67, v67
	v_mul_f32_e32 v67, 0x3fb8aa3b, v67
	v_exp_f32_e32 v67, v67
	v_mul_f32_e32 v84, 0.5, v58
	v_add_f32_e32 v67, 1.0, v67
	v_rcp_f32_e32 v67, v67
	s_nop 0
	v_fma_f32 v67, v67, -2.0, 1.0
	v_add_f32_e32 v67, 1.0, v67
	v_mul_f32_e32 v67, v84, v67
	v_mul_f32_e32 v84, 0x3d372713, v59
	v_mul_f32_e32 v84, v59, v84
	v_fma_f32 v84, v59, v84, v59
	v_mul_f32_e32 v84, 0x3f4c422a, v84
	v_add_f32_e32 v84, v84, v84
	v_mul_f32_e32 v84, 0x3fb8aa3b, v84
	v_exp_f32_e32 v84, v84
	s_nop 0
	v_add_f32_e32 v84, 1.0, v84
	v_rcp_f32_e32 v84, v84
	s_nop 0
	v_fma_f32 v84, v84, -2.0, 1.0
	v_add_f32_e32 v84, 1.0, v84
	v_mul_f32_e32 v84, v85, v84
	v_cvt_pk_bf16_f32 v67, v67, v84
	v_lshl_add_u64 v[84:85], v[76:77], 0, v[128:129]
	global_store_dwordx4 v[84:85], v[64:67], off sc1

.LBB0_694:
	v_pk_mul_f32 v[60:61], v[60:61], s[52:53] op_sel_hi:[1,0]
	v_mov_b32_e32 v129, v145
	v_pk_mul_f32 v[66:67], v[58:59], s[52:53] op_sel_hi:[1,0]
	v_pk_mul_f32 v[58:59], v[56:57], s[52:53] op_sel_hi:[1,0]
	v_cvt_pk_bf16_f32 v56, v60, v61
	v_lshl_add_u64 v[60:61], v[64:65], 0, v[128:129]
	v_pk_mul_f32 v[62:63], v[62:63], s[52:53] op_sel_hi:[1,0]
	s_nop 0
	v_cvt_pk_bf16_f32 v57, v62, v63
	v_cvt_pk_bf16_f32 v58, v58, v59
	v_cvt_pk_bf16_f32 v59, v66, v67
	global_store_dwordx4 v[60:61], v[56:59], off sc1
	s_and_b64 vcc, exec, s[8:9]
	s_mov_b64 s[42:43], -1
	s_cbranch_vccz .LBB0_804

.LBB0_696:
	v_pk_mul_f32 v[52:53], v[52:53], s[52:53] op_sel_hi:[1,0]
	v_mov_b32_e32 v129, v145
	v_pk_mul_f32 v[56:57], v[50:51], s[52:53] op_sel_hi:[1,0]
	v_pk_mul_f32 v[50:51], v[48:49], s[52:53] op_sel_hi:[1,0]
	v_cvt_pk_bf16_f32 v48, v52, v53
	v_lshl_add_u64 v[52:53], v[64:65], 0, v[128:129]
	v_pk_mul_f32 v[54:55], v[54:55], s[52:53] op_sel_hi:[1,0]
	s_nop 0
	v_cvt_pk_bf16_f32 v49, v54, v55
	v_cvt_pk_bf16_f32 v50, v50, v51
	v_cvt_pk_bf16_f32 v51, v56, v57
	global_store_dwordx4 v[52:53], v[48:51], off offset:256 sc1
.LBB0_697:
	s_nop 1
	v_or_b32_e32 v48, s31, v156
	v_bitop3_b32 v51, s31, v197, v156 bitop3:0xc8
	v_bitop3_b32 v50, s31, v196, v156 bitop3:0xc8
	v_ashrrev_i32_e32 v49, 31, v48
	v_lshlrev_b32_e32 v144, 1, v51
	v_lshlrev_b64 v[62:63], 10, v[48:49]
	v_lshl_add_u64 v[56:57], v[168:169], 0, v[144:145]
	v_lshlrev_b32_e32 v144, 1, v50
	v_bfe_u32 v48, v48, 6, 4
	v_lshl_add_u64 v[58:59], v[166:167], 0, v[144:145]
	v_lshlrev_b32_e32 v144, 11, v50
	v_or_b32_e32 v66, s36, v48
	v_lshrrev_b32_e32 v48, 5, v50
	v_lshl_add_u64 v[60:61], s[64:65], 0, v[62:63]
	v_lshl_add_u64 v[54:55], s[12:13], 0, v[144:145]
	v_or_b32_e32 v67, s37, v48
	v_or_b32_e32 v64, s26, v51
	v_or_b32_e32 v65, s27, v50
	v_lshl_add_u64 v[52:53], s[24:25], 0, v[144:145]
	s_and_b64 vcc, exec, s[8:9]
	s_mov_b64 s[42:43], -1
	s_cbranch_vccnz .LBB0_708
	s_and_b64 vcc, exec, s[6:7]
	s_cbranch_vccnz .LBB0_817
	s_andn2_b64 vcc, exec, s[60:61]
	s_cbranch_vccnz .LBB0_705
	s_andn2_b64 vcc, exec, s[58:59]
	s_cbranch_vccnz .LBB0_702
	v_mul_f32_e32 v48, 0x3d372713, v44
	v_mul_f32_e32 v48, v44, v48
	v_fma_f32 v48, v44, v48, v44
	v_mul_f32_e32 v48, 0x3f4c422a, v48
	v_add_f32_e32 v48, v48, v48
	v_mul_f32_e32 v48, 0x3fb8aa3b, v48
	v_exp_f32_e32 v48, v48
	v_mul_f32_e32 v49, 0.5, v44
	v_mul_f32_e32 v50, 0.5, v45
	v_mul_f32_e32 v51, 0.5, v47
	v_add_f32_e32 v48, 1.0, v48
	v_rcp_f32_e32 v48, v48
	v_mul_f32_e32 v68, 0.5, v41
	v_mul_f32_e32 v69, 0.5, v43
	v_mov_b32_e32 v129, v145
	v_fma_f32 v48, v48, -2.0, 1.0
	v_add_f32_e32 v48, 1.0, v48
	v_mul_f32_e32 v48, v49, v48
	v_mul_f32_e32 v49, 0x3d372713, v45
	v_mul_f32_e32 v49, v45, v49
	v_fma_f32 v49, v45, v49, v45
	v_mul_f32_e32 v49, 0x3f4c422a, v49
	v_add_f32_e32 v49, v49, v49
	v_mul_f32_e32 v49, 0x3fb8aa3b, v49
	v_exp_f32_e32 v49, v49
	s_mov_b64 s[42:43], 0
	v_add_f32_e32 v49, 1.0, v49
	v_rcp_f32_e32 v49, v49
	s_nop 0
	v_fma_f32 v49, v49, -2.0, 1.0
	v_add_f32_e32 v49, 1.0, v49
	v_mul_f32_e32 v49, v50, v49
	v_cvt_pk_bf16_f32 v48, v48, v49
	v_mul_f32_e32 v49, 0x3d372713, v46
	v_mul_f32_e32 v49, v46, v49
	v_fma_f32 v49, v46, v49, v46
	v_mul_f32_e32 v49, 0x3f4c422a, v49
	v_add_f32_e32 v49, v49, v49
	v_mul_f32_e32 v49, 0x3fb8aa3b, v49
	v_exp_f32_e32 v49, v49
	v_mul_f32_e32 v50, 0.5, v46
	v_add_f32_e32 v49, 1.0, v49
	v_rcp_f32_e32 v49, v49
	s_nop 0
	v_fma_f32 v49, v49, -2.0, 1.0
	v_add_f32_e32 v49, 1.0, v49
	v_mul_f32_e32 v49, v50, v49
	v_mul_f32_e32 v50, 0x3d372713, v47
	v_mul_f32_e32 v50, v47, v50
	v_fma_f32 v50, v47, v50, v47
	v_mul_f32_e32 v50, 0x3f4c422a, v50
	v_add_f32_e32 v50, v50, v50
	v_mul_f32_e32 v50, 0x3fb8aa3b, v50
	v_exp_f32_e32 v50, v50
	s_nop 0
	v_add_f32_e32 v50, 1.0, v50
	v_rcp_f32_e32 v50, v50
	s_nop 0
	v_fma_f32 v50, v50, -2.0, 1.0
	v_add_f32_e32 v50, 1.0, v50
	v_mul_f32_e32 v50, v51, v50
	v_cvt_pk_bf16_f32 v49, v49, v50
	v_mul_f32_e32 v50, 0x3d372713, v40
	v_mul_f32_e32 v50, v40, v50
	v_fma_f32 v50, v40, v50, v40
	v_mul_f32_e32 v50, 0x3f4c422a, v50
	v_add_f32_e32 v50, v50, v50
	v_mul_f32_e32 v50, 0x3fb8aa3b, v50
	v_exp_f32_e32 v50, v50
	v_mul_f32_e32 v51, 0.5, v40
	v_add_f32_e32 v50, 1.0, v50
	v_rcp_f32_e32 v50, v50
	s_nop 0
	v_fma_f32 v50, v50, -2.0, 1.0
	v_add_f32_e32 v50, 1.0, v50
	v_mul_f32_e32 v50, v51, v50
	v_mul_f32_e32 v51, 0x3d372713, v41
	v_mul_f32_e32 v51, v41, v51
	v_fma_f32 v51, v41, v51, v41
	v_mul_f32_e32 v51, 0x3f4c422a, v51
	v_add_f32_e32 v51, v51, v51
	v_mul_f32_e32 v51, 0x3fb8aa3b, v51
	v_exp_f32_e32 v51, v51
	s_nop 0
	v_add_f32_e32 v51, 1.0, v51
	v_rcp_f32_e32 v51, v51
	s_nop 0
	v_fma_f32 v51, v51, -2.0, 1.0
	v_add_f32_e32 v51, 1.0, v51
	v_mul_f32_e32 v51, v68, v51
	v_cvt_pk_bf16_f32 v50, v50, v51
	v_mul_f32_e32 v51, 0x3d372713, v42
	v_mul_f32_e32 v51, v42, v51
	v_fma_f32 v51, v42, v51, v42
	v_mul_f32_e32 v51, 0x3f4c422a, v51
	v_add_f32_e32 v51, v51, v51
	v_mul_f32_e32 v51, 0x3fb8aa3b, v51
	v_exp_f32_e32 v51, v51
	v_mul_f32_e32 v68, 0.5, v42
	v_add_f32_e32 v51, 1.0, v51
	v_rcp_f32_e32 v51, v51
	s_nop 0
	v_fma_f32 v51, v51, -2.0, 1.0
	v_add_f32_e32 v51, 1.0, v51
	v_mul_f32_e32 v51, v68, v51
	v_mul_f32_e32 v68, 0x3d372713, v43
	v_mul_f32_e32 v68, v43, v68
	v_fma_f32 v68, v43, v68, v43
	v_mul_f32_e32 v68, 0x3f4c422a, v68
	v_add_f32_e32 v68, v68, v68
	v_mul_f32_e32 v68, 0x3fb8aa3b, v68
	v_exp_f32_e32 v68, v68
	s_nop 0
	v_add_f32_e32 v68, 1.0, v68
	v_rcp_f32_e32 v68, v68
	s_nop 0
	v_fma_f32 v68, v68, -2.0, 1.0
	v_add_f32_e32 v68, 1.0, v68
	v_mul_f32_e32 v68, v69, v68
	v_cvt_pk_bf16_f32 v51, v51, v68
	v_lshl_add_u64 v[68:69], v[60:61], 0, v[128:129]
	global_store_dwordx4 v[68:69], v[48:51], off sc1

.LBB0_709:
	v_pk_mul_f32 v[44:45], v[44:45], s[52:53] op_sel_hi:[1,0]
	v_mov_b32_e32 v129, v145
	v_pk_mul_f32 v[50:51], v[42:43], s[52:53] op_sel_hi:[1,0]
	v_pk_mul_f32 v[42:43], v[40:41], s[52:53] op_sel_hi:[1,0]
	v_cvt_pk_bf16_f32 v40, v44, v45
	v_lshl_add_u64 v[44:45], v[48:49], 0, v[128:129]
	v_pk_mul_f32 v[46:47], v[46:47], s[52:53] op_sel_hi:[1,0]
	s_nop 0
	v_cvt_pk_bf16_f32 v41, v46, v47
	v_cvt_pk_bf16_f32 v42, v42, v43
	v_cvt_pk_bf16_f32 v43, v50, v51
	global_store_dwordx4 v[44:45], v[40:43], off sc1
	s_and_b64 vcc, exec, s[8:9]
	s_mov_b64 s[42:43], -1
	s_cbranch_vccz .LBB0_822

.LBB0_711:
	v_pk_mul_f32 v[36:37], v[36:37], s[52:53] op_sel_hi:[1,0]
	v_mov_b32_e32 v129, v145
	v_pk_mul_f32 v[40:41], v[34:35], s[52:53] op_sel_hi:[1,0]
	v_pk_mul_f32 v[34:35], v[32:33], s[52:53] op_sel_hi:[1,0]
	v_cvt_pk_bf16_f32 v32, v36, v37
	v_lshl_add_u64 v[36:37], v[48:49], 0, v[128:129]
	v_pk_mul_f32 v[38:39], v[38:39], s[52:53] op_sel_hi:[1,0]
	s_nop 0
	v_cvt_pk_bf16_f32 v33, v38, v39
	v_cvt_pk_bf16_f32 v34, v34, v35
	v_cvt_pk_bf16_f32 v35, v40, v41
	global_store_dwordx4 v[36:37], v[32:35], off offset:256 sc1
.LBB0_712:
	s_nop 1
	v_bitop3_b32 v35, s31, v199, v158 bitop3:0xc8
	v_or_b32_e32 v32, s31, v158
	v_bitop3_b32 v34, s31, v198, v158 bitop3:0xc8
	v_lshlrev_b32_e32 v144, 1, v35
	v_ashrrev_i32_e32 v33, 31, v32
	v_lshl_add_u64 v[40:41], v[168:169], 0, v[144:145]
	v_lshlrev_b32_e32 v144, 1, v34
	v_lshlrev_b64 v[46:47], 10, v[32:33]
	v_lshl_add_u64 v[42:43], v[166:167], 0, v[144:145]
	v_lshlrev_b32_e32 v144, 11, v34
	v_bfe_u32 v33, v32, 6, 4
	v_bfe_u32 v32, v32, 5, 3
	v_lshl_add_u64 v[44:45], s[64:65], 0, v[46:47]
	v_lshl_add_u64 v[38:39], s[12:13], 0, v[144:145]
	v_or_b32_e32 v50, s36, v33
	v_or_b32_e32 v51, s37, v32
	v_or_b32_e32 v48, s26, v35
	v_or_b32_e32 v49, s27, v34
	v_lshl_add_u64 v[36:37], s[24:25], 0, v[144:145]
	s_and_b64 vcc, exec, s[8:9]
	s_mov_b64 s[42:43], -1
	s_cbranch_vccnz .LBB0_723
	s_and_b64 vcc, exec, s[6:7]
	s_cbranch_vccnz .LBB0_835
	s_andn2_b64 vcc, exec, s[60:61]
	s_cbranch_vccnz .LBB0_720
	s_andn2_b64 vcc, exec, s[58:59]
	s_cbranch_vccnz .LBB0_717
	v_mul_f32_e32 v32, 0x3d372713, v28
	v_mul_f32_e32 v32, v28, v32
	v_fma_f32 v32, v28, v32, v28
	v_mul_f32_e32 v32, 0x3f4c422a, v32
	v_add_f32_e32 v32, v32, v32
	v_mul_f32_e32 v32, 0x3fb8aa3b, v32
	v_exp_f32_e32 v32, v32
	v_mul_f32_e32 v33, 0.5, v28
	v_mul_f32_e32 v34, 0.5, v29
	v_mul_f32_e32 v35, 0.5, v31
	v_add_f32_e32 v32, 1.0, v32
	v_rcp_f32_e32 v32, v32
	v_mul_f32_e32 v52, 0.5, v25
	v_mul_f32_e32 v53, 0.5, v27
	v_mov_b32_e32 v129, v145
	v_fma_f32 v32, v32, -2.0, 1.0
	v_add_f32_e32 v32, 1.0, v32
	v_mul_f32_e32 v32, v33, v32
	v_mul_f32_e32 v33, 0x3d372713, v29
	v_mul_f32_e32 v33, v29, v33
	v_fma_f32 v33, v29, v33, v29
	v_mul_f32_e32 v33, 0x3f4c422a, v33
	v_add_f32_e32 v33, v33, v33
	v_mul_f32_e32 v33, 0x3fb8aa3b, v33
	v_exp_f32_e32 v33, v33
	s_mov_b64 s[42:43], 0
	v_add_f32_e32 v33, 1.0, v33
	v_rcp_f32_e32 v33, v33
	s_nop 0
	v_fma_f32 v33, v33, -2.0, 1.0
	v_add_f32_e32 v33, 1.0, v33
	v_mul_f32_e32 v33, v34, v33
	v_cvt_pk_bf16_f32 v32, v32, v33
	v_mul_f32_e32 v33, 0x3d372713, v30
	v_mul_f32_e32 v33, v30, v33
	v_fma_f32 v33, v30, v33, v30
	v_mul_f32_e32 v33, 0x3f4c422a, v33
	v_add_f32_e32 v33, v33, v33
	v_mul_f32_e32 v33, 0x3fb8aa3b, v33
	v_exp_f32_e32 v33, v33
	v_mul_f32_e32 v34, 0.5, v30
	v_add_f32_e32 v33, 1.0, v33
	v_rcp_f32_e32 v33, v33
	s_nop 0
	v_fma_f32 v33, v33, -2.0, 1.0
	v_add_f32_e32 v33, 1.0, v33
	v_mul_f32_e32 v33, v34, v33
	v_mul_f32_e32 v34, 0x3d372713, v31
	v_mul_f32_e32 v34, v31, v34
	v_fma_f32 v34, v31, v34, v31
	v_mul_f32_e32 v34, 0x3f4c422a, v34
	v_add_f32_e32 v34, v34, v34
	v_mul_f32_e32 v34, 0x3fb8aa3b, v34
	v_exp_f32_e32 v34, v34
	s_nop 0
	v_add_f32_e32 v34, 1.0, v34
	v_rcp_f32_e32 v34, v34
	s_nop 0
	v_fma_f32 v34, v34, -2.0, 1.0
	v_add_f32_e32 v34, 1.0, v34
	v_mul_f32_e32 v34, v35, v34
	v_cvt_pk_bf16_f32 v33, v33, v34
	v_mul_f32_e32 v34, 0x3d372713, v24
	v_mul_f32_e32 v34, v24, v34
	v_fma_f32 v34, v24, v34, v24
	v_mul_f32_e32 v34, 0x3f4c422a, v34
	v_add_f32_e32 v34, v34, v34
	v_mul_f32_e32 v34, 0x3fb8aa3b, v34
	v_exp_f32_e32 v34, v34
	v_mul_f32_e32 v35, 0.5, v24
	v_add_f32_e32 v34, 1.0, v34
	v_rcp_f32_e32 v34, v34
	s_nop 0
	v_fma_f32 v34, v34, -2.0, 1.0
	v_add_f32_e32 v34, 1.0, v34
	v_mul_f32_e32 v34, v35, v34
	v_mul_f32_e32 v35, 0x3d372713, v25
	v_mul_f32_e32 v35, v25, v35
	v_fma_f32 v35, v25, v35, v25
	v_mul_f32_e32 v35, 0x3f4c422a, v35
	v_add_f32_e32 v35, v35, v35
	v_mul_f32_e32 v35, 0x3fb8aa3b, v35
	v_exp_f32_e32 v35, v35
	s_nop 0
	v_add_f32_e32 v35, 1.0, v35
	v_rcp_f32_e32 v35, v35
	s_nop 0
	v_fma_f32 v35, v35, -2.0, 1.0
	v_add_f32_e32 v35, 1.0, v35
	v_mul_f32_e32 v35, v52, v35
	v_cvt_pk_bf16_f32 v34, v34, v35
	v_mul_f32_e32 v35, 0x3d372713, v26
	v_mul_f32_e32 v35, v26, v35
	v_fma_f32 v35, v26, v35, v26
	v_mul_f32_e32 v35, 0x3f4c422a, v35
	v_add_f32_e32 v35, v35, v35
	v_mul_f32_e32 v35, 0x3fb8aa3b, v35
	v_exp_f32_e32 v35, v35
	v_mul_f32_e32 v52, 0.5, v26
	v_add_f32_e32 v35, 1.0, v35
	v_rcp_f32_e32 v35, v35
	s_nop 0
	v_fma_f32 v35, v35, -2.0, 1.0
	v_add_f32_e32 v35, 1.0, v35
	v_mul_f32_e32 v35, v52, v35
	v_mul_f32_e32 v52, 0x3d372713, v27
	v_mul_f32_e32 v52, v27, v52
	v_fma_f32 v52, v27, v52, v27
	v_mul_f32_e32 v52, 0x3f4c422a, v52
	v_add_f32_e32 v52, v52, v52
	v_mul_f32_e32 v52, 0x3fb8aa3b, v52
	v_exp_f32_e32 v52, v52
	s_nop 0
	v_add_f32_e32 v52, 1.0, v52
	v_rcp_f32_e32 v52, v52
	s_nop 0
	v_fma_f32 v52, v52, -2.0, 1.0
	v_add_f32_e32 v52, 1.0, v52
	v_mul_f32_e32 v52, v53, v52
	v_cvt_pk_bf16_f32 v35, v35, v52
	v_lshl_add_u64 v[52:53], v[44:45], 0, v[128:129]
	global_store_dwordx4 v[52:53], v[32:35], off sc1

.LBB0_724:
	v_pk_mul_f32 v[28:29], v[28:29], s[52:53] op_sel_hi:[1,0]
	v_mov_b32_e32 v129, v145
	v_pk_mul_f32 v[34:35], v[26:27], s[52:53] op_sel_hi:[1,0]
	v_pk_mul_f32 v[26:27], v[24:25], s[52:53] op_sel_hi:[1,0]
	v_cvt_pk_bf16_f32 v24, v28, v29
	v_lshl_add_u64 v[28:29], v[32:33], 0, v[128:129]
	v_pk_mul_f32 v[30:31], v[30:31], s[52:53] op_sel_hi:[1,0]
	s_nop 0
	v_cvt_pk_bf16_f32 v25, v30, v31
	v_cvt_pk_bf16_f32 v26, v26, v27
	v_cvt_pk_bf16_f32 v27, v34, v35
	global_store_dwordx4 v[28:29], v[24:27], off sc1
	s_and_b64 vcc, exec, s[8:9]
	s_mov_b64 s[42:43], -1
	s_cbranch_vccz .LBB0_840

.LBB0_726:
	v_pk_mul_f32 v[20:21], v[20:21], s[52:53] op_sel_hi:[1,0]
	v_mov_b32_e32 v129, v145
	v_pk_mul_f32 v[24:25], v[18:19], s[52:53] op_sel_hi:[1,0]
	v_pk_mul_f32 v[18:19], v[16:17], s[52:53] op_sel_hi:[1,0]
	v_cvt_pk_bf16_f32 v16, v20, v21
	v_lshl_add_u64 v[20:21], v[32:33], 0, v[128:129]
	v_pk_mul_f32 v[22:23], v[22:23], s[52:53] op_sel_hi:[1,0]
	s_nop 0
	v_cvt_pk_bf16_f32 v17, v22, v23
	v_cvt_pk_bf16_f32 v18, v18, v19
	v_cvt_pk_bf16_f32 v19, v24, v25
	global_store_dwordx4 v[20:21], v[16:19], off offset:256 sc1
.LBB0_727:
	s_nop 1
	v_bitop3_b32 v19, s31, v201, v160 bitop3:0xc8
	v_or_b32_e32 v16, s31, v160
	v_bitop3_b32 v18, s31, v200, v160 bitop3:0xc8
	v_lshlrev_b32_e32 v144, 1, v19
	v_ashrrev_i32_e32 v17, 31, v16
	v_lshl_add_u64 v[24:25], v[168:169], 0, v[144:145]
	v_lshlrev_b32_e32 v144, 1, v18
	v_lshlrev_b64 v[30:31], 10, v[16:17]
	v_lshl_add_u64 v[26:27], v[166:167], 0, v[144:145]
	v_lshlrev_b32_e32 v144, 11, v18
	v_bfe_u32 v17, v16, 6, 4
	v_bfe_u32 v16, v16, 5, 3
	v_lshl_add_u64 v[28:29], s[64:65], 0, v[30:31]
	v_lshl_add_u64 v[22:23], s[12:13], 0, v[144:145]
	v_or_b32_e32 v34, s36, v17
	v_or_b32_e32 v35, s37, v16
	v_or_b32_e32 v32, s26, v19
	v_or_b32_e32 v33, s27, v18
	v_lshl_add_u64 v[20:21], s[24:25], 0, v[144:145]
	s_and_b64 vcc, exec, s[8:9]
	s_mov_b64 s[42:43], -1
	s_cbranch_vccnz .LBB0_738
	s_and_b64 vcc, exec, s[6:7]
	s_cbranch_vccnz .LBB0_853
	s_andn2_b64 vcc, exec, s[60:61]
	s_cbranch_vccnz .LBB0_735
	s_andn2_b64 vcc, exec, s[58:59]
	s_cbranch_vccnz .LBB0_732
	v_mul_f32_e32 v16, 0x3d372713, v12
	v_mul_f32_e32 v16, v12, v16
	v_fma_f32 v16, v12, v16, v12
	v_mul_f32_e32 v16, 0x3f4c422a, v16
	v_add_f32_e32 v16, v16, v16
	v_mul_f32_e32 v16, 0x3fb8aa3b, v16
	v_exp_f32_e32 v16, v16
	v_mul_f32_e32 v17, 0.5, v12
	v_mul_f32_e32 v18, 0.5, v13
	v_mul_f32_e32 v19, 0.5, v15
	v_add_f32_e32 v16, 1.0, v16
	v_rcp_f32_e32 v16, v16
	v_mul_f32_e32 v36, 0.5, v9
	v_mul_f32_e32 v37, 0.5, v11
	v_mov_b32_e32 v129, v145
	v_fma_f32 v16, v16, -2.0, 1.0
	v_add_f32_e32 v16, 1.0, v16
	v_mul_f32_e32 v16, v17, v16
	v_mul_f32_e32 v17, 0x3d372713, v13
	v_mul_f32_e32 v17, v13, v17
	v_fma_f32 v17, v13, v17, v13
	v_mul_f32_e32 v17, 0x3f4c422a, v17
	v_add_f32_e32 v17, v17, v17
	v_mul_f32_e32 v17, 0x3fb8aa3b, v17
	v_exp_f32_e32 v17, v17
	s_mov_b64 s[42:43], 0
	v_add_f32_e32 v17, 1.0, v17
	v_rcp_f32_e32 v17, v17
	s_nop 0
	v_fma_f32 v17, v17, -2.0, 1.0
	v_add_f32_e32 v17, 1.0, v17
	v_mul_f32_e32 v17, v18, v17
	v_cvt_pk_bf16_f32 v16, v16, v17
	v_mul_f32_e32 v17, 0x3d372713, v14
	v_mul_f32_e32 v17, v14, v17
	v_fma_f32 v17, v14, v17, v14
	v_mul_f32_e32 v17, 0x3f4c422a, v17
	v_add_f32_e32 v17, v17, v17
	v_mul_f32_e32 v17, 0x3fb8aa3b, v17
	v_exp_f32_e32 v17, v17
	v_mul_f32_e32 v18, 0.5, v14
	v_add_f32_e32 v17, 1.0, v17
	v_rcp_f32_e32 v17, v17
	s_nop 0
	v_fma_f32 v17, v17, -2.0, 1.0
	v_add_f32_e32 v17, 1.0, v17
	v_mul_f32_e32 v17, v18, v17
	v_mul_f32_e32 v18, 0x3d372713, v15
	v_mul_f32_e32 v18, v15, v18
	v_fma_f32 v18, v15, v18, v15
	v_mul_f32_e32 v18, 0x3f4c422a, v18
	v_add_f32_e32 v18, v18, v18
	v_mul_f32_e32 v18, 0x3fb8aa3b, v18
	v_exp_f32_e32 v18, v18
	s_nop 0
	v_add_f32_e32 v18, 1.0, v18
	v_rcp_f32_e32 v18, v18
	s_nop 0
	v_fma_f32 v18, v18, -2.0, 1.0
	v_add_f32_e32 v18, 1.0, v18
	v_mul_f32_e32 v18, v19, v18
	v_cvt_pk_bf16_f32 v17, v17, v18
	v_mul_f32_e32 v18, 0x3d372713, v8
	v_mul_f32_e32 v18, v8, v18
	v_fma_f32 v18, v8, v18, v8
	v_mul_f32_e32 v18, 0x3f4c422a, v18
	v_add_f32_e32 v18, v18, v18
	v_mul_f32_e32 v18, 0x3fb8aa3b, v18
	v_exp_f32_e32 v18, v18
	v_mul_f32_e32 v19, 0.5, v8
	v_add_f32_e32 v18, 1.0, v18
	v_rcp_f32_e32 v18, v18
	s_nop 0
	v_fma_f32 v18, v18, -2.0, 1.0
	v_add_f32_e32 v18, 1.0, v18
	v_mul_f32_e32 v18, v19, v18
	v_mul_f32_e32 v19, 0x3d372713, v9
	v_mul_f32_e32 v19, v9, v19
	v_fma_f32 v19, v9, v19, v9
	v_mul_f32_e32 v19, 0x3f4c422a, v19
	v_add_f32_e32 v19, v19, v19
	v_mul_f32_e32 v19, 0x3fb8aa3b, v19
	v_exp_f32_e32 v19, v19
	s_nop 0
	v_add_f32_e32 v19, 1.0, v19
	v_rcp_f32_e32 v19, v19
	s_nop 0
	v_fma_f32 v19, v19, -2.0, 1.0
	v_add_f32_e32 v19, 1.0, v19
	v_mul_f32_e32 v19, v36, v19
	v_cvt_pk_bf16_f32 v18, v18, v19
	v_mul_f32_e32 v19, 0x3d372713, v10
	v_mul_f32_e32 v19, v10, v19
	v_fma_f32 v19, v10, v19, v10
	v_mul_f32_e32 v19, 0x3f4c422a, v19
	v_add_f32_e32 v19, v19, v19
	v_mul_f32_e32 v19, 0x3fb8aa3b, v19
	v_exp_f32_e32 v19, v19
	v_mul_f32_e32 v36, 0.5, v10
	v_add_f32_e32 v19, 1.0, v19
	v_rcp_f32_e32 v19, v19
	s_nop 0
	v_fma_f32 v19, v19, -2.0, 1.0
	v_add_f32_e32 v19, 1.0, v19
	v_mul_f32_e32 v19, v36, v19
	v_mul_f32_e32 v36, 0x3d372713, v11
	v_mul_f32_e32 v36, v11, v36
	v_fma_f32 v36, v11, v36, v11
	v_mul_f32_e32 v36, 0x3f4c422a, v36
	v_add_f32_e32 v36, v36, v36
	v_mul_f32_e32 v36, 0x3fb8aa3b, v36
	v_exp_f32_e32 v36, v36
	s_nop 0
	v_add_f32_e32 v36, 1.0, v36
	v_rcp_f32_e32 v36, v36
	s_nop 0
	v_fma_f32 v36, v36, -2.0, 1.0
	v_add_f32_e32 v36, 1.0, v36
	v_mul_f32_e32 v36, v37, v36
	v_cvt_pk_bf16_f32 v19, v19, v36
	v_lshl_add_u64 v[36:37], v[28:29], 0, v[128:129]
	global_store_dwordx4 v[36:37], v[16:19], off sc1

.LBB0_739:
	v_pk_mul_f32 v[12:13], v[12:13], s[52:53] op_sel_hi:[1,0]
	v_mov_b32_e32 v129, v145
	v_pk_mul_f32 v[18:19], v[10:11], s[52:53] op_sel_hi:[1,0]
	v_pk_mul_f32 v[10:11], v[8:9], s[52:53] op_sel_hi:[1,0]
	v_cvt_pk_bf16_f32 v8, v12, v13
	v_lshl_add_u64 v[12:13], v[16:17], 0, v[128:129]
	v_pk_mul_f32 v[14:15], v[14:15], s[52:53] op_sel_hi:[1,0]
	s_nop 0
	v_cvt_pk_bf16_f32 v9, v14, v15
	v_cvt_pk_bf16_f32 v10, v10, v11
	v_cvt_pk_bf16_f32 v11, v18, v19
	global_store_dwordx4 v[12:13], v[8:11], off sc1
	s_and_b64 vcc, exec, s[8:9]
	s_mov_b64 s[8:9], -1
	s_cbranch_vccz .LBB0_858

.LBB0_741:
	v_pk_mul_f32 v[4:5], v[4:5], s[52:53] op_sel_hi:[1,0]
	v_mov_b32_e32 v129, v145
	v_pk_mul_f32 v[8:9], v[2:3], s[52:53] op_sel_hi:[1,0]
	v_pk_mul_f32 v[2:3], v[0:1], s[52:53] op_sel_hi:[1,0]
	v_cvt_pk_bf16_f32 v0, v4, v5
	v_lshl_add_u64 v[4:5], v[16:17], 0, v[128:129]
	v_pk_mul_f32 v[6:7], v[6:7], s[52:53] op_sel_hi:[1,0]
	s_nop 0
	v_cvt_pk_bf16_f32 v1, v6, v7
	v_cvt_pk_bf16_f32 v2, v2, v3
	v_cvt_pk_bf16_f32 v3, v8, v9
	global_store_dwordx4 v[4:5], v[0:3], off offset:256 sc1
	s_andn2_b64 vcc, exec, s[10:11]
	s_mov_b64 s[4:5], -1
	s_cbranch_vccnz .LBB0_586
	s_branch .LBB0_918

.LBB0_745:
	s_andn2_b64 vcc, exec, s[42:43]
	s_cbranch_vccnz .LBB0_748
	v_or_b32_e32 v112, s91, v142
	s_and_b64 s[42:43], s[4:5], exec
	v_lshrrev_b32_e32 v113, 6, v112
	s_cselect_b32 s27, 8, 10
	v_cndmask_b32_e64 v114, v130, v131, s[4:5]
	v_lshl_add_u32 v114, v113, s27, v114
	v_ashrrev_i32_e32 v115, 31, v114
	s_cselect_b32 s43, s47, s69
	s_cselect_b32 s42, s46, s2
	v_lshlrev_b64 v[114:115], 7, v[114:115]
	v_lshl_add_u64 v[114:115], s[42:43], 0, v[114:115]
	v_lshlrev_b32_e32 v144, 1, v154
	v_lshl_add_u64 v[114:115], v[114:115], 0, v[144:145]
	s_andn2_b64 vcc, exec, s[4:5]
	v_cvt_pk_bf16_f32 v170, v108, v109
	v_cvt_pk_bf16_f32 v171, v110, v111
	v_cvt_pk_bf16_f32 v172, v104, v105
	v_cvt_pk_bf16_f32 v173, v106, v107
	global_store_dwordx4 v[114:115], v[170:173], off sc1
	s_cbranch_vccnz .LBB0_748
	s_or_b32 s42, s73, s70
	s_ashr_i32 s43, s42, 31
	s_lshl_b64 s[42:43], s[42:43], 19
	v_lshl_add_u64 v[114:115], v[116:117], 0, s[42:43]
	v_mov_b32_e32 v113, v145
	v_lshl_add_u64 v[112:113], v[112:113], 2, v[114:115]
	global_store_dwordx4 v[112:113], v[108:111], off nt
	global_store_dwordx4 v[112:113], v[104:107], off offset:16 nt

.LBB0_750:
	s_and_b64 vcc, exec, s[6:7]
	s_cbranch_vccnz .LBB0_871
	s_andn2_b64 vcc, exec, s[60:61]
	s_cbranch_vccnz .LBB0_757
	s_andn2_b64 vcc, exec, s[58:59]
	s_cbranch_vccnz .LBB0_754
	v_mul_f32_e32 v104, 0x3d372713, v100
	v_mul_f32_e32 v104, v100, v104
	v_fma_f32 v104, v100, v104, v100
	v_mul_f32_e32 v104, 0x3f4c422a, v104
	v_add_f32_e32 v104, v104, v104
	v_mul_f32_e32 v104, 0x3fb8aa3b, v104
	v_exp_f32_e32 v104, v104
	v_mul_f32_e32 v105, 0.5, v100
	v_mul_f32_e32 v106, 0.5, v101
	v_mul_f32_e32 v107, 0.5, v103
	v_add_f32_e32 v104, 1.0, v104
	v_rcp_f32_e32 v104, v104
	v_mul_f32_e32 v108, 0.5, v97
	v_mul_f32_e32 v109, 0.5, v99
	v_mov_b32_e32 v129, v145
	v_fma_f32 v104, v104, -2.0, 1.0
	v_add_f32_e32 v104, 1.0, v104
	v_mul_f32_e32 v104, v105, v104
	v_mul_f32_e32 v105, 0x3d372713, v101
	v_mul_f32_e32 v105, v101, v105
	v_fma_f32 v105, v101, v105, v101
	v_mul_f32_e32 v105, 0x3f4c422a, v105
	v_add_f32_e32 v105, v105, v105
	v_mul_f32_e32 v105, 0x3fb8aa3b, v105
	v_exp_f32_e32 v105, v105
	s_mov_b64 s[42:43], 0
	v_add_f32_e32 v105, 1.0, v105
	v_rcp_f32_e32 v105, v105
	s_nop 0
	v_fma_f32 v105, v105, -2.0, 1.0
	v_add_f32_e32 v105, 1.0, v105
	v_mul_f32_e32 v105, v106, v105
	v_cvt_pk_bf16_f32 v104, v104, v105
	v_mul_f32_e32 v105, 0x3d372713, v102
	v_mul_f32_e32 v105, v102, v105
	v_fma_f32 v105, v102, v105, v102
	v_mul_f32_e32 v105, 0x3f4c422a, v105
	v_add_f32_e32 v105, v105, v105
	v_mul_f32_e32 v105, 0x3fb8aa3b, v105
	v_exp_f32_e32 v105, v105
	v_mul_f32_e32 v106, 0.5, v102
	v_add_f32_e32 v105, 1.0, v105
	v_rcp_f32_e32 v105, v105
	s_nop 0
	v_fma_f32 v105, v105, -2.0, 1.0
	v_add_f32_e32 v105, 1.0, v105
	v_mul_f32_e32 v105, v106, v105
	v_mul_f32_e32 v106, 0x3d372713, v103
	v_mul_f32_e32 v106, v103, v106
	v_fma_f32 v106, v103, v106, v103
	v_mul_f32_e32 v106, 0x3f4c422a, v106
	v_add_f32_e32 v106, v106, v106
	v_mul_f32_e32 v106, 0x3fb8aa3b, v106
	v_exp_f32_e32 v106, v106
	s_nop 0
	v_add_f32_e32 v106, 1.0, v106
	v_rcp_f32_e32 v106, v106
	s_nop 0
	v_fma_f32 v106, v106, -2.0, 1.0
	v_add_f32_e32 v106, 1.0, v106
	v_mul_f32_e32 v106, v107, v106
	v_cvt_pk_bf16_f32 v105, v105, v106
	v_mul_f32_e32 v106, 0x3d372713, v96
	v_mul_f32_e32 v106, v96, v106
	v_fma_f32 v106, v96, v106, v96
	v_mul_f32_e32 v106, 0x3f4c422a, v106
	v_add_f32_e32 v106, v106, v106
	v_mul_f32_e32 v106, 0x3fb8aa3b, v106
	v_exp_f32_e32 v106, v106
	v_mul_f32_e32 v107, 0.5, v96
	v_add_f32_e32 v106, 1.0, v106
	v_rcp_f32_e32 v106, v106
	s_nop 0
	v_fma_f32 v106, v106, -2.0, 1.0
	v_add_f32_e32 v106, 1.0, v106
	v_mul_f32_e32 v106, v107, v106
	v_mul_f32_e32 v107, 0x3d372713, v97
	v_mul_f32_e32 v107, v97, v107
	v_fma_f32 v107, v97, v107, v97
	v_mul_f32_e32 v107, 0x3f4c422a, v107
	v_add_f32_e32 v107, v107, v107
	v_mul_f32_e32 v107, 0x3fb8aa3b, v107
	v_exp_f32_e32 v107, v107
	s_nop 0
	v_add_f32_e32 v107, 1.0, v107
	v_rcp_f32_e32 v107, v107
	s_nop 0
	v_fma_f32 v107, v107, -2.0, 1.0
	v_add_f32_e32 v107, 1.0, v107
	v_mul_f32_e32 v107, v108, v107
	v_cvt_pk_bf16_f32 v106, v106, v107
	v_mul_f32_e32 v107, 0x3d372713, v98
	v_mul_f32_e32 v107, v98, v107
	v_fma_f32 v107, v98, v107, v98
	v_mul_f32_e32 v107, 0x3f4c422a, v107
	v_add_f32_e32 v107, v107, v107
	v_mul_f32_e32 v107, 0x3fb8aa3b, v107
	v_exp_f32_e32 v107, v107
	v_mul_f32_e32 v108, 0.5, v98
	v_add_f32_e32 v107, 1.0, v107
	v_rcp_f32_e32 v107, v107
	s_nop 0
	v_fma_f32 v107, v107, -2.0, 1.0
	v_add_f32_e32 v107, 1.0, v107
	v_mul_f32_e32 v107, v108, v107
	v_mul_f32_e32 v108, 0x3d372713, v99
	v_mul_f32_e32 v108, v99, v108
	v_fma_f32 v108, v99, v108, v99
	v_mul_f32_e32 v108, 0x3f4c422a, v108
	v_add_f32_e32 v108, v108, v108
	v_mul_f32_e32 v108, 0x3fb8aa3b, v108
	v_exp_f32_e32 v108, v108
	s_nop 0
	v_add_f32_e32 v108, 1.0, v108
	v_rcp_f32_e32 v108, v108
	s_nop 0
	v_fma_f32 v108, v108, -2.0, 1.0
	v_add_f32_e32 v108, 1.0, v108
	v_mul_f32_e32 v108, v109, v108
	v_cvt_pk_bf16_f32 v107, v107, v108
	v_lshl_add_u64 v[108:109], v[124:125], 0, v[128:129]
	global_store_dwordx4 v[108:109], v[104:107], off offset:256 sc1

.LBB0_763:
	s_andn2_b64 vcc, exec, s[42:43]
	s_cbranch_vccnz .LBB0_766
	v_or_b32_e32 v96, s91, v142
	s_and_b64 s[42:43], s[4:5], exec
	v_lshrrev_b32_e32 v97, 6, v96
	s_cselect_b32 s27, 8, 10
	v_cndmask_b32_e64 v98, v112, v113, s[4:5]
	v_lshl_add_u32 v98, v97, s27, v98
	v_ashrrev_i32_e32 v99, 31, v98
	s_cselect_b32 s43, s47, s69
	s_cselect_b32 s42, s46, s2
	v_lshlrev_b64 v[98:99], 7, v[98:99]
	v_lshl_add_u64 v[98:99], s[42:43], 0, v[98:99]
	v_lshlrev_b32_e32 v144, 1, v154
	v_lshl_add_u64 v[98:99], v[98:99], 0, v[144:145]
	s_andn2_b64 vcc, exec, s[4:5]
	v_cvt_pk_bf16_f32 v116, v92, v93
	v_cvt_pk_bf16_f32 v117, v94, v95
	v_cvt_pk_bf16_f32 v118, v88, v89
	v_cvt_pk_bf16_f32 v119, v90, v91
	global_store_dwordx4 v[98:99], v[116:119], off sc1
	s_cbranch_vccnz .LBB0_766
	s_or_b32 s42, s73, s70
	s_ashr_i32 s43, s42, 31
	s_lshl_b64 s[42:43], s[42:43], 19
	v_lshl_add_u64 v[98:99], v[100:101], 0, s[42:43]
	v_mov_b32_e32 v97, v145
	v_lshl_add_u64 v[96:97], v[96:97], 2, v[98:99]
	global_store_dwordx4 v[96:97], v[92:95], off nt
	global_store_dwordx4 v[96:97], v[88:91], off offset:16 nt

.LBB0_768:
	s_and_b64 vcc, exec, s[6:7]
	s_cbranch_vccnz .LBB0_878
	s_andn2_b64 vcc, exec, s[60:61]
	s_cbranch_vccnz .LBB0_775
	s_andn2_b64 vcc, exec, s[58:59]
	s_cbranch_vccnz .LBB0_772
	v_mul_f32_e32 v88, 0x3d372713, v84
	v_mul_f32_e32 v88, v84, v88
	v_fma_f32 v88, v84, v88, v84
	v_mul_f32_e32 v88, 0x3f4c422a, v88
	v_add_f32_e32 v88, v88, v88
	v_mul_f32_e32 v88, 0x3fb8aa3b, v88
	v_exp_f32_e32 v88, v88
	v_mul_f32_e32 v89, 0.5, v84
	v_mul_f32_e32 v90, 0.5, v85
	v_mul_f32_e32 v91, 0.5, v87
	v_add_f32_e32 v88, 1.0, v88
	v_rcp_f32_e32 v88, v88
	v_mul_f32_e32 v92, 0.5, v81
	v_mul_f32_e32 v93, 0.5, v83
	v_mov_b32_e32 v129, v145
	v_fma_f32 v88, v88, -2.0, 1.0
	v_add_f32_e32 v88, 1.0, v88
	v_mul_f32_e32 v88, v89, v88
	v_mul_f32_e32 v89, 0x3d372713, v85
	v_mul_f32_e32 v89, v85, v89
	v_fma_f32 v89, v85, v89, v85
	v_mul_f32_e32 v89, 0x3f4c422a, v89
	v_add_f32_e32 v89, v89, v89
	v_mul_f32_e32 v89, 0x3fb8aa3b, v89
	v_exp_f32_e32 v89, v89
	s_mov_b64 s[42:43], 0
	v_add_f32_e32 v89, 1.0, v89
	v_rcp_f32_e32 v89, v89
	s_nop 0
	v_fma_f32 v89, v89, -2.0, 1.0
	v_add_f32_e32 v89, 1.0, v89
	v_mul_f32_e32 v89, v90, v89
	v_cvt_pk_bf16_f32 v88, v88, v89
	v_mul_f32_e32 v89, 0x3d372713, v86
	v_mul_f32_e32 v89, v86, v89
	v_fma_f32 v89, v86, v89, v86
	v_mul_f32_e32 v89, 0x3f4c422a, v89
	v_add_f32_e32 v89, v89, v89
	v_mul_f32_e32 v89, 0x3fb8aa3b, v89
	v_exp_f32_e32 v89, v89
	v_mul_f32_e32 v90, 0.5, v86
	v_add_f32_e32 v89, 1.0, v89
	v_rcp_f32_e32 v89, v89
	s_nop 0
	v_fma_f32 v89, v89, -2.0, 1.0
	v_add_f32_e32 v89, 1.0, v89
	v_mul_f32_e32 v89, v90, v89
	v_mul_f32_e32 v90, 0x3d372713, v87
	v_mul_f32_e32 v90, v87, v90
	v_fma_f32 v90, v87, v90, v87
	v_mul_f32_e32 v90, 0x3f4c422a, v90
	v_add_f32_e32 v90, v90, v90
	v_mul_f32_e32 v90, 0x3fb8aa3b, v90
	v_exp_f32_e32 v90, v90
	s_nop 0
	v_add_f32_e32 v90, 1.0, v90
	v_rcp_f32_e32 v90, v90
	s_nop 0
	v_fma_f32 v90, v90, -2.0, 1.0
	v_add_f32_e32 v90, 1.0, v90
	v_mul_f32_e32 v90, v91, v90
	v_cvt_pk_bf16_f32 v89, v89, v90
	v_mul_f32_e32 v90, 0x3d372713, v80
	v_mul_f32_e32 v90, v80, v90
	v_fma_f32 v90, v80, v90, v80
	v_mul_f32_e32 v90, 0x3f4c422a, v90
	v_add_f32_e32 v90, v90, v90
	v_mul_f32_e32 v90, 0x3fb8aa3b, v90
	v_exp_f32_e32 v90, v90
	v_mul_f32_e32 v91, 0.5, v80
	v_add_f32_e32 v90, 1.0, v90
	v_rcp_f32_e32 v90, v90
	s_nop 0
	v_fma_f32 v90, v90, -2.0, 1.0
	v_add_f32_e32 v90, 1.0, v90
	v_mul_f32_e32 v90, v91, v90
	v_mul_f32_e32 v91, 0x3d372713, v81
	v_mul_f32_e32 v91, v81, v91
	v_fma_f32 v91, v81, v91, v81
	v_mul_f32_e32 v91, 0x3f4c422a, v91
	v_add_f32_e32 v91, v91, v91
	v_mul_f32_e32 v91, 0x3fb8aa3b, v91
	v_exp_f32_e32 v91, v91
	s_nop 0
	v_add_f32_e32 v91, 1.0, v91
	v_rcp_f32_e32 v91, v91
	s_nop 0
	v_fma_f32 v91, v91, -2.0, 1.0
	v_add_f32_e32 v91, 1.0, v91
	v_mul_f32_e32 v91, v92, v91
	v_cvt_pk_bf16_f32 v90, v90, v91
	v_mul_f32_e32 v91, 0x3d372713, v82
	v_mul_f32_e32 v91, v82, v91
	v_fma_f32 v91, v82, v91, v82
	v_mul_f32_e32 v91, 0x3f4c422a, v91
	v_add_f32_e32 v91, v91, v91
	v_mul_f32_e32 v91, 0x3fb8aa3b, v91
	v_exp_f32_e32 v91, v91
	v_mul_f32_e32 v92, 0.5, v82
	v_add_f32_e32 v91, 1.0, v91
	v_rcp_f32_e32 v91, v91
	s_nop 0
	v_fma_f32 v91, v91, -2.0, 1.0
	v_add_f32_e32 v91, 1.0, v91
	v_mul_f32_e32 v91, v92, v91
	v_mul_f32_e32 v92, 0x3d372713, v83
	v_mul_f32_e32 v92, v83, v92
	v_fma_f32 v92, v83, v92, v83
	v_mul_f32_e32 v92, 0x3f4c422a, v92
	v_add_f32_e32 v92, v92, v92
	v_mul_f32_e32 v92, 0x3fb8aa3b, v92
	v_exp_f32_e32 v92, v92
	s_nop 0
	v_add_f32_e32 v92, 1.0, v92
	v_rcp_f32_e32 v92, v92
	s_nop 0
	v_fma_f32 v92, v92, -2.0, 1.0
	v_add_f32_e32 v92, 1.0, v92
	v_mul_f32_e32 v92, v93, v92
	v_cvt_pk_bf16_f32 v91, v91, v92
	v_lshl_add_u64 v[92:93], v[108:109], 0, v[128:129]
	global_store_dwordx4 v[92:93], v[88:91], off offset:256 sc1

.LBB0_781:
	s_andn2_b64 vcc, exec, s[42:43]
	s_cbranch_vccnz .LBB0_784
	v_or_b32_e32 v80, s91, v142
	s_and_b64 s[26:27], s[4:5], exec
	v_lshrrev_b32_e32 v81, 6, v80
	s_cselect_b32 s31, 8, 10
	v_cndmask_b32_e64 v82, v96, v97, s[4:5]
	v_lshl_add_u32 v82, v81, s31, v82
	v_ashrrev_i32_e32 v83, 31, v82
	s_cselect_b32 s27, s47, s69
	s_cselect_b32 s26, s46, s2
	v_lshlrev_b64 v[82:83], 7, v[82:83]
	v_lshl_add_u64 v[82:83], s[26:27], 0, v[82:83]
	v_lshlrev_b32_e32 v144, 1, v154
	v_lshl_add_u64 v[82:83], v[82:83], 0, v[144:145]
	s_andn2_b64 vcc, exec, s[4:5]
	v_cvt_pk_bf16_f32 v100, v76, v77
	v_cvt_pk_bf16_f32 v101, v78, v79
	v_cvt_pk_bf16_f32 v102, v72, v73
	v_cvt_pk_bf16_f32 v103, v74, v75
	global_store_dwordx4 v[82:83], v[100:103], off sc1
	s_cbranch_vccnz .LBB0_784
	s_or_b32 s26, s73, s70
	s_ashr_i32 s27, s26, 31
	s_lshl_b64 s[26:27], s[26:27], 19
	v_lshl_add_u64 v[82:83], v[84:85], 0, s[26:27]
	v_mov_b32_e32 v81, v145
	v_lshl_add_u64 v[80:81], v[80:81], 2, v[82:83]
	global_store_dwordx4 v[80:81], v[76:79], off nt
	global_store_dwordx4 v[80:81], v[72:75], off offset:16 nt

.LBB0_786:
	s_and_b64 vcc, exec, s[6:7]
	s_cbranch_vccnz .LBB0_885
	s_andn2_b64 vcc, exec, s[60:61]
	s_cbranch_vccnz .LBB0_793
	s_andn2_b64 vcc, exec, s[58:59]
	s_cbranch_vccnz .LBB0_790
	v_mul_f32_e32 v72, 0x3d372713, v68
	v_mul_f32_e32 v72, v68, v72
	v_fma_f32 v72, v68, v72, v68
	v_mul_f32_e32 v72, 0x3f4c422a, v72
	v_add_f32_e32 v72, v72, v72
	v_mul_f32_e32 v72, 0x3fb8aa3b, v72
	v_exp_f32_e32 v72, v72
	v_mul_f32_e32 v73, 0.5, v68
	v_mul_f32_e32 v74, 0.5, v69
	v_mul_f32_e32 v75, 0.5, v71
	v_add_f32_e32 v72, 1.0, v72
	v_rcp_f32_e32 v72, v72
	v_mul_f32_e32 v76, 0.5, v65
	v_mul_f32_e32 v77, 0.5, v67
	v_mov_b32_e32 v129, v145
	v_fma_f32 v72, v72, -2.0, 1.0
	v_add_f32_e32 v72, 1.0, v72
	v_mul_f32_e32 v72, v73, v72
	v_mul_f32_e32 v73, 0x3d372713, v69
	v_mul_f32_e32 v73, v69, v73
	v_fma_f32 v73, v69, v73, v69
	v_mul_f32_e32 v73, 0x3f4c422a, v73
	v_add_f32_e32 v73, v73, v73
	v_mul_f32_e32 v73, 0x3fb8aa3b, v73
	v_exp_f32_e32 v73, v73
	s_mov_b64 s[42:43], 0
	v_add_f32_e32 v73, 1.0, v73
	v_rcp_f32_e32 v73, v73
	s_nop 0
	v_fma_f32 v73, v73, -2.0, 1.0
	v_add_f32_e32 v73, 1.0, v73
	v_mul_f32_e32 v73, v74, v73
	v_cvt_pk_bf16_f32 v72, v72, v73
	v_mul_f32_e32 v73, 0x3d372713, v70
	v_mul_f32_e32 v73, v70, v73
	v_fma_f32 v73, v70, v73, v70
	v_mul_f32_e32 v73, 0x3f4c422a, v73
	v_add_f32_e32 v73, v73, v73
	v_mul_f32_e32 v73, 0x3fb8aa3b, v73
	v_exp_f32_e32 v73, v73
	v_mul_f32_e32 v74, 0.5, v70
	v_add_f32_e32 v73, 1.0, v73
	v_rcp_f32_e32 v73, v73
	s_nop 0
	v_fma_f32 v73, v73, -2.0, 1.0
	v_add_f32_e32 v73, 1.0, v73
	v_mul_f32_e32 v73, v74, v73
	v_mul_f32_e32 v74, 0x3d372713, v71
	v_mul_f32_e32 v74, v71, v74
	v_fma_f32 v74, v71, v74, v71
	v_mul_f32_e32 v74, 0x3f4c422a, v74
	v_add_f32_e32 v74, v74, v74
	v_mul_f32_e32 v74, 0x3fb8aa3b, v74
	v_exp_f32_e32 v74, v74
	s_nop 0
	v_add_f32_e32 v74, 1.0, v74
	v_rcp_f32_e32 v74, v74
	s_nop 0
	v_fma_f32 v74, v74, -2.0, 1.0
	v_add_f32_e32 v74, 1.0, v74
	v_mul_f32_e32 v74, v75, v74
	v_cvt_pk_bf16_f32 v73, v73, v74
	v_mul_f32_e32 v74, 0x3d372713, v64
	v_mul_f32_e32 v74, v64, v74
	v_fma_f32 v74, v64, v74, v64
	v_mul_f32_e32 v74, 0x3f4c422a, v74
	v_add_f32_e32 v74, v74, v74
	v_mul_f32_e32 v74, 0x3fb8aa3b, v74
	v_exp_f32_e32 v74, v74
	v_mul_f32_e32 v75, 0.5, v64
	v_add_f32_e32 v74, 1.0, v74
	v_rcp_f32_e32 v74, v74
	s_nop 0
	v_fma_f32 v74, v74, -2.0, 1.0
	v_add_f32_e32 v74, 1.0, v74
	v_mul_f32_e32 v74, v75, v74
	v_mul_f32_e32 v75, 0x3d372713, v65
	v_mul_f32_e32 v75, v65, v75
	v_fma_f32 v75, v65, v75, v65
	v_mul_f32_e32 v75, 0x3f4c422a, v75
	v_add_f32_e32 v75, v75, v75
	v_mul_f32_e32 v75, 0x3fb8aa3b, v75
	v_exp_f32_e32 v75, v75
	s_nop 0
	v_add_f32_e32 v75, 1.0, v75
	v_rcp_f32_e32 v75, v75
	s_nop 0
	v_fma_f32 v75, v75, -2.0, 1.0
	v_add_f32_e32 v75, 1.0, v75
	v_mul_f32_e32 v75, v76, v75
	v_cvt_pk_bf16_f32 v74, v74, v75
	v_mul_f32_e32 v75, 0x3d372713, v66
	v_mul_f32_e32 v75, v66, v75
	v_fma_f32 v75, v66, v75, v66
	v_mul_f32_e32 v75, 0x3f4c422a, v75
	v_add_f32_e32 v75, v75, v75
	v_mul_f32_e32 v75, 0x3fb8aa3b, v75
	v_exp_f32_e32 v75, v75
	v_mul_f32_e32 v76, 0.5, v66
	v_add_f32_e32 v75, 1.0, v75
	v_rcp_f32_e32 v75, v75
	s_nop 0
	v_fma_f32 v75, v75, -2.0, 1.0
	v_add_f32_e32 v75, 1.0, v75
	v_mul_f32_e32 v75, v76, v75
	v_mul_f32_e32 v76, 0x3d372713, v67
	v_mul_f32_e32 v76, v67, v76
	v_fma_f32 v76, v67, v76, v67
	v_mul_f32_e32 v76, 0x3f4c422a, v76
	v_add_f32_e32 v76, v76, v76
	v_mul_f32_e32 v76, 0x3fb8aa3b, v76
	v_exp_f32_e32 v76, v76
	s_nop 0
	v_add_f32_e32 v76, 1.0, v76
	v_rcp_f32_e32 v76, v76
	s_nop 0
	v_fma_f32 v76, v76, -2.0, 1.0
	v_add_f32_e32 v76, 1.0, v76
	v_mul_f32_e32 v76, v77, v76
	v_cvt_pk_bf16_f32 v75, v75, v76
	v_lshl_add_u64 v[76:77], v[92:93], 0, v[128:129]
	global_store_dwordx4 v[76:77], v[72:75], off offset:256 sc1

.LBB0_799:
	s_andn2_b64 vcc, exec, s[42:43]
	s_cbranch_vccnz .LBB0_802
	v_or_b32_e32 v64, s91, v142
	s_and_b64 s[42:43], s[4:5], exec
	v_lshrrev_b32_e32 v65, 6, v64
	s_cselect_b32 s38, 8, 10
	v_cndmask_b32_e64 v66, v80, v81, s[4:5]
	v_lshl_add_u32 v66, v65, s38, v66
	v_ashrrev_i32_e32 v67, 31, v66
	s_cselect_b32 s43, s47, s69
	s_cselect_b32 s42, s46, s2
	v_lshlrev_b64 v[66:67], 7, v[66:67]
	v_lshl_add_u64 v[66:67], s[42:43], 0, v[66:67]
	v_lshlrev_b32_e32 v144, 1, v154
	v_lshl_add_u64 v[66:67], v[66:67], 0, v[144:145]
	s_andn2_b64 vcc, exec, s[4:5]
	v_cvt_pk_bf16_f32 v84, v60, v61
	v_cvt_pk_bf16_f32 v85, v62, v63
	v_cvt_pk_bf16_f32 v86, v56, v57
	v_cvt_pk_bf16_f32 v87, v58, v59
	global_store_dwordx4 v[66:67], v[84:87], off sc1
	s_cbranch_vccnz .LBB0_802
	s_or_b32 s42, s73, s70
	s_ashr_i32 s43, s42, 31
	s_lshl_b64 s[42:43], s[42:43], 19
	v_lshl_add_u64 v[66:67], v[68:69], 0, s[42:43]
	v_mov_b32_e32 v65, v145
	v_lshl_add_u64 v[64:65], v[64:65], 2, v[66:67]
	global_store_dwordx4 v[64:65], v[60:63], off nt
	global_store_dwordx4 v[64:65], v[56:59], off offset:16 nt

.LBB0_804:
	s_and_b64 vcc, exec, s[6:7]
	s_cbranch_vccnz .LBB0_892
	s_andn2_b64 vcc, exec, s[60:61]
	s_cbranch_vccnz .LBB0_811
	s_andn2_b64 vcc, exec, s[58:59]
	s_cbranch_vccnz .LBB0_808
	v_mul_f32_e32 v56, 0x3d372713, v52
	v_mul_f32_e32 v56, v52, v56
	v_fma_f32 v56, v52, v56, v52
	v_mul_f32_e32 v56, 0x3f4c422a, v56
	v_add_f32_e32 v56, v56, v56
	v_mul_f32_e32 v56, 0x3fb8aa3b, v56
	v_exp_f32_e32 v56, v56
	v_mul_f32_e32 v57, 0.5, v52
	v_mul_f32_e32 v58, 0.5, v53
	v_mul_f32_e32 v59, 0.5, v55
	v_add_f32_e32 v56, 1.0, v56
	v_rcp_f32_e32 v56, v56
	v_mul_f32_e32 v60, 0.5, v49
	v_mul_f32_e32 v61, 0.5, v51
	v_mov_b32_e32 v129, v145
	v_fma_f32 v56, v56, -2.0, 1.0
	v_add_f32_e32 v56, 1.0, v56
	v_mul_f32_e32 v56, v57, v56
	v_mul_f32_e32 v57, 0x3d372713, v53
	v_mul_f32_e32 v57, v53, v57
	v_fma_f32 v57, v53, v57, v53
	v_mul_f32_e32 v57, 0x3f4c422a, v57
	v_add_f32_e32 v57, v57, v57
	v_mul_f32_e32 v57, 0x3fb8aa3b, v57
	v_exp_f32_e32 v57, v57
	s_mov_b64 s[42:43], 0
	v_add_f32_e32 v57, 1.0, v57
	v_rcp_f32_e32 v57, v57
	s_nop 0
	v_fma_f32 v57, v57, -2.0, 1.0
	v_add_f32_e32 v57, 1.0, v57
	v_mul_f32_e32 v57, v58, v57
	v_cvt_pk_bf16_f32 v56, v56, v57
	v_mul_f32_e32 v57, 0x3d372713, v54
	v_mul_f32_e32 v57, v54, v57
	v_fma_f32 v57, v54, v57, v54
	v_mul_f32_e32 v57, 0x3f4c422a, v57
	v_add_f32_e32 v57, v57, v57
	v_mul_f32_e32 v57, 0x3fb8aa3b, v57
	v_exp_f32_e32 v57, v57
	v_mul_f32_e32 v58, 0.5, v54
	v_add_f32_e32 v57, 1.0, v57
	v_rcp_f32_e32 v57, v57
	s_nop 0
	v_fma_f32 v57, v57, -2.0, 1.0
	v_add_f32_e32 v57, 1.0, v57
	v_mul_f32_e32 v57, v58, v57
	v_mul_f32_e32 v58, 0x3d372713, v55
	v_mul_f32_e32 v58, v55, v58
	v_fma_f32 v58, v55, v58, v55
	v_mul_f32_e32 v58, 0x3f4c422a, v58
	v_add_f32_e32 v58, v58, v58
	v_mul_f32_e32 v58, 0x3fb8aa3b, v58
	v_exp_f32_e32 v58, v58
	s_nop 0
	v_add_f32_e32 v58, 1.0, v58
	v_rcp_f32_e32 v58, v58
	s_nop 0
	v_fma_f32 v58, v58, -2.0, 1.0
	v_add_f32_e32 v58, 1.0, v58
	v_mul_f32_e32 v58, v59, v58
	v_cvt_pk_bf16_f32 v57, v57, v58
	v_mul_f32_e32 v58, 0x3d372713, v48
	v_mul_f32_e32 v58, v48, v58
	v_fma_f32 v58, v48, v58, v48
	v_mul_f32_e32 v58, 0x3f4c422a, v58
	v_add_f32_e32 v58, v58, v58
	v_mul_f32_e32 v58, 0x3fb8aa3b, v58
	v_exp_f32_e32 v58, v58
	v_mul_f32_e32 v59, 0.5, v48
	v_add_f32_e32 v58, 1.0, v58
	v_rcp_f32_e32 v58, v58
	s_nop 0
	v_fma_f32 v58, v58, -2.0, 1.0
	v_add_f32_e32 v58, 1.0, v58
	v_mul_f32_e32 v58, v59, v58
	v_mul_f32_e32 v59, 0x3d372713, v49
	v_mul_f32_e32 v59, v49, v59
	v_fma_f32 v59, v49, v59, v49
	v_mul_f32_e32 v59, 0x3f4c422a, v59
	v_add_f32_e32 v59, v59, v59
	v_mul_f32_e32 v59, 0x3fb8aa3b, v59
	v_exp_f32_e32 v59, v59
	s_nop 0
	v_add_f32_e32 v59, 1.0, v59
	v_rcp_f32_e32 v59, v59
	s_nop 0
	v_fma_f32 v59, v59, -2.0, 1.0
	v_add_f32_e32 v59, 1.0, v59
	v_mul_f32_e32 v59, v60, v59
	v_cvt_pk_bf16_f32 v58, v58, v59
	v_mul_f32_e32 v59, 0x3d372713, v50
	v_mul_f32_e32 v59, v50, v59
	v_fma_f32 v59, v50, v59, v50
	v_mul_f32_e32 v59, 0x3f4c422a, v59
	v_add_f32_e32 v59, v59, v59
	v_mul_f32_e32 v59, 0x3fb8aa3b, v59
	v_exp_f32_e32 v59, v59
	v_mul_f32_e32 v60, 0.5, v50
	v_add_f32_e32 v59, 1.0, v59
	v_rcp_f32_e32 v59, v59
	s_nop 0
	v_fma_f32 v59, v59, -2.0, 1.0
	v_add_f32_e32 v59, 1.0, v59
	v_mul_f32_e32 v59, v60, v59
	v_mul_f32_e32 v60, 0x3d372713, v51
	v_mul_f32_e32 v60, v51, v60
	v_fma_f32 v60, v51, v60, v51
	v_mul_f32_e32 v60, 0x3f4c422a, v60
	v_add_f32_e32 v60, v60, v60
	v_mul_f32_e32 v60, 0x3fb8aa3b, v60
	v_exp_f32_e32 v60, v60
	s_nop 0
	v_add_f32_e32 v60, 1.0, v60
	v_rcp_f32_e32 v60, v60
	s_nop 0
	v_fma_f32 v60, v60, -2.0, 1.0
	v_add_f32_e32 v60, 1.0, v60
	v_mul_f32_e32 v60, v61, v60
	v_cvt_pk_bf16_f32 v59, v59, v60
	v_lshl_add_u64 v[60:61], v[76:77], 0, v[128:129]
	global_store_dwordx4 v[60:61], v[56:59], off offset:256 sc1

.LBB0_817:
	s_andn2_b64 vcc, exec, s[42:43]
	s_cbranch_vccnz .LBB0_820
	v_or_b32_e32 v48, s91, v142
	s_and_b64 s[42:43], s[4:5], exec
	v_lshrrev_b32_e32 v49, 6, v48
	s_cselect_b32 s38, 8, 10
	v_cndmask_b32_e64 v50, v64, v65, s[4:5]
	v_lshl_add_u32 v50, v49, s38, v50
	v_ashrrev_i32_e32 v51, 31, v50
	s_cselect_b32 s43, s47, s69
	s_cselect_b32 s42, s46, s2
	v_lshlrev_b64 v[50:51], 7, v[50:51]
	v_lshl_add_u64 v[50:51], s[42:43], 0, v[50:51]
	v_lshlrev_b32_e32 v144, 1, v154
	v_lshl_add_u64 v[50:51], v[50:51], 0, v[144:145]
	s_andn2_b64 vcc, exec, s[4:5]
	v_cvt_pk_bf16_f32 v68, v44, v45
	v_cvt_pk_bf16_f32 v69, v46, v47
	v_cvt_pk_bf16_f32 v70, v40, v41
	v_cvt_pk_bf16_f32 v71, v42, v43
	global_store_dwordx4 v[50:51], v[68:71], off sc1
	s_cbranch_vccnz .LBB0_820
	s_or_b32 s42, s73, s70
	s_ashr_i32 s43, s42, 31
	s_lshl_b64 s[42:43], s[42:43], 19
	v_lshl_add_u64 v[50:51], v[52:53], 0, s[42:43]
	v_mov_b32_e32 v49, v145
	v_lshl_add_u64 v[48:49], v[48:49], 2, v[50:51]
	global_store_dwordx4 v[48:49], v[44:47], off nt
	global_store_dwordx4 v[48:49], v[40:43], off offset:16 nt

.LBB0_822:
	s_and_b64 vcc, exec, s[6:7]
	s_cbranch_vccnz .LBB0_899
	s_andn2_b64 vcc, exec, s[60:61]
	s_cbranch_vccnz .LBB0_829
	s_andn2_b64 vcc, exec, s[58:59]
	s_cbranch_vccnz .LBB0_826
	v_mul_f32_e32 v40, 0x3d372713, v36
	v_mul_f32_e32 v40, v36, v40
	v_fma_f32 v40, v36, v40, v36
	v_mul_f32_e32 v40, 0x3f4c422a, v40
	v_add_f32_e32 v40, v40, v40
	v_mul_f32_e32 v40, 0x3fb8aa3b, v40
	v_exp_f32_e32 v40, v40
	v_mul_f32_e32 v41, 0.5, v36
	v_mul_f32_e32 v42, 0.5, v37
	v_mul_f32_e32 v43, 0.5, v39
	v_add_f32_e32 v40, 1.0, v40
	v_rcp_f32_e32 v40, v40
	v_mul_f32_e32 v44, 0.5, v33
	v_mul_f32_e32 v45, 0.5, v35
	v_mov_b32_e32 v129, v145
	v_fma_f32 v40, v40, -2.0, 1.0
	v_add_f32_e32 v40, 1.0, v40
	v_mul_f32_e32 v40, v41, v40
	v_mul_f32_e32 v41, 0x3d372713, v37
	v_mul_f32_e32 v41, v37, v41
	v_fma_f32 v41, v37, v41, v37
	v_mul_f32_e32 v41, 0x3f4c422a, v41
	v_add_f32_e32 v41, v41, v41
	v_mul_f32_e32 v41, 0x3fb8aa3b, v41
	v_exp_f32_e32 v41, v41
	s_mov_b64 s[42:43], 0
	v_add_f32_e32 v41, 1.0, v41
	v_rcp_f32_e32 v41, v41
	s_nop 0
	v_fma_f32 v41, v41, -2.0, 1.0
	v_add_f32_e32 v41, 1.0, v41
	v_mul_f32_e32 v41, v42, v41
	v_cvt_pk_bf16_f32 v40, v40, v41
	v_mul_f32_e32 v41, 0x3d372713, v38
	v_mul_f32_e32 v41, v38, v41
	v_fma_f32 v41, v38, v41, v38
	v_mul_f32_e32 v41, 0x3f4c422a, v41
	v_add_f32_e32 v41, v41, v41
	v_mul_f32_e32 v41, 0x3fb8aa3b, v41
	v_exp_f32_e32 v41, v41
	v_mul_f32_e32 v42, 0.5, v38
	v_add_f32_e32 v41, 1.0, v41
	v_rcp_f32_e32 v41, v41
	s_nop 0
	v_fma_f32 v41, v41, -2.0, 1.0
	v_add_f32_e32 v41, 1.0, v41
	v_mul_f32_e32 v41, v42, v41
	v_mul_f32_e32 v42, 0x3d372713, v39
	v_mul_f32_e32 v42, v39, v42
	v_fma_f32 v42, v39, v42, v39
	v_mul_f32_e32 v42, 0x3f4c422a, v42
	v_add_f32_e32 v42, v42, v42
	v_mul_f32_e32 v42, 0x3fb8aa3b, v42
	v_exp_f32_e32 v42, v42
	s_nop 0
	v_add_f32_e32 v42, 1.0, v42
	v_rcp_f32_e32 v42, v42
	s_nop 0
	v_fma_f32 v42, v42, -2.0, 1.0
	v_add_f32_e32 v42, 1.0, v42
	v_mul_f32_e32 v42, v43, v42
	v_cvt_pk_bf16_f32 v41, v41, v42
	v_mul_f32_e32 v42, 0x3d372713, v32
	v_mul_f32_e32 v42, v32, v42
	v_fma_f32 v42, v32, v42, v32
	v_mul_f32_e32 v42, 0x3f4c422a, v42
	v_add_f32_e32 v42, v42, v42
	v_mul_f32_e32 v42, 0x3fb8aa3b, v42
	v_exp_f32_e32 v42, v42
	v_mul_f32_e32 v43, 0.5, v32
	v_add_f32_e32 v42, 1.0, v42
	v_rcp_f32_e32 v42, v42
	s_nop 0
	v_fma_f32 v42, v42, -2.0, 1.0
	v_add_f32_e32 v42, 1.0, v42
	v_mul_f32_e32 v42, v43, v42
	v_mul_f32_e32 v43, 0x3d372713, v33
	v_mul_f32_e32 v43, v33, v43
	v_fma_f32 v43, v33, v43, v33
	v_mul_f32_e32 v43, 0x3f4c422a, v43
	v_add_f32_e32 v43, v43, v43
	v_mul_f32_e32 v43, 0x3fb8aa3b, v43
	v_exp_f32_e32 v43, v43
	s_nop 0
	v_add_f32_e32 v43, 1.0, v43
	v_rcp_f32_e32 v43, v43
	s_nop 0
	v_fma_f32 v43, v43, -2.0, 1.0
	v_add_f32_e32 v43, 1.0, v43
	v_mul_f32_e32 v43, v44, v43
	v_cvt_pk_bf16_f32 v42, v42, v43
	v_mul_f32_e32 v43, 0x3d372713, v34
	v_mul_f32_e32 v43, v34, v43
	v_fma_f32 v43, v34, v43, v34
	v_mul_f32_e32 v43, 0x3f4c422a, v43
	v_add_f32_e32 v43, v43, v43
	v_mul_f32_e32 v43, 0x3fb8aa3b, v43
	v_exp_f32_e32 v43, v43
	v_mul_f32_e32 v44, 0.5, v34
	v_add_f32_e32 v43, 1.0, v43
	v_rcp_f32_e32 v43, v43
	s_nop 0
	v_fma_f32 v43, v43, -2.0, 1.0
	v_add_f32_e32 v43, 1.0, v43
	v_mul_f32_e32 v43, v44, v43
	v_mul_f32_e32 v44, 0x3d372713, v35
	v_mul_f32_e32 v44, v35, v44
	v_fma_f32 v44, v35, v44, v35
	v_mul_f32_e32 v44, 0x3f4c422a, v44
	v_add_f32_e32 v44, v44, v44
	v_mul_f32_e32 v44, 0x3fb8aa3b, v44
	v_exp_f32_e32 v44, v44
	s_nop 0
	v_add_f32_e32 v44, 1.0, v44
	v_rcp_f32_e32 v44, v44
	s_nop 0
	v_fma_f32 v44, v44, -2.0, 1.0
	v_add_f32_e32 v44, 1.0, v44
	v_mul_f32_e32 v44, v45, v44
	v_cvt_pk_bf16_f32 v43, v43, v44
	v_lshl_add_u64 v[44:45], v[60:61], 0, v[128:129]
	global_store_dwordx4 v[44:45], v[40:43], off offset:256 sc1

.LBB0_835:
	s_andn2_b64 vcc, exec, s[42:43]
	s_cbranch_vccnz .LBB0_838
	v_or_b32_e32 v32, s91, v142
	s_and_b64 s[42:43], s[4:5], exec
	v_lshrrev_b32_e32 v33, 6, v32
	s_cselect_b32 s38, 8, 10
	v_cndmask_b32_e64 v34, v48, v49, s[4:5]
	v_lshl_add_u32 v34, v33, s38, v34
	v_ashrrev_i32_e32 v35, 31, v34
	s_cselect_b32 s43, s47, s69
	s_cselect_b32 s42, s46, s2
	v_lshlrev_b64 v[34:35], 7, v[34:35]
	v_lshl_add_u64 v[34:35], s[42:43], 0, v[34:35]
	v_lshlrev_b32_e32 v144, 1, v154
	v_lshl_add_u64 v[34:35], v[34:35], 0, v[144:145]
	s_andn2_b64 vcc, exec, s[4:5]
	v_cvt_pk_bf16_f32 v52, v28, v29
	v_cvt_pk_bf16_f32 v53, v30, v31
	v_cvt_pk_bf16_f32 v54, v24, v25
	v_cvt_pk_bf16_f32 v55, v26, v27
	global_store_dwordx4 v[34:35], v[52:55], off sc1
	s_cbranch_vccnz .LBB0_838
	s_or_b32 s42, s73, s70
	s_ashr_i32 s43, s42, 31
	s_lshl_b64 s[42:43], s[42:43], 19
	v_lshl_add_u64 v[34:35], v[36:37], 0, s[42:43]
	v_mov_b32_e32 v33, v145
	v_lshl_add_u64 v[32:33], v[32:33], 2, v[34:35]
	global_store_dwordx4 v[32:33], v[28:31], off nt
	global_store_dwordx4 v[32:33], v[24:27], off offset:16 nt

.LBB0_840:
	s_and_b64 vcc, exec, s[6:7]
	s_cbranch_vccnz .LBB0_906
	s_andn2_b64 vcc, exec, s[60:61]
	s_cbranch_vccnz .LBB0_847
	s_andn2_b64 vcc, exec, s[58:59]
	s_cbranch_vccnz .LBB0_844
	v_mul_f32_e32 v24, 0x3d372713, v20
	v_mul_f32_e32 v24, v20, v24
	v_fma_f32 v24, v20, v24, v20
	v_mul_f32_e32 v24, 0x3f4c422a, v24
	v_add_f32_e32 v24, v24, v24
	v_mul_f32_e32 v24, 0x3fb8aa3b, v24
	v_exp_f32_e32 v24, v24
	v_mul_f32_e32 v25, 0.5, v20
	v_mul_f32_e32 v26, 0.5, v21
	v_mul_f32_e32 v27, 0.5, v23
	v_add_f32_e32 v24, 1.0, v24
	v_rcp_f32_e32 v24, v24
	v_mul_f32_e32 v28, 0.5, v17
	v_mul_f32_e32 v29, 0.5, v19
	v_mov_b32_e32 v129, v145
	v_fma_f32 v24, v24, -2.0, 1.0
	v_add_f32_e32 v24, 1.0, v24
	v_mul_f32_e32 v24, v25, v24
	v_mul_f32_e32 v25, 0x3d372713, v21
	v_mul_f32_e32 v25, v21, v25
	v_fma_f32 v25, v21, v25, v21
	v_mul_f32_e32 v25, 0x3f4c422a, v25
	v_add_f32_e32 v25, v25, v25
	v_mul_f32_e32 v25, 0x3fb8aa3b, v25
	v_exp_f32_e32 v25, v25
	s_mov_b64 s[42:43], 0
	v_add_f32_e32 v25, 1.0, v25
	v_rcp_f32_e32 v25, v25
	s_nop 0
	v_fma_f32 v25, v25, -2.0, 1.0
	v_add_f32_e32 v25, 1.0, v25
	v_mul_f32_e32 v25, v26, v25
	v_cvt_pk_bf16_f32 v24, v24, v25
	v_mul_f32_e32 v25, 0x3d372713, v22
	v_mul_f32_e32 v25, v22, v25
	v_fma_f32 v25, v22, v25, v22
	v_mul_f32_e32 v25, 0x3f4c422a, v25
	v_add_f32_e32 v25, v25, v25
	v_mul_f32_e32 v25, 0x3fb8aa3b, v25
	v_exp_f32_e32 v25, v25
	v_mul_f32_e32 v26, 0.5, v22
	v_add_f32_e32 v25, 1.0, v25
	v_rcp_f32_e32 v25, v25
	s_nop 0
	v_fma_f32 v25, v25, -2.0, 1.0
	v_add_f32_e32 v25, 1.0, v25
	v_mul_f32_e32 v25, v26, v25
	v_mul_f32_e32 v26, 0x3d372713, v23
	v_mul_f32_e32 v26, v23, v26
	v_fma_f32 v26, v23, v26, v23
	v_mul_f32_e32 v26, 0x3f4c422a, v26
	v_add_f32_e32 v26, v26, v26
	v_mul_f32_e32 v26, 0x3fb8aa3b, v26
	v_exp_f32_e32 v26, v26
	s_nop 0
	v_add_f32_e32 v26, 1.0, v26
	v_rcp_f32_e32 v26, v26
	s_nop 0
	v_fma_f32 v26, v26, -2.0, 1.0
	v_add_f32_e32 v26, 1.0, v26
	v_mul_f32_e32 v26, v27, v26
	v_cvt_pk_bf16_f32 v25, v25, v26
	v_mul_f32_e32 v26, 0x3d372713, v16
	v_mul_f32_e32 v26, v16, v26
	v_fma_f32 v26, v16, v26, v16
	v_mul_f32_e32 v26, 0x3f4c422a, v26
	v_add_f32_e32 v26, v26, v26
	v_mul_f32_e32 v26, 0x3fb8aa3b, v26
	v_exp_f32_e32 v26, v26
	v_mul_f32_e32 v27, 0.5, v16
	v_add_f32_e32 v26, 1.0, v26
	v_rcp_f32_e32 v26, v26
	s_nop 0
	v_fma_f32 v26, v26, -2.0, 1.0
	v_add_f32_e32 v26, 1.0, v26
	v_mul_f32_e32 v26, v27, v26
	v_mul_f32_e32 v27, 0x3d372713, v17
	v_mul_f32_e32 v27, v17, v27
	v_fma_f32 v27, v17, v27, v17
	v_mul_f32_e32 v27, 0x3f4c422a, v27
	v_add_f32_e32 v27, v27, v27
	v_mul_f32_e32 v27, 0x3fb8aa3b, v27
	v_exp_f32_e32 v27, v27
	s_nop 0
	v_add_f32_e32 v27, 1.0, v27
	v_rcp_f32_e32 v27, v27
	s_nop 0
	v_fma_f32 v27, v27, -2.0, 1.0
	v_add_f32_e32 v27, 1.0, v27
	v_mul_f32_e32 v27, v28, v27
	v_cvt_pk_bf16_f32 v26, v26, v27
	v_mul_f32_e32 v27, 0x3d372713, v18
	v_mul_f32_e32 v27, v18, v27
	v_fma_f32 v27, v18, v27, v18
	v_mul_f32_e32 v27, 0x3f4c422a, v27
	v_add_f32_e32 v27, v27, v27
	v_mul_f32_e32 v27, 0x3fb8aa3b, v27
	v_exp_f32_e32 v27, v27
	v_mul_f32_e32 v28, 0.5, v18
	v_add_f32_e32 v27, 1.0, v27
	v_rcp_f32_e32 v27, v27
	s_nop 0
	v_fma_f32 v27, v27, -2.0, 1.0
	v_add_f32_e32 v27, 1.0, v27
	v_mul_f32_e32 v27, v28, v27
	v_mul_f32_e32 v28, 0x3d372713, v19
	v_mul_f32_e32 v28, v19, v28
	v_fma_f32 v28, v19, v28, v19
	v_mul_f32_e32 v28, 0x3f4c422a, v28
	v_add_f32_e32 v28, v28, v28
	v_mul_f32_e32 v28, 0x3fb8aa3b, v28
	v_exp_f32_e32 v28, v28
	s_nop 0
	v_add_f32_e32 v28, 1.0, v28
	v_rcp_f32_e32 v28, v28
	s_nop 0
	v_fma_f32 v28, v28, -2.0, 1.0
	v_add_f32_e32 v28, 1.0, v28
	v_mul_f32_e32 v28, v29, v28
	v_cvt_pk_bf16_f32 v27, v27, v28
	v_lshl_add_u64 v[28:29], v[44:45], 0, v[128:129]
	global_store_dwordx4 v[28:29], v[24:27], off offset:256 sc1

.LBB0_853:
	s_andn2_b64 vcc, exec, s[42:43]
	s_cbranch_vccnz .LBB0_856
	v_or_b32_e32 v16, s91, v142
	s_and_b64 s[26:27], s[4:5], exec
	v_lshrrev_b32_e32 v17, 6, v16
	s_cselect_b32 s31, 8, 10
	v_cndmask_b32_e64 v18, v32, v33, s[4:5]
	v_lshl_add_u32 v18, v17, s31, v18
	v_ashrrev_i32_e32 v19, 31, v18
	s_cselect_b32 s27, s47, s69
	s_cselect_b32 s26, s46, s2
	v_lshlrev_b64 v[18:19], 7, v[18:19]
	v_lshl_add_u64 v[18:19], s[26:27], 0, v[18:19]
	v_lshlrev_b32_e32 v144, 1, v154
	v_lshl_add_u64 v[18:19], v[18:19], 0, v[144:145]
	s_andn2_b64 vcc, exec, s[4:5]
	v_cvt_pk_bf16_f32 v36, v12, v13
	v_cvt_pk_bf16_f32 v37, v14, v15
	v_cvt_pk_bf16_f32 v38, v8, v9
	v_cvt_pk_bf16_f32 v39, v10, v11
	global_store_dwordx4 v[18:19], v[36:39], off sc1
	s_cbranch_vccnz .LBB0_856
	s_or_b32 s26, s73, s70
	s_ashr_i32 s27, s26, 31
	s_lshl_b64 s[26:27], s[26:27], 19
	v_lshl_add_u64 v[18:19], v[20:21], 0, s[26:27]
	v_mov_b32_e32 v17, v145
	v_lshl_add_u64 v[16:17], v[16:17], 2, v[18:19]
	global_store_dwordx4 v[16:17], v[12:15], off nt
	global_store_dwordx4 v[16:17], v[8:11], off offset:16 nt

.LBB0_858:
	s_and_b64 vcc, exec, s[6:7]
	s_mov_b64 s[6:7], -1
	s_cbranch_vccnz .LBB0_913
	s_andn2_b64 vcc, exec, s[60:61]
	s_cbranch_vccnz .LBB0_865
	s_andn2_b64 vcc, exec, s[58:59]
	s_cbranch_vccnz .LBB0_862
	v_mul_f32_e32 v8, 0x3d372713, v4
	v_mul_f32_e32 v8, v4, v8
	v_fma_f32 v8, v4, v8, v4
	v_mul_f32_e32 v8, 0x3f4c422a, v8
	v_add_f32_e32 v8, v8, v8
	v_mul_f32_e32 v8, 0x3fb8aa3b, v8
	v_exp_f32_e32 v8, v8
	v_mul_f32_e32 v9, 0.5, v4
	v_mul_f32_e32 v10, 0.5, v5
	v_mul_f32_e32 v11, 0.5, v7
	v_add_f32_e32 v8, 1.0, v8
	v_rcp_f32_e32 v8, v8
	v_mul_f32_e32 v12, 0.5, v1
	v_mul_f32_e32 v13, 0.5, v3
	v_mov_b32_e32 v129, v145
	v_fma_f32 v8, v8, -2.0, 1.0
	v_add_f32_e32 v8, 1.0, v8
	v_mul_f32_e32 v8, v9, v8
	v_mul_f32_e32 v9, 0x3d372713, v5
	v_mul_f32_e32 v9, v5, v9
	v_fma_f32 v9, v5, v9, v5
	v_mul_f32_e32 v9, 0x3f4c422a, v9
	v_add_f32_e32 v9, v9, v9
	v_mul_f32_e32 v9, 0x3fb8aa3b, v9
	v_exp_f32_e32 v9, v9
	s_mov_b64 s[6:7], 0
	v_add_f32_e32 v9, 1.0, v9
	v_rcp_f32_e32 v9, v9
	s_nop 0
	v_fma_f32 v9, v9, -2.0, 1.0
	v_add_f32_e32 v9, 1.0, v9
	v_mul_f32_e32 v9, v10, v9
	v_cvt_pk_bf16_f32 v8, v8, v9
	v_mul_f32_e32 v9, 0x3d372713, v6
	v_mul_f32_e32 v9, v6, v9
	v_fma_f32 v9, v6, v9, v6
	v_mul_f32_e32 v9, 0x3f4c422a, v9
	v_add_f32_e32 v9, v9, v9
	v_mul_f32_e32 v9, 0x3fb8aa3b, v9
	v_exp_f32_e32 v9, v9
	v_mul_f32_e32 v10, 0.5, v6
	v_add_f32_e32 v9, 1.0, v9
	v_rcp_f32_e32 v9, v9
	s_nop 0
	v_fma_f32 v9, v9, -2.0, 1.0
	v_add_f32_e32 v9, 1.0, v9
	v_mul_f32_e32 v9, v10, v9
	v_mul_f32_e32 v10, 0x3d372713, v7
	v_mul_f32_e32 v10, v7, v10
	v_fma_f32 v10, v7, v10, v7
	v_mul_f32_e32 v10, 0x3f4c422a, v10
	v_add_f32_e32 v10, v10, v10
	v_mul_f32_e32 v10, 0x3fb8aa3b, v10
	v_exp_f32_e32 v10, v10
	s_nop 0
	v_add_f32_e32 v10, 1.0, v10
	v_rcp_f32_e32 v10, v10
	s_nop 0
	v_fma_f32 v10, v10, -2.0, 1.0
	v_add_f32_e32 v10, 1.0, v10
	v_mul_f32_e32 v10, v11, v10
	v_cvt_pk_bf16_f32 v9, v9, v10
	v_mul_f32_e32 v10, 0x3d372713, v0
	v_mul_f32_e32 v10, v0, v10
	v_fma_f32 v10, v0, v10, v0
	v_mul_f32_e32 v10, 0x3f4c422a, v10
	v_add_f32_e32 v10, v10, v10
	v_mul_f32_e32 v10, 0x3fb8aa3b, v10
	v_exp_f32_e32 v10, v10
	v_mul_f32_e32 v11, 0.5, v0
	v_add_f32_e32 v10, 1.0, v10
	v_rcp_f32_e32 v10, v10
	s_nop 0
	v_fma_f32 v10, v10, -2.0, 1.0
	v_add_f32_e32 v10, 1.0, v10
	v_mul_f32_e32 v10, v11, v10
	v_mul_f32_e32 v11, 0x3d372713, v1
	v_mul_f32_e32 v11, v1, v11
	v_fma_f32 v11, v1, v11, v1
	v_mul_f32_e32 v11, 0x3f4c422a, v11
	v_add_f32_e32 v11, v11, v11
	v_mul_f32_e32 v11, 0x3fb8aa3b, v11
	v_exp_f32_e32 v11, v11
	s_nop 0
	v_add_f32_e32 v11, 1.0, v11
	v_rcp_f32_e32 v11, v11
	s_nop 0
	v_fma_f32 v11, v11, -2.0, 1.0
	v_add_f32_e32 v11, 1.0, v11
	v_mul_f32_e32 v11, v12, v11
	v_cvt_pk_bf16_f32 v10, v10, v11
	v_mul_f32_e32 v11, 0x3d372713, v2
	v_mul_f32_e32 v11, v2, v11
	v_fma_f32 v11, v2, v11, v2
	v_mul_f32_e32 v11, 0x3f4c422a, v11
	v_add_f32_e32 v11, v11, v11
	v_mul_f32_e32 v11, 0x3fb8aa3b, v11
	v_exp_f32_e32 v11, v11
	v_mul_f32_e32 v12, 0.5, v2
	v_add_f32_e32 v11, 1.0, v11
	v_rcp_f32_e32 v11, v11
	s_nop 0
	v_fma_f32 v11, v11, -2.0, 1.0
	v_add_f32_e32 v11, 1.0, v11
	v_mul_f32_e32 v11, v12, v11
	v_mul_f32_e32 v12, 0x3d372713, v3
	v_mul_f32_e32 v12, v3, v12
	v_fma_f32 v12, v3, v12, v3
	v_mul_f32_e32 v12, 0x3f4c422a, v12
	v_add_f32_e32 v12, v12, v12
	v_mul_f32_e32 v12, 0x3fb8aa3b, v12
	v_exp_f32_e32 v12, v12
	s_nop 0
	v_add_f32_e32 v12, 1.0, v12
	v_rcp_f32_e32 v12, v12
	s_nop 0
	v_fma_f32 v12, v12, -2.0, 1.0
	v_add_f32_e32 v12, 1.0, v12
	v_mul_f32_e32 v12, v13, v12
	v_cvt_pk_bf16_f32 v11, v11, v12
	v_lshl_add_u64 v[12:13], v[28:29], 0, v[128:129]
	global_store_dwordx4 v[12:13], v[8:11], off offset:256 sc1

.LBB0_871:
	s_andn2_b64 vcc, exec, s[42:43]
	s_cbranch_vccnz .LBB0_874
	v_or_b32_e32 v108, s91, v143
	s_and_b64 s[42:43], s[4:5], exec
	v_lshrrev_b32_e32 v108, 6, v108
	s_cselect_b32 s27, 8, 10
	v_cndmask_b32_e64 v109, v130, v131, s[4:5]
	v_lshl_add_u32 v108, v108, s27, v109
	v_ashrrev_i32_e32 v109, 31, v108
	s_cselect_b32 s43, s47, s69
	s_cselect_b32 s42, s46, s2
	v_lshlrev_b64 v[108:109], 7, v[108:109]
	v_lshl_add_u64 v[108:109], s[42:43], 0, v[108:109]
	v_lshlrev_b32_e32 v144, 1, v154
	v_lshl_add_u64 v[108:109], v[108:109], 0, v[144:145]
	s_andn2_b64 vcc, exec, s[4:5]
	v_cvt_pk_bf16_f32 v104, v100, v101
	v_cvt_pk_bf16_f32 v105, v102, v103
	v_cvt_pk_bf16_f32 v106, v96, v97
	v_cvt_pk_bf16_f32 v107, v98, v99
	global_store_dwordx4 v[108:109], v[104:107], off sc1
	s_cbranch_vccnz .LBB0_874
	s_or_b32 s42, s73, s70
	s_ashr_i32 s43, s42, 31
	s_lshl_b64 s[42:43], s[42:43], 19
	v_lshl_add_u64 v[104:105], v[116:117], 0, s[42:43]
	v_add_u32_e32 v144, s91, v142
	v_lshl_add_u64 v[104:105], v[144:145], 2, v[104:105]
	global_store_dwordx4 v[104:105], v[100:103], off offset:512 nt
	global_store_dwordx4 v[104:105], v[96:99], off offset:528 nt

.LBB0_878:
	s_andn2_b64 vcc, exec, s[42:43]
	s_cbranch_vccnz .LBB0_881
	v_or_b32_e32 v92, s91, v143
	s_and_b64 s[42:43], s[4:5], exec
	v_lshrrev_b32_e32 v92, 6, v92
	s_cselect_b32 s27, 8, 10
	v_cndmask_b32_e64 v93, v112, v113, s[4:5]
	v_lshl_add_u32 v92, v92, s27, v93
	v_ashrrev_i32_e32 v93, 31, v92
	s_cselect_b32 s43, s47, s69
	s_cselect_b32 s42, s46, s2
	v_lshlrev_b64 v[92:93], 7, v[92:93]
	v_lshl_add_u64 v[92:93], s[42:43], 0, v[92:93]
	v_lshlrev_b32_e32 v144, 1, v154
	v_lshl_add_u64 v[92:93], v[92:93], 0, v[144:145]
	s_andn2_b64 vcc, exec, s[4:5]
	v_cvt_pk_bf16_f32 v88, v84, v85
	v_cvt_pk_bf16_f32 v89, v86, v87
	v_cvt_pk_bf16_f32 v90, v80, v81
	v_cvt_pk_bf16_f32 v91, v82, v83
	global_store_dwordx4 v[92:93], v[88:91], off sc1
	s_cbranch_vccnz .LBB0_881
	s_or_b32 s42, s73, s70
	s_ashr_i32 s43, s42, 31
	s_lshl_b64 s[42:43], s[42:43], 19
	v_lshl_add_u64 v[88:89], v[100:101], 0, s[42:43]
	v_add_u32_e32 v144, s91, v142
	v_lshl_add_u64 v[88:89], v[144:145], 2, v[88:89]
	global_store_dwordx4 v[88:89], v[84:87], off offset:512 nt
	global_store_dwordx4 v[88:89], v[80:83], off offset:528 nt

.LBB0_885:
	s_andn2_b64 vcc, exec, s[42:43]
	s_cbranch_vccnz .LBB0_888
	v_or_b32_e32 v76, s91, v143
	s_and_b64 s[26:27], s[4:5], exec
	v_lshrrev_b32_e32 v76, 6, v76
	s_cselect_b32 s30, 8, 10
	v_cndmask_b32_e64 v77, v96, v97, s[4:5]
	v_lshl_add_u32 v76, v76, s30, v77
	v_ashrrev_i32_e32 v77, 31, v76
	s_cselect_b32 s27, s47, s69
	s_cselect_b32 s26, s46, s2
	v_lshlrev_b64 v[76:77], 7, v[76:77]
	v_lshl_add_u64 v[76:77], s[26:27], 0, v[76:77]
	v_lshlrev_b32_e32 v144, 1, v154
	v_lshl_add_u64 v[76:77], v[76:77], 0, v[144:145]
	s_andn2_b64 vcc, exec, s[4:5]
	v_cvt_pk_bf16_f32 v72, v68, v69
	v_cvt_pk_bf16_f32 v73, v70, v71
	v_cvt_pk_bf16_f32 v74, v64, v65
	v_cvt_pk_bf16_f32 v75, v66, v67
	global_store_dwordx4 v[76:77], v[72:75], off sc1
	s_cbranch_vccnz .LBB0_888
	s_or_b32 s26, s73, s70
	s_ashr_i32 s27, s26, 31
	s_lshl_b64 s[26:27], s[26:27], 19
	v_lshl_add_u64 v[72:73], v[84:85], 0, s[26:27]
	v_add_u32_e32 v144, s91, v142
	v_lshl_add_u64 v[72:73], v[144:145], 2, v[72:73]
	global_store_dwordx4 v[72:73], v[68:71], off offset:512 nt
	global_store_dwordx4 v[72:73], v[64:67], off offset:528 nt

.LBB0_892:
	s_andn2_b64 vcc, exec, s[42:43]
	s_cbranch_vccnz .LBB0_895
	v_or_b32_e32 v60, s91, v143
	s_and_b64 s[42:43], s[4:5], exec
	v_lshrrev_b32_e32 v60, 6, v60
	s_cselect_b32 s38, 8, 10
	v_cndmask_b32_e64 v61, v80, v81, s[4:5]
	v_lshl_add_u32 v60, v60, s38, v61
	v_ashrrev_i32_e32 v61, 31, v60
	s_cselect_b32 s43, s47, s69
	s_cselect_b32 s42, s46, s2
	v_lshlrev_b64 v[60:61], 7, v[60:61]
	v_lshl_add_u64 v[60:61], s[42:43], 0, v[60:61]
	v_lshlrev_b32_e32 v144, 1, v154
	v_lshl_add_u64 v[60:61], v[60:61], 0, v[144:145]
	s_andn2_b64 vcc, exec, s[4:5]
	v_cvt_pk_bf16_f32 v56, v52, v53
	v_cvt_pk_bf16_f32 v57, v54, v55
	v_cvt_pk_bf16_f32 v58, v48, v49
	v_cvt_pk_bf16_f32 v59, v50, v51
	global_store_dwordx4 v[60:61], v[56:59], off sc1
	s_cbranch_vccnz .LBB0_895
	s_or_b32 s42, s73, s70
	s_ashr_i32 s43, s42, 31
	s_lshl_b64 s[42:43], s[42:43], 19
	v_lshl_add_u64 v[56:57], v[68:69], 0, s[42:43]
	v_add_u32_e32 v144, s91, v142
	v_lshl_add_u64 v[56:57], v[144:145], 2, v[56:57]
	global_store_dwordx4 v[56:57], v[52:55], off offset:512 nt
	global_store_dwordx4 v[56:57], v[48:51], off offset:528 nt

.LBB0_899:
	s_andn2_b64 vcc, exec, s[42:43]
	s_cbranch_vccnz .LBB0_902
	v_or_b32_e32 v44, s91, v143
	s_and_b64 s[42:43], s[4:5], exec
	v_lshrrev_b32_e32 v44, 6, v44
	s_cselect_b32 s38, 8, 10
	v_cndmask_b32_e64 v45, v64, v65, s[4:5]
	v_lshl_add_u32 v44, v44, s38, v45
	v_ashrrev_i32_e32 v45, 31, v44
	s_cselect_b32 s43, s47, s69
	s_cselect_b32 s42, s46, s2
	v_lshlrev_b64 v[44:45], 7, v[44:45]
	v_lshl_add_u64 v[44:45], s[42:43], 0, v[44:45]
	v_lshlrev_b32_e32 v144, 1, v154
	v_lshl_add_u64 v[44:45], v[44:45], 0, v[144:145]
	s_andn2_b64 vcc, exec, s[4:5]
	v_cvt_pk_bf16_f32 v40, v36, v37
	v_cvt_pk_bf16_f32 v41, v38, v39
	v_cvt_pk_bf16_f32 v42, v32, v33
	v_cvt_pk_bf16_f32 v43, v34, v35
	global_store_dwordx4 v[44:45], v[40:43], off sc1
	s_cbranch_vccnz .LBB0_902
	s_or_b32 s42, s73, s70
	s_ashr_i32 s43, s42, 31
	s_lshl_b64 s[42:43], s[42:43], 19
	v_lshl_add_u64 v[40:41], v[52:53], 0, s[42:43]
	v_add_u32_e32 v144, s91, v142
	v_lshl_add_u64 v[40:41], v[144:145], 2, v[40:41]
	global_store_dwordx4 v[40:41], v[36:39], off offset:512 nt
	global_store_dwordx4 v[40:41], v[32:35], off offset:528 nt

.LBB0_906:
	s_andn2_b64 vcc, exec, s[42:43]
	s_cbranch_vccnz .LBB0_909
	v_or_b32_e32 v28, s91, v143
	s_and_b64 s[42:43], s[4:5], exec
	v_lshrrev_b32_e32 v28, 6, v28
	s_cselect_b32 s38, 8, 10
	v_cndmask_b32_e64 v29, v48, v49, s[4:5]
	v_lshl_add_u32 v28, v28, s38, v29
	v_ashrrev_i32_e32 v29, 31, v28
	s_cselect_b32 s43, s47, s69
	s_cselect_b32 s42, s46, s2
	v_lshlrev_b64 v[28:29], 7, v[28:29]
	v_lshl_add_u64 v[28:29], s[42:43], 0, v[28:29]
	v_lshlrev_b32_e32 v144, 1, v154
	v_lshl_add_u64 v[28:29], v[28:29], 0, v[144:145]
	s_andn2_b64 vcc, exec, s[4:5]
	v_cvt_pk_bf16_f32 v24, v20, v21
	v_cvt_pk_bf16_f32 v25, v22, v23
	v_cvt_pk_bf16_f32 v26, v16, v17
	v_cvt_pk_bf16_f32 v27, v18, v19
	global_store_dwordx4 v[28:29], v[24:27], off sc1
	s_cbranch_vccnz .LBB0_909
	s_or_b32 s42, s73, s70
	s_ashr_i32 s43, s42, 31
	s_lshl_b64 s[42:43], s[42:43], 19
	v_lshl_add_u64 v[24:25], v[36:37], 0, s[42:43]
	v_add_u32_e32 v144, s91, v142
	v_lshl_add_u64 v[24:25], v[144:145], 2, v[24:25]
	global_store_dwordx4 v[24:25], v[20:23], off offset:512 nt
	global_store_dwordx4 v[24:25], v[16:19], off offset:528 nt

.LBB0_913:
	s_andn2_b64 vcc, exec, s[6:7]
	s_cbranch_vccnz .LBB0_916
	v_or_b32_e32 v12, s91, v143
	s_and_b64 s[6:7], s[4:5], exec
	v_lshrrev_b32_e32 v12, 6, v12
	s_cselect_b32 s8, 8, 10
	v_cndmask_b32_e64 v13, v32, v33, s[4:5]
	v_lshl_add_u32 v12, v12, s8, v13
	v_ashrrev_i32_e32 v13, 31, v12
	s_cselect_b32 s7, s47, s69
	s_cselect_b32 s6, s46, s2
	v_lshlrev_b64 v[12:13], 7, v[12:13]
	v_lshl_add_u64 v[12:13], s[6:7], 0, v[12:13]
	v_lshlrev_b32_e32 v144, 1, v154
	v_lshl_add_u64 v[12:13], v[12:13], 0, v[144:145]
	s_andn2_b64 vcc, exec, s[4:5]
	v_cvt_pk_bf16_f32 v8, v4, v5
	v_cvt_pk_bf16_f32 v9, v6, v7
	v_cvt_pk_bf16_f32 v10, v0, v1
	v_cvt_pk_bf16_f32 v11, v2, v3
	global_store_dwordx4 v[12:13], v[8:11], off sc1
	s_cbranch_vccnz .LBB0_916
	s_or_b32 s4, s73, s70
	s_ashr_i32 s5, s4, 31
	s_lshl_b64 s[4:5], s[4:5], 19
	v_lshl_add_u64 v[8:9], v[20:21], 0, s[4:5]
	v_add_u32_e32 v144, s91, v142
	v_lshl_add_u64 v[8:9], v[144:145], 2, v[8:9]
	global_store_dwordx4 v[8:9], v[4:7], off offset:512 nt
	global_store_dwordx4 v[8:9], v[0:3], off offset:528 nt

.LBB0_982:
	s_lshl_b32 s6, s22, 10
	s_lshl_b32 s7, s21, 8
	s_or_b32 s6, s7, s6
	v_add_u32_e32 v134, s6, v129
	v_add_u32_e32 v130, 0x1000, v134
	v_ashrrev_i32_e32 v131, 31, v130
	v_lshlrev_b64 v[130:131], 11, v[130:131]
	v_lshl_add_u64 v[130:131], s[4:5], 0, v[130:131]
	s_lshl_b32 s38, s27, 1
	v_mov_b32_e32 v129, v145
	v_lshl_add_u64 v[130:131], v[130:131], 0, s[38:39]
	v_lshl_add_u64 v[130:131], v[130:131], 0, v[128:129]
	s_mov_b32 s8, 0x4800000
	v_cvt_pk_bf16_f32 v124, v124, v125
	v_cvt_pk_bf16_f32 v125, v126, v127
	v_cvt_pk_bf16_f32 v126, v120, v121
	v_add_co_u32_e32 v120, vcc, s8, v130
	v_cvt_pk_bf16_f32 v127, v122, v123
	s_mov_b64 s[6:7], 0x4800400
	s_nop 0
	v_addc_co_u32_e32 v121, vcc, 0, v131, vcc
	global_store_dwordx4 v[120:121], v[124:127], off offset:1024 sc1
	v_cvt_pk_bf16_f32 v116, v116, v117
	v_cvt_pk_bf16_f32 v117, v118, v119
	v_cvt_pk_bf16_f32 v118, v108, v109
	v_add_u32_e32 v108, 0x1010, v134
	v_ashrrev_i32_e32 v109, 31, v108
	v_lshlrev_b64 v[108:109], 11, v[108:109]
	v_lshl_add_u64 v[108:109], s[4:5], 0, v[108:109]
	v_lshl_add_u64 v[132:133], v[130:131], 0, s[6:7]
	v_lshl_add_u64 v[108:109], v[108:109], 0, s[38:39]
	v_cvt_pk_bf16_f32 v119, v110, v111
	global_store_dwordx4 v[132:133], v[116:119], off offset:256 sc1
	s_nop 1
	v_lshl_add_u64 v[116:117], v[108:109], 0, v[128:129]
	v_cvt_pk_bf16_f32 v108, v112, v113
	v_cvt_pk_bf16_f32 v109, v114, v115
	v_cvt_pk_bf16_f32 v110, v104, v105
	v_add_co_u32_e32 v104, vcc, s8, v116
	v_cvt_pk_bf16_f32 v111, v106, v107
	v_lshl_add_u64 v[118:119], v[116:117], 0, s[6:7]
	s_nop 0
	v_addc_co_u32_e32 v105, vcc, 0, v117, vcc
	global_store_dwordx4 v[104:105], v[108:111], off offset:1024 sc1
	v_cvt_pk_bf16_f32 v100, v100, v101
	v_cvt_pk_bf16_f32 v101, v102, v103
	v_cvt_pk_bf16_f32 v102, v92, v93
	v_add_u32_e32 v92, 0x1020, v134
	v_ashrrev_i32_e32 v93, 31, v92
	v_lshlrev_b64 v[92:93], 11, v[92:93]
	v_lshl_add_u64 v[92:93], s[4:5], 0, v[92:93]
	v_lshl_add_u64 v[92:93], v[92:93], 0, s[38:39]
	v_cvt_pk_bf16_f32 v103, v94, v95
	global_store_dwordx4 v[118:119], v[100:103], off offset:256 sc1
	s_nop 1
	v_lshl_add_u64 v[100:101], v[92:93], 0, v[128:129]
	v_cvt_pk_bf16_f32 v92, v96, v97
	v_cvt_pk_bf16_f32 v93, v98, v99
	v_cvt_pk_bf16_f32 v94, v88, v89
	v_add_co_u32_e32 v88, vcc, s8, v100
	v_cvt_pk_bf16_f32 v95, v90, v91
	v_lshl_add_u64 v[102:103], v[100:101], 0, s[6:7]
	s_nop 0
	v_addc_co_u32_e32 v89, vcc, 0, v101, vcc
	global_store_dwordx4 v[88:89], v[92:95], off offset:1024 sc1
	v_cvt_pk_bf16_f32 v84, v84, v85
	v_cvt_pk_bf16_f32 v85, v86, v87
	v_cvt_pk_bf16_f32 v86, v76, v77
	v_add_u32_e32 v76, 0x1030, v134
	v_ashrrev_i32_e32 v77, 31, v76
	v_lshlrev_b64 v[76:77], 11, v[76:77]
	v_lshl_add_u64 v[76:77], s[4:5], 0, v[76:77]
	v_lshl_add_u64 v[76:77], v[76:77], 0, s[38:39]
	v_cvt_pk_bf16_f32 v87, v78, v79
	global_store_dwordx4 v[102:103], v[84:87], off offset:256 sc1
	s_nop 1
	v_lshl_add_u64 v[84:85], v[76:77], 0, v[128:129]
	v_cvt_pk_bf16_f32 v76, v80, v81
	v_cvt_pk_bf16_f32 v77, v82, v83
	v_cvt_pk_bf16_f32 v78, v72, v73
	v_add_co_u32_e32 v72, vcc, s8, v84
	v_lshl_add_u64 v[86:87], v[84:85], 0, s[6:7]
	s_nop 0
	v_addc_co_u32_e32 v73, vcc, 0, v85, vcc
	s_mov_b64 s[6:7], 0x4840400
	v_cvt_pk_bf16_f32 v79, v74, v75
	global_store_dwordx4 v[72:73], v[76:79], off offset:1024 sc1
	v_cvt_pk_bf16_f32 v68, v68, v69
	v_cvt_pk_bf16_f32 v69, v70, v71
	v_cvt_pk_bf16_f32 v70, v64, v65
	v_lshl_add_u64 v[64:65], v[130:131], 0, s[6:7]
	s_mov_b32 s6, 0x4840000
	v_cvt_pk_bf16_f32 v71, v66, v67
	global_store_dwordx4 v[86:87], v[68:71], off offset:256 sc1
	v_cvt_pk_bf16_f32 v60, v60, v61
	v_cvt_pk_bf16_f32 v61, v62, v63
	v_cvt_pk_bf16_f32 v62, v56, v57
	v_add_co_u32_e32 v56, vcc, s6, v130
	v_cvt_pk_bf16_f32 v63, v58, v59
	s_mov_b64 s[6:7], 0x4848400
	s_nop 0
	v_addc_co_u32_e32 v57, vcc, 0, v131, vcc
	global_store_dwordx4 v[56:57], v[60:63], off offset:1024 sc1
	v_cvt_pk_bf16_f32 v48, v48, v49
	v_cvt_pk_bf16_f32 v49, v50, v51
	v_cvt_pk_bf16_f32 v50, v40, v41
	v_cvt_pk_bf16_f32 v51, v42, v43
	global_store_dwordx4 v[64:65], v[48:51], off offset:256 sc1
	v_cvt_pk_bf16_f32 v40, v52, v53
	v_cvt_pk_bf16_f32 v41, v54, v55
	v_cvt_pk_bf16_f32 v42, v44, v45
	v_cvt_pk_bf16_f32 v43, v46, v47
	s_nop 1
	v_lshl_add_u64 v[48:49], v[130:131], 0, s[6:7]
	s_mov_b32 s6, 0x4848000
	v_add_co_u32_e32 v44, vcc, s6, v130
	s_mov_b64 s[6:7], 0x4850400
	s_nop 0
	v_addc_co_u32_e32 v45, vcc, 0, v131, vcc
	global_store_dwordx4 v[44:45], v[40:43], off offset:1024 sc1
	v_cvt_pk_bf16_f32 v32, v32, v33
	v_cvt_pk_bf16_f32 v33, v34, v35
	v_cvt_pk_bf16_f32 v34, v24, v25
	v_cvt_pk_bf16_f32 v35, v26, v27
	global_store_dwordx4 v[48:49], v[32:35], off offset:256 sc1
	v_cvt_pk_bf16_f32 v24, v36, v37
	v_cvt_pk_bf16_f32 v25, v38, v39
	v_cvt_pk_bf16_f32 v26, v28, v29
	v_cvt_pk_bf16_f32 v27, v30, v31
	s_nop 1
	v_lshl_add_u64 v[32:33], v[130:131], 0, s[6:7]
	s_mov_b32 s6, 0x4850000
	v_add_co_u32_e32 v28, vcc, s6, v130
	s_mov_b64 s[6:7], 0x4858400
	s_nop 0
	v_addc_co_u32_e32 v29, vcc, 0, v131, vcc
	global_store_dwordx4 v[28:29], v[24:27], off offset:1024 sc1
	v_cvt_pk_bf16_f32 v16, v16, v17
	v_cvt_pk_bf16_f32 v17, v18, v19
	v_cvt_pk_bf16_f32 v18, v8, v9
	v_cvt_pk_bf16_f32 v19, v10, v11
	global_store_dwordx4 v[32:33], v[16:19], off offset:256 sc1
	v_cvt_pk_bf16_f32 v8, v20, v21
	v_cvt_pk_bf16_f32 v9, v22, v23
	v_cvt_pk_bf16_f32 v10, v12, v13
	v_cvt_pk_bf16_f32 v11, v14, v15
	s_nop 1
	v_lshl_add_u64 v[16:17], v[130:131], 0, s[6:7]
	s_mov_b32 s6, 0x4858000
	v_add_co_u32_e32 v12, vcc, s6, v130
	s_nop 1
	v_addc_co_u32_e32 v13, vcc, 0, v131, vcc
	global_store_dwordx4 v[12:13], v[8:11], off offset:1024 sc1
	v_cvt_pk_bf16_f32 v4, v4, v5
	v_cvt_pk_bf16_f32 v5, v6, v7
	v_cvt_pk_bf16_f32 v6, v0, v1
	v_cvt_pk_bf16_f32 v7, v2, v3
	global_store_dwordx4 v[16:17], v[4:7], off offset:256 sc1
	s_waitcnt vmcnt(0)
	s_barrier

.LBB0_990:
	v_lshl_add_u32 v132, s38, 8, v129
	v_ashrrev_i32_e32 v133, 31, v132
	v_lshlrev_b64 v[130:131], 11, v[132:133]
	v_lshl_add_u64 v[130:131], s[6:7], 0, v[130:131]
	s_lshl_b32 s38, s27, 1
	v_mov_b32_e32 v129, v145
	v_lshl_add_u64 v[130:131], v[130:131], 0, s[38:39]
	v_lshl_add_u64 v[130:131], v[130:131], 0, v[128:129]
	s_mov_b32 s10, 0x4800000
	v_cvt_pk_bf16_f32 v124, v124, v125
	v_cvt_pk_bf16_f32 v125, v126, v127
	v_cvt_pk_bf16_f32 v126, v120, v121
	v_add_co_u32_e32 v120, vcc, s10, v130
	v_cvt_pk_bf16_f32 v127, v122, v123
	s_mov_b64 s[8:9], 0x4800400
	s_nop 0
	v_addc_co_u32_e32 v121, vcc, 0, v131, vcc
	global_store_dwordx4 v[120:121], v[124:127], off offset:1024 sc1
	v_cvt_pk_bf16_f32 v116, v116, v117
	v_cvt_pk_bf16_f32 v117, v118, v119
	v_cvt_pk_bf16_f32 v118, v108, v109
	v_or_b32_e32 v108, 16, v132
	v_ashrrev_i32_e32 v109, 31, v108
	v_lshlrev_b64 v[108:109], 11, v[108:109]
	v_lshl_add_u64 v[108:109], s[6:7], 0, v[108:109]
	v_lshl_add_u64 v[134:135], v[130:131], 0, s[8:9]
	v_lshl_add_u64 v[108:109], v[108:109], 0, s[38:39]
	v_cvt_pk_bf16_f32 v119, v110, v111
	global_store_dwordx4 v[134:135], v[116:119], off offset:256 sc1
	s_nop 1
	v_lshl_add_u64 v[116:117], v[108:109], 0, v[128:129]
	v_cvt_pk_bf16_f32 v108, v112, v113
	v_cvt_pk_bf16_f32 v109, v114, v115
	v_cvt_pk_bf16_f32 v110, v104, v105
	v_add_co_u32_e32 v104, vcc, s10, v116
	v_cvt_pk_bf16_f32 v111, v106, v107
	v_lshl_add_u64 v[118:119], v[116:117], 0, s[8:9]
	s_nop 0
	v_addc_co_u32_e32 v105, vcc, 0, v117, vcc
	global_store_dwordx4 v[104:105], v[108:111], off offset:1024 sc1
	v_cvt_pk_bf16_f32 v100, v100, v101
	v_cvt_pk_bf16_f32 v101, v102, v103
	v_cvt_pk_bf16_f32 v102, v92, v93
	v_or_b32_e32 v92, 32, v132
	v_ashrrev_i32_e32 v93, 31, v92
	v_lshlrev_b64 v[92:93], 11, v[92:93]
	v_lshl_add_u64 v[92:93], s[6:7], 0, v[92:93]
	v_lshl_add_u64 v[92:93], v[92:93], 0, s[38:39]
	v_cvt_pk_bf16_f32 v103, v94, v95
	global_store_dwordx4 v[118:119], v[100:103], off offset:256 sc1
	s_nop 1
	v_lshl_add_u64 v[100:101], v[92:93], 0, v[128:129]
	v_cvt_pk_bf16_f32 v92, v96, v97
	v_cvt_pk_bf16_f32 v93, v98, v99
	v_cvt_pk_bf16_f32 v94, v88, v89
	v_add_co_u32_e32 v88, vcc, s10, v100
	v_cvt_pk_bf16_f32 v95, v90, v91
	v_lshl_add_u64 v[102:103], v[100:101], 0, s[8:9]
	s_nop 0
	v_addc_co_u32_e32 v89, vcc, 0, v101, vcc
	global_store_dwordx4 v[88:89], v[92:95], off offset:1024 sc1
	v_cvt_pk_bf16_f32 v84, v84, v85
	v_cvt_pk_bf16_f32 v85, v86, v87
	v_cvt_pk_bf16_f32 v86, v76, v77
	v_or_b32_e32 v76, 48, v132
	v_ashrrev_i32_e32 v77, 31, v76
	v_lshlrev_b64 v[76:77], 11, v[76:77]
	v_lshl_add_u64 v[76:77], s[6:7], 0, v[76:77]
	v_lshl_add_u64 v[76:77], v[76:77], 0, s[38:39]
	v_cvt_pk_bf16_f32 v87, v78, v79
	global_store_dwordx4 v[102:103], v[84:87], off offset:256 sc1
	s_mov_b64 s[6:7], 0x4840400
	s_nop 0
	v_lshl_add_u64 v[84:85], v[76:77], 0, v[128:129]
	v_cvt_pk_bf16_f32 v76, v80, v81
	v_cvt_pk_bf16_f32 v77, v82, v83
	v_cvt_pk_bf16_f32 v78, v72, v73
	v_add_co_u32_e32 v72, vcc, s10, v84
	v_lshl_add_u64 v[86:87], v[84:85], 0, s[8:9]
	s_nop 0
	v_addc_co_u32_e32 v73, vcc, 0, v85, vcc
	v_cvt_pk_bf16_f32 v79, v74, v75
	global_store_dwordx4 v[72:73], v[76:79], off offset:1024 sc1
	v_cvt_pk_bf16_f32 v68, v68, v69
	v_cvt_pk_bf16_f32 v69, v70, v71
	v_cvt_pk_bf16_f32 v70, v64, v65
	v_lshl_add_u64 v[64:65], v[130:131], 0, s[6:7]
	s_mov_b32 s6, 0x4840000
	v_cvt_pk_bf16_f32 v71, v66, v67
	global_store_dwordx4 v[86:87], v[68:71], off offset:256 sc1
	v_cvt_pk_bf16_f32 v60, v60, v61
	v_cvt_pk_bf16_f32 v61, v62, v63
	v_cvt_pk_bf16_f32 v62, v56, v57
	v_add_co_u32_e32 v56, vcc, s6, v130
	v_cvt_pk_bf16_f32 v63, v58, v59
	s_mov_b64 s[6:7], 0x4848400
	s_nop 0
	v_addc_co_u32_e32 v57, vcc, 0, v131, vcc
	global_store_dwordx4 v[56:57], v[60:63], off offset:1024 sc1
	v_cvt_pk_bf16_f32 v48, v48, v49
	v_cvt_pk_bf16_f32 v49, v50, v51
	v_cvt_pk_bf16_f32 v50, v40, v41
	v_cvt_pk_bf16_f32 v51, v42, v43
	global_store_dwordx4 v[64:65], v[48:51], off offset:256 sc1
	v_cvt_pk_bf16_f32 v40, v52, v53
	v_cvt_pk_bf16_f32 v41, v54, v55
	v_cvt_pk_bf16_f32 v42, v44, v45
	v_cvt_pk_bf16_f32 v43, v46, v47
	s_nop 1
	v_lshl_add_u64 v[48:49], v[130:131], 0, s[6:7]
	s_mov_b32 s6, 0x4848000
	v_add_co_u32_e32 v44, vcc, s6, v130
	s_mov_b64 s[6:7], 0x4850400
	s_nop 0
	v_addc_co_u32_e32 v45, vcc, 0, v131, vcc
	global_store_dwordx4 v[44:45], v[40:43], off offset:1024 sc1
	v_cvt_pk_bf16_f32 v32, v32, v33
	v_cvt_pk_bf16_f32 v33, v34, v35
	v_cvt_pk_bf16_f32 v34, v24, v25
	v_cvt_pk_bf16_f32 v35, v26, v27
	global_store_dwordx4 v[48:49], v[32:35], off offset:256 sc1
	v_cvt_pk_bf16_f32 v24, v36, v37
	v_cvt_pk_bf16_f32 v25, v38, v39
	v_cvt_pk_bf16_f32 v26, v28, v29
	v_cvt_pk_bf16_f32 v27, v30, v31
	s_nop 1
	v_lshl_add_u64 v[32:33], v[130:131], 0, s[6:7]
	s_mov_b32 s6, 0x4850000
	v_add_co_u32_e32 v28, vcc, s6, v130
	s_mov_b64 s[6:7], 0x4858400
	s_nop 0
	v_addc_co_u32_e32 v29, vcc, 0, v131, vcc
	global_store_dwordx4 v[28:29], v[24:27], off offset:1024 sc1
	v_cvt_pk_bf16_f32 v16, v16, v17
	v_cvt_pk_bf16_f32 v17, v18, v19
	v_cvt_pk_bf16_f32 v18, v8, v9
	v_cvt_pk_bf16_f32 v19, v10, v11
	global_store_dwordx4 v[32:33], v[16:19], off offset:256 sc1
	v_cvt_pk_bf16_f32 v8, v20, v21
	v_cvt_pk_bf16_f32 v9, v22, v23
	v_cvt_pk_bf16_f32 v10, v12, v13
	v_cvt_pk_bf16_f32 v11, v14, v15
	s_nop 1
	v_lshl_add_u64 v[16:17], v[130:131], 0, s[6:7]
	s_mov_b32 s6, 0x4858000
	v_add_co_u32_e32 v12, vcc, s6, v130
	s_nop 1
	v_addc_co_u32_e32 v13, vcc, 0, v131, vcc
	global_store_dwordx4 v[12:13], v[8:11], off offset:1024 sc1
	v_cvt_pk_bf16_f32 v4, v4, v5
	v_cvt_pk_bf16_f32 v5, v6, v7
	v_cvt_pk_bf16_f32 v6, v0, v1
	v_cvt_pk_bf16_f32 v7, v2, v3
	global_store_dwordx4 v[16:17], v[4:7], off offset:256 sc1
	s_waitcnt vmcnt(0)
	s_barrier

.LBB0_1000:
	v_mul_f32_e32 v135, 0x3d372713, v124
	v_mul_f32_e32 v135, v124, v135
	v_fma_f32 v135, v124, v135, v124
	v_mul_f32_e32 v135, 0x3f4c422a, v135
	v_add_f32_e32 v135, v135, v135
	v_mul_f32_e32 v135, 0x3fb8aa3b, v135
	v_exp_f32_e32 v135, v135
	v_mul_f32_e32 v124, 0.5, v124
	s_lshl_b32 s6, s20, 9
	s_add_u32 s4, s4, s6
	v_add_f32_e32 v135, 1.0, v135
	v_rcp_f32_e32 v135, v135
	s_addc_u32 s5, s5, 0
	s_add_u32 s4, s4, 0x3fff000
	s_addc_u32 s5, s5, 0
	v_fma_f32 v135, v135, -2.0, 1.0
	v_add_f32_e32 v135, 1.0, v135
	v_mul_f32_e32 v124, v124, v135
	v_mul_f32_e32 v135, 0x3d372713, v125
	v_mul_f32_e32 v135, v125, v135
	v_fma_f32 v135, v125, v135, v125
	v_mul_f32_e32 v135, 0x3f4c422a, v135
	v_add_f32_e32 v135, v135, v135
	v_mul_f32_e32 v135, 0x3fb8aa3b, v135
	v_exp_f32_e32 v135, v135
	v_mul_f32_e32 v125, 0.5, v125
	s_lshl_b32 s6, s38, 8
	s_add_i32 s6, s24, s6
	v_add_f32_e32 v135, 1.0, v135
	v_rcp_f32_e32 v135, v135
	v_or_b32_e32 v130, s6, v140
	v_ashrrev_i32_e32 v131, 31, v130
	v_or_b32_e32 v134, s26, v129
	v_fma_f32 v135, v135, -2.0, 1.0
	v_add_f32_e32 v135, 1.0, v135
	v_mul_f32_e32 v125, v125, v135
	v_cvt_pk_bf16_f32 v124, v124, v125
	v_mul_f32_e32 v125, 0x3d372713, v126
	v_mul_f32_e32 v125, v126, v125
	v_fma_f32 v125, v126, v125, v126
	v_mul_f32_e32 v125, 0x3f4c422a, v125
	v_add_f32_e32 v125, v125, v125
	v_mul_f32_e32 v125, 0x3fb8aa3b, v125
	v_exp_f32_e32 v125, v125
	v_mul_f32_e32 v126, 0.5, v126
	v_lshlrev_b64 v[130:131], 10, v[130:131]
	v_lshl_add_u64 v[130:131], s[4:5], 0, v[130:131]
	v_add_f32_e32 v125, 1.0, v125
	v_rcp_f32_e32 v125, v125
	v_lshlrev_b32_e32 v144, 1, v134
	v_or_b32_e32 v133, 16, v140
	v_or_b32_e32 v132, 32, v140
	v_fma_f32 v125, v125, -2.0, 1.0
	v_add_f32_e32 v125, 1.0, v125
	v_mul_f32_e32 v125, v126, v125
	v_mul_f32_e32 v126, 0x3d372713, v127
	v_mul_f32_e32 v126, v127, v126
	v_fma_f32 v126, v127, v126, v127
	v_mul_f32_e32 v126, 0x3f4c422a, v126
	v_add_f32_e32 v126, v126, v126
	v_mul_f32_e32 v126, 0x3fb8aa3b, v126
	v_exp_f32_e32 v126, v126
	v_mul_f32_e32 v127, 0.5, v127
	v_or_b32_e32 v129, 48, v140
	v_add_f32_e32 v126, 1.0, v126
	v_rcp_f32_e32 v126, v126
	s_nop 0
	v_fma_f32 v126, v126, -2.0, 1.0
	v_add_f32_e32 v126, 1.0, v126
	v_mul_f32_e32 v126, v127, v126
	v_cvt_pk_bf16_f32 v125, v125, v126
	v_mul_f32_e32 v126, 0x3d372713, v120
	v_mul_f32_e32 v126, v120, v126
	v_fma_f32 v126, v120, v126, v120
	v_mul_f32_e32 v126, 0x3f4c422a, v126
	v_add_f32_e32 v126, v126, v126
	v_mul_f32_e32 v126, 0x3fb8aa3b, v126
	v_exp_f32_e32 v126, v126
	v_mul_f32_e32 v120, 0.5, v120
	v_add_f32_e32 v126, 1.0, v126
	v_rcp_f32_e32 v126, v126
	s_nop 0
	v_fma_f32 v126, v126, -2.0, 1.0
	v_add_f32_e32 v126, 1.0, v126
	v_mul_f32_e32 v120, v120, v126
	v_mul_f32_e32 v126, 0x3d372713, v121
	v_mul_f32_e32 v126, v121, v126
	v_fma_f32 v126, v121, v126, v121
	v_mul_f32_e32 v126, 0x3f4c422a, v126
	v_add_f32_e32 v126, v126, v126
	v_mul_f32_e32 v126, 0x3fb8aa3b, v126
	v_exp_f32_e32 v126, v126
	v_mul_f32_e32 v121, 0.5, v121
	v_add_f32_e32 v126, 1.0, v126
	v_rcp_f32_e32 v126, v126
	s_nop 0
	v_fma_f32 v126, v126, -2.0, 1.0
	v_add_f32_e32 v126, 1.0, v126
	v_mul_f32_e32 v121, v121, v126
	v_cvt_pk_bf16_f32 v126, v120, v121
	v_mul_f32_e32 v120, 0x3d372713, v122
	v_mul_f32_e32 v120, v122, v120
	v_fma_f32 v120, v122, v120, v122
	v_mul_f32_e32 v120, 0x3f4c422a, v120
	v_add_f32_e32 v120, v120, v120
	v_mul_f32_e32 v120, 0x3fb8aa3b, v120
	v_exp_f32_e32 v120, v120
	v_mul_f32_e32 v121, 0.5, v122
	v_mul_f32_e32 v122, 0.5, v123
	v_add_f32_e32 v120, 1.0, v120
	v_rcp_f32_e32 v120, v120
	s_nop 0
	v_fma_f32 v120, v120, -2.0, 1.0
	v_add_f32_e32 v120, 1.0, v120
	v_mul_f32_e32 v120, v121, v120
	v_mul_f32_e32 v121, 0x3d372713, v123
	v_mul_f32_e32 v121, v123, v121
	v_fma_f32 v121, v123, v121, v123
	v_mul_f32_e32 v121, 0x3f4c422a, v121
	v_add_f32_e32 v121, v121, v121
	v_mul_f32_e32 v121, 0x3fb8aa3b, v121
	v_exp_f32_e32 v121, v121
	s_nop 0
	v_add_f32_e32 v121, 1.0, v121
	v_rcp_f32_e32 v121, v121
	s_nop 0
	v_fma_f32 v121, v121, -2.0, 1.0
	v_add_f32_e32 v121, 1.0, v121
	v_mul_f32_e32 v121, v122, v121
	v_mul_f32_e32 v122, 0x3d372713, v116
	v_mul_f32_e32 v122, v116, v122
	v_fma_f32 v122, v116, v122, v116
	v_mul_f32_e32 v122, 0x3f4c422a, v122
	v_add_f32_e32 v122, v122, v122
	v_mul_f32_e32 v122, 0x3fb8aa3b, v122
	v_exp_f32_e32 v122, v122
	v_mul_f32_e32 v116, 0.5, v116
	v_cvt_pk_bf16_f32 v127, v120, v121
	v_lshl_add_u64 v[120:121], v[130:131], 0, v[144:145]
	v_add_f32_e32 v122, 1.0, v122
	v_rcp_f32_e32 v122, v122
	global_store_dwordx4 v[120:121], v[124:127], off sc1
	v_fma_f32 v122, v122, -2.0, 1.0
	v_add_f32_e32 v122, 1.0, v122
	v_mul_f32_e32 v116, v116, v122
	v_mul_f32_e32 v122, 0x3d372713, v117
	v_mul_f32_e32 v122, v117, v122
	v_fma_f32 v122, v117, v122, v117
	v_mul_f32_e32 v122, 0x3f4c422a, v122
	v_add_f32_e32 v122, v122, v122
	v_mul_f32_e32 v122, 0x3fb8aa3b, v122
	v_exp_f32_e32 v122, v122
	v_mul_f32_e32 v117, 0.5, v117
	v_add_f32_e32 v122, 1.0, v122
	v_rcp_f32_e32 v122, v122
	s_nop 0
	v_fma_f32 v122, v122, -2.0, 1.0
	v_add_f32_e32 v122, 1.0, v122
	v_mul_f32_e32 v117, v117, v122
	v_cvt_pk_bf16_f32 v116, v116, v117
	v_mul_f32_e32 v117, 0x3d372713, v118
	v_mul_f32_e32 v117, v118, v117
	v_fma_f32 v117, v118, v117, v118
	v_mul_f32_e32 v117, 0x3f4c422a, v117
	v_add_f32_e32 v117, v117, v117
	v_mul_f32_e32 v117, 0x3fb8aa3b, v117
	v_exp_f32_e32 v117, v117
	v_mul_f32_e32 v118, 0.5, v118
	v_add_f32_e32 v117, 1.0, v117
	v_rcp_f32_e32 v117, v117
	s_nop 0
	v_fma_f32 v117, v117, -2.0, 1.0
	v_add_f32_e32 v117, 1.0, v117
	v_mul_f32_e32 v117, v118, v117
	v_mul_f32_e32 v118, 0x3d372713, v119
	v_mul_f32_e32 v118, v119, v118
	v_fma_f32 v118, v119, v118, v119
	v_mul_f32_e32 v118, 0x3f4c422a, v118
	v_add_f32_e32 v118, v118, v118
	v_mul_f32_e32 v118, 0x3fb8aa3b, v118
	v_exp_f32_e32 v118, v118
	v_mul_f32_e32 v119, 0.5, v119
	v_add_f32_e32 v118, 1.0, v118
	v_rcp_f32_e32 v118, v118
	s_nop 0
	v_fma_f32 v118, v118, -2.0, 1.0
	v_add_f32_e32 v118, 1.0, v118
	v_mul_f32_e32 v118, v119, v118
	v_cvt_pk_bf16_f32 v117, v117, v118
	v_mul_f32_e32 v118, 0x3d372713, v112
	v_mul_f32_e32 v118, v112, v118
	v_fma_f32 v118, v112, v118, v112
	v_mul_f32_e32 v118, 0x3f4c422a, v118
	v_add_f32_e32 v118, v118, v118
	v_mul_f32_e32 v118, 0x3fb8aa3b, v118
	v_exp_f32_e32 v118, v118
	v_mul_f32_e32 v112, 0.5, v112
	v_add_f32_e32 v118, 1.0, v118
	v_rcp_f32_e32 v118, v118
	s_nop 0
	v_fma_f32 v118, v118, -2.0, 1.0
	v_add_f32_e32 v118, 1.0, v118
	v_mul_f32_e32 v112, v112, v118
	v_mul_f32_e32 v118, 0x3d372713, v113
	v_mul_f32_e32 v118, v113, v118
	v_fma_f32 v118, v113, v118, v113
	v_mul_f32_e32 v118, 0x3f4c422a, v118
	v_add_f32_e32 v118, v118, v118
	v_mul_f32_e32 v118, 0x3fb8aa3b, v118
	v_exp_f32_e32 v118, v118
	v_mul_f32_e32 v113, 0.5, v113
	v_add_f32_e32 v118, 1.0, v118
	v_rcp_f32_e32 v118, v118
	s_nop 0
	v_fma_f32 v118, v118, -2.0, 1.0
	v_add_f32_e32 v118, 1.0, v118
	v_mul_f32_e32 v113, v113, v118
	v_cvt_pk_bf16_f32 v118, v112, v113
	v_mul_f32_e32 v112, 0x3d372713, v114
	v_mul_f32_e32 v112, v114, v112
	v_fma_f32 v112, v114, v112, v114
	v_mul_f32_e32 v112, 0x3f4c422a, v112
	v_add_f32_e32 v112, v112, v112
	v_mul_f32_e32 v112, 0x3fb8aa3b, v112
	v_exp_f32_e32 v112, v112
	v_mul_f32_e32 v113, 0.5, v114
	v_mul_f32_e32 v114, 0.5, v115
	v_add_f32_e32 v112, 1.0, v112
	v_rcp_f32_e32 v112, v112
	s_nop 0
	v_fma_f32 v112, v112, -2.0, 1.0
	v_add_f32_e32 v112, 1.0, v112
	v_mul_f32_e32 v112, v113, v112
	v_mul_f32_e32 v113, 0x3d372713, v115
	v_mul_f32_e32 v113, v115, v113
	v_fma_f32 v113, v115, v113, v115
	v_mul_f32_e32 v113, 0x3f4c422a, v113
	v_add_f32_e32 v113, v113, v113
	v_mul_f32_e32 v113, 0x3fb8aa3b, v113
	v_exp_f32_e32 v113, v113
	s_nop 0
	v_add_f32_e32 v113, 1.0, v113
	v_rcp_f32_e32 v113, v113
	s_nop 0
	v_fma_f32 v113, v113, -2.0, 1.0
	v_add_f32_e32 v113, 1.0, v113
	v_mul_f32_e32 v113, v114, v113
	v_mul_f32_e32 v114, 0x3d372713, v108
	v_mul_f32_e32 v114, v108, v114
	v_fma_f32 v114, v108, v114, v108
	v_mul_f32_e32 v114, 0x3f4c422a, v114
	v_add_f32_e32 v114, v114, v114
	v_mul_f32_e32 v114, 0x3fb8aa3b, v114
	v_exp_f32_e32 v114, v114
	v_mul_f32_e32 v108, 0.5, v108
	v_cvt_pk_bf16_f32 v119, v112, v113
	global_store_dwordx4 v[120:121], v[116:119], off offset:256 sc1
	v_add_f32_e32 v114, 1.0, v114
	v_rcp_f32_e32 v114, v114
	v_or_b32_e32 v112, s6, v133
	v_ashrrev_i32_e32 v113, 31, v112
	v_lshlrev_b64 v[112:113], 10, v[112:113]
	v_fma_f32 v114, v114, -2.0, 1.0
	v_add_f32_e32 v114, 1.0, v114
	v_mul_f32_e32 v108, v108, v114
	v_mul_f32_e32 v114, 0x3d372713, v109
	v_mul_f32_e32 v114, v109, v114
	v_fma_f32 v114, v109, v114, v109
	v_mul_f32_e32 v114, 0x3f4c422a, v114
	v_add_f32_e32 v114, v114, v114
	v_mul_f32_e32 v114, 0x3fb8aa3b, v114
	v_exp_f32_e32 v114, v114
	v_mul_f32_e32 v109, 0.5, v109
	v_lshl_add_u64 v[112:113], s[4:5], 0, v[112:113]
	v_add_f32_e32 v114, 1.0, v114
	v_rcp_f32_e32 v114, v114
	s_nop 0
	v_fma_f32 v114, v114, -2.0, 1.0
	v_add_f32_e32 v114, 1.0, v114
	v_mul_f32_e32 v109, v109, v114
	v_cvt_pk_bf16_f32 v108, v108, v109
	v_mul_f32_e32 v109, 0x3d372713, v110
	v_mul_f32_e32 v109, v110, v109
	v_fma_f32 v109, v110, v109, v110
	v_mul_f32_e32 v109, 0x3f4c422a, v109
	v_add_f32_e32 v109, v109, v109
	v_mul_f32_e32 v109, 0x3fb8aa3b, v109
	v_exp_f32_e32 v109, v109
	v_mul_f32_e32 v110, 0.5, v110
	v_add_f32_e32 v109, 1.0, v109
	v_rcp_f32_e32 v109, v109
	s_nop 0
	v_fma_f32 v109, v109, -2.0, 1.0
	v_add_f32_e32 v109, 1.0, v109
	v_mul_f32_e32 v109, v110, v109
	v_mul_f32_e32 v110, 0x3d372713, v111
	v_mul_f32_e32 v110, v111, v110
	v_fma_f32 v110, v111, v110, v111
	v_mul_f32_e32 v110, 0x3f4c422a, v110
	v_add_f32_e32 v110, v110, v110
	v_mul_f32_e32 v110, 0x3fb8aa3b, v110
	v_exp_f32_e32 v110, v110
	v_mul_f32_e32 v111, 0.5, v111
	v_add_f32_e32 v110, 1.0, v110
	v_rcp_f32_e32 v110, v110
	s_nop 0
	v_fma_f32 v110, v110, -2.0, 1.0
	v_add_f32_e32 v110, 1.0, v110
	v_mul_f32_e32 v110, v111, v110
	v_cvt_pk_bf16_f32 v109, v109, v110
	v_mul_f32_e32 v110, 0x3d372713, v104
	v_mul_f32_e32 v110, v104, v110
	v_fma_f32 v110, v104, v110, v104
	v_mul_f32_e32 v110, 0x3f4c422a, v110
	v_add_f32_e32 v110, v110, v110
	v_mul_f32_e32 v110, 0x3fb8aa3b, v110
	v_exp_f32_e32 v110, v110
	v_mul_f32_e32 v104, 0.5, v104
	v_add_f32_e32 v110, 1.0, v110
	v_rcp_f32_e32 v110, v110
	s_nop 0
	v_fma_f32 v110, v110, -2.0, 1.0
	v_add_f32_e32 v110, 1.0, v110
	v_mul_f32_e32 v104, v104, v110
	v_mul_f32_e32 v110, 0x3d372713, v105
	v_mul_f32_e32 v110, v105, v110
	v_fma_f32 v110, v105, v110, v105
	v_mul_f32_e32 v110, 0x3f4c422a, v110
	v_add_f32_e32 v110, v110, v110
	v_mul_f32_e32 v110, 0x3fb8aa3b, v110
	v_exp_f32_e32 v110, v110
	v_mul_f32_e32 v105, 0.5, v105
	v_add_f32_e32 v110, 1.0, v110
	v_rcp_f32_e32 v110, v110
	s_nop 0
	v_fma_f32 v110, v110, -2.0, 1.0
	v_add_f32_e32 v110, 1.0, v110
	v_mul_f32_e32 v105, v105, v110
	v_cvt_pk_bf16_f32 v110, v104, v105
	v_mul_f32_e32 v104, 0x3d372713, v106
	v_mul_f32_e32 v104, v106, v104
	v_fma_f32 v104, v106, v104, v106
	v_mul_f32_e32 v104, 0x3f4c422a, v104
	v_add_f32_e32 v104, v104, v104
	v_mul_f32_e32 v104, 0x3fb8aa3b, v104
	v_exp_f32_e32 v104, v104
	v_mul_f32_e32 v105, 0.5, v106
	v_mul_f32_e32 v106, 0.5, v107
	v_add_f32_e32 v104, 1.0, v104
	v_rcp_f32_e32 v104, v104
	s_nop 0
	v_fma_f32 v104, v104, -2.0, 1.0
	v_add_f32_e32 v104, 1.0, v104
	v_mul_f32_e32 v104, v105, v104
	v_mul_f32_e32 v105, 0x3d372713, v107
	v_mul_f32_e32 v105, v107, v105
	v_fma_f32 v105, v107, v105, v107
	v_mul_f32_e32 v105, 0x3f4c422a, v105
	v_add_f32_e32 v105, v105, v105
	v_mul_f32_e32 v105, 0x3fb8aa3b, v105
	v_exp_f32_e32 v105, v105
	s_nop 0
	v_add_f32_e32 v105, 1.0, v105
	v_rcp_f32_e32 v105, v105
	s_nop 0
	v_fma_f32 v105, v105, -2.0, 1.0
	v_add_f32_e32 v105, 1.0, v105
	v_mul_f32_e32 v105, v106, v105
	v_mul_f32_e32 v106, 0x3d372713, v100
	v_mul_f32_e32 v106, v100, v106
	v_fma_f32 v106, v100, v106, v100
	v_mul_f32_e32 v106, 0x3f4c422a, v106
	v_add_f32_e32 v106, v106, v106
	v_mul_f32_e32 v106, 0x3fb8aa3b, v106
	v_exp_f32_e32 v106, v106
	v_mul_f32_e32 v100, 0.5, v100
	v_cvt_pk_bf16_f32 v111, v104, v105
	v_lshl_add_u64 v[104:105], v[112:113], 0, v[144:145]
	v_add_f32_e32 v106, 1.0, v106
	v_rcp_f32_e32 v106, v106
	global_store_dwordx4 v[104:105], v[108:111], off sc1
	v_fma_f32 v106, v106, -2.0, 1.0
	v_add_f32_e32 v106, 1.0, v106
	v_mul_f32_e32 v100, v100, v106
	v_mul_f32_e32 v106, 0x3d372713, v101
	v_mul_f32_e32 v106, v101, v106
	v_fma_f32 v106, v101, v106, v101
	v_mul_f32_e32 v106, 0x3f4c422a, v106
	v_add_f32_e32 v106, v106, v106
	v_mul_f32_e32 v106, 0x3fb8aa3b, v106
	v_exp_f32_e32 v106, v106
	v_mul_f32_e32 v101, 0.5, v101
	v_add_f32_e32 v106, 1.0, v106
	v_rcp_f32_e32 v106, v106
	s_nop 0
	v_fma_f32 v106, v106, -2.0, 1.0
	v_add_f32_e32 v106, 1.0, v106
	v_mul_f32_e32 v101, v101, v106
	v_cvt_pk_bf16_f32 v100, v100, v101
	v_mul_f32_e32 v101, 0x3d372713, v102
	v_mul_f32_e32 v101, v102, v101
	v_fma_f32 v101, v102, v101, v102
	v_mul_f32_e32 v101, 0x3f4c422a, v101
	v_add_f32_e32 v101, v101, v101
	v_mul_f32_e32 v101, 0x3fb8aa3b, v101
	v_exp_f32_e32 v101, v101
	v_mul_f32_e32 v102, 0.5, v102
	v_add_f32_e32 v101, 1.0, v101
	v_rcp_f32_e32 v101, v101
	s_nop 0
	v_fma_f32 v101, v101, -2.0, 1.0
	v_add_f32_e32 v101, 1.0, v101
	v_mul_f32_e32 v101, v102, v101
	v_mul_f32_e32 v102, 0x3d372713, v103
	v_mul_f32_e32 v102, v103, v102
	v_fma_f32 v102, v103, v102, v103
	v_mul_f32_e32 v102, 0x3f4c422a, v102
	v_add_f32_e32 v102, v102, v102
	v_mul_f32_e32 v102, 0x3fb8aa3b, v102
	v_exp_f32_e32 v102, v102
	v_mul_f32_e32 v103, 0.5, v103
	v_add_f32_e32 v102, 1.0, v102
	v_rcp_f32_e32 v102, v102
	s_nop 0
	v_fma_f32 v102, v102, -2.0, 1.0
	v_add_f32_e32 v102, 1.0, v102
	v_mul_f32_e32 v102, v103, v102
	v_cvt_pk_bf16_f32 v101, v101, v102
	v_mul_f32_e32 v102, 0x3d372713, v96
	v_mul_f32_e32 v102, v96, v102
	v_fma_f32 v102, v96, v102, v96
	v_mul_f32_e32 v102, 0x3f4c422a, v102
	v_add_f32_e32 v102, v102, v102
	v_mul_f32_e32 v102, 0x3fb8aa3b, v102
	v_exp_f32_e32 v102, v102
	v_mul_f32_e32 v96, 0.5, v96
	v_add_f32_e32 v102, 1.0, v102
	v_rcp_f32_e32 v102, v102
	s_nop 0
	v_fma_f32 v102, v102, -2.0, 1.0
	v_add_f32_e32 v102, 1.0, v102
	v_mul_f32_e32 v96, v96, v102
	v_mul_f32_e32 v102, 0x3d372713, v97
	v_mul_f32_e32 v102, v97, v102
	v_fma_f32 v102, v97, v102, v97
	v_mul_f32_e32 v102, 0x3f4c422a, v102
	v_add_f32_e32 v102, v102, v102
	v_mul_f32_e32 v102, 0x3fb8aa3b, v102
	v_exp_f32_e32 v102, v102
	v_mul_f32_e32 v97, 0.5, v97
	v_add_f32_e32 v102, 1.0, v102
	v_rcp_f32_e32 v102, v102
	s_nop 0
	v_fma_f32 v102, v102, -2.0, 1.0
	v_add_f32_e32 v102, 1.0, v102
	v_mul_f32_e32 v97, v97, v102
	v_cvt_pk_bf16_f32 v102, v96, v97
	v_mul_f32_e32 v96, 0x3d372713, v98
	v_mul_f32_e32 v96, v98, v96
	v_fma_f32 v96, v98, v96, v98
	v_mul_f32_e32 v96, 0x3f4c422a, v96
	v_add_f32_e32 v96, v96, v96
	v_mul_f32_e32 v96, 0x3fb8aa3b, v96
	v_exp_f32_e32 v96, v96
	v_mul_f32_e32 v97, 0.5, v98
	v_mul_f32_e32 v98, 0.5, v99
	v_add_f32_e32 v96, 1.0, v96
	v_rcp_f32_e32 v96, v96
	s_nop 0
	v_fma_f32 v96, v96, -2.0, 1.0
	v_add_f32_e32 v96, 1.0, v96
	v_mul_f32_e32 v96, v97, v96
	v_mul_f32_e32 v97, 0x3d372713, v99
	v_mul_f32_e32 v97, v99, v97
	v_fma_f32 v97, v99, v97, v99
	v_mul_f32_e32 v97, 0x3f4c422a, v97
	v_add_f32_e32 v97, v97, v97
	v_mul_f32_e32 v97, 0x3fb8aa3b, v97
	v_exp_f32_e32 v97, v97
	s_nop 0
	v_add_f32_e32 v97, 1.0, v97
	v_rcp_f32_e32 v97, v97
	s_nop 0
	v_fma_f32 v97, v97, -2.0, 1.0
	v_add_f32_e32 v97, 1.0, v97
	v_mul_f32_e32 v97, v98, v97
	v_mul_f32_e32 v98, 0x3d372713, v92
	v_mul_f32_e32 v98, v92, v98
	v_fma_f32 v98, v92, v98, v92
	v_mul_f32_e32 v98, 0x3f4c422a, v98
	v_add_f32_e32 v98, v98, v98
	v_mul_f32_e32 v98, 0x3fb8aa3b, v98
	v_exp_f32_e32 v98, v98
	v_mul_f32_e32 v92, 0.5, v92
	v_cvt_pk_bf16_f32 v103, v96, v97
	global_store_dwordx4 v[104:105], v[100:103], off offset:256 sc1
	v_add_f32_e32 v98, 1.0, v98
	v_rcp_f32_e32 v98, v98
	v_or_b32_e32 v96, s6, v132
	v_ashrrev_i32_e32 v97, 31, v96
	v_lshlrev_b64 v[96:97], 10, v[96:97]
	v_fma_f32 v98, v98, -2.0, 1.0
	v_add_f32_e32 v98, 1.0, v98
	v_mul_f32_e32 v92, v92, v98
	v_mul_f32_e32 v98, 0x3d372713, v93
	v_mul_f32_e32 v98, v93, v98
	v_fma_f32 v98, v93, v98, v93
	v_mul_f32_e32 v98, 0x3f4c422a, v98
	v_add_f32_e32 v98, v98, v98
	v_mul_f32_e32 v98, 0x3fb8aa3b, v98
	v_exp_f32_e32 v98, v98
	v_mul_f32_e32 v93, 0.5, v93
	v_lshl_add_u64 v[96:97], s[4:5], 0, v[96:97]
	v_add_f32_e32 v98, 1.0, v98
	v_rcp_f32_e32 v98, v98
	s_nop 0
	v_fma_f32 v98, v98, -2.0, 1.0
	v_add_f32_e32 v98, 1.0, v98
	v_mul_f32_e32 v93, v93, v98
	v_cvt_pk_bf16_f32 v92, v92, v93
	v_mul_f32_e32 v93, 0x3d372713, v94
	v_mul_f32_e32 v93, v94, v93
	v_fma_f32 v93, v94, v93, v94
	v_mul_f32_e32 v93, 0x3f4c422a, v93
	v_add_f32_e32 v93, v93, v93
	v_mul_f32_e32 v93, 0x3fb8aa3b, v93
	v_exp_f32_e32 v93, v93
	v_mul_f32_e32 v94, 0.5, v94
	v_add_f32_e32 v93, 1.0, v93
	v_rcp_f32_e32 v93, v93
	s_nop 0
	v_fma_f32 v93, v93, -2.0, 1.0
	v_add_f32_e32 v93, 1.0, v93
	v_mul_f32_e32 v93, v94, v93
	v_mul_f32_e32 v94, 0x3d372713, v95
	v_mul_f32_e32 v94, v95, v94
	v_fma_f32 v94, v95, v94, v95
	v_mul_f32_e32 v94, 0x3f4c422a, v94
	v_add_f32_e32 v94, v94, v94
	v_mul_f32_e32 v94, 0x3fb8aa3b, v94
	v_exp_f32_e32 v94, v94
	v_mul_f32_e32 v95, 0.5, v95
	v_add_f32_e32 v94, 1.0, v94
	v_rcp_f32_e32 v94, v94
	s_nop 0
	v_fma_f32 v94, v94, -2.0, 1.0
	v_add_f32_e32 v94, 1.0, v94
	v_mul_f32_e32 v94, v95, v94
	v_cvt_pk_bf16_f32 v93, v93, v94
	v_mul_f32_e32 v94, 0x3d372713, v88
	v_mul_f32_e32 v94, v88, v94
	v_fma_f32 v94, v88, v94, v88
	v_mul_f32_e32 v94, 0x3f4c422a, v94
	v_add_f32_e32 v94, v94, v94
	v_mul_f32_e32 v94, 0x3fb8aa3b, v94
	v_exp_f32_e32 v94, v94
	v_mul_f32_e32 v88, 0.5, v88
	v_add_f32_e32 v94, 1.0, v94
	v_rcp_f32_e32 v94, v94
	s_nop 0
	v_fma_f32 v94, v94, -2.0, 1.0
	v_add_f32_e32 v94, 1.0, v94
	v_mul_f32_e32 v88, v88, v94
	v_mul_f32_e32 v94, 0x3d372713, v89
	v_mul_f32_e32 v94, v89, v94
	v_fma_f32 v94, v89, v94, v89
	v_mul_f32_e32 v94, 0x3f4c422a, v94
	v_add_f32_e32 v94, v94, v94
	v_mul_f32_e32 v94, 0x3fb8aa3b, v94
	v_exp_f32_e32 v94, v94
	v_mul_f32_e32 v89, 0.5, v89
	v_add_f32_e32 v94, 1.0, v94
	v_rcp_f32_e32 v94, v94
	s_nop 0
	v_fma_f32 v94, v94, -2.0, 1.0
	v_add_f32_e32 v94, 1.0, v94
	v_mul_f32_e32 v89, v89, v94
	v_cvt_pk_bf16_f32 v94, v88, v89
	v_mul_f32_e32 v88, 0x3d372713, v90
	v_mul_f32_e32 v88, v90, v88
	v_fma_f32 v88, v90, v88, v90
	v_mul_f32_e32 v88, 0x3f4c422a, v88
	v_add_f32_e32 v88, v88, v88
	v_mul_f32_e32 v88, 0x3fb8aa3b, v88
	v_exp_f32_e32 v88, v88
	v_mul_f32_e32 v89, 0.5, v90
	v_mul_f32_e32 v90, 0.5, v91
	v_add_f32_e32 v88, 1.0, v88
	v_rcp_f32_e32 v88, v88
	s_nop 0
	v_fma_f32 v88, v88, -2.0, 1.0
	v_add_f32_e32 v88, 1.0, v88
	v_mul_f32_e32 v88, v89, v88
	v_mul_f32_e32 v89, 0x3d372713, v91
	v_mul_f32_e32 v89, v91, v89
	v_fma_f32 v89, v91, v89, v91
	v_mul_f32_e32 v89, 0x3f4c422a, v89
	v_add_f32_e32 v89, v89, v89
	v_mul_f32_e32 v89, 0x3fb8aa3b, v89
	v_exp_f32_e32 v89, v89
	s_nop 0
	v_add_f32_e32 v89, 1.0, v89
	v_rcp_f32_e32 v89, v89
	s_nop 0
	v_fma_f32 v89, v89, -2.0, 1.0
	v_add_f32_e32 v89, 1.0, v89
	v_mul_f32_e32 v89, v90, v89
	v_mul_f32_e32 v90, 0x3d372713, v84
	v_mul_f32_e32 v90, v84, v90
	v_fma_f32 v90, v84, v90, v84
	v_mul_f32_e32 v90, 0x3f4c422a, v90
	v_add_f32_e32 v90, v90, v90
	v_mul_f32_e32 v90, 0x3fb8aa3b, v90
	v_exp_f32_e32 v90, v90
	v_mul_f32_e32 v84, 0.5, v84
	v_cvt_pk_bf16_f32 v95, v88, v89
	v_lshl_add_u64 v[88:89], v[96:97], 0, v[144:145]
	v_add_f32_e32 v90, 1.0, v90
	v_rcp_f32_e32 v90, v90
	global_store_dwordx4 v[88:89], v[92:95], off sc1
	v_fma_f32 v90, v90, -2.0, 1.0
	v_add_f32_e32 v90, 1.0, v90
	v_mul_f32_e32 v84, v84, v90
	v_mul_f32_e32 v90, 0x3d372713, v85
	v_mul_f32_e32 v90, v85, v90
	v_fma_f32 v90, v85, v90, v85
	v_mul_f32_e32 v90, 0x3f4c422a, v90
	v_add_f32_e32 v90, v90, v90
	v_mul_f32_e32 v90, 0x3fb8aa3b, v90
	v_exp_f32_e32 v90, v90
	v_mul_f32_e32 v85, 0.5, v85
	v_add_f32_e32 v90, 1.0, v90
	v_rcp_f32_e32 v90, v90
	s_nop 0
	v_fma_f32 v90, v90, -2.0, 1.0
	v_add_f32_e32 v90, 1.0, v90
	v_mul_f32_e32 v85, v85, v90
	v_cvt_pk_bf16_f32 v84, v84, v85
	v_mul_f32_e32 v85, 0x3d372713, v86
	v_mul_f32_e32 v85, v86, v85
	v_fma_f32 v85, v86, v85, v86
	v_mul_f32_e32 v85, 0x3f4c422a, v85
	v_add_f32_e32 v85, v85, v85
	v_mul_f32_e32 v85, 0x3fb8aa3b, v85
	v_exp_f32_e32 v85, v85
	v_mul_f32_e32 v86, 0.5, v86
	v_add_f32_e32 v85, 1.0, v85
	v_rcp_f32_e32 v85, v85
	s_nop 0
	v_fma_f32 v85, v85, -2.0, 1.0
	v_add_f32_e32 v85, 1.0, v85
	v_mul_f32_e32 v85, v86, v85
	v_mul_f32_e32 v86, 0x3d372713, v87
	v_mul_f32_e32 v86, v87, v86
	v_fma_f32 v86, v87, v86, v87
	v_mul_f32_e32 v86, 0x3f4c422a, v86
	v_add_f32_e32 v86, v86, v86
	v_mul_f32_e32 v86, 0x3fb8aa3b, v86
	v_exp_f32_e32 v86, v86
	v_mul_f32_e32 v87, 0.5, v87
	v_add_f32_e32 v86, 1.0, v86
	v_rcp_f32_e32 v86, v86
	s_nop 0
	v_fma_f32 v86, v86, -2.0, 1.0
	v_add_f32_e32 v86, 1.0, v86
	v_mul_f32_e32 v86, v87, v86
	v_cvt_pk_bf16_f32 v85, v85, v86
	v_mul_f32_e32 v86, 0x3d372713, v80
	v_mul_f32_e32 v86, v80, v86
	v_fma_f32 v86, v80, v86, v80
	v_mul_f32_e32 v86, 0x3f4c422a, v86
	v_add_f32_e32 v86, v86, v86
	v_mul_f32_e32 v86, 0x3fb8aa3b, v86
	v_exp_f32_e32 v86, v86
	v_mul_f32_e32 v80, 0.5, v80
	v_add_f32_e32 v86, 1.0, v86
	v_rcp_f32_e32 v86, v86
	s_nop 0
	v_fma_f32 v86, v86, -2.0, 1.0
	v_add_f32_e32 v86, 1.0, v86
	v_mul_f32_e32 v80, v80, v86
	v_mul_f32_e32 v86, 0x3d372713, v81
	v_mul_f32_e32 v86, v81, v86
	v_fma_f32 v86, v81, v86, v81
	v_mul_f32_e32 v86, 0x3f4c422a, v86
	v_add_f32_e32 v86, v86, v86
	v_mul_f32_e32 v86, 0x3fb8aa3b, v86
	v_exp_f32_e32 v86, v86
	v_mul_f32_e32 v81, 0.5, v81
	v_add_f32_e32 v86, 1.0, v86
	v_rcp_f32_e32 v86, v86
	s_nop 0
	v_fma_f32 v86, v86, -2.0, 1.0
	v_add_f32_e32 v86, 1.0, v86
	v_mul_f32_e32 v81, v81, v86
	v_cvt_pk_bf16_f32 v86, v80, v81
	v_mul_f32_e32 v80, 0x3d372713, v82
	v_mul_f32_e32 v80, v82, v80
	v_fma_f32 v80, v82, v80, v82
	v_mul_f32_e32 v80, 0x3f4c422a, v80
	v_add_f32_e32 v80, v80, v80
	v_mul_f32_e32 v80, 0x3fb8aa3b, v80
	v_exp_f32_e32 v80, v80
	v_mul_f32_e32 v81, 0.5, v82
	v_mul_f32_e32 v82, 0.5, v83
	v_add_f32_e32 v80, 1.0, v80
	v_rcp_f32_e32 v80, v80
	s_nop 0
	v_fma_f32 v80, v80, -2.0, 1.0
	v_add_f32_e32 v80, 1.0, v80
	v_mul_f32_e32 v80, v81, v80
	v_mul_f32_e32 v81, 0x3d372713, v83
	v_mul_f32_e32 v81, v83, v81
	v_fma_f32 v81, v83, v81, v83
	v_mul_f32_e32 v81, 0x3f4c422a, v81
	v_add_f32_e32 v81, v81, v81
	v_mul_f32_e32 v81, 0x3fb8aa3b, v81
	v_exp_f32_e32 v81, v81
	s_nop 0
	v_add_f32_e32 v81, 1.0, v81
	v_rcp_f32_e32 v81, v81
	s_nop 0
	v_fma_f32 v81, v81, -2.0, 1.0
	v_add_f32_e32 v81, 1.0, v81
	v_mul_f32_e32 v81, v82, v81
	v_mul_f32_e32 v82, 0x3d372713, v76
	v_mul_f32_e32 v82, v76, v82
	v_fma_f32 v82, v76, v82, v76
	v_mul_f32_e32 v82, 0x3f4c422a, v82
	v_add_f32_e32 v82, v82, v82
	v_mul_f32_e32 v82, 0x3fb8aa3b, v82
	v_exp_f32_e32 v82, v82
	v_mul_f32_e32 v76, 0.5, v76
	v_cvt_pk_bf16_f32 v87, v80, v81
	global_store_dwordx4 v[88:89], v[84:87], off offset:256 sc1
	v_add_f32_e32 v82, 1.0, v82
	v_rcp_f32_e32 v82, v82
	v_or_b32_e32 v80, s6, v129
	v_ashrrev_i32_e32 v81, 31, v80
	v_lshlrev_b64 v[80:81], 10, v[80:81]
	v_fma_f32 v82, v82, -2.0, 1.0
	v_add_f32_e32 v82, 1.0, v82
	v_mul_f32_e32 v76, v76, v82
	v_mul_f32_e32 v82, 0x3d372713, v77
	v_mul_f32_e32 v82, v77, v82
	v_fma_f32 v82, v77, v82, v77
	v_mul_f32_e32 v82, 0x3f4c422a, v82
	v_add_f32_e32 v82, v82, v82
	v_mul_f32_e32 v82, 0x3fb8aa3b, v82
	v_exp_f32_e32 v82, v82
	v_mul_f32_e32 v77, 0.5, v77
	v_lshl_add_u64 v[80:81], s[4:5], 0, v[80:81]
	s_addk_i32 s6, 0x80
	v_add_f32_e32 v82, 1.0, v82
	v_rcp_f32_e32 v82, v82
	s_nop 0
	v_fma_f32 v82, v82, -2.0, 1.0
	v_add_f32_e32 v82, 1.0, v82
	v_mul_f32_e32 v77, v77, v82
	v_cvt_pk_bf16_f32 v76, v76, v77
	v_mul_f32_e32 v77, 0x3d372713, v78
	v_mul_f32_e32 v77, v78, v77
	v_fma_f32 v77, v78, v77, v78
	v_mul_f32_e32 v77, 0x3f4c422a, v77
	v_add_f32_e32 v77, v77, v77
	v_mul_f32_e32 v77, 0x3fb8aa3b, v77
	v_exp_f32_e32 v77, v77
	v_mul_f32_e32 v78, 0.5, v78
	v_add_f32_e32 v77, 1.0, v77
	v_rcp_f32_e32 v77, v77
	s_nop 0
	v_fma_f32 v77, v77, -2.0, 1.0
	v_add_f32_e32 v77, 1.0, v77
	v_mul_f32_e32 v77, v78, v77
	v_mul_f32_e32 v78, 0x3d372713, v79
	v_mul_f32_e32 v78, v79, v78
	v_fma_f32 v78, v79, v78, v79
	v_mul_f32_e32 v78, 0x3f4c422a, v78
	v_add_f32_e32 v78, v78, v78
	v_mul_f32_e32 v78, 0x3fb8aa3b, v78
	v_exp_f32_e32 v78, v78
	v_mul_f32_e32 v79, 0.5, v79
	v_add_f32_e32 v78, 1.0, v78
	v_rcp_f32_e32 v78, v78
	s_nop 0
	v_fma_f32 v78, v78, -2.0, 1.0
	v_add_f32_e32 v78, 1.0, v78
	v_mul_f32_e32 v78, v79, v78
	v_cvt_pk_bf16_f32 v77, v77, v78
	v_mul_f32_e32 v78, 0x3d372713, v72
	v_mul_f32_e32 v78, v72, v78
	v_fma_f32 v78, v72, v78, v72
	v_mul_f32_e32 v78, 0x3f4c422a, v78
	v_add_f32_e32 v78, v78, v78
	v_mul_f32_e32 v78, 0x3fb8aa3b, v78
	v_exp_f32_e32 v78, v78
	v_mul_f32_e32 v72, 0.5, v72
	v_add_f32_e32 v78, 1.0, v78
	v_rcp_f32_e32 v78, v78
	s_nop 0
	v_fma_f32 v78, v78, -2.0, 1.0
	v_add_f32_e32 v78, 1.0, v78
	v_mul_f32_e32 v72, v72, v78
	v_mul_f32_e32 v78, 0x3d372713, v73
	v_mul_f32_e32 v78, v73, v78
	v_fma_f32 v78, v73, v78, v73
	v_mul_f32_e32 v78, 0x3f4c422a, v78
	v_add_f32_e32 v78, v78, v78
	v_mul_f32_e32 v78, 0x3fb8aa3b, v78
	v_exp_f32_e32 v78, v78
	v_mul_f32_e32 v73, 0.5, v73
	v_add_f32_e32 v78, 1.0, v78
	v_rcp_f32_e32 v78, v78
	s_nop 0
	v_fma_f32 v78, v78, -2.0, 1.0
	v_add_f32_e32 v78, 1.0, v78
	v_mul_f32_e32 v73, v73, v78
	v_cvt_pk_bf16_f32 v78, v72, v73
	v_mul_f32_e32 v72, 0x3d372713, v74
	v_mul_f32_e32 v72, v74, v72
	v_fma_f32 v72, v74, v72, v74
	v_mul_f32_e32 v72, 0x3f4c422a, v72
	v_add_f32_e32 v72, v72, v72
	v_mul_f32_e32 v72, 0x3fb8aa3b, v72
	v_exp_f32_e32 v72, v72
	v_mul_f32_e32 v73, 0.5, v74
	v_mul_f32_e32 v74, 0.5, v75
	v_add_f32_e32 v72, 1.0, v72
	v_rcp_f32_e32 v72, v72
	s_nop 0
	v_fma_f32 v72, v72, -2.0, 1.0
	v_add_f32_e32 v72, 1.0, v72
	v_mul_f32_e32 v72, v73, v72
	v_mul_f32_e32 v73, 0x3d372713, v75
	v_mul_f32_e32 v73, v75, v73
	v_fma_f32 v73, v75, v73, v75
	v_mul_f32_e32 v73, 0x3f4c422a, v73
	v_add_f32_e32 v73, v73, v73
	v_mul_f32_e32 v73, 0x3fb8aa3b, v73
	v_exp_f32_e32 v73, v73
	s_nop 0
	v_add_f32_e32 v73, 1.0, v73
	v_rcp_f32_e32 v73, v73
	s_nop 0
	v_fma_f32 v73, v73, -2.0, 1.0
	v_add_f32_e32 v73, 1.0, v73
	v_mul_f32_e32 v73, v74, v73
	v_mul_f32_e32 v74, 0x3d372713, v68
	v_mul_f32_e32 v74, v68, v74
	v_fma_f32 v74, v68, v74, v68
	v_mul_f32_e32 v74, 0x3f4c422a, v74
	v_add_f32_e32 v74, v74, v74
	v_mul_f32_e32 v74, 0x3fb8aa3b, v74
	v_exp_f32_e32 v74, v74
	v_mul_f32_e32 v68, 0.5, v68
	v_cvt_pk_bf16_f32 v79, v72, v73
	v_lshl_add_u64 v[72:73], v[80:81], 0, v[144:145]
	v_add_f32_e32 v74, 1.0, v74
	v_rcp_f32_e32 v74, v74
	global_store_dwordx4 v[72:73], v[76:79], off sc1
	v_fma_f32 v74, v74, -2.0, 1.0
	v_add_f32_e32 v74, 1.0, v74
	v_mul_f32_e32 v68, v68, v74
	v_mul_f32_e32 v74, 0x3d372713, v69
	v_mul_f32_e32 v74, v69, v74
	v_fma_f32 v74, v69, v74, v69
	v_mul_f32_e32 v74, 0x3f4c422a, v74
	v_add_f32_e32 v74, v74, v74
	v_mul_f32_e32 v74, 0x3fb8aa3b, v74
	v_exp_f32_e32 v74, v74
	v_mul_f32_e32 v69, 0.5, v69
	v_add_f32_e32 v74, 1.0, v74
	v_rcp_f32_e32 v74, v74
	s_nop 0
	v_fma_f32 v74, v74, -2.0, 1.0
	v_add_f32_e32 v74, 1.0, v74
	v_mul_f32_e32 v69, v69, v74
	v_cvt_pk_bf16_f32 v68, v68, v69
	v_mul_f32_e32 v69, 0x3d372713, v70
	v_mul_f32_e32 v69, v70, v69
	v_fma_f32 v69, v70, v69, v70
	v_mul_f32_e32 v69, 0x3f4c422a, v69
	v_add_f32_e32 v69, v69, v69
	v_mul_f32_e32 v69, 0x3fb8aa3b, v69
	v_exp_f32_e32 v69, v69
	v_mul_f32_e32 v70, 0.5, v70
	v_add_f32_e32 v69, 1.0, v69
	v_rcp_f32_e32 v69, v69
	s_nop 0
	v_fma_f32 v69, v69, -2.0, 1.0
	v_add_f32_e32 v69, 1.0, v69
	v_mul_f32_e32 v69, v70, v69
	v_mul_f32_e32 v70, 0x3d372713, v71
	v_mul_f32_e32 v70, v71, v70
	v_fma_f32 v70, v71, v70, v71
	v_mul_f32_e32 v70, 0x3f4c422a, v70
	v_add_f32_e32 v70, v70, v70
	v_mul_f32_e32 v70, 0x3fb8aa3b, v70
	v_exp_f32_e32 v70, v70
	v_mul_f32_e32 v71, 0.5, v71
	v_add_f32_e32 v70, 1.0, v70
	v_rcp_f32_e32 v70, v70
	s_nop 0
	v_fma_f32 v70, v70, -2.0, 1.0
	v_add_f32_e32 v70, 1.0, v70
	v_mul_f32_e32 v70, v71, v70
	v_cvt_pk_bf16_f32 v69, v69, v70
	v_mul_f32_e32 v70, 0x3d372713, v64
	v_mul_f32_e32 v70, v64, v70
	v_fma_f32 v70, v64, v70, v64
	v_mul_f32_e32 v70, 0x3f4c422a, v70
	v_add_f32_e32 v70, v70, v70
	v_mul_f32_e32 v70, 0x3fb8aa3b, v70
	v_exp_f32_e32 v70, v70
	v_mul_f32_e32 v64, 0.5, v64
	v_add_f32_e32 v70, 1.0, v70
	v_rcp_f32_e32 v70, v70
	s_nop 0
	v_fma_f32 v70, v70, -2.0, 1.0
	v_add_f32_e32 v70, 1.0, v70
	v_mul_f32_e32 v64, v64, v70
	v_mul_f32_e32 v70, 0x3d372713, v65
	v_mul_f32_e32 v70, v65, v70
	v_fma_f32 v70, v65, v70, v65
	v_mul_f32_e32 v70, 0x3f4c422a, v70
	v_add_f32_e32 v70, v70, v70
	v_mul_f32_e32 v70, 0x3fb8aa3b, v70
	v_exp_f32_e32 v70, v70
	v_mul_f32_e32 v65, 0.5, v65
	v_add_f32_e32 v70, 1.0, v70
	v_rcp_f32_e32 v70, v70
	s_nop 0
	v_fma_f32 v70, v70, -2.0, 1.0
	v_add_f32_e32 v70, 1.0, v70
	v_mul_f32_e32 v65, v65, v70
	v_cvt_pk_bf16_f32 v70, v64, v65
	v_mul_f32_e32 v64, 0x3d372713, v66
	v_mul_f32_e32 v64, v66, v64
	v_fma_f32 v64, v66, v64, v66
	v_mul_f32_e32 v64, 0x3f4c422a, v64
	v_add_f32_e32 v64, v64, v64
	v_mul_f32_e32 v64, 0x3fb8aa3b, v64
	v_exp_f32_e32 v64, v64
	v_mul_f32_e32 v65, 0.5, v66
	v_mul_f32_e32 v66, 0.5, v67
	v_add_f32_e32 v64, 1.0, v64
	v_rcp_f32_e32 v64, v64
	s_nop 0
	v_fma_f32 v64, v64, -2.0, 1.0
	v_add_f32_e32 v64, 1.0, v64
	v_mul_f32_e32 v64, v65, v64
	v_mul_f32_e32 v65, 0x3d372713, v67
	v_mul_f32_e32 v65, v67, v65
	v_fma_f32 v65, v67, v65, v67
	v_mul_f32_e32 v65, 0x3f4c422a, v65
	v_add_f32_e32 v65, v65, v65
	v_mul_f32_e32 v65, 0x3fb8aa3b, v65
	v_exp_f32_e32 v65, v65
	s_nop 0
	v_add_f32_e32 v65, 1.0, v65
	v_rcp_f32_e32 v65, v65
	s_nop 0
	v_fma_f32 v65, v65, -2.0, 1.0
	v_add_f32_e32 v65, 1.0, v65
	v_mul_f32_e32 v65, v66, v65
	v_mul_f32_e32 v66, 0x3d372713, v60
	v_mul_f32_e32 v66, v60, v66
	v_fma_f32 v66, v60, v66, v60
	v_mul_f32_e32 v66, 0x3f4c422a, v66
	v_add_f32_e32 v66, v66, v66
	v_mul_f32_e32 v66, 0x3fb8aa3b, v66
	v_exp_f32_e32 v66, v66
	v_mul_f32_e32 v60, 0.5, v60
	v_cvt_pk_bf16_f32 v71, v64, v65
	global_store_dwordx4 v[72:73], v[68:71], off offset:256 sc1
	v_add_f32_e32 v66, 1.0, v66
	v_rcp_f32_e32 v66, v66
	v_or_b32_e32 v64, s6, v140
	v_ashrrev_i32_e32 v65, 31, v64
	v_lshlrev_b64 v[64:65], 10, v[64:65]
	v_fma_f32 v66, v66, -2.0, 1.0
	v_add_f32_e32 v66, 1.0, v66
	v_mul_f32_e32 v60, v60, v66
	v_mul_f32_e32 v66, 0x3d372713, v61
	v_mul_f32_e32 v66, v61, v66
	v_fma_f32 v66, v61, v66, v61
	v_mul_f32_e32 v66, 0x3f4c422a, v66
	v_add_f32_e32 v66, v66, v66
	v_mul_f32_e32 v66, 0x3fb8aa3b, v66
	v_exp_f32_e32 v66, v66
	v_mul_f32_e32 v61, 0.5, v61
	v_lshl_add_u64 v[64:65], s[4:5], 0, v[64:65]
	v_add_f32_e32 v66, 1.0, v66
	v_rcp_f32_e32 v66, v66
	s_nop 0
	v_fma_f32 v66, v66, -2.0, 1.0
	v_add_f32_e32 v66, 1.0, v66
	v_mul_f32_e32 v61, v61, v66
	v_cvt_pk_bf16_f32 v60, v60, v61
	v_mul_f32_e32 v61, 0x3d372713, v62
	v_mul_f32_e32 v61, v62, v61
	v_fma_f32 v61, v62, v61, v62
	v_mul_f32_e32 v61, 0x3f4c422a, v61
	v_add_f32_e32 v61, v61, v61
	v_mul_f32_e32 v61, 0x3fb8aa3b, v61
	v_exp_f32_e32 v61, v61
	v_mul_f32_e32 v62, 0.5, v62
	v_add_f32_e32 v61, 1.0, v61
	v_rcp_f32_e32 v61, v61
	s_nop 0
	v_fma_f32 v61, v61, -2.0, 1.0
	v_add_f32_e32 v61, 1.0, v61
	v_mul_f32_e32 v61, v62, v61
	v_mul_f32_e32 v62, 0x3d372713, v63
	v_mul_f32_e32 v62, v63, v62
	v_fma_f32 v62, v63, v62, v63
	v_mul_f32_e32 v62, 0x3f4c422a, v62
	v_add_f32_e32 v62, v62, v62
	v_mul_f32_e32 v62, 0x3fb8aa3b, v62
	v_exp_f32_e32 v62, v62
	v_mul_f32_e32 v63, 0.5, v63
	v_add_f32_e32 v62, 1.0, v62
	v_rcp_f32_e32 v62, v62
	s_nop 0
	v_fma_f32 v62, v62, -2.0, 1.0
	v_add_f32_e32 v62, 1.0, v62
	v_mul_f32_e32 v62, v63, v62
	v_cvt_pk_bf16_f32 v61, v61, v62
	v_mul_f32_e32 v62, 0x3d372713, v56
	v_mul_f32_e32 v62, v56, v62
	v_fma_f32 v62, v56, v62, v56
	v_mul_f32_e32 v62, 0x3f4c422a, v62
	v_add_f32_e32 v62, v62, v62
	v_mul_f32_e32 v62, 0x3fb8aa3b, v62
	v_exp_f32_e32 v62, v62
	v_mul_f32_e32 v56, 0.5, v56
	v_add_f32_e32 v62, 1.0, v62
	v_rcp_f32_e32 v62, v62
	s_nop 0
	v_fma_f32 v62, v62, -2.0, 1.0
	v_add_f32_e32 v62, 1.0, v62
	v_mul_f32_e32 v56, v56, v62
	v_mul_f32_e32 v62, 0x3d372713, v57
	v_mul_f32_e32 v62, v57, v62
	v_fma_f32 v62, v57, v62, v57
	v_mul_f32_e32 v62, 0x3f4c422a, v62
	v_add_f32_e32 v62, v62, v62
	v_mul_f32_e32 v62, 0x3fb8aa3b, v62
	v_exp_f32_e32 v62, v62
	v_mul_f32_e32 v57, 0.5, v57
	v_add_f32_e32 v62, 1.0, v62
	v_rcp_f32_e32 v62, v62
	s_nop 0
	v_fma_f32 v62, v62, -2.0, 1.0
	v_add_f32_e32 v62, 1.0, v62
	v_mul_f32_e32 v57, v57, v62
	v_cvt_pk_bf16_f32 v62, v56, v57
	v_mul_f32_e32 v56, 0x3d372713, v58
	v_mul_f32_e32 v56, v58, v56
	v_fma_f32 v56, v58, v56, v58
	v_mul_f32_e32 v56, 0x3f4c422a, v56
	v_add_f32_e32 v56, v56, v56
	v_mul_f32_e32 v56, 0x3fb8aa3b, v56
	v_exp_f32_e32 v56, v56
	v_mul_f32_e32 v57, 0.5, v58
	v_mul_f32_e32 v58, 0.5, v59
	v_add_f32_e32 v56, 1.0, v56
	v_rcp_f32_e32 v56, v56
	s_nop 0
	v_fma_f32 v56, v56, -2.0, 1.0
	v_add_f32_e32 v56, 1.0, v56
	v_mul_f32_e32 v56, v57, v56
	v_mul_f32_e32 v57, 0x3d372713, v59
	v_mul_f32_e32 v57, v59, v57
	v_fma_f32 v57, v59, v57, v59
	v_mul_f32_e32 v57, 0x3f4c422a, v57
	v_add_f32_e32 v57, v57, v57
	v_mul_f32_e32 v57, 0x3fb8aa3b, v57
	v_exp_f32_e32 v57, v57
	s_nop 0
	v_add_f32_e32 v57, 1.0, v57
	v_rcp_f32_e32 v57, v57
	s_nop 0
	v_fma_f32 v57, v57, -2.0, 1.0
	v_add_f32_e32 v57, 1.0, v57
	v_mul_f32_e32 v57, v58, v57
	v_mul_f32_e32 v58, 0x3d372713, v52
	v_mul_f32_e32 v58, v52, v58
	v_fma_f32 v58, v52, v58, v52
	v_mul_f32_e32 v58, 0x3f4c422a, v58
	v_add_f32_e32 v58, v58, v58
	v_mul_f32_e32 v58, 0x3fb8aa3b, v58
	v_exp_f32_e32 v58, v58
	v_mul_f32_e32 v52, 0.5, v52
	v_cvt_pk_bf16_f32 v63, v56, v57
	v_lshl_add_u64 v[56:57], v[64:65], 0, v[144:145]
	v_add_f32_e32 v58, 1.0, v58
	v_rcp_f32_e32 v58, v58
	global_store_dwordx4 v[56:57], v[60:63], off sc1
	v_fma_f32 v58, v58, -2.0, 1.0
	v_add_f32_e32 v58, 1.0, v58
	v_mul_f32_e32 v52, v52, v58
	v_mul_f32_e32 v58, 0x3d372713, v53
	v_mul_f32_e32 v58, v53, v58
	v_fma_f32 v58, v53, v58, v53
	v_mul_f32_e32 v58, 0x3f4c422a, v58
	v_add_f32_e32 v58, v58, v58
	v_mul_f32_e32 v58, 0x3fb8aa3b, v58
	v_exp_f32_e32 v58, v58
	v_mul_f32_e32 v53, 0.5, v53
	v_add_f32_e32 v58, 1.0, v58
	v_rcp_f32_e32 v58, v58
	s_nop 0
	v_fma_f32 v58, v58, -2.0, 1.0
	v_add_f32_e32 v58, 1.0, v58
	v_mul_f32_e32 v53, v53, v58
	v_cvt_pk_bf16_f32 v52, v52, v53
	v_mul_f32_e32 v53, 0x3d372713, v54
	v_mul_f32_e32 v53, v54, v53
	v_fma_f32 v53, v54, v53, v54
	v_mul_f32_e32 v53, 0x3f4c422a, v53
	v_add_f32_e32 v53, v53, v53
	v_mul_f32_e32 v53, 0x3fb8aa3b, v53
	v_exp_f32_e32 v53, v53
	v_mul_f32_e32 v54, 0.5, v54
	v_add_f32_e32 v53, 1.0, v53
	v_rcp_f32_e32 v53, v53
	s_nop 0
	v_fma_f32 v53, v53, -2.0, 1.0
	v_add_f32_e32 v53, 1.0, v53
	v_mul_f32_e32 v53, v54, v53
	v_mul_f32_e32 v54, 0x3d372713, v55
	v_mul_f32_e32 v54, v55, v54
	v_fma_f32 v54, v55, v54, v55
	v_mul_f32_e32 v54, 0x3f4c422a, v54
	v_add_f32_e32 v54, v54, v54
	v_mul_f32_e32 v54, 0x3fb8aa3b, v54
	v_exp_f32_e32 v54, v54
	v_mul_f32_e32 v55, 0.5, v55
	v_add_f32_e32 v54, 1.0, v54
	v_rcp_f32_e32 v54, v54
	s_nop 0
	v_fma_f32 v54, v54, -2.0, 1.0
	v_add_f32_e32 v54, 1.0, v54
	v_mul_f32_e32 v54, v55, v54
	v_cvt_pk_bf16_f32 v53, v53, v54
	v_mul_f32_e32 v54, 0x3d372713, v48
	v_mul_f32_e32 v54, v48, v54
	v_fma_f32 v54, v48, v54, v48
	v_mul_f32_e32 v54, 0x3f4c422a, v54
	v_add_f32_e32 v54, v54, v54
	v_mul_f32_e32 v54, 0x3fb8aa3b, v54
	v_exp_f32_e32 v54, v54
	v_mul_f32_e32 v48, 0.5, v48
	v_add_f32_e32 v54, 1.0, v54
	v_rcp_f32_e32 v54, v54
	s_nop 0
	v_fma_f32 v54, v54, -2.0, 1.0
	v_add_f32_e32 v54, 1.0, v54
	v_mul_f32_e32 v48, v48, v54
	v_mul_f32_e32 v54, 0x3d372713, v49
	v_mul_f32_e32 v54, v49, v54
	v_fma_f32 v54, v49, v54, v49
	v_mul_f32_e32 v54, 0x3f4c422a, v54
	v_add_f32_e32 v54, v54, v54
	v_mul_f32_e32 v54, 0x3fb8aa3b, v54
	v_exp_f32_e32 v54, v54
	v_mul_f32_e32 v49, 0.5, v49
	v_add_f32_e32 v54, 1.0, v54
	v_rcp_f32_e32 v54, v54
	s_nop 0
	v_fma_f32 v54, v54, -2.0, 1.0
	v_add_f32_e32 v54, 1.0, v54
	v_mul_f32_e32 v49, v49, v54
	v_cvt_pk_bf16_f32 v54, v48, v49
	v_mul_f32_e32 v48, 0x3d372713, v50
	v_mul_f32_e32 v48, v50, v48
	v_fma_f32 v48, v50, v48, v50
	v_mul_f32_e32 v48, 0x3f4c422a, v48
	v_add_f32_e32 v48, v48, v48
	v_mul_f32_e32 v48, 0x3fb8aa3b, v48
	v_exp_f32_e32 v48, v48
	v_mul_f32_e32 v49, 0.5, v50
	v_mul_f32_e32 v50, 0.5, v51
	v_add_f32_e32 v48, 1.0, v48
	v_rcp_f32_e32 v48, v48
	s_nop 0
	v_fma_f32 v48, v48, -2.0, 1.0
	v_add_f32_e32 v48, 1.0, v48
	v_mul_f32_e32 v48, v49, v48
	v_mul_f32_e32 v49, 0x3d372713, v51
	v_mul_f32_e32 v49, v51, v49
	v_fma_f32 v49, v51, v49, v51
	v_mul_f32_e32 v49, 0x3f4c422a, v49
	v_add_f32_e32 v49, v49, v49
	v_mul_f32_e32 v49, 0x3fb8aa3b, v49
	v_exp_f32_e32 v49, v49
	s_nop 0
	v_add_f32_e32 v49, 1.0, v49
	v_rcp_f32_e32 v49, v49
	s_nop 0
	v_fma_f32 v49, v49, -2.0, 1.0
	v_add_f32_e32 v49, 1.0, v49
	v_mul_f32_e32 v49, v50, v49
	v_mul_f32_e32 v50, 0x3d372713, v44
	v_mul_f32_e32 v50, v44, v50
	v_fma_f32 v50, v44, v50, v44
	v_mul_f32_e32 v50, 0x3f4c422a, v50
	v_add_f32_e32 v50, v50, v50
	v_mul_f32_e32 v50, 0x3fb8aa3b, v50
	v_exp_f32_e32 v50, v50
	v_mul_f32_e32 v44, 0.5, v44
	v_cvt_pk_bf16_f32 v55, v48, v49
	global_store_dwordx4 v[56:57], v[52:55], off offset:256 sc1
	v_add_f32_e32 v50, 1.0, v50
	v_rcp_f32_e32 v50, v50
	v_or_b32_e32 v48, s6, v133
	v_ashrrev_i32_e32 v49, 31, v48
	v_lshlrev_b64 v[48:49], 10, v[48:49]
	v_fma_f32 v50, v50, -2.0, 1.0
	v_add_f32_e32 v50, 1.0, v50
	v_mul_f32_e32 v44, v44, v50
	v_mul_f32_e32 v50, 0x3d372713, v45
	v_mul_f32_e32 v50, v45, v50
	v_fma_f32 v50, v45, v50, v45
	v_mul_f32_e32 v50, 0x3f4c422a, v50
	v_add_f32_e32 v50, v50, v50
	v_mul_f32_e32 v50, 0x3fb8aa3b, v50
	v_exp_f32_e32 v50, v50
	v_mul_f32_e32 v45, 0.5, v45
	v_lshl_add_u64 v[48:49], s[4:5], 0, v[48:49]
	v_add_f32_e32 v50, 1.0, v50
	v_rcp_f32_e32 v50, v50
	s_nop 0
	v_fma_f32 v50, v50, -2.0, 1.0
	v_add_f32_e32 v50, 1.0, v50
	v_mul_f32_e32 v45, v45, v50
	v_cvt_pk_bf16_f32 v44, v44, v45
	v_mul_f32_e32 v45, 0x3d372713, v46
	v_mul_f32_e32 v45, v46, v45
	v_fma_f32 v45, v46, v45, v46
	v_mul_f32_e32 v45, 0x3f4c422a, v45
	v_add_f32_e32 v45, v45, v45
	v_mul_f32_e32 v45, 0x3fb8aa3b, v45
	v_exp_f32_e32 v45, v45
	v_mul_f32_e32 v46, 0.5, v46
	v_add_f32_e32 v45, 1.0, v45
	v_rcp_f32_e32 v45, v45
	s_nop 0
	v_fma_f32 v45, v45, -2.0, 1.0
	v_add_f32_e32 v45, 1.0, v45
	v_mul_f32_e32 v45, v46, v45
	v_mul_f32_e32 v46, 0x3d372713, v47
	v_mul_f32_e32 v46, v47, v46
	v_fma_f32 v46, v47, v46, v47
	v_mul_f32_e32 v46, 0x3f4c422a, v46
	v_add_f32_e32 v46, v46, v46
	v_mul_f32_e32 v46, 0x3fb8aa3b, v46
	v_exp_f32_e32 v46, v46
	v_mul_f32_e32 v47, 0.5, v47
	v_add_f32_e32 v46, 1.0, v46
	v_rcp_f32_e32 v46, v46
	s_nop 0
	v_fma_f32 v46, v46, -2.0, 1.0
	v_add_f32_e32 v46, 1.0, v46
	v_mul_f32_e32 v46, v47, v46
	v_cvt_pk_bf16_f32 v45, v45, v46
	v_mul_f32_e32 v46, 0x3d372713, v40
	v_mul_f32_e32 v46, v40, v46
	v_fma_f32 v46, v40, v46, v40
	v_mul_f32_e32 v46, 0x3f4c422a, v46
	v_add_f32_e32 v46, v46, v46
	v_mul_f32_e32 v46, 0x3fb8aa3b, v46
	v_exp_f32_e32 v46, v46
	v_mul_f32_e32 v40, 0.5, v40
	v_add_f32_e32 v46, 1.0, v46
	v_rcp_f32_e32 v46, v46
	s_nop 0
	v_fma_f32 v46, v46, -2.0, 1.0
	v_add_f32_e32 v46, 1.0, v46
	v_mul_f32_e32 v40, v40, v46
	v_mul_f32_e32 v46, 0x3d372713, v41
	v_mul_f32_e32 v46, v41, v46
	v_fma_f32 v46, v41, v46, v41
	v_mul_f32_e32 v46, 0x3f4c422a, v46
	v_add_f32_e32 v46, v46, v46
	v_mul_f32_e32 v46, 0x3fb8aa3b, v46
	v_exp_f32_e32 v46, v46
	v_mul_f32_e32 v41, 0.5, v41
	v_add_f32_e32 v46, 1.0, v46
	v_rcp_f32_e32 v46, v46
	s_nop 0
	v_fma_f32 v46, v46, -2.0, 1.0
	v_add_f32_e32 v46, 1.0, v46
	v_mul_f32_e32 v41, v41, v46
	v_cvt_pk_bf16_f32 v46, v40, v41
	v_mul_f32_e32 v40, 0x3d372713, v42
	v_mul_f32_e32 v40, v42, v40
	v_fma_f32 v40, v42, v40, v42
	v_mul_f32_e32 v40, 0x3f4c422a, v40
	v_add_f32_e32 v40, v40, v40
	v_mul_f32_e32 v40, 0x3fb8aa3b, v40
	v_exp_f32_e32 v40, v40
	v_mul_f32_e32 v41, 0.5, v42
	v_mul_f32_e32 v42, 0.5, v43
	v_add_f32_e32 v40, 1.0, v40
	v_rcp_f32_e32 v40, v40
	s_nop 0
	v_fma_f32 v40, v40, -2.0, 1.0
	v_add_f32_e32 v40, 1.0, v40
	v_mul_f32_e32 v40, v41, v40
	v_mul_f32_e32 v41, 0x3d372713, v43
	v_mul_f32_e32 v41, v43, v41
	v_fma_f32 v41, v43, v41, v43
	v_mul_f32_e32 v41, 0x3f4c422a, v41
	v_add_f32_e32 v41, v41, v41
	v_mul_f32_e32 v41, 0x3fb8aa3b, v41
	v_exp_f32_e32 v41, v41
	s_nop 0
	v_add_f32_e32 v41, 1.0, v41
	v_rcp_f32_e32 v41, v41
	s_nop 0
	v_fma_f32 v41, v41, -2.0, 1.0
	v_add_f32_e32 v41, 1.0, v41
	v_mul_f32_e32 v41, v42, v41
	v_mul_f32_e32 v42, 0x3d372713, v36
	v_mul_f32_e32 v42, v36, v42
	v_fma_f32 v42, v36, v42, v36
	v_mul_f32_e32 v42, 0x3f4c422a, v42
	v_add_f32_e32 v42, v42, v42
	v_mul_f32_e32 v42, 0x3fb8aa3b, v42
	v_exp_f32_e32 v42, v42
	v_mul_f32_e32 v36, 0.5, v36
	v_cvt_pk_bf16_f32 v47, v40, v41
	v_lshl_add_u64 v[40:41], v[48:49], 0, v[144:145]
	v_add_f32_e32 v42, 1.0, v42
	v_rcp_f32_e32 v42, v42
	global_store_dwordx4 v[40:41], v[44:47], off sc1
	v_fma_f32 v42, v42, -2.0, 1.0
	v_add_f32_e32 v42, 1.0, v42
	v_mul_f32_e32 v36, v36, v42
	v_mul_f32_e32 v42, 0x3d372713, v37
	v_mul_f32_e32 v42, v37, v42
	v_fma_f32 v42, v37, v42, v37
	v_mul_f32_e32 v42, 0x3f4c422a, v42
	v_add_f32_e32 v42, v42, v42
	v_mul_f32_e32 v42, 0x3fb8aa3b, v42
	v_exp_f32_e32 v42, v42
	v_mul_f32_e32 v37, 0.5, v37
	v_add_f32_e32 v42, 1.0, v42
	v_rcp_f32_e32 v42, v42
	s_nop 0
	v_fma_f32 v42, v42, -2.0, 1.0
	v_add_f32_e32 v42, 1.0, v42
	v_mul_f32_e32 v37, v37, v42
	v_cvt_pk_bf16_f32 v36, v36, v37
	v_mul_f32_e32 v37, 0x3d372713, v38
	v_mul_f32_e32 v37, v38, v37
	v_fma_f32 v37, v38, v37, v38
	v_mul_f32_e32 v37, 0x3f4c422a, v37
	v_add_f32_e32 v37, v37, v37
	v_mul_f32_e32 v37, 0x3fb8aa3b, v37
	v_exp_f32_e32 v37, v37
	v_mul_f32_e32 v38, 0.5, v38
	v_add_f32_e32 v37, 1.0, v37
	v_rcp_f32_e32 v37, v37
	s_nop 0
	v_fma_f32 v37, v37, -2.0, 1.0
	v_add_f32_e32 v37, 1.0, v37
	v_mul_f32_e32 v37, v38, v37
	v_mul_f32_e32 v38, 0x3d372713, v39
	v_mul_f32_e32 v38, v39, v38
	v_fma_f32 v38, v39, v38, v39
	v_mul_f32_e32 v38, 0x3f4c422a, v38
	v_add_f32_e32 v38, v38, v38
	v_mul_f32_e32 v38, 0x3fb8aa3b, v38
	v_exp_f32_e32 v38, v38
	v_mul_f32_e32 v39, 0.5, v39
	v_add_f32_e32 v38, 1.0, v38
	v_rcp_f32_e32 v38, v38
	s_nop 0
	v_fma_f32 v38, v38, -2.0, 1.0
	v_add_f32_e32 v38, 1.0, v38
	v_mul_f32_e32 v38, v39, v38
	v_cvt_pk_bf16_f32 v37, v37, v38
	v_mul_f32_e32 v38, 0x3d372713, v32
	v_mul_f32_e32 v38, v32, v38
	v_fma_f32 v38, v32, v38, v32
	v_mul_f32_e32 v38, 0x3f4c422a, v38
	v_add_f32_e32 v38, v38, v38
	v_mul_f32_e32 v38, 0x3fb8aa3b, v38
	v_exp_f32_e32 v38, v38
	v_mul_f32_e32 v32, 0.5, v32
	v_add_f32_e32 v38, 1.0, v38
	v_rcp_f32_e32 v38, v38
	s_nop 0
	v_fma_f32 v38, v38, -2.0, 1.0
	v_add_f32_e32 v38, 1.0, v38
	v_mul_f32_e32 v32, v32, v38
	v_mul_f32_e32 v38, 0x3d372713, v33
	v_mul_f32_e32 v38, v33, v38
	v_fma_f32 v38, v33, v38, v33
	v_mul_f32_e32 v38, 0x3f4c422a, v38
	v_add_f32_e32 v38, v38, v38
	v_mul_f32_e32 v38, 0x3fb8aa3b, v38
	v_exp_f32_e32 v38, v38
	v_mul_f32_e32 v33, 0.5, v33
	v_add_f32_e32 v38, 1.0, v38
	v_rcp_f32_e32 v38, v38
	s_nop 0
	v_fma_f32 v38, v38, -2.0, 1.0
	v_add_f32_e32 v38, 1.0, v38
	v_mul_f32_e32 v33, v33, v38
	v_cvt_pk_bf16_f32 v38, v32, v33
	v_mul_f32_e32 v32, 0x3d372713, v34
	v_mul_f32_e32 v32, v34, v32
	v_fma_f32 v32, v34, v32, v34
	v_mul_f32_e32 v32, 0x3f4c422a, v32
	v_add_f32_e32 v32, v32, v32
	v_mul_f32_e32 v32, 0x3fb8aa3b, v32
	v_exp_f32_e32 v32, v32
	v_mul_f32_e32 v33, 0.5, v34
	v_mul_f32_e32 v34, 0.5, v35
	v_add_f32_e32 v32, 1.0, v32
	v_rcp_f32_e32 v32, v32
	s_nop 0
	v_fma_f32 v32, v32, -2.0, 1.0
	v_add_f32_e32 v32, 1.0, v32
	v_mul_f32_e32 v32, v33, v32
	v_mul_f32_e32 v33, 0x3d372713, v35
	v_mul_f32_e32 v33, v35, v33
	v_fma_f32 v33, v35, v33, v35
	v_mul_f32_e32 v33, 0x3f4c422a, v33
	v_add_f32_e32 v33, v33, v33
	v_mul_f32_e32 v33, 0x3fb8aa3b, v33
	v_exp_f32_e32 v33, v33
	s_nop 0
	v_add_f32_e32 v33, 1.0, v33
	v_rcp_f32_e32 v33, v33
	s_nop 0
	v_fma_f32 v33, v33, -2.0, 1.0
	v_add_f32_e32 v33, 1.0, v33
	v_mul_f32_e32 v33, v34, v33
	v_mul_f32_e32 v34, 0x3d372713, v28
	v_mul_f32_e32 v34, v28, v34
	v_fma_f32 v34, v28, v34, v28
	v_mul_f32_e32 v34, 0x3f4c422a, v34
	v_add_f32_e32 v34, v34, v34
	v_mul_f32_e32 v34, 0x3fb8aa3b, v34
	v_exp_f32_e32 v34, v34
	v_mul_f32_e32 v28, 0.5, v28
	v_cvt_pk_bf16_f32 v39, v32, v33
	global_store_dwordx4 v[40:41], v[36:39], off offset:256 sc1
	v_add_f32_e32 v34, 1.0, v34
	v_rcp_f32_e32 v34, v34
	v_or_b32_e32 v32, s6, v132
	v_ashrrev_i32_e32 v33, 31, v32
	v_lshlrev_b64 v[32:33], 10, v[32:33]
	v_fma_f32 v34, v34, -2.0, 1.0
	v_add_f32_e32 v34, 1.0, v34
	v_mul_f32_e32 v28, v28, v34
	v_mul_f32_e32 v34, 0x3d372713, v29
	v_mul_f32_e32 v34, v29, v34
	v_fma_f32 v34, v29, v34, v29
	v_mul_f32_e32 v34, 0x3f4c422a, v34
	v_add_f32_e32 v34, v34, v34
	v_mul_f32_e32 v34, 0x3fb8aa3b, v34
	v_exp_f32_e32 v34, v34
	v_mul_f32_e32 v29, 0.5, v29
	v_lshl_add_u64 v[32:33], s[4:5], 0, v[32:33]
	v_add_f32_e32 v34, 1.0, v34
	v_rcp_f32_e32 v34, v34
	s_nop 0
	v_fma_f32 v34, v34, -2.0, 1.0
	v_add_f32_e32 v34, 1.0, v34
	v_mul_f32_e32 v29, v29, v34
	v_cvt_pk_bf16_f32 v28, v28, v29
	v_mul_f32_e32 v29, 0x3d372713, v30
	v_mul_f32_e32 v29, v30, v29
	v_fma_f32 v29, v30, v29, v30
	v_mul_f32_e32 v29, 0x3f4c422a, v29
	v_add_f32_e32 v29, v29, v29
	v_mul_f32_e32 v29, 0x3fb8aa3b, v29
	v_exp_f32_e32 v29, v29
	v_mul_f32_e32 v30, 0.5, v30
	v_add_f32_e32 v29, 1.0, v29
	v_rcp_f32_e32 v29, v29
	s_nop 0
	v_fma_f32 v29, v29, -2.0, 1.0
	v_add_f32_e32 v29, 1.0, v29
	v_mul_f32_e32 v29, v30, v29
	v_mul_f32_e32 v30, 0x3d372713, v31
	v_mul_f32_e32 v30, v31, v30
	v_fma_f32 v30, v31, v30, v31
	v_mul_f32_e32 v30, 0x3f4c422a, v30
	v_add_f32_e32 v30, v30, v30
	v_mul_f32_e32 v30, 0x3fb8aa3b, v30
	v_exp_f32_e32 v30, v30
	v_mul_f32_e32 v31, 0.5, v31
	v_add_f32_e32 v30, 1.0, v30
	v_rcp_f32_e32 v30, v30
	s_nop 0
	v_fma_f32 v30, v30, -2.0, 1.0
	v_add_f32_e32 v30, 1.0, v30
	v_mul_f32_e32 v30, v31, v30
	v_cvt_pk_bf16_f32 v29, v29, v30
	v_mul_f32_e32 v30, 0x3d372713, v24
	v_mul_f32_e32 v30, v24, v30
	v_fma_f32 v30, v24, v30, v24
	v_mul_f32_e32 v30, 0x3f4c422a, v30
	v_add_f32_e32 v30, v30, v30
	v_mul_f32_e32 v30, 0x3fb8aa3b, v30
	v_exp_f32_e32 v30, v30
	v_mul_f32_e32 v24, 0.5, v24
	v_add_f32_e32 v30, 1.0, v30
	v_rcp_f32_e32 v30, v30
	s_nop 0
	v_fma_f32 v30, v30, -2.0, 1.0
	v_add_f32_e32 v30, 1.0, v30
	v_mul_f32_e32 v24, v24, v30
	v_mul_f32_e32 v30, 0x3d372713, v25
	v_mul_f32_e32 v30, v25, v30
	v_fma_f32 v30, v25, v30, v25
	v_mul_f32_e32 v30, 0x3f4c422a, v30
	v_add_f32_e32 v30, v30, v30
	v_mul_f32_e32 v30, 0x3fb8aa3b, v30
	v_exp_f32_e32 v30, v30
	v_mul_f32_e32 v25, 0.5, v25
	v_add_f32_e32 v30, 1.0, v30
	v_rcp_f32_e32 v30, v30
	s_nop 0
	v_fma_f32 v30, v30, -2.0, 1.0
	v_add_f32_e32 v30, 1.0, v30
	v_mul_f32_e32 v25, v25, v30
	v_cvt_pk_bf16_f32 v30, v24, v25
	v_mul_f32_e32 v24, 0x3d372713, v26
	v_mul_f32_e32 v24, v26, v24
	v_fma_f32 v24, v26, v24, v26
	v_mul_f32_e32 v24, 0x3f4c422a, v24
	v_add_f32_e32 v24, v24, v24
	v_mul_f32_e32 v24, 0x3fb8aa3b, v24
	v_exp_f32_e32 v24, v24
	v_mul_f32_e32 v25, 0.5, v26
	v_mul_f32_e32 v26, 0.5, v27
	v_add_f32_e32 v24, 1.0, v24
	v_rcp_f32_e32 v24, v24
	s_nop 0
	v_fma_f32 v24, v24, -2.0, 1.0
	v_add_f32_e32 v24, 1.0, v24
	v_mul_f32_e32 v24, v25, v24
	v_mul_f32_e32 v25, 0x3d372713, v27
	v_mul_f32_e32 v25, v27, v25
	v_fma_f32 v25, v27, v25, v27
	v_mul_f32_e32 v25, 0x3f4c422a, v25
	v_add_f32_e32 v25, v25, v25
	v_mul_f32_e32 v25, 0x3fb8aa3b, v25
	v_exp_f32_e32 v25, v25
	s_nop 0
	v_add_f32_e32 v25, 1.0, v25
	v_rcp_f32_e32 v25, v25
	s_nop 0
	v_fma_f32 v25, v25, -2.0, 1.0
	v_add_f32_e32 v25, 1.0, v25
	v_mul_f32_e32 v25, v26, v25
	v_mul_f32_e32 v26, 0x3d372713, v20
	v_mul_f32_e32 v26, v20, v26
	v_fma_f32 v26, v20, v26, v20
	v_mul_f32_e32 v26, 0x3f4c422a, v26
	v_add_f32_e32 v26, v26, v26
	v_mul_f32_e32 v26, 0x3fb8aa3b, v26
	v_exp_f32_e32 v26, v26
	v_mul_f32_e32 v20, 0.5, v20
	v_cvt_pk_bf16_f32 v31, v24, v25
	v_lshl_add_u64 v[24:25], v[32:33], 0, v[144:145]
	v_add_f32_e32 v26, 1.0, v26
	v_rcp_f32_e32 v26, v26
	global_store_dwordx4 v[24:25], v[28:31], off sc1
	v_fma_f32 v26, v26, -2.0, 1.0
	v_add_f32_e32 v26, 1.0, v26
	v_mul_f32_e32 v20, v20, v26
	v_mul_f32_e32 v26, 0x3d372713, v21
	v_mul_f32_e32 v26, v21, v26
	v_fma_f32 v26, v21, v26, v21
	v_mul_f32_e32 v26, 0x3f4c422a, v26
	v_add_f32_e32 v26, v26, v26
	v_mul_f32_e32 v26, 0x3fb8aa3b, v26
	v_exp_f32_e32 v26, v26
	v_mul_f32_e32 v21, 0.5, v21
	v_add_f32_e32 v26, 1.0, v26
	v_rcp_f32_e32 v26, v26
	s_nop 0
	v_fma_f32 v26, v26, -2.0, 1.0
	v_add_f32_e32 v26, 1.0, v26
	v_mul_f32_e32 v21, v21, v26
	v_cvt_pk_bf16_f32 v20, v20, v21
	v_mul_f32_e32 v21, 0x3d372713, v22
	v_mul_f32_e32 v21, v22, v21
	v_fma_f32 v21, v22, v21, v22
	v_mul_f32_e32 v21, 0x3f4c422a, v21
	v_add_f32_e32 v21, v21, v21
	v_mul_f32_e32 v21, 0x3fb8aa3b, v21
	v_exp_f32_e32 v21, v21
	v_mul_f32_e32 v22, 0.5, v22
	v_add_f32_e32 v21, 1.0, v21
	v_rcp_f32_e32 v21, v21
	s_nop 0
	v_fma_f32 v21, v21, -2.0, 1.0
	v_add_f32_e32 v21, 1.0, v21
	v_mul_f32_e32 v21, v22, v21
	v_mul_f32_e32 v22, 0x3d372713, v23
	v_mul_f32_e32 v22, v23, v22
	v_fma_f32 v22, v23, v22, v23
	v_mul_f32_e32 v22, 0x3f4c422a, v22
	v_add_f32_e32 v22, v22, v22
	v_mul_f32_e32 v22, 0x3fb8aa3b, v22
	v_exp_f32_e32 v22, v22
	v_mul_f32_e32 v23, 0.5, v23
	v_add_f32_e32 v22, 1.0, v22
	v_rcp_f32_e32 v22, v22
	s_nop 0
	v_fma_f32 v22, v22, -2.0, 1.0
	v_add_f32_e32 v22, 1.0, v22
	v_mul_f32_e32 v22, v23, v22
	v_cvt_pk_bf16_f32 v21, v21, v22
	v_mul_f32_e32 v22, 0x3d372713, v16
	v_mul_f32_e32 v22, v16, v22
	v_fma_f32 v22, v16, v22, v16
	v_mul_f32_e32 v22, 0x3f4c422a, v22
	v_add_f32_e32 v22, v22, v22
	v_mul_f32_e32 v22, 0x3fb8aa3b, v22
	v_exp_f32_e32 v22, v22
	v_mul_f32_e32 v16, 0.5, v16
	v_add_f32_e32 v22, 1.0, v22
	v_rcp_f32_e32 v22, v22
	s_nop 0
	v_fma_f32 v22, v22, -2.0, 1.0
	v_add_f32_e32 v22, 1.0, v22
	v_mul_f32_e32 v16, v16, v22
	v_mul_f32_e32 v22, 0x3d372713, v17
	v_mul_f32_e32 v22, v17, v22
	v_fma_f32 v22, v17, v22, v17
	v_mul_f32_e32 v22, 0x3f4c422a, v22
	v_add_f32_e32 v22, v22, v22
	v_mul_f32_e32 v22, 0x3fb8aa3b, v22
	v_exp_f32_e32 v22, v22
	v_mul_f32_e32 v17, 0.5, v17
	v_add_f32_e32 v22, 1.0, v22
	v_rcp_f32_e32 v22, v22
	s_nop 0
	v_fma_f32 v22, v22, -2.0, 1.0
	v_add_f32_e32 v22, 1.0, v22
	v_mul_f32_e32 v17, v17, v22
	v_cvt_pk_bf16_f32 v22, v16, v17
	v_mul_f32_e32 v16, 0x3d372713, v18
	v_mul_f32_e32 v16, v18, v16
	v_fma_f32 v16, v18, v16, v18
	v_mul_f32_e32 v16, 0x3f4c422a, v16
	v_add_f32_e32 v16, v16, v16
	v_mul_f32_e32 v16, 0x3fb8aa3b, v16
	v_exp_f32_e32 v16, v16
	v_mul_f32_e32 v17, 0.5, v18
	v_mul_f32_e32 v18, 0.5, v19
	v_add_f32_e32 v16, 1.0, v16
	v_rcp_f32_e32 v16, v16
	s_nop 0
	v_fma_f32 v16, v16, -2.0, 1.0
	v_add_f32_e32 v16, 1.0, v16
	v_mul_f32_e32 v16, v17, v16
	v_mul_f32_e32 v17, 0x3d372713, v19
	v_mul_f32_e32 v17, v19, v17
	v_fma_f32 v17, v19, v17, v19
	v_mul_f32_e32 v17, 0x3f4c422a, v17
	v_add_f32_e32 v17, v17, v17
	v_mul_f32_e32 v17, 0x3fb8aa3b, v17
	v_exp_f32_e32 v17, v17
	s_nop 0
	v_add_f32_e32 v17, 1.0, v17
	v_rcp_f32_e32 v17, v17
	s_nop 0
	v_fma_f32 v17, v17, -2.0, 1.0
	v_add_f32_e32 v17, 1.0, v17
	v_mul_f32_e32 v17, v18, v17
	v_mul_f32_e32 v18, 0x3d372713, v12
	v_mul_f32_e32 v18, v12, v18
	v_fma_f32 v18, v12, v18, v12
	v_mul_f32_e32 v18, 0x3f4c422a, v18
	v_add_f32_e32 v18, v18, v18
	v_mul_f32_e32 v18, 0x3fb8aa3b, v18
	v_exp_f32_e32 v18, v18
	v_mul_f32_e32 v12, 0.5, v12
	v_cvt_pk_bf16_f32 v23, v16, v17
	global_store_dwordx4 v[24:25], v[20:23], off offset:256 sc1
	v_add_f32_e32 v18, 1.0, v18
	v_rcp_f32_e32 v18, v18
	v_or_b32_e32 v16, s6, v129
	v_ashrrev_i32_e32 v17, 31, v16
	v_lshlrev_b64 v[16:17], 10, v[16:17]
	v_fma_f32 v18, v18, -2.0, 1.0
	v_add_f32_e32 v18, 1.0, v18
	v_mul_f32_e32 v12, v12, v18
	v_mul_f32_e32 v18, 0x3d372713, v13
	v_mul_f32_e32 v18, v13, v18
	v_fma_f32 v18, v13, v18, v13
	v_mul_f32_e32 v18, 0x3f4c422a, v18
	v_add_f32_e32 v18, v18, v18
	v_mul_f32_e32 v18, 0x3fb8aa3b, v18
	v_exp_f32_e32 v18, v18
	v_mul_f32_e32 v13, 0.5, v13
	v_lshl_add_u64 v[16:17], s[4:5], 0, v[16:17]
	v_add_f32_e32 v18, 1.0, v18
	v_rcp_f32_e32 v18, v18
	s_nop 0
	v_fma_f32 v18, v18, -2.0, 1.0
	v_add_f32_e32 v18, 1.0, v18
	v_mul_f32_e32 v13, v13, v18
	v_cvt_pk_bf16_f32 v12, v12, v13
	v_mul_f32_e32 v13, 0x3d372713, v14
	v_mul_f32_e32 v13, v14, v13
	v_fma_f32 v13, v14, v13, v14
	v_mul_f32_e32 v13, 0x3f4c422a, v13
	v_add_f32_e32 v13, v13, v13
	v_mul_f32_e32 v13, 0x3fb8aa3b, v13
	v_exp_f32_e32 v13, v13
	v_mul_f32_e32 v14, 0.5, v14
	v_add_f32_e32 v13, 1.0, v13
	v_rcp_f32_e32 v13, v13
	s_nop 0
	v_fma_f32 v13, v13, -2.0, 1.0
	v_add_f32_e32 v13, 1.0, v13
	v_mul_f32_e32 v13, v14, v13
	v_mul_f32_e32 v14, 0x3d372713, v15
	v_mul_f32_e32 v14, v15, v14
	v_fma_f32 v14, v15, v14, v15
	v_mul_f32_e32 v14, 0x3f4c422a, v14
	v_add_f32_e32 v14, v14, v14
	v_mul_f32_e32 v14, 0x3fb8aa3b, v14
	v_exp_f32_e32 v14, v14
	v_mul_f32_e32 v15, 0.5, v15
	v_add_f32_e32 v14, 1.0, v14
	v_rcp_f32_e32 v14, v14
	s_nop 0
	v_fma_f32 v14, v14, -2.0, 1.0
	v_add_f32_e32 v14, 1.0, v14
	v_mul_f32_e32 v14, v15, v14
	v_cvt_pk_bf16_f32 v13, v13, v14
	v_mul_f32_e32 v14, 0x3d372713, v8
	v_mul_f32_e32 v14, v8, v14
	v_fma_f32 v14, v8, v14, v8
	v_mul_f32_e32 v14, 0x3f4c422a, v14
	v_add_f32_e32 v14, v14, v14
	v_mul_f32_e32 v14, 0x3fb8aa3b, v14
	v_exp_f32_e32 v14, v14
	v_mul_f32_e32 v8, 0.5, v8
	v_add_f32_e32 v14, 1.0, v14
	v_rcp_f32_e32 v14, v14
	s_nop 0
	v_fma_f32 v14, v14, -2.0, 1.0
	v_add_f32_e32 v14, 1.0, v14
	v_mul_f32_e32 v8, v8, v14
	v_mul_f32_e32 v14, 0x3d372713, v9
	v_mul_f32_e32 v14, v9, v14
	v_fma_f32 v14, v9, v14, v9
	v_mul_f32_e32 v14, 0x3f4c422a, v14
	v_add_f32_e32 v14, v14, v14
	v_mul_f32_e32 v14, 0x3fb8aa3b, v14
	v_exp_f32_e32 v14, v14
	v_mul_f32_e32 v9, 0.5, v9
	v_add_f32_e32 v14, 1.0, v14
	v_rcp_f32_e32 v14, v14
	s_nop 0
	v_fma_f32 v14, v14, -2.0, 1.0
	v_add_f32_e32 v14, 1.0, v14
	v_mul_f32_e32 v9, v9, v14
	v_cvt_pk_bf16_f32 v14, v8, v9
	v_mul_f32_e32 v8, 0x3d372713, v10
	v_mul_f32_e32 v8, v10, v8
	v_fma_f32 v8, v10, v8, v10
	v_mul_f32_e32 v8, 0x3f4c422a, v8
	v_add_f32_e32 v8, v8, v8
	v_mul_f32_e32 v8, 0x3fb8aa3b, v8
	v_exp_f32_e32 v8, v8
	v_mul_f32_e32 v9, 0.5, v10
	v_mul_f32_e32 v10, 0.5, v11
	v_add_f32_e32 v8, 1.0, v8
	v_rcp_f32_e32 v8, v8
	s_nop 0
	v_fma_f32 v8, v8, -2.0, 1.0
	v_add_f32_e32 v8, 1.0, v8
	v_mul_f32_e32 v8, v9, v8
	v_mul_f32_e32 v9, 0x3d372713, v11
	v_mul_f32_e32 v9, v11, v9
	v_fma_f32 v9, v11, v9, v11
	v_mul_f32_e32 v9, 0x3f4c422a, v9
	v_add_f32_e32 v9, v9, v9
	v_mul_f32_e32 v9, 0x3fb8aa3b, v9
	v_exp_f32_e32 v9, v9
	s_nop 0
	v_add_f32_e32 v9, 1.0, v9
	v_rcp_f32_e32 v9, v9
	s_nop 0
	v_fma_f32 v9, v9, -2.0, 1.0
	v_add_f32_e32 v9, 1.0, v9
	v_mul_f32_e32 v9, v10, v9
	v_mul_f32_e32 v10, 0x3d372713, v4
	v_mul_f32_e32 v10, v4, v10
	v_fma_f32 v10, v4, v10, v4
	v_mul_f32_e32 v10, 0x3f4c422a, v10
	v_add_f32_e32 v10, v10, v10
	v_mul_f32_e32 v10, 0x3fb8aa3b, v10
	v_exp_f32_e32 v10, v10
	v_mul_f32_e32 v4, 0.5, v4
	v_cvt_pk_bf16_f32 v15, v8, v9
	v_lshl_add_u64 v[8:9], v[16:17], 0, v[144:145]
	v_add_f32_e32 v10, 1.0, v10
	v_rcp_f32_e32 v10, v10
	global_store_dwordx4 v[8:9], v[12:15], off sc1
	v_fma_f32 v10, v10, -2.0, 1.0
	v_add_f32_e32 v10, 1.0, v10
	v_mul_f32_e32 v4, v4, v10
	v_mul_f32_e32 v10, 0x3d372713, v5
	v_mul_f32_e32 v10, v5, v10
	v_fma_f32 v10, v5, v10, v5
	v_mul_f32_e32 v10, 0x3f4c422a, v10
	v_add_f32_e32 v10, v10, v10
	v_mul_f32_e32 v10, 0x3fb8aa3b, v10
	v_exp_f32_e32 v10, v10
	v_mul_f32_e32 v5, 0.5, v5
	v_add_f32_e32 v10, 1.0, v10
	v_rcp_f32_e32 v10, v10
	s_nop 0
	v_fma_f32 v10, v10, -2.0, 1.0
	v_add_f32_e32 v10, 1.0, v10
	v_mul_f32_e32 v5, v5, v10
	v_cvt_pk_bf16_f32 v4, v4, v5
	v_mul_f32_e32 v5, 0x3d372713, v6
	v_mul_f32_e32 v5, v6, v5
	v_fma_f32 v5, v6, v5, v6
	v_mul_f32_e32 v5, 0x3f4c422a, v5
	v_add_f32_e32 v5, v5, v5
	v_mul_f32_e32 v5, 0x3fb8aa3b, v5
	v_exp_f32_e32 v5, v5
	v_mul_f32_e32 v6, 0.5, v6
	v_add_f32_e32 v5, 1.0, v5
	v_rcp_f32_e32 v5, v5
	s_nop 0
	v_fma_f32 v5, v5, -2.0, 1.0
	v_add_f32_e32 v5, 1.0, v5
	v_mul_f32_e32 v5, v6, v5
	v_mul_f32_e32 v6, 0x3d372713, v7
	v_mul_f32_e32 v6, v7, v6
	v_fma_f32 v6, v7, v6, v7
	v_mul_f32_e32 v6, 0x3f4c422a, v6
	v_add_f32_e32 v6, v6, v6
	v_mul_f32_e32 v6, 0x3fb8aa3b, v6
	v_exp_f32_e32 v6, v6
	v_mul_f32_e32 v7, 0.5, v7
	v_add_f32_e32 v6, 1.0, v6
	v_rcp_f32_e32 v6, v6
	s_nop 0
	v_fma_f32 v6, v6, -2.0, 1.0
	v_add_f32_e32 v6, 1.0, v6
	v_mul_f32_e32 v6, v7, v6
	v_cvt_pk_bf16_f32 v5, v5, v6
	v_mul_f32_e32 v6, 0x3d372713, v0
	v_mul_f32_e32 v6, v0, v6
	v_fma_f32 v6, v0, v6, v0
	v_mul_f32_e32 v6, 0x3f4c422a, v6
	v_add_f32_e32 v6, v6, v6
	v_mul_f32_e32 v6, 0x3fb8aa3b, v6
	v_exp_f32_e32 v6, v6
	v_mul_f32_e32 v0, 0.5, v0
	v_add_f32_e32 v6, 1.0, v6
	v_rcp_f32_e32 v6, v6
	s_nop 0
	v_fma_f32 v6, v6, -2.0, 1.0
	v_add_f32_e32 v6, 1.0, v6
	v_mul_f32_e32 v0, v0, v6
	v_mul_f32_e32 v6, 0x3d372713, v1
	v_mul_f32_e32 v6, v1, v6
	v_fma_f32 v6, v1, v6, v1
	v_mul_f32_e32 v6, 0x3f4c422a, v6
	v_add_f32_e32 v6, v6, v6
	v_mul_f32_e32 v6, 0x3fb8aa3b, v6
	v_exp_f32_e32 v6, v6
	v_mul_f32_e32 v1, 0.5, v1
	v_add_f32_e32 v6, 1.0, v6
	v_rcp_f32_e32 v6, v6
	s_nop 0
	v_fma_f32 v6, v6, -2.0, 1.0
	v_add_f32_e32 v6, 1.0, v6
	v_mul_f32_e32 v1, v1, v6
	v_cvt_pk_bf16_f32 v6, v0, v1
	v_mul_f32_e32 v0, 0x3d372713, v2
	v_mul_f32_e32 v0, v2, v0
	v_fma_f32 v0, v2, v0, v2
	v_mul_f32_e32 v0, 0x3f4c422a, v0
	v_add_f32_e32 v0, v0, v0
	v_mul_f32_e32 v0, 0x3fb8aa3b, v0
	v_exp_f32_e32 v0, v0
	v_mul_f32_e32 v1, 0.5, v2
	v_mul_f32_e32 v2, 0.5, v3
	v_add_f32_e32 v0, 1.0, v0
	v_rcp_f32_e32 v0, v0
	s_nop 0
	v_fma_f32 v0, v0, -2.0, 1.0
	v_add_f32_e32 v0, 1.0, v0
	v_mul_f32_e32 v0, v1, v0
	v_mul_f32_e32 v1, 0x3d372713, v3
	v_mul_f32_e32 v1, v3, v1
	v_fma_f32 v1, v3, v1, v3
	v_mul_f32_e32 v1, 0x3f4c422a, v1
	v_add_f32_e32 v1, v1, v1
	v_mul_f32_e32 v1, 0x3fb8aa3b, v1
	v_exp_f32_e32 v1, v1
	s_nop 0
	v_add_f32_e32 v1, 1.0, v1
	v_rcp_f32_e32 v1, v1
	s_nop 0
	v_fma_f32 v1, v1, -2.0, 1.0
	v_add_f32_e32 v1, 1.0, v1
	v_mul_f32_e32 v1, v2, v1
	v_cvt_pk_bf16_f32 v7, v0, v1
	global_store_dwordx4 v[8:9], v[4:7], off offset:256 sc1
	s_waitcnt vmcnt(0)
	s_barrier

.LBB0_1019:
	s_or_b64 exec, exec, s[6:7]
	v_readfirstlane_b32 s19, v0
	s_cmp_gt_u32 s19, 7
	s_cselect_b64 s[6:7], -1, 0
	s_and_b64 vcc, exec, s[6:7]
	s_cbranch_vccnz .LBB0_1014
	s_load_dwordx2 s[8:9], s[56:57], 0x98
	s_load_dwordx2 s[14:15], s[56:57], 0x88
	s_load_dwordx2 s[12:13], s[56:57], 0x78
	s_lshr_b32 s20, s19, 1
	v_readlane_b32 s22, v255, 23
	s_waitcnt lgkmcnt(0)
	s_add_u32 s16, s8, 0x4000000
	s_addc_u32 s17, s9, 0
	v_readlane_b32 s23, v255, 24
	s_add_u32 s14, s14, s22
	s_mov_b32 s11, s39
	v_lshl_add_u64 v[0:1], s[16:17], 0, v[80:81]
	s_addc_u32 s15, s15, s23
	s_lshl_b32 s10, s20, 7
	v_lshl_add_u64 v[4:5], v[0:1], 0, s[10:11]
	v_lshl_add_u64 v[0:1], s[16:17], 0, v[82:83]
	v_lshl_add_u64 v[16:17], v[0:1], 0, s[10:11]
	global_load_dwordx4 v[74:77], v[4:5], off offset:528
	global_load_dwordx4 v[86:89], v[4:5], off offset:576
	global_load_dwordx4 v[20:23], v[4:5], off offset:624
	global_load_dwordx4 v[24:27], v[4:5], off offset:608
	global_load_dwordx4 v[90:93], v[4:5], off offset:592
	global_load_dwordx4 v[94:97], v[16:17], off offset:528
	global_load_dwordx4 v[8:11], v[4:5], off offset:560
	global_load_dwordx4 v[12:15], v[16:17], off offset:560
	global_load_dwordx4 v[98:101], v[16:17], off offset:576
	global_load_dwordx4 v[28:31], v[16:17], off offset:624
	global_load_dwordx4 v[44:47], v[16:17], off offset:608
	global_load_dwordx4 v[102:105], v[16:17], off offset:592
	global_load_dwordx4 v[0:3], v[4:5], off offset:512
	global_load_dwordx4 v[108:111], v[4:5], off offset:544
	s_nop 0
	global_load_dwordx4 v[4:7], v[16:17], off offset:512
	global_load_dwordx4 v[132:135], v[16:17], off offset:544
	s_lshl_b32 s18, s20, 15
	v_readlane_b32 s21, v255, 16
	s_lshl_b32 s19, s19, 6
	s_or_b32 s18, s18, s21
	s_lshl_b32 s38, s20, 6
	s_and_b32 s19, s19, 64
	s_add_u32 s20, s8, s18
	s_addc_u32 s21, s9, 0
	s_add_u32 s16, s16, s10
	s_addc_u32 s17, s17, 0
	s_waitcnt vmcnt(10)
	v_lshlrev_b32_e32 v56, 16, v94
	v_lshlrev_b32_e32 v57, 16, v74
	v_lshlrev_b32_e32 v115, 16, v88
	v_lshlrev_b32_e32 v49, 16, v23
	v_lshlrev_b32_e32 v48, 16, v22
	v_and_b32_e32 v51, 0xffff0000, v23
	v_and_b32_e32 v50, 0xffff0000, v22
	v_lshlrev_b32_e32 v53, 16, v21
	v_lshlrev_b32_e32 v52, 16, v20
	v_and_b32_e32 v55, 0xffff0000, v21
	v_and_b32_e32 v54, 0xffff0000, v20
	v_lshlrev_b32_e32 v63, 16, v27
	v_lshlrev_b32_e32 v62, 16, v26
	v_and_b32_e32 v65, 0xffff0000, v27
	v_and_b32_e32 v64, 0xffff0000, v26
	v_lshlrev_b32_e32 v67, 16, v25
	v_lshlrev_b32_e32 v66, 16, v24
	v_and_b32_e32 v69, 0xffff0000, v25
	v_and_b32_e32 v68, 0xffff0000, v24
	s_waitcnt vmcnt(6)
	v_lshlrev_b32_e32 v21, 16, v31
	v_lshlrev_b32_e32 v20, 16, v30
	v_and_b32_e32 v23, 0xffff0000, v31
	v_and_b32_e32 v22, 0xffff0000, v30
	v_lshlrev_b32_e32 v25, 16, v29
	v_lshlrev_b32_e32 v24, 16, v28
	v_and_b32_e32 v27, 0xffff0000, v29
	v_and_b32_e32 v26, 0xffff0000, v28
	s_waitcnt vmcnt(5)
	v_lshlrev_b32_e32 v29, 16, v47
	v_lshlrev_b32_e32 v28, 16, v46
	v_and_b32_e32 v31, 0xffff0000, v47
	v_and_b32_e32 v30, 0xffff0000, v46
	v_lshlrev_b32_e32 v71, 16, v93
	v_lshlrev_b32_e32 v70, 16, v92
	v_and_b32_e32 v73, 0xffff0000, v93
	v_and_b32_e32 v72, 0xffff0000, v92
	v_pk_add_f32 v[92:93], v[62:63], v[64:65]
	v_pk_add_f32 v[136:137], v[28:29], v[30:31]
	v_and_b32_e32 v117, 0xffff0000, v88
	v_mov_b32_e32 v88, v137
	v_mov_b32_e32 v137, v92
	s_waitcnt vmcnt(1)
	v_and_b32_e32 v92, 0xffff0000, v7
	v_lshlrev_b32_e32 v190, 16, v7
	v_lshlrev_b32_e32 v7, 16, v1
	v_and_b32_e32 v205, 0xffff0000, v1
	v_lshlrev_b32_e32 v207, 16, v0
	v_lshlrev_b32_e32 v206, 16, v4
	v_and_b32_e32 v1, 0xffff0000, v0
	v_and_b32_e32 v0, 0xffff0000, v4
	v_lshlrev_b32_e32 v119, 16, v89
	v_and_b32_e32 v121, 0xffff0000, v89
	v_mov_b32_e32 v89, v93
	v_and_b32_e32 v93, 0xffff0000, v3
	v_lshlrev_b32_e32 v191, 16, v3
	v_and_b32_e32 v193, 0xffff0000, v2
	v_and_b32_e32 v192, 0xffff0000, v6
	v_lshlrev_b32_e32 v3, 16, v2
	v_lshlrev_b32_e32 v2, 16, v6
	v_lshlrev_b32_e32 v6, 16, v5
	v_and_b32_e32 v204, 0xffff0000, v5
	v_pk_add_f32 v[210:211], v[206:207], v[0:1]
	v_pk_add_f32 v[208:209], v[6:7], v[204:205]
	v_pk_add_f32 v[210:211], v[210:211], 0 op_sel_hi:[1,0]
	v_pk_add_f32 v[164:165], v[2:3], v[192:193]
	v_pk_add_f32 v[208:209], v[208:209], v[210:211]
	v_and_b32_e32 v61, 0xffff0000, v74
	v_and_b32_e32 v60, 0xffff0000, v94
	v_pk_add_f32 v[162:163], v[190:191], v[92:93]
	v_pk_add_f32 v[164:165], v[164:165], v[208:209]
	v_lshlrev_b32_e32 v35, 16, v75
	v_and_b32_e32 v33, 0xffff0000, v75
	v_lshlrev_b32_e32 v34, 16, v95
	v_and_b32_e32 v32, 0xffff0000, v95
	v_lshlrev_b32_e32 v37, 16, v45
	v_lshlrev_b32_e32 v36, 16, v44
	v_and_b32_e32 v39, 0xffff0000, v45
	v_and_b32_e32 v38, 0xffff0000, v44
	v_lshlrev_b32_e32 v45, 16, v105
	v_lshlrev_b32_e32 v44, 16, v104
	v_and_b32_e32 v47, 0xffff0000, v105
	v_and_b32_e32 v46, 0xffff0000, v104
	v_pk_add_f32 v[74:75], v[48:49], v[50:51]
	v_pk_add_f32 v[94:95], v[20:21], v[22:23]
	v_pk_add_f32 v[104:105], v[24:25], v[26:27]
	v_pk_add_f32 v[4:5], v[56:57], v[60:61]
	v_pk_add_f32 v[162:163], v[162:163], v[164:165]
	v_lshlrev_b32_e32 v18, 16, v98
	v_and_b32_e32 v16, 0xffff0000, v98
	v_pk_add_f32 v[78:79], v[52:53], v[54:55]
	v_lshlrev_b32_e32 v58, 16, v99
	v_and_b32_e32 v112, 0xffff0000, v99
	v_lshlrev_b32_e32 v123, 16, v90
	v_lshlrev_b32_e32 v122, 16, v102
	v_and_b32_e32 v125, 0xffff0000, v90
	v_and_b32_e32 v124, 0xffff0000, v102
	v_lshlrev_b32_e32 v126, 16, v103
	v_and_b32_e32 v130, 0xffff0000, v103
	v_mov_b32_e32 v90, v104
	v_mov_b32_e32 v98, v94
	v_mov_b32_e32 v99, v74
	v_mov_b32_e32 v74, v95
	v_lshlrev_b32_e32 v95, 16, v76
	v_lshlrev_b32_e32 v94, 16, v96
	v_and_b32_e32 v103, 0xffff0000, v76
	v_and_b32_e32 v102, 0xffff0000, v96
	v_lshlrev_b32_e32 v104, 16, v97
	v_and_b32_e32 v76, 0xffff0000, v97
	v_lshlrev_b32_e32 v97, 16, v108
	s_waitcnt vmcnt(0)
	v_lshlrev_b32_e32 v96, 16, v132
	v_and_b32_e32 v171, 0xffff0000, v108
	v_and_b32_e32 v170, 0xffff0000, v132
	v_lshlrev_b32_e32 v172, 16, v133
	v_and_b32_e32 v108, 0xffff0000, v133
	v_pk_add_f32 v[132:133], v[34:35], v[32:33]
	v_pk_add_f32 v[4:5], v[4:5], v[162:163]
	v_lshlrev_b32_e32 v127, 16, v91
	v_and_b32_e32 v131, 0xffff0000, v91
	v_mov_b32_e32 v91, v78
	v_mov_b32_e32 v78, v105
	v_lshlrev_b32_e32 v105, 16, v77
	v_and_b32_e32 v77, 0xffff0000, v77
	v_pk_add_f32 v[210:211], v[94:95], v[102:103]
	v_pk_add_f32 v[4:5], v[132:133], v[4:5]
	v_pk_add_f32 v[212:213], v[104:105], v[76:77]
	v_pk_add_f32 v[4:5], v[210:211], v[4:5]
	v_lshlrev_b32_e32 v173, 16, v109
	v_and_b32_e32 v109, 0xffff0000, v109
	v_pk_add_f32 v[214:215], v[96:97], v[170:171]
	v_pk_add_f32 v[4:5], v[212:213], v[4:5]
	v_lshlrev_b32_e32 v175, 16, v110
	v_lshlrev_b32_e32 v174, 16, v134
	v_and_b32_e32 v177, 0xffff0000, v110
	v_and_b32_e32 v176, 0xffff0000, v134
	v_pk_add_f32 v[216:217], v[172:173], v[108:109]
	v_pk_add_f32 v[4:5], v[214:215], v[4:5]
	v_lshlrev_b32_e32 v179, 16, v111
	v_lshlrev_b32_e32 v178, 16, v135
	v_and_b32_e32 v111, 0xffff0000, v111
	v_and_b32_e32 v110, 0xffff0000, v135
	v_pk_add_f32 v[218:219], v[174:175], v[176:177]
	v_pk_add_f32 v[4:5], v[216:217], v[4:5]
	v_lshlrev_b32_e32 v40, 16, v15
	v_and_b32_e32 v42, 0xffff0000, v15
	v_lshlrev_b32_e32 v118, 16, v101
	v_and_b32_e32 v120, 0xffff0000, v101
	v_and_b32_e32 v15, 0xffff0000, v9
	v_lshlrev_b32_e32 v101, 16, v9
	v_lshlrev_b32_e32 v181, 16, v8
	v_lshlrev_b32_e32 v180, 16, v12
	v_and_b32_e32 v9, 0xffff0000, v8
	v_and_b32_e32 v8, 0xffff0000, v12
	v_pk_add_f32 v[220:221], v[178:179], v[110:111]
	v_pk_add_f32 v[4:5], v[218:219], v[4:5]
	v_lshlrev_b32_e32 v41, 16, v11
	v_and_b32_e32 v43, 0xffff0000, v11
	v_lshlrev_b32_e32 v114, 16, v100
	v_and_b32_e32 v116, 0xffff0000, v100
	v_and_b32_e32 v107, 0xffff0000, v10
	v_and_b32_e32 v106, 0xffff0000, v14
	v_lshlrev_b32_e32 v11, 16, v10
	v_lshlrev_b32_e32 v10, 16, v14
	v_and_b32_e32 v14, 0xffff0000, v13
	v_lshlrev_b32_e32 v100, 16, v13
	v_pk_add_f32 v[222:223], v[180:181], v[8:9]
	v_pk_add_f32 v[4:5], v[220:221], v[4:5]
	v_mov_b32_e32 v12, v36
	v_mov_b32_e32 v13, v66
	v_mov_b32_e32 v134, v38
	v_mov_b32_e32 v135, v68
	v_pk_add_f32 v[208:209], v[100:101], v[14:15]
	v_pk_add_f32 v[4:5], v[222:223], v[4:5]
	v_pk_add_f32 v[12:13], v[12:13], v[134:135]
	v_mov_b32_e32 v134, v37
	v_mov_b32_e32 v135, v67
	v_mov_b32_e32 v138, v39
	v_mov_b32_e32 v139, v69
	v_pk_add_f32 v[164:165], v[10:11], v[106:107]
	v_pk_add_f32 v[4:5], v[208:209], v[4:5]
	v_lshlrev_b32_e32 v19, 16, v86
	v_and_b32_e32 v17, 0xffff0000, v86
	v_pk_add_f32 v[134:135], v[134:135], v[138:139]
	v_mov_b32_e32 v138, v44
	v_mov_b32_e32 v139, v70
	v_mov_b32_e32 v140, v46
	v_mov_b32_e32 v141, v72
	v_pk_add_f32 v[162:163], v[40:41], v[42:43]
	v_pk_add_f32 v[4:5], v[164:165], v[4:5]
	v_lshlrev_b32_e32 v59, 16, v87
	v_and_b32_e32 v113, 0xffff0000, v87
	v_pk_add_f32 v[86:87], v[18:19], v[16:17]
	v_pk_add_f32 v[138:139], v[138:139], v[140:141]
	v_mov_b32_e32 v140, v45
	v_mov_b32_e32 v141, v71
	v_mov_b32_e32 v142, v47
	v_mov_b32_e32 v143, v73
	v_pk_add_f32 v[4:5], v[162:163], v[4:5]
	v_pk_add_f32 v[140:141], v[140:141], v[142:143]
	v_pk_add_f32 v[142:143], v[58:59], v[112:113]
	v_pk_add_f32 v[4:5], v[86:87], v[4:5]
	v_pk_add_f32 v[154:155], v[114:115], v[116:117]
	v_pk_add_f32 v[4:5], v[142:143], v[4:5]
	v_pk_add_f32 v[156:157], v[118:119], v[120:121]
	v_pk_add_f32 v[4:5], v[154:155], v[4:5]
	v_pk_add_f32 v[158:159], v[122:123], v[124:125]
	v_pk_add_f32 v[4:5], v[156:157], v[4:5]
	v_pk_add_f32 v[160:161], v[126:127], v[130:131]
	v_pk_add_f32 v[4:5], v[158:159], v[4:5]
	s_nop 0
	v_pk_add_f32 v[4:5], v[160:161], v[4:5]
	s_nop 0
	v_pk_add_f32 v[4:5], v[138:139], v[4:5]
	s_nop 0
	v_pk_add_f32 v[4:5], v[140:141], v[4:5]
	s_nop 0
	v_pk_add_f32 v[4:5], v[12:13], v[4:5]
	s_nop 0
	v_pk_add_f32 v[4:5], v[134:135], v[4:5]
	s_nop 0
	v_pk_add_f32 v[4:5], v[136:137], v[4:5]
	s_nop 0
	v_pk_add_f32 v[4:5], v[88:89], v[4:5]
	s_nop 0
	v_pk_add_f32 v[4:5], v[90:91], v[4:5]
	s_nop 0
	v_pk_add_f32 v[4:5], v[78:79], v[4:5]
	s_nop 0
	v_pk_add_f32 v[4:5], v[98:99], v[4:5]
	s_nop 0
	v_pk_add_f32 v[4:5], v[74:75], v[4:5]
	s_nop 0
	v_pk_mul_f32 v[208:209], v[4:5], s[66:67] op_sel_hi:[1,0]
	v_pk_fma_f32 v[134:135], v[4:5], s[66:67], v[0:1] op_sel_hi:[1,0,1] neg_lo:[1,0,0] neg_hi:[1,0,0]
	v_pk_add_f32 v[138:139], v[50:51], v[208:209] op_sel:[0,1] neg_lo:[0,1] neg_hi:[0,1]
	v_pk_fma_f32 v[50:51], v[4:5], s[66:67], v[204:205] op_sel_hi:[1,0,1] neg_lo:[1,0,0] neg_hi:[1,0,0]
	v_pk_add_f32 v[142:143], v[54:55], v[208:209] op_sel:[0,1] neg_lo:[0,1] neg_hi:[0,1]
	v_pk_add_f32 v[136:137], v[48:49], v[208:209] op_sel:[0,1] neg_lo:[0,1] neg_hi:[0,1]
	v_pk_fma_f32 v[132:133], v[4:5], s[66:67], v[206:207] op_sel_hi:[1,0,1] neg_lo:[1,0,0] neg_hi:[1,0,0]
	v_pk_mul_f32 v[0:1], v[134:135], v[134:135]
	v_pk_fma_f32 v[48:49], v[4:5], s[66:67], v[6:7] op_sel_hi:[1,0,1] neg_lo:[1,0,0] neg_hi:[1,0,0]
	v_pk_mul_f32 v[6:7], v[50:51], v[50:51]
	v_pk_fma_f32 v[54:55], v[4:5], s[66:67], v[192:193] op_sel_hi:[1,0,1] neg_lo:[1,0,0] neg_hi:[1,0,0]
	v_pk_add_f32 v[140:141], v[52:53], v[208:209] op_sel:[0,1] neg_lo:[0,1] neg_hi:[0,1]
	v_pk_fma_f32 v[0:1], v[132:133], v[132:133], v[0:1]
	v_pk_fma_f32 v[6:7], v[48:49], v[48:49], v[6:7]
	v_pk_fma_f32 v[52:53], v[4:5], s[66:67], v[2:3] op_sel_hi:[1,0,1] neg_lo:[1,0,0] neg_hi:[1,0,0]
	v_pk_mul_f32 v[2:3], v[54:55], v[54:55]
	v_pk_add_f32 v[156:157], v[64:65], v[208:209] op_sel:[0,1] neg_lo:[0,1] neg_hi:[0,1]
	v_pk_add_f32 v[0:1], v[0:1], v[6:7]
	v_pk_fma_f32 v[2:3], v[52:53], v[52:53], v[2:3]
	v_pk_fma_f32 v[64:65], v[4:5], s[66:67], v[92:93] op_sel_hi:[1,0,1] neg_lo:[1,0,0] neg_hi:[1,0,0]
	v_pk_add_f32 v[154:155], v[62:63], v[208:209] op_sel:[0,1] neg_lo:[0,1] neg_hi:[0,1]
	v_pk_add_f32 v[0:1], v[2:3], v[0:1]
	v_pk_fma_f32 v[62:63], v[4:5], s[66:67], v[190:191] op_sel_hi:[1,0,1] neg_lo:[1,0,0] neg_hi:[1,0,0]
	v_pk_mul_f32 v[2:3], v[64:65], v[64:65]
	v_pk_fma_f32 v[60:61], v[4:5], s[66:67], v[60:61] op_sel_hi:[1,0,1] neg_lo:[1,0,0] neg_hi:[1,0,0]
	v_pk_fma_f32 v[2:3], v[62:63], v[62:63], v[2:3]
	v_pk_fma_f32 v[56:57], v[4:5], s[66:67], v[56:57] op_sel_hi:[1,0,1] neg_lo:[1,0,0] neg_hi:[1,0,0]
	v_pk_add_f32 v[0:1], v[2:3], v[0:1]
	v_pk_mul_f32 v[2:3], v[60:61], v[60:61]
	v_pk_fma_f32 v[32:33], v[4:5], s[66:67], v[32:33] op_sel_hi:[1,0,1] neg_lo:[1,0,0] neg_hi:[1,0,0]
	v_pk_fma_f32 v[2:3], v[56:57], v[56:57], v[2:3]
	v_pk_fma_f32 v[34:35], v[4:5], s[66:67], v[34:35] op_sel_hi:[1,0,1] neg_lo:[1,0,0] neg_hi:[1,0,0]
	v_pk_add_f32 v[0:1], v[2:3], v[0:1]
	v_pk_mul_f32 v[2:3], v[32:33], v[32:33]
	v_pk_add_f32 v[160:161], v[68:69], v[208:209] op_sel:[0,1] neg_lo:[0,1] neg_hi:[0,1]
	v_pk_fma_f32 v[2:3], v[34:35], v[34:35], v[2:3]
	v_pk_fma_f32 v[68:69], v[4:5], s[66:67], v[102:103] op_sel_hi:[1,0,1] neg_lo:[1,0,0] neg_hi:[1,0,0]
	v_pk_add_f32 v[158:159], v[66:67], v[208:209] op_sel:[0,1] neg_lo:[0,1] neg_hi:[0,1]
	v_pk_add_f32 v[0:1], v[2:3], v[0:1]
	v_pk_fma_f32 v[66:67], v[4:5], s[66:67], v[94:95] op_sel_hi:[1,0,1] neg_lo:[1,0,0] neg_hi:[1,0,0]
	v_pk_mul_f32 v[2:3], v[68:69], v[68:69]
	v_pk_add_f32 v[164:165], v[72:73], v[208:209] op_sel:[0,1] neg_lo:[0,1] neg_hi:[0,1]
	v_pk_fma_f32 v[2:3], v[66:67], v[66:67], v[2:3]
	v_pk_fma_f32 v[72:73], v[4:5], s[66:67], v[76:77] op_sel_hi:[1,0,1] neg_lo:[1,0,0] neg_hi:[1,0,0]
	v_pk_add_f32 v[162:163], v[70:71], v[208:209] op_sel:[0,1] neg_lo:[0,1] neg_hi:[0,1]
	v_pk_add_f32 v[0:1], v[2:3], v[0:1]
	v_pk_fma_f32 v[70:71], v[4:5], s[66:67], v[104:105] op_sel_hi:[1,0,1] neg_lo:[1,0,0] neg_hi:[1,0,0]
	v_pk_mul_f32 v[2:3], v[72:73], v[72:73]
	v_pk_fma_f32 v[76:77], v[4:5], s[66:67], v[170:171] op_sel_hi:[1,0,1] neg_lo:[1,0,0] neg_hi:[1,0,0]
	v_pk_fma_f32 v[2:3], v[70:71], v[70:71], v[2:3]
	v_pk_fma_f32 v[74:75], v[4:5], s[66:67], v[96:97] op_sel_hi:[1,0,1] neg_lo:[1,0,0] neg_hi:[1,0,0]
	v_pk_add_f32 v[0:1], v[2:3], v[0:1]
	v_pk_mul_f32 v[2:3], v[76:77], v[76:77]
	v_pk_fma_f32 v[86:87], v[4:5], s[66:67], v[108:109] op_sel_hi:[1,0,1] neg_lo:[1,0,0] neg_hi:[1,0,0]
	v_pk_fma_f32 v[2:3], v[74:75], v[74:75], v[2:3]
	v_pk_fma_f32 v[78:79], v[4:5], s[66:67], v[172:173] op_sel_hi:[1,0,1] neg_lo:[1,0,0] neg_hi:[1,0,0]
	v_pk_add_f32 v[0:1], v[2:3], v[0:1]
	v_pk_mul_f32 v[2:3], v[86:87], v[86:87]
	v_pk_fma_f32 v[90:91], v[4:5], s[66:67], v[176:177] op_sel_hi:[1,0,1] neg_lo:[1,0,0] neg_hi:[1,0,0]
	v_pk_fma_f32 v[2:3], v[78:79], v[78:79], v[2:3]
	v_pk_fma_f32 v[88:89], v[4:5], s[66:67], v[174:175] op_sel_hi:[1,0,1] neg_lo:[1,0,0] neg_hi:[1,0,0]
	v_pk_add_f32 v[0:1], v[2:3], v[0:1]
	v_pk_mul_f32 v[2:3], v[90:91], v[90:91]
	v_pk_fma_f32 v[94:95], v[4:5], s[66:67], v[110:111] op_sel_hi:[1,0,1] neg_lo:[1,0,0] neg_hi:[1,0,0]
	v_pk_fma_f32 v[2:3], v[88:89], v[88:89], v[2:3]
	v_pk_fma_f32 v[92:93], v[4:5], s[66:67], v[178:179] op_sel_hi:[1,0,1] neg_lo:[1,0,0] neg_hi:[1,0,0]
	v_pk_add_f32 v[0:1], v[2:3], v[0:1]
	v_pk_mul_f32 v[2:3], v[94:95], v[94:95]
	v_pk_fma_f32 v[98:99], v[4:5], s[66:67], v[8:9] op_sel_hi:[1,0,1] neg_lo:[1,0,0] neg_hi:[1,0,0]
	v_pk_fma_f32 v[2:3], v[92:93], v[92:93], v[2:3]
	v_pk_fma_f32 v[96:97], v[4:5], s[66:67], v[180:181] op_sel_hi:[1,0,1] neg_lo:[1,0,0] neg_hi:[1,0,0]
	v_pk_add_f32 v[0:1], v[2:3], v[0:1]
	v_pk_mul_f32 v[2:3], v[98:99], v[98:99]
	v_pk_fma_f32 v[102:103], v[4:5], s[66:67], v[14:15] op_sel_hi:[1,0,1] neg_lo:[1,0,0] neg_hi:[1,0,0]
	v_pk_fma_f32 v[2:3], v[96:97], v[96:97], v[2:3]
	v_pk_fma_f32 v[100:101], v[4:5], s[66:67], v[100:101] op_sel_hi:[1,0,1] neg_lo:[1,0,0] neg_hi:[1,0,0]
	v_pk_add_f32 v[0:1], v[2:3], v[0:1]
	v_pk_mul_f32 v[2:3], v[102:103], v[102:103]
	v_pk_fma_f32 v[106:107], v[4:5], s[66:67], v[106:107] op_sel_hi:[1,0,1] neg_lo:[1,0,0] neg_hi:[1,0,0]
	v_pk_fma_f32 v[2:3], v[100:101], v[100:101], v[2:3]
	v_pk_fma_f32 v[104:105], v[4:5], s[66:67], v[10:11] op_sel_hi:[1,0,1] neg_lo:[1,0,0] neg_hi:[1,0,0]
	v_pk_add_f32 v[0:1], v[2:3], v[0:1]
	v_pk_mul_f32 v[2:3], v[106:107], v[106:107]
	v_pk_fma_f32 v[42:43], v[4:5], s[66:67], v[42:43] op_sel_hi:[1,0,1] neg_lo:[1,0,0] neg_hi:[1,0,0]
	v_pk_fma_f32 v[2:3], v[104:105], v[104:105], v[2:3]
	v_pk_fma_f32 v[40:41], v[4:5], s[66:67], v[40:41] op_sel_hi:[1,0,1] neg_lo:[1,0,0] neg_hi:[1,0,0]
	v_pk_add_f32 v[0:1], v[2:3], v[0:1]
	v_pk_mul_f32 v[2:3], v[42:43], v[42:43]
	v_pk_fma_f32 v[110:111], v[4:5], s[66:67], v[16:17] op_sel_hi:[1,0,1] neg_lo:[1,0,0] neg_hi:[1,0,0]
	v_pk_fma_f32 v[2:3], v[40:41], v[40:41], v[2:3]
	v_pk_fma_f32 v[108:109], v[4:5], s[66:67], v[18:19] op_sel_hi:[1,0,1] neg_lo:[1,0,0] neg_hi:[1,0,0]
	v_pk_add_f32 v[0:1], v[2:3], v[0:1]
	v_pk_mul_f32 v[2:3], v[110:111], v[110:111]
	v_pk_fma_f32 v[112:113], v[4:5], s[66:67], v[112:113] op_sel_hi:[1,0,1] neg_lo:[1,0,0] neg_hi:[1,0,0]
	v_pk_fma_f32 v[2:3], v[108:109], v[108:109], v[2:3]
	v_pk_fma_f32 v[58:59], v[4:5], s[66:67], v[58:59] op_sel_hi:[1,0,1] neg_lo:[1,0,0] neg_hi:[1,0,0]
	v_pk_add_f32 v[0:1], v[2:3], v[0:1]
	v_pk_mul_f32 v[2:3], v[112:113], v[112:113]
	v_pk_fma_f32 v[116:117], v[4:5], s[66:67], v[116:117] op_sel_hi:[1,0,1] neg_lo:[1,0,0] neg_hi:[1,0,0]
	v_pk_fma_f32 v[2:3], v[58:59], v[58:59], v[2:3]
	v_pk_fma_f32 v[114:115], v[4:5], s[66:67], v[114:115] op_sel_hi:[1,0,1] neg_lo:[1,0,0] neg_hi:[1,0,0]
	v_pk_add_f32 v[0:1], v[2:3], v[0:1]
	v_pk_mul_f32 v[2:3], v[116:117], v[116:117]
	v_pk_fma_f32 v[120:121], v[4:5], s[66:67], v[120:121] op_sel_hi:[1,0,1] neg_lo:[1,0,0] neg_hi:[1,0,0]
	v_pk_fma_f32 v[2:3], v[114:115], v[114:115], v[2:3]
	v_pk_fma_f32 v[118:119], v[4:5], s[66:67], v[118:119] op_sel_hi:[1,0,1] neg_lo:[1,0,0] neg_hi:[1,0,0]
	v_pk_add_f32 v[0:1], v[2:3], v[0:1]
	v_pk_mul_f32 v[2:3], v[120:121], v[120:121]
	v_pk_fma_f32 v[124:125], v[4:5], s[66:67], v[124:125] op_sel_hi:[1,0,1] neg_lo:[1,0,0] neg_hi:[1,0,0]
	v_pk_fma_f32 v[2:3], v[118:119], v[118:119], v[2:3]
	v_pk_fma_f32 v[122:123], v[4:5], s[66:67], v[122:123] op_sel_hi:[1,0,1] neg_lo:[1,0,0] neg_hi:[1,0,0]
	v_pk_add_f32 v[0:1], v[2:3], v[0:1]
	v_pk_mul_f32 v[2:3], v[124:125], v[124:125]
	v_pk_fma_f32 v[130:131], v[4:5], s[66:67], v[130:131] op_sel_hi:[1,0,1] neg_lo:[1,0,0] neg_hi:[1,0,0]
	v_pk_fma_f32 v[2:3], v[122:123], v[122:123], v[2:3]
	v_pk_mul_f32 v[12:13], v[164:165], v[164:165]
	v_pk_add_f32 v[0:1], v[2:3], v[0:1]
	v_pk_fma_f32 v[126:127], v[4:5], s[66:67], v[126:127] op_sel_hi:[1,0,1] neg_lo:[1,0,0] neg_hi:[1,0,0]
	v_pk_mul_f32 v[2:3], v[130:131], v[130:131]
	v_pk_fma_f32 v[210:211], v[162:163], v[162:163], v[12:13]
	v_pk_mul_f32 v[12:13], v[160:161], v[160:161]
	v_pk_fma_f32 v[2:3], v[126:127], v[126:127], v[2:3]
	v_pk_add_f32 v[18:19], v[46:47], v[208:209] op_sel_hi:[1,0] neg_lo:[0,1] neg_hi:[0,1]
	v_pk_fma_f32 v[212:213], v[158:159], v[158:159], v[12:13]
	v_pk_mul_f32 v[12:13], v[156:157], v[156:157]
	v_pk_add_f32 v[0:1], v[2:3], v[0:1]
	v_pk_add_f32 v[16:17], v[44:45], v[208:209] op_sel_hi:[1,0] neg_lo:[0,1] neg_hi:[0,1]
	v_pk_mul_f32 v[2:3], v[18:19], v[18:19]
	v_pk_fma_f32 v[214:215], v[154:155], v[154:155], v[12:13]
	v_pk_mul_f32 v[12:13], v[142:143], v[142:143]
	v_pk_fma_f32 v[44:45], v[16:17], v[16:17], v[2:3]
	v_pk_fma_f32 v[216:217], v[140:141], v[140:141], v[12:13]
	v_pk_mul_f32 v[12:13], v[138:139], v[138:139]
	v_mov_b32_e32 v2, v44
	v_mov_b32_e32 v3, v210
	v_pk_add_f32 v[14:15], v[38:39], v[208:209] op_sel_hi:[1,0] neg_lo:[0,1] neg_hi:[0,1]
	v_pk_fma_f32 v[218:219], v[136:137], v[136:137], v[12:13]
	v_pk_add_f32 v[46:47], v[2:3], v[0:1]
	v_pk_add_f32 v[12:13], v[36:37], v[208:209] op_sel_hi:[1,0] neg_lo:[0,1] neg_hi:[0,1]
	v_pk_mul_f32 v[0:1], v[14:15], v[14:15]
	v_pk_add_f32 v[10:11], v[30:31], v[208:209] op_sel_hi:[1,0] neg_lo:[0,1] neg_hi:[0,1]
	v_pk_fma_f32 v[36:37], v[12:13], v[12:13], v[0:1]
	v_mov_b32_e32 v210, v45
	v_pk_add_f32 v[8:9], v[28:29], v[208:209] op_sel_hi:[1,0] neg_lo:[0,1] neg_hi:[0,1]
	v_pk_mul_f32 v[0:1], v[10:11], v[10:11]
	v_pk_add_f32 v[6:7], v[26:27], v[208:209] op_sel_hi:[1,0] neg_lo:[0,1] neg_hi:[0,1]
	v_pk_add_f32 v[2:3], v[22:23], v[208:209] op_sel_hi:[1,0] neg_lo:[0,1] neg_hi:[0,1]
	v_pk_add_f32 v[22:23], v[210:211], v[46:47]
	v_mov_b32_e32 v26, v36
	v_mov_b32_e32 v27, v212
	v_pk_fma_f32 v[28:29], v[8:9], v[8:9], v[0:1]
	v_pk_add_f32 v[22:23], v[26:27], v[22:23]
	v_mov_b32_e32 v212, v37
	v_pk_add_f32 v[4:5], v[24:25], v[208:209] op_sel_hi:[1,0] neg_lo:[0,1] neg_hi:[0,1]
	v_pk_mul_f32 v[0:1], v[6:7], v[6:7]
	v_pk_add_f32 v[22:23], v[212:213], v[22:23]
	v_mov_b32_e32 v26, v28
	v_mov_b32_e32 v27, v214
	v_pk_fma_f32 v[24:25], v[4:5], v[4:5], v[0:1]
	v_pk_add_f32 v[22:23], v[26:27], v[22:23]
	v_mov_b32_e32 v214, v29
	v_pk_add_f32 v[0:1], v[20:21], v[208:209] op_sel_hi:[1,0] neg_lo:[0,1] neg_hi:[0,1]
	v_pk_mul_f32 v[20:21], v[2:3], v[2:3]
	v_pk_add_f32 v[22:23], v[214:215], v[22:23]
	v_mov_b32_e32 v26, v24
	v_mov_b32_e32 v27, v216
	v_pk_fma_f32 v[20:21], v[0:1], v[0:1], v[20:21]
	v_pk_add_f32 v[22:23], v[26:27], v[22:23]
	v_mov_b32_e32 v216, v25
	v_pk_add_f32 v[22:23], v[216:217], v[22:23]
	v_mov_b32_e32 v24, v20
	v_mov_b32_e32 v25, v218
	v_pk_add_f32 v[22:23], v[24:25], v[22:23]
	v_mov_b32_e32 v218, v21
	v_pk_add_f32 v[20:21], v[218:219], v[22:23]
	s_nop 0
	v_pk_fma_f32 v[20:21], v[20:21], s[66:67], v[146:147] op_sel_hi:[1,0,0]
	s_nop 0
	v_mul_f32_e32 v22, 0x4b800000, v21
	v_cmp_gt_f32_e32 vcc, s72, v21
	s_nop 1
	v_cndmask_b32_e32 v21, v21, v22, vcc
	v_rsq_f32_e32 v21, v21
	s_nop 0
	v_mul_f32_e32 v22, 0x45800000, v21
	v_cndmask_b32_e32 v21, v21, v22, vcc
	v_mul_f32_e32 v22, v133, v21
	v_mul_f32_e32 v23, v135, v21
	v_cvt_pk_bf16_f32 v22, v22, v23
	ds_write_b16 v129, v22
	ds_write_b16_d16_hi v129, v22 offset:272
	v_mul_f32_e32 v22, v49, v21
	v_mul_f32_e32 v23, v51, v21
	v_cvt_pk_bf16_f32 v22, v22, v23
	ds_write_b16 v129, v22 offset:544
	ds_write_b16_d16_hi v129, v22 offset:816
	v_mul_f32_e32 v22, v53, v21
	v_mul_f32_e32 v23, v55, v21
	v_cvt_pk_bf16_f32 v22, v22, v23
	ds_write_b16 v129, v22 offset:1088
	ds_write_b16_d16_hi v129, v22 offset:1360
	v_mul_f32_e32 v22, v63, v21
	v_mul_f32_e32 v23, v65, v21
	v_cvt_pk_bf16_f32 v22, v22, v23
	ds_write_b16 v129, v22 offset:1632
	ds_write_b16_d16_hi v129, v22 offset:1904
	v_mul_f32_e32 v22, v57, v21
	v_mul_f32_e32 v23, v61, v21
	v_cvt_pk_bf16_f32 v22, v22, v23
	ds_write_b16 v129, v22 offset:2176
	ds_write_b16_d16_hi v129, v22 offset:2448
	v_mul_f32_e32 v22, v35, v21
	v_mul_f32_e32 v23, v33, v21
	v_cvt_pk_bf16_f32 v22, v22, v23
	ds_write_b16 v129, v22 offset:2720
	ds_write_b16_d16_hi v129, v22 offset:2992
	v_mul_f32_e32 v22, v67, v21
	v_mul_f32_e32 v23, v69, v21
	v_cvt_pk_bf16_f32 v22, v22, v23
	ds_write_b16 v129, v22 offset:3264
	ds_write_b16_d16_hi v129, v22 offset:3536
	v_mul_f32_e32 v22, v71, v21
	v_mul_f32_e32 v23, v73, v21
	v_cvt_pk_bf16_f32 v22, v22, v23
	ds_write_b16 v129, v22 offset:3808
	ds_write_b16_d16_hi v129, v22 offset:4080
	v_mul_f32_e32 v22, v75, v21
	v_mul_f32_e32 v23, v77, v21
	v_cvt_pk_bf16_f32 v22, v22, v23
	ds_write_b16 v129, v22 offset:4352
	ds_write_b16_d16_hi v129, v22 offset:4624
	v_mul_f32_e32 v22, v79, v21
	v_mul_f32_e32 v23, v87, v21
	v_cvt_pk_bf16_f32 v22, v22, v23
	ds_write_b16 v129, v22 offset:4896
	ds_write_b16_d16_hi v129, v22 offset:5168
	v_mul_f32_e32 v22, v89, v21
	v_mul_f32_e32 v23, v91, v21
	v_cvt_pk_bf16_f32 v22, v22, v23
	ds_write_b16 v129, v22 offset:5440
	ds_write_b16_d16_hi v129, v22 offset:5712
	v_mul_f32_e32 v22, v93, v21
	v_mul_f32_e32 v23, v95, v21
	v_cvt_pk_bf16_f32 v22, v22, v23
	ds_write_b16 v129, v22 offset:5984
	ds_write_b16_d16_hi v129, v22 offset:6256
	v_mul_f32_e32 v22, v97, v21
	v_mul_f32_e32 v23, v99, v21
	v_cvt_pk_bf16_f32 v22, v22, v23
	ds_write_b16 v129, v22 offset:6528
	ds_write_b16_d16_hi v129, v22 offset:6800
	v_mul_f32_e32 v22, v101, v21
	v_mul_f32_e32 v23, v103, v21
	v_cvt_pk_bf16_f32 v22, v22, v23
	ds_write_b16 v129, v22 offset:7072
	ds_write_b16_d16_hi v129, v22 offset:7344
	v_mul_f32_e32 v22, v105, v21
	v_mul_f32_e32 v23, v107, v21
	v_cvt_pk_bf16_f32 v22, v22, v23
	ds_write_b16 v129, v22 offset:7616
	ds_write_b16_d16_hi v129, v22 offset:7888
	v_mul_f32_e32 v22, v41, v21
	v_mul_f32_e32 v23, v43, v21
	v_cvt_pk_bf16_f32 v22, v22, v23
	ds_write_b16 v129, v22 offset:8160
	ds_write_b16_d16_hi v129, v22 offset:8432
	v_mul_f32_e32 v22, v109, v21
	v_mul_f32_e32 v23, v111, v21
	v_cvt_pk_bf16_f32 v22, v22, v23
	ds_write_b16 v129, v22 offset:8704
	ds_write_b16_d16_hi v129, v22 offset:8976
	v_mul_f32_e32 v22, v59, v21
	v_mul_f32_e32 v23, v113, v21
	v_cvt_pk_bf16_f32 v22, v22, v23
	ds_write_b16 v129, v22 offset:9248
	ds_write_b16_d16_hi v129, v22 offset:9520
	v_mul_f32_e32 v22, v115, v21
	v_mul_f32_e32 v23, v117, v21
	v_cvt_pk_bf16_f32 v22, v22, v23
	ds_write_b16 v129, v22 offset:9792
	ds_write_b16_d16_hi v129, v22 offset:10064
	v_mul_f32_e32 v22, v119, v21
	v_mul_f32_e32 v23, v121, v21
	v_cvt_pk_bf16_f32 v22, v22, v23
	ds_write_b16 v129, v22 offset:10336
	ds_write_b16_d16_hi v129, v22 offset:10608
	v_mul_f32_e32 v22, v123, v21
	v_mul_f32_e32 v23, v125, v21
	v_cvt_pk_bf16_f32 v22, v22, v23
	ds_write_b16 v129, v22 offset:10880
	ds_write_b16_d16_hi v129, v22 offset:11152
	v_mul_f32_e32 v22, v127, v21
	v_mul_f32_e32 v23, v131, v21
	v_cvt_pk_bf16_f32 v22, v22, v23
	ds_write_b16 v129, v22 offset:11424
	ds_write_b16_d16_hi v129, v22 offset:11696
	v_mul_f32_e32 v22, v162, v21
	v_mul_f32_e32 v23, v164, v21
	v_cvt_pk_bf16_f32 v22, v22, v23
	ds_write_b16 v129, v22 offset:11968
	ds_write_b16_d16_hi v129, v22 offset:12240
	v_mul_f32_e32 v22, v163, v21
	v_mul_f32_e32 v23, v165, v21
	v_cvt_pk_bf16_f32 v22, v22, v23
	ds_write_b16 v129, v22 offset:12512
	ds_write_b16_d16_hi v129, v22 offset:12784
	v_mul_f32_e32 v22, v158, v21
	v_mul_f32_e32 v23, v160, v21
	v_cvt_pk_bf16_f32 v22, v22, v23
	ds_write_b16 v129, v22 offset:13056
	ds_write_b16_d16_hi v129, v22 offset:13328
	v_mul_f32_e32 v22, v159, v21
	v_mul_f32_e32 v23, v161, v21
	v_cvt_pk_bf16_f32 v22, v22, v23
	ds_write_b16 v129, v22 offset:13600
	ds_write_b16_d16_hi v129, v22 offset:13872
	v_mul_f32_e32 v22, v154, v21
	v_mul_f32_e32 v23, v156, v21
	v_cvt_pk_bf16_f32 v22, v22, v23
	ds_write_b16 v129, v22 offset:14144
	ds_write_b16_d16_hi v129, v22 offset:14416
	v_mul_f32_e32 v22, v155, v21
	v_mul_f32_e32 v23, v157, v21
	v_cvt_pk_bf16_f32 v22, v22, v23
	ds_write_b16 v129, v22 offset:14688
	ds_write_b16_d16_hi v129, v22 offset:14960
	v_mul_f32_e32 v22, v140, v21
	v_mul_f32_e32 v23, v142, v21
	v_cvt_pk_bf16_f32 v22, v22, v23
	ds_write_b16 v129, v22 offset:15232
	ds_write_b16_d16_hi v129, v22 offset:15504
	v_mul_f32_e32 v22, v141, v21
	v_mul_f32_e32 v23, v143, v21
	v_cvt_pk_bf16_f32 v22, v22, v23
	ds_write_b16 v129, v22 offset:15776
	ds_write_b16_d16_hi v129, v22 offset:16048
	v_mul_f32_e32 v22, v136, v21
	v_mul_f32_e32 v23, v138, v21
	v_cvt_pk_bf16_f32 v22, v22, v23
	v_mul_f32_e32 v23, 0x4b800000, v20
	v_cmp_gt_f32_e32 vcc, s72, v20
	ds_write_b16 v129, v22 offset:16320
	ds_write_b16_d16_hi v129, v22 offset:16592
	v_cndmask_b32_e32 v20, v20, v23, vcc
	v_rsq_f32_e32 v20, v20
	v_mul_f32_e32 v22, v137, v21
	v_mul_f32_e32 v21, v139, v21
	v_cvt_pk_bf16_f32 v21, v22, v21
	ds_write_b16 v129, v21 offset:16864
	ds_write_b16_d16_hi v129, v21 offset:17136
	v_mul_f32_e32 v21, 0x45800000, v20
	v_cndmask_b32_e32 v20, v20, v21, vcc
	v_mul_f32_e32 v21, v132, v20
	v_mul_f32_e32 v22, v134, v20
	v_cvt_pk_bf16_f32 v21, v21, v22
	ds_write_b16 v129, v21 offset:128
	ds_write_b16_d16_hi v129, v21 offset:400
	v_mul_f32_e32 v21, v48, v20
	v_mul_f32_e32 v22, v50, v20
	v_cvt_pk_bf16_f32 v21, v21, v22
	ds_write_b16 v129, v21 offset:672
	ds_write_b16_d16_hi v129, v21 offset:944
	v_mul_f32_e32 v21, v52, v20
	v_mul_f32_e32 v22, v54, v20
	v_cvt_pk_bf16_f32 v21, v21, v22
	ds_write_b16 v129, v21 offset:1216
	ds_write_b16_d16_hi v129, v21 offset:1488
	v_mul_f32_e32 v21, v62, v20
	v_mul_f32_e32 v22, v64, v20
	v_cvt_pk_bf16_f32 v21, v21, v22
	ds_write_b16 v129, v21 offset:1760
	ds_write_b16_d16_hi v129, v21 offset:2032
	v_mul_f32_e32 v21, v56, v20
	v_mul_f32_e32 v22, v60, v20
	v_cvt_pk_bf16_f32 v21, v21, v22
	ds_write_b16 v129, v21 offset:2304
	ds_write_b16_d16_hi v129, v21 offset:2576
	v_mul_f32_e32 v21, v34, v20
	v_mul_f32_e32 v22, v32, v20
	v_cvt_pk_bf16_f32 v21, v21, v22
	ds_write_b16 v129, v21 offset:2848
	ds_write_b16_d16_hi v129, v21 offset:3120
	v_mul_f32_e32 v21, v66, v20
	v_mul_f32_e32 v22, v68, v20
	v_cvt_pk_bf16_f32 v21, v21, v22
	ds_write_b16 v129, v21 offset:3392
	ds_write_b16_d16_hi v129, v21 offset:3664
	v_mul_f32_e32 v21, v70, v20
	v_mul_f32_e32 v22, v72, v20
	v_cvt_pk_bf16_f32 v21, v21, v22
	ds_write_b16 v129, v21 offset:3936
	ds_write_b16_d16_hi v129, v21 offset:4208
	v_mul_f32_e32 v21, v74, v20
	v_mul_f32_e32 v22, v76, v20
	v_cvt_pk_bf16_f32 v21, v21, v22
	ds_write_b16 v129, v21 offset:4480
	ds_write_b16_d16_hi v129, v21 offset:4752
	v_mul_f32_e32 v21, v78, v20
	v_mul_f32_e32 v22, v86, v20
	v_cvt_pk_bf16_f32 v21, v21, v22
	ds_write_b16 v129, v21 offset:5024
	ds_write_b16_d16_hi v129, v21 offset:5296
	v_mul_f32_e32 v21, v88, v20
	v_mul_f32_e32 v22, v90, v20
	v_cvt_pk_bf16_f32 v21, v21, v22
	ds_write_b16 v129, v21 offset:5568
	ds_write_b16_d16_hi v129, v21 offset:5840
	v_mul_f32_e32 v21, v92, v20
	v_mul_f32_e32 v22, v94, v20
	v_cvt_pk_bf16_f32 v21, v21, v22
	ds_write_b16 v129, v21 offset:6112
	ds_write_b16_d16_hi v129, v21 offset:6384
	v_mul_f32_e32 v21, v96, v20
	v_mul_f32_e32 v22, v98, v20
	v_cvt_pk_bf16_f32 v21, v21, v22
	ds_write_b16 v129, v21 offset:6656
	ds_write_b16_d16_hi v129, v21 offset:6928
	v_mul_f32_e32 v21, v100, v20
	v_mul_f32_e32 v22, v102, v20
	v_cvt_pk_bf16_f32 v21, v21, v22
	ds_write_b16 v129, v21 offset:7200
	ds_write_b16_d16_hi v129, v21 offset:7472
	v_mul_f32_e32 v21, v104, v20
	v_mul_f32_e32 v22, v106, v20
	v_cvt_pk_bf16_f32 v21, v21, v22
	ds_write_b16 v129, v21 offset:7744
	ds_write_b16_d16_hi v129, v21 offset:8016
	v_mul_f32_e32 v21, v40, v20
	v_mul_f32_e32 v22, v42, v20
	v_cvt_pk_bf16_f32 v21, v21, v22
	ds_write_b16 v129, v21 offset:8288
	ds_write_b16_d16_hi v129, v21 offset:8560
	v_mul_f32_e32 v21, v108, v20
	v_mul_f32_e32 v22, v110, v20
	v_cvt_pk_bf16_f32 v21, v21, v22
	ds_write_b16 v129, v21 offset:8832
	ds_write_b16_d16_hi v129, v21 offset:9104
	v_mul_f32_e32 v21, v58, v20
	v_mul_f32_e32 v22, v112, v20
	v_cvt_pk_bf16_f32 v21, v21, v22
	ds_write_b16 v129, v21 offset:9376
	ds_write_b16_d16_hi v129, v21 offset:9648
	v_mul_f32_e32 v21, v114, v20
	v_mul_f32_e32 v22, v116, v20
	v_cvt_pk_bf16_f32 v21, v21, v22
	ds_write_b16 v129, v21 offset:9920
	ds_write_b16_d16_hi v129, v21 offset:10192
	v_mul_f32_e32 v21, v118, v20
	v_mul_f32_e32 v22, v120, v20
	v_cvt_pk_bf16_f32 v21, v21, v22
	ds_write_b16 v129, v21 offset:10464
	ds_write_b16_d16_hi v129, v21 offset:10736
	v_mul_f32_e32 v21, v122, v20
	v_mul_f32_e32 v22, v124, v20
	v_cvt_pk_bf16_f32 v21, v21, v22
	ds_write_b16 v129, v21 offset:11008
	ds_write_b16_d16_hi v129, v21 offset:11280
	v_mul_f32_e32 v21, v126, v20
	v_mul_f32_e32 v22, v130, v20
	v_cvt_pk_bf16_f32 v21, v21, v22
	v_mul_f32_e32 v16, v16, v20
	ds_write_b16 v129, v21 offset:11552
	ds_write_b16_d16_hi v129, v21 offset:11824
	v_mul_f32_e32 v18, v18, v20
	v_cvt_pk_bf16_f32 v16, v16, v18
	ds_write_b16 v129, v16 offset:12096
	ds_write_b16_d16_hi v129, v16 offset:12368
	v_mul_f32_e32 v16, v17, v20
	v_mul_f32_e32 v17, v19, v20
	v_cvt_pk_bf16_f32 v16, v16, v17
	v_mul_f32_e32 v12, v12, v20
	ds_write_b16 v129, v16 offset:12640
	ds_write_b16_d16_hi v129, v16 offset:12912
	v_mul_f32_e32 v14, v14, v20
	v_cvt_pk_bf16_f32 v12, v12, v14
	ds_write_b16 v129, v12 offset:13184
	ds_write_b16_d16_hi v129, v12 offset:13456
	v_mul_f32_e32 v12, v13, v20
	v_mul_f32_e32 v13, v15, v20
	v_cvt_pk_bf16_f32 v12, v12, v13
	v_mul_f32_e32 v8, v8, v20
	ds_write_b16 v129, v12 offset:13728
	ds_write_b16_d16_hi v129, v12 offset:14000
	v_mul_f32_e32 v10, v10, v20
	v_cvt_pk_bf16_f32 v8, v8, v10
	ds_write_b16 v129, v8 offset:14272
	ds_write_b16_d16_hi v129, v8 offset:14544
	v_mul_f32_e32 v8, v9, v20
	v_mul_f32_e32 v9, v11, v20
	v_cvt_pk_bf16_f32 v8, v8, v9
	v_mul_f32_e32 v4, v4, v20
	ds_write_b16 v129, v8 offset:14816
	ds_write_b16_d16_hi v129, v8 offset:15088
	v_mul_f32_e32 v6, v6, v20
	v_cvt_pk_bf16_f32 v4, v4, v6
	ds_write_b16 v129, v4 offset:15360
	ds_write_b16_d16_hi v129, v4 offset:15632
	v_mul_f32_e32 v4, v5, v20
	v_mul_f32_e32 v5, v7, v20
	v_cvt_pk_bf16_f32 v4, v4, v5
	v_mul_f32_e32 v0, v0, v20
	ds_write_b16 v129, v4 offset:15904
	ds_write_b16_d16_hi v129, v4 offset:16176
	v_mul_f32_e32 v2, v2, v20
	v_cvt_pk_bf16_f32 v0, v0, v2
	ds_write_b16 v129, v0 offset:16448
	ds_write_b16_d16_hi v129, v0 offset:16720
	v_mul_f32_e32 v0, v1, v20
	v_mul_f32_e32 v1, v3, v20
	v_cvt_pk_bf16_f32 v0, v0, v1
	ds_write_b16 v129, v0 offset:16992
	ds_write_b16_d16_hi v129, v0 offset:17264
	v_lshl_add_u64 v[0:1], s[20:21], 0, v[144:145]
	s_mov_b64 s[20:21], 0xf00000
	v_or_b32_e32 v2, s19, v85
	s_waitcnt lgkmcnt(0)
	v_lshl_add_u64 v[0:1], v[0:1], 0, s[20:21]
	v_lshlrev_b32_e32 v2, 8, v2
	v_mov_b32_e32 v3, v145
	v_lshl_add_u64 v[2:3], v[0:1], 0, v[2:3]
	global_load_dwordx4 v[76:79], v[2:3], off
	global_load_dwordx4 v[72:75], v[2:3], off offset:64
	global_load_dwordx4 v[68:71], v[2:3], off offset:128
	global_load_dwordx4 v[64:67], v[2:3], off offset:192
	v_or_b32_e32 v4, s10, v85
	v_or_b32_e32 v88, s19, v167
	v_lshlrev_b32_e32 v86, 1, v84
	v_mov_b32_e32 v87, v145
	v_ashrrev_i32_e32 v89, 31, v88
	v_or_b32_e32 v4, s19, v4
	v_mov_b32_e32 v5, v145
	v_lshl_add_u64 v[90:91], s[16:17], 0, v[86:87]
	v_lshlrev_b64 v[2:3], 10, v[88:89]
	v_lshl_add_u64 v[126:127], v[4:5], 2, s[14:15]
	s_or_b32 s14, s19, 16
	s_or_b32 s15, s19, 32
	s_or_b32 s16, s19, 48
	v_readlane_b32 s18, v255, 25
	v_lshl_add_u64 v[2:3], v[90:91], 0, v[2:3]
	v_readlane_b32 s19, v255, 26
	s_add_u32 s17, s12, s18
	global_load_dwordx2 v[124:125], v[2:3], off
	global_load_dword v140, v[126:127], off
	s_addc_u32 s18, s13, s19
	s_lshl_b64 s[12:13], s[38:39], 2
	s_add_u32 s12, s17, s12
	s_addc_u32 s13, s18, s13
	v_lshlrev_b32_e32 v138, 2, v84
	global_load_dwordx4 v[28:31], v138, s[12:13]
	global_load_dwordx2 v[130:131], v[2:3], off offset:32
	global_load_dwordx2 v[132:133], v[2:3], off offset:64
	global_load_dwordx2 v[134:135], v[2:3], off offset:96
	v_or_b32_e32 v2, s14, v85
	v_lshlrev_b32_e32 v2, 8, v2
	v_mov_b32_e32 v3, v145
	v_lshl_add_u64 v[2:3], v[0:1], 0, v[2:3]
	global_load_dwordx4 v[60:63], v[2:3], off
	global_load_dwordx4 v[56:59], v[2:3], off offset:64
	global_load_dwordx4 v[52:55], v[2:3], off offset:128
	global_load_dwordx4 v[48:51], v[2:3], off offset:192
	v_or_b32_e32 v2, s14, v167
	v_ashrrev_i32_e32 v3, 31, v2
	v_lshlrev_b64 v[2:3], 10, v[2:3]
	v_lshl_add_u64 v[2:3], v[90:91], 0, v[2:3]
	global_load_dwordx2 v[136:137], v[2:3], off
	global_load_dwordx2 v[110:111], v[2:3], off offset:32
	global_load_dwordx2 v[108:109], v[2:3], off offset:64
	global_load_dwordx2 v[106:107], v[2:3], off offset:96
	v_or_b32_e32 v2, s15, v85
	v_lshlrev_b32_e32 v2, 8, v2
	v_mov_b32_e32 v3, v145
	v_lshl_add_u64 v[2:3], v[0:1], 0, v[2:3]
	global_load_dwordx4 v[44:47], v[2:3], off
	global_load_dwordx4 v[40:43], v[2:3], off offset:64
	global_load_dwordx4 v[36:39], v[2:3], off offset:128
	global_load_dwordx4 v[32:35], v[2:3], off offset:192
	global_load_dwordx4 v[20:23], v138, s[12:13] offset:64
	v_or_b32_e32 v2, s15, v167
	v_ashrrev_i32_e32 v3, 31, v2
	v_lshlrev_b64 v[2:3], 10, v[2:3]
	v_lshl_add_u64 v[2:3], v[90:91], 0, v[2:3]
	global_load_dwordx2 v[104:105], v[2:3], off
	global_load_dwordx2 v[102:103], v[2:3], off offset:32
	global_load_dwordx2 v[100:101], v[2:3], off offset:64
	global_load_dwordx2 v[98:99], v[2:3], off offset:96
	ds_read_b128 v[12:15], v168
	v_or_b32_e32 v2, s16, v85
	v_lshlrev_b32_e32 v2, 8, v2
	v_mov_b32_e32 v3, v145
	v_lshl_add_u64 v[0:1], v[0:1], 0, v[2:3]
	global_load_dwordx4 v[16:19], v[0:1], off
	global_load_dwordx4 v[8:11], v[0:1], off offset:64
	ds_read_b128 v[24:27], v168 offset:64
	global_load_dwordx4 v[4:7], v[0:1], off offset:128
	s_nop 0
	global_load_dwordx4 v[0:3], v[0:1], off offset:192
	ds_read_b128 v[112:115], v168 offset:128
	ds_read_b128 v[116:119], v168 offset:192
	s_waitcnt vmcnt(30) lgkmcnt(3)
	v_mfma_f32_16x16x32_bf16 v[12:15], v[12:15], v[76:79], 0
	v_or_b32_e32 v92, s16, v167
	v_ashrrev_i32_e32 v93, 31, v92
	v_lshlrev_b64 v[92:93], 10, v[92:93]
	s_waitcnt vmcnt(29) lgkmcnt(2)
	v_mfma_f32_16x16x32_bf16 v[12:15], v[24:27], v[72:75], v[12:15]
	v_lshl_add_u64 v[90:91], v[90:91], 0, v[92:93]
	global_load_dwordx2 v[96:97], v[90:91], off
	global_load_dwordx2 v[94:95], v[90:91], off offset:32
	global_load_dwordx2 v[92:93], v[90:91], off offset:64
	s_nop 0
	global_load_dwordx2 v[90:91], v[90:91], off offset:96
	s_mov_b64 s[14:15], 0x4800600
	s_waitcnt vmcnt(32) lgkmcnt(1)
	v_mfma_f32_16x16x32_bf16 v[120:123], v[112:115], v[68:71], v[12:15]
	global_load_dword v113, v[126:127], off offset:64
	global_load_dword v141, v[126:127], off offset:128
	global_load_dword v112, v[126:127], off offset:192
	global_load_dwordx4 v[24:27], v138, s[12:13] offset:128
	global_load_dwordx4 v[12:15], v138, s[12:13] offset:192
	v_lshlrev_b64 v[138:139], 11, v[88:89]
	v_lshl_add_u64 v[138:139], s[8:9], 0, v[138:139]
	s_waitcnt vmcnt(36) lgkmcnt(0)
	v_mfma_f32_16x16x32_bf16 v[114:117], v[116:119], v[64:67], v[120:123]
	v_lshl_add_u64 v[138:139], v[138:139], 0, s[10:11]
	v_lshl_add_u64 v[138:139], v[138:139], 0, v[86:87]
	s_mov_b32 s12, 0x4800000
	s_waitcnt vmcnt(35)
	v_lshlrev_b32_e32 v118, 16, v124
	v_and_b32_e32 v119, 0xffff0000, v124
	v_lshlrev_b32_e32 v120, 16, v125
	v_and_b32_e32 v121, 0xffff0000, v125
	s_waitcnt vmcnt(33)
	v_fma_f32 v114, v28, v114, v140
	v_fma_f32 v115, v29, v115, v140
	v_mul_f32_e32 v114, v114, v118
	v_mul_f32_e32 v115, v115, v119
	v_cvt_pk_bf16_f32 v126, v114, v115
	v_fma_f32 v114, v30, v116, v140
	v_fma_f32 v115, v31, v117, v140
	v_mul_f32_e32 v114, v114, v120
	v_mul_f32_e32 v115, v115, v121
	v_cvt_pk_bf16_f32 v127, v114, v115
	ds_read_b128 v[114:117], v168 offset:4352
	ds_read_b128 v[118:121], v168 offset:4416
	s_waitcnt lgkmcnt(1)
	v_mfma_f32_16x16x32_bf16 v[114:117], v[114:117], v[76:79], 0
	ds_read_b128 v[122:125], v168 offset:4480
	s_waitcnt vmcnt(32)
	v_lshlrev_b32_e32 v89, 16, v130
	s_waitcnt lgkmcnt(1)
	v_mfma_f32_16x16x32_bf16 v[114:117], v[118:121], v[72:75], v[114:117]
	ds_read_b128 v[118:121], v168 offset:4544
	s_waitcnt lgkmcnt(1)
	v_mfma_f32_16x16x32_bf16 v[114:117], v[122:125], v[68:71], v[114:117]
	v_add_co_u32_e32 v122, vcc, s12, v138
	s_waitcnt lgkmcnt(0)
	v_mfma_f32_16x16x32_bf16 v[114:117], v[118:121], v[64:67], v[114:117]
	v_and_b32_e32 v118, 0xffff0000, v130
	v_addc_co_u32_e32 v123, vcc, 0, v139, vcc
	global_store_dwordx2 v[122:123], v[126:127], off offset:1536 sc1
	v_and_b32_e32 v120, 0xffff0000, v131
	s_waitcnt vmcnt(18)
	s_nop 2
	v_fma_f32 v114, v20, v114, v140
	v_mul_f32_e32 v89, v114, v89
	v_fma_f32 v114, v21, v115, v140
	v_mul_f32_e32 v114, v114, v118
	v_cvt_pk_bf16_f32 v126, v89, v114
	v_fma_f32 v114, v23, v117, v140
	v_lshlrev_b32_e32 v119, 16, v131
	v_fma_f32 v89, v22, v116, v140
	v_mul_f32_e32 v114, v114, v120
	v_mul_f32_e32 v89, v89, v119
	v_cvt_pk_bf16_f32 v127, v89, v114
	ds_read_b128 v[114:117], v168 offset:8704
	ds_read_b128 v[118:121], v168 offset:8768
	s_waitcnt lgkmcnt(1)
	v_mfma_f32_16x16x32_bf16 v[114:117], v[114:117], v[76:79], 0
	ds_read_b128 v[122:125], v168 offset:8832
	v_lshlrev_b32_e32 v89, 16, v132
	s_waitcnt lgkmcnt(1)
	v_mfma_f32_16x16x32_bf16 v[114:117], v[118:121], v[72:75], v[114:117]
	ds_read_b128 v[118:121], v168 offset:8896
	s_waitcnt lgkmcnt(1)
	v_mfma_f32_16x16x32_bf16 v[114:117], v[122:125], v[68:71], v[114:117]
	v_lshl_add_u64 v[122:123], v[138:139], 0, s[14:15]
	global_store_dwordx2 v[122:123], v[126:127], off offset:32 sc1
	s_waitcnt lgkmcnt(0)
	v_mfma_f32_16x16x32_bf16 v[114:117], v[118:121], v[64:67], v[114:117]
	v_and_b32_e32 v118, 0xffff0000, v132
	v_and_b32_e32 v120, 0xffff0000, v133
	v_lshlrev_b32_e32 v119, 16, v133
	s_waitcnt vmcnt(3)
	s_nop 3
	v_fma_f32 v114, v24, v114, v140
	v_mul_f32_e32 v89, v114, v89
	v_fma_f32 v114, v25, v115, v140
	v_mul_f32_e32 v114, v114, v118
	v_cvt_pk_bf16_f32 v124, v89, v114
	v_fma_f32 v114, v27, v117, v140
	v_fma_f32 v89, v26, v116, v140
	v_mul_f32_e32 v114, v114, v120
	v_mul_f32_e32 v89, v89, v119
	v_cvt_pk_bf16_f32 v125, v89, v114
	ds_read_b128 v[114:117], v169
	ds_read_b128 v[118:121], v169 offset:64
	s_waitcnt lgkmcnt(1)
	v_mfma_f32_16x16x32_bf16 v[76:79], v[114:117], v[76:79], 0
	ds_read_b128 v[114:117], v169 offset:128
	global_store_dwordx2 v[122:123], v[124:125], off offset:64 sc1
	s_waitcnt lgkmcnt(1)
	v_mfma_f32_16x16x32_bf16 v[72:75], v[118:121], v[72:75], v[76:79]
	s_nop 3
	ds_read_b128 v[76:79], v169 offset:192
	s_waitcnt lgkmcnt(1)
	v_mfma_f32_16x16x32_bf16 v[68:71], v[114:117], v[68:71], v[72:75]
	s_waitcnt lgkmcnt(0)
	v_mfma_f32_16x16x32_bf16 v[64:67], v[76:79], v[64:67], v[68:71]
	s_nop 5
	v_lshlrev_b32_e32 v68, 16, v134
	v_and_b32_e32 v69, 0xffff0000, v134
	v_lshlrev_b32_e32 v70, 16, v135
	s_waitcnt vmcnt(3)
	v_fma_f32 v64, v12, v64, v140
	v_mul_f32_e32 v64, v64, v68
	v_fma_f32 v65, v13, v65, v140
	v_and_b32_e32 v71, 0xffff0000, v135
	v_mul_f32_e32 v65, v65, v69
	v_cvt_pk_bf16_f32 v76, v64, v65
	v_fma_f32 v64, v14, v66, v140
	v_fmac_f32_e32 v140, v15, v67
	v_mul_f32_e32 v64, v64, v70
	v_mul_f32_e32 v65, v140, v71
	v_cvt_pk_bf16_f32 v77, v64, v65
	ds_read_b128 v[64:67], v168
	ds_read_b128 v[68:71], v168 offset:64
	s_waitcnt lgkmcnt(1)
	v_mfma_f32_16x16x32_bf16 v[64:67], v[64:67], v[60:63], 0
	ds_read_b128 v[72:75], v168 offset:128
	global_store_dwordx2 v[122:123], v[76:77], off offset:96 sc1
	v_or_b32_e32 v78, 16, v88
	s_waitcnt lgkmcnt(1)
	v_mfma_f32_16x16x32_bf16 v[64:67], v[68:71], v[56:59], v[64:67]
	ds_read_b128 v[68:71], v168 offset:192
	v_ashrrev_i32_e32 v79, 31, v78
	v_lshlrev_b64 v[78:79], 11, v[78:79]
	s_waitcnt lgkmcnt(1)
	v_mfma_f32_16x16x32_bf16 v[64:67], v[72:75], v[52:55], v[64:67]
	v_lshl_add_u64 v[78:79], s[8:9], 0, v[78:79]
	v_lshl_add_u64 v[78:79], v[78:79], 0, s[10:11]
	v_lshl_add_u64 v[78:79], v[78:79], 0, v[86:87]
	s_waitcnt lgkmcnt(0)
	v_mfma_f32_16x16x32_bf16 v[64:67], v[68:71], v[48:51], v[64:67]
	v_lshlrev_b32_e32 v68, 16, v136
	v_and_b32_e32 v69, 0xffff0000, v136
	v_lshlrev_b32_e32 v70, 16, v137
	v_and_b32_e32 v71, 0xffff0000, v137
	s_nop 3
	v_fma_f32 v64, v28, v64, v113
	v_fma_f32 v65, v29, v65, v113
	v_mul_f32_e32 v64, v64, v68
	v_mul_f32_e32 v65, v65, v69
	v_cvt_pk_bf16_f32 v76, v64, v65
	v_fma_f32 v64, v30, v66, v113
	v_fma_f32 v65, v31, v67, v113
	v_mul_f32_e32 v64, v64, v70
	v_mul_f32_e32 v65, v65, v71
	v_cvt_pk_bf16_f32 v77, v64, v65
	ds_read_b128 v[64:67], v168 offset:4352
	ds_read_b128 v[68:71], v168 offset:4416
	ds_read_b128 v[72:75], v168 offset:4480
	s_waitcnt lgkmcnt(2)
	v_mfma_f32_16x16x32_bf16 v[64:67], v[64:67], v[60:63], 0
	s_waitcnt lgkmcnt(1)
	v_mfma_f32_16x16x32_bf16 v[64:67], v[68:71], v[56:59], v[64:67]
	ds_read_b128 v[68:71], v168 offset:4544
	s_waitcnt lgkmcnt(1)
	v_mfma_f32_16x16x32_bf16 v[64:67], v[72:75], v[52:55], v[64:67]
	v_add_co_u32_e32 v72, vcc, s12, v78
	s_waitcnt lgkmcnt(0)
	v_mfma_f32_16x16x32_bf16 v[64:67], v[68:71], v[48:51], v[64:67]
	v_lshlrev_b32_e32 v68, 16, v110
	v_and_b32_e32 v69, 0xffff0000, v110
	v_addc_co_u32_e32 v73, vcc, 0, v79, vcc
	s_nop 4
	v_fma_f32 v64, v20, v64, v113
	v_fma_f32 v65, v21, v65, v113
	v_mul_f32_e32 v64, v64, v68
	v_mul_f32_e32 v65, v65, v69
	global_store_dwordx2 v[72:73], v[76:77], off offset:1536 sc1
	v_lshlrev_b32_e32 v70, 16, v111
	v_and_b32_e32 v71, 0xffff0000, v111
	v_cvt_pk_bf16_f32 v76, v64, v65
	v_fma_f32 v64, v22, v66, v113
	v_fma_f32 v65, v23, v67, v113
	v_mul_f32_e32 v64, v64, v70
	v_mul_f32_e32 v65, v65, v71
	v_cvt_pk_bf16_f32 v77, v64, v65
	ds_read_b128 v[64:67], v168 offset:8704
	ds_read_b128 v[68:71], v168 offset:8768
	s_waitcnt lgkmcnt(1)
	v_mfma_f32_16x16x32_bf16 v[64:67], v[64:67], v[60:63], 0
	ds_read_b128 v[72:75], v168 offset:8832
	s_waitcnt lgkmcnt(1)
	v_mfma_f32_16x16x32_bf16 v[64:67], v[68:71], v[56:59], v[64:67]
	ds_read_b128 v[68:71], v168 offset:8896
	s_waitcnt lgkmcnt(1)
	v_mfma_f32_16x16x32_bf16 v[64:67], v[72:75], v[52:55], v[64:67]
	v_lshl_add_u64 v[72:73], v[78:79], 0, s[14:15]
	global_store_dwordx2 v[72:73], v[76:77], off offset:32 sc1
	s_waitcnt lgkmcnt(0)
	v_mfma_f32_16x16x32_bf16 v[64:67], v[68:71], v[48:51], v[64:67]
	v_lshlrev_b32_e32 v68, 16, v108
	v_and_b32_e32 v69, 0xffff0000, v108
	v_lshlrev_b32_e32 v70, 16, v109
	v_and_b32_e32 v71, 0xffff0000, v109
	s_nop 3
	v_fma_f32 v64, v24, v64, v113
	v_fma_f32 v65, v25, v65, v113
	v_mul_f32_e32 v64, v64, v68
	v_mul_f32_e32 v65, v65, v69
	v_cvt_pk_bf16_f32 v74, v64, v65
	v_fma_f32 v64, v26, v66, v113
	v_fma_f32 v65, v27, v67, v113
	v_mul_f32_e32 v64, v64, v70
	v_mul_f32_e32 v65, v65, v71
	v_cvt_pk_bf16_f32 v75, v64, v65
	ds_read_b128 v[64:67], v169
	ds_read_b128 v[68:71], v169 offset:64
	s_waitcnt lgkmcnt(1)
	v_mfma_f32_16x16x32_bf16 v[60:63], v[64:67], v[60:63], 0
	ds_read_b128 v[64:67], v169 offset:128
	global_store_dwordx2 v[72:73], v[74:75], off offset:64 sc1
	s_waitcnt lgkmcnt(1)
	v_mfma_f32_16x16x32_bf16 v[56:59], v[68:71], v[56:59], v[60:63]
	s_nop 3
	ds_read_b128 v[60:63], v169 offset:192
	s_waitcnt lgkmcnt(1)
	v_mfma_f32_16x16x32_bf16 v[52:55], v[64:67], v[52:55], v[56:59]
	s_waitcnt lgkmcnt(0)
	v_mfma_f32_16x16x32_bf16 v[48:51], v[60:63], v[48:51], v[52:55]
	s_nop 5
	v_lshlrev_b32_e32 v52, 16, v106
	v_and_b32_e32 v53, 0xffff0000, v106
	v_lshlrev_b32_e32 v54, 16, v107
	v_fma_f32 v48, v12, v48, v113
	v_mul_f32_e32 v48, v48, v52
	v_fma_f32 v49, v13, v49, v113
	v_and_b32_e32 v55, 0xffff0000, v107
	v_mul_f32_e32 v49, v49, v53
	v_cvt_pk_bf16_f32 v60, v48, v49
	v_fma_f32 v48, v14, v50, v113
	v_fmac_f32_e32 v113, v15, v51
	v_mul_f32_e32 v48, v48, v54
	v_mul_f32_e32 v49, v113, v55
	v_cvt_pk_bf16_f32 v61, v48, v49
	ds_read_b128 v[48:51], v168
	ds_read_b128 v[52:55], v168 offset:64
	s_waitcnt lgkmcnt(1)
	v_mfma_f32_16x16x32_bf16 v[48:51], v[48:51], v[44:47], 0
	ds_read_b128 v[56:59], v168 offset:128
	global_store_dwordx2 v[72:73], v[60:61], off offset:96 sc1
	v_or_b32_e32 v62, 32, v88
	s_waitcnt lgkmcnt(1)
	v_mfma_f32_16x16x32_bf16 v[48:51], v[52:55], v[40:43], v[48:51]
	ds_read_b128 v[52:55], v168 offset:192
	v_ashrrev_i32_e32 v63, 31, v62
	v_lshlrev_b64 v[62:63], 11, v[62:63]
	s_waitcnt lgkmcnt(1)
	v_mfma_f32_16x16x32_bf16 v[48:51], v[56:59], v[36:39], v[48:51]
	v_lshl_add_u64 v[62:63], s[8:9], 0, v[62:63]
	v_lshl_add_u64 v[62:63], v[62:63], 0, s[10:11]
	v_lshl_add_u64 v[62:63], v[62:63], 0, v[86:87]
	s_waitcnt lgkmcnt(0)
	v_mfma_f32_16x16x32_bf16 v[48:51], v[52:55], v[32:35], v[48:51]
	v_lshlrev_b32_e32 v52, 16, v104
	v_and_b32_e32 v53, 0xffff0000, v104
	v_lshlrev_b32_e32 v54, 16, v105
	v_and_b32_e32 v55, 0xffff0000, v105
	s_nop 3
	v_fma_f32 v48, v28, v48, v141
	v_fma_f32 v49, v29, v49, v141
	v_mul_f32_e32 v48, v48, v52
	v_mul_f32_e32 v49, v49, v53
	v_cvt_pk_bf16_f32 v60, v48, v49
	v_fma_f32 v48, v30, v50, v141
	v_fma_f32 v49, v31, v51, v141
	v_mul_f32_e32 v48, v48, v54
	v_mul_f32_e32 v49, v49, v55
	v_cvt_pk_bf16_f32 v61, v48, v49
	ds_read_b128 v[48:51], v168 offset:4352
	ds_read_b128 v[52:55], v168 offset:4416
	ds_read_b128 v[56:59], v168 offset:4480
	s_waitcnt lgkmcnt(2)
	v_mfma_f32_16x16x32_bf16 v[48:51], v[48:51], v[44:47], 0
	s_waitcnt lgkmcnt(1)
	v_mfma_f32_16x16x32_bf16 v[48:51], v[52:55], v[40:43], v[48:51]
	ds_read_b128 v[52:55], v168 offset:4544
	s_waitcnt lgkmcnt(1)
	v_mfma_f32_16x16x32_bf16 v[48:51], v[56:59], v[36:39], v[48:51]
	v_add_co_u32_e32 v56, vcc, s12, v62
	s_waitcnt lgkmcnt(0)
	v_mfma_f32_16x16x32_bf16 v[48:51], v[52:55], v[32:35], v[48:51]
	v_lshlrev_b32_e32 v52, 16, v102
	v_and_b32_e32 v53, 0xffff0000, v102
	v_addc_co_u32_e32 v57, vcc, 0, v63, vcc
	s_nop 4
	v_fma_f32 v48, v20, v48, v141
	v_fma_f32 v49, v21, v49, v141
	v_mul_f32_e32 v48, v48, v52
	v_mul_f32_e32 v49, v49, v53
	global_store_dwordx2 v[56:57], v[60:61], off offset:1536 sc1
	v_lshlrev_b32_e32 v54, 16, v103
	v_and_b32_e32 v55, 0xffff0000, v103
	v_cvt_pk_bf16_f32 v60, v48, v49
	v_fma_f32 v48, v22, v50, v141
	v_fma_f32 v49, v23, v51, v141
	v_mul_f32_e32 v48, v48, v54
	v_mul_f32_e32 v49, v49, v55
	v_cvt_pk_bf16_f32 v61, v48, v49
	ds_read_b128 v[48:51], v168 offset:8704
	ds_read_b128 v[52:55], v168 offset:8768
	s_waitcnt lgkmcnt(1)
	v_mfma_f32_16x16x32_bf16 v[48:51], v[48:51], v[44:47], 0
	ds_read_b128 v[56:59], v168 offset:8832
	s_waitcnt lgkmcnt(1)
	v_mfma_f32_16x16x32_bf16 v[48:51], v[52:55], v[40:43], v[48:51]
	ds_read_b128 v[52:55], v168 offset:8896
	s_waitcnt lgkmcnt(1)
	v_mfma_f32_16x16x32_bf16 v[48:51], v[56:59], v[36:39], v[48:51]
	v_lshl_add_u64 v[56:57], v[62:63], 0, s[14:15]
	global_store_dwordx2 v[56:57], v[60:61], off offset:32 sc1
	s_waitcnt lgkmcnt(0)
	v_mfma_f32_16x16x32_bf16 v[48:51], v[52:55], v[32:35], v[48:51]
	v_lshlrev_b32_e32 v52, 16, v100
	v_and_b32_e32 v53, 0xffff0000, v100
	v_lshlrev_b32_e32 v54, 16, v101
	v_and_b32_e32 v55, 0xffff0000, v101
	s_nop 3
	v_fma_f32 v48, v24, v48, v141
	v_fma_f32 v49, v25, v49, v141
	v_mul_f32_e32 v48, v48, v52
	v_mul_f32_e32 v49, v49, v53
	v_cvt_pk_bf16_f32 v58, v48, v49
	v_fma_f32 v48, v26, v50, v141
	v_fma_f32 v49, v27, v51, v141
	v_mul_f32_e32 v48, v48, v54
	v_mul_f32_e32 v49, v49, v55
	v_cvt_pk_bf16_f32 v59, v48, v49
	ds_read_b128 v[48:51], v169
	ds_read_b128 v[52:55], v169 offset:64
	s_waitcnt lgkmcnt(1)
	v_mfma_f32_16x16x32_bf16 v[44:47], v[48:51], v[44:47], 0
	ds_read_b128 v[48:51], v169 offset:128
	global_store_dwordx2 v[56:57], v[58:59], off offset:64 sc1
	s_waitcnt lgkmcnt(1)
	v_mfma_f32_16x16x32_bf16 v[40:43], v[52:55], v[40:43], v[44:47]
	s_nop 3
	ds_read_b128 v[44:47], v169 offset:192
	s_waitcnt lgkmcnt(1)
	v_mfma_f32_16x16x32_bf16 v[36:39], v[48:51], v[36:39], v[40:43]
	s_waitcnt lgkmcnt(0)
	v_mfma_f32_16x16x32_bf16 v[32:35], v[44:47], v[32:35], v[36:39]
	s_nop 5
	v_lshlrev_b32_e32 v36, 16, v98
	v_and_b32_e32 v37, 0xffff0000, v98
	v_lshlrev_b32_e32 v38, 16, v99
	v_fma_f32 v32, v12, v32, v141
	v_mul_f32_e32 v32, v32, v36
	v_fma_f32 v33, v13, v33, v141
	v_and_b32_e32 v39, 0xffff0000, v99
	v_mul_f32_e32 v33, v33, v37
	v_cvt_pk_bf16_f32 v44, v32, v33
	v_fma_f32 v32, v14, v34, v141
	v_fmac_f32_e32 v141, v15, v35
	v_mul_f32_e32 v32, v32, v38
	v_mul_f32_e32 v33, v141, v39
	v_cvt_pk_bf16_f32 v45, v32, v33
	ds_read_b128 v[32:35], v168
	ds_read_b128 v[36:39], v168 offset:64
	s_waitcnt lgkmcnt(1)
	v_mfma_f32_16x16x32_bf16 v[32:35], v[32:35], v[16:19], 0
	ds_read_b128 v[40:43], v168 offset:128
	global_store_dwordx2 v[56:57], v[44:45], off offset:96 sc1
	s_waitcnt lgkmcnt(1)
	v_mfma_f32_16x16x32_bf16 v[32:35], v[36:39], v[8:11], v[32:35]
	ds_read_b128 v[36:39], v168 offset:192
	s_waitcnt lgkmcnt(1)
	v_mfma_f32_16x16x32_bf16 v[32:35], v[40:43], v[4:7], v[32:35]
	v_or_b32_e32 v42, 48, v88
	v_ashrrev_i32_e32 v43, 31, v42
	v_lshlrev_b64 v[42:43], 11, v[42:43]
	s_waitcnt lgkmcnt(0)
	v_mfma_f32_16x16x32_bf16 v[32:35], v[36:39], v[0:3], v[32:35]
	v_lshlrev_b32_e32 v36, 16, v96
	v_and_b32_e32 v37, 0xffff0000, v96
	v_lshlrev_b32_e32 v38, 16, v97
	v_and_b32_e32 v39, 0xffff0000, v97
	v_lshl_add_u64 v[42:43], s[8:9], 0, v[42:43]
	s_nop 2
	v_fma_f32 v28, v28, v32, v112
	v_fma_f32 v29, v29, v33, v112
	v_mul_f32_e32 v28, v28, v36
	v_mul_f32_e32 v29, v29, v37
	v_cvt_pk_bf16_f32 v40, v28, v29
	v_fma_f32 v28, v30, v34, v112
	v_fma_f32 v29, v31, v35, v112
	v_mul_f32_e32 v28, v28, v38
	v_mul_f32_e32 v29, v29, v39
	v_cvt_pk_bf16_f32 v41, v28, v29
	ds_read_b128 v[28:31], v168 offset:4352
	ds_read_b128 v[32:35], v168 offset:4416
	ds_read_b128 v[36:39], v168 offset:4480
	s_waitcnt lgkmcnt(2)
	v_mfma_f32_16x16x32_bf16 v[28:31], v[28:31], v[16:19], 0
	v_lshl_add_u64 v[42:43], v[42:43], 0, s[10:11]
	v_lshl_add_u64 v[42:43], v[42:43], 0, v[86:87]
	s_waitcnt lgkmcnt(1)
	v_mfma_f32_16x16x32_bf16 v[28:31], v[32:35], v[8:11], v[28:31]
	ds_read_b128 v[32:35], v168 offset:4544
	s_waitcnt lgkmcnt(1)
	v_mfma_f32_16x16x32_bf16 v[28:31], v[36:39], v[4:7], v[28:31]
	v_add_co_u32_e32 v36, vcc, s12, v42
	s_waitcnt lgkmcnt(0)
	v_mfma_f32_16x16x32_bf16 v[28:31], v[32:35], v[0:3], v[28:31]
	v_lshlrev_b32_e32 v32, 16, v94
	v_and_b32_e32 v33, 0xffff0000, v94
	v_addc_co_u32_e32 v37, vcc, 0, v43, vcc
	s_nop 4
	v_fma_f32 v20, v20, v28, v112
	v_fma_f32 v21, v21, v29, v112
	v_mul_f32_e32 v20, v20, v32
	v_mul_f32_e32 v21, v21, v33
	global_store_dwordx2 v[36:37], v[40:41], off offset:1536 sc1
	v_lshlrev_b32_e32 v34, 16, v95
	v_and_b32_e32 v35, 0xffff0000, v95
	v_cvt_pk_bf16_f32 v36, v20, v21
	v_fma_f32 v20, v22, v30, v112
	v_fma_f32 v21, v23, v31, v112
	v_mul_f32_e32 v20, v20, v34
	v_mul_f32_e32 v21, v21, v35
	v_cvt_pk_bf16_f32 v37, v20, v21
	ds_read_b128 v[20:23], v168 offset:8704
	ds_read_b128 v[28:31], v168 offset:8768
	s_waitcnt lgkmcnt(1)
	v_mfma_f32_16x16x32_bf16 v[20:23], v[20:23], v[16:19], 0
	ds_read_b128 v[32:35], v168 offset:8832
	s_waitcnt lgkmcnt(1)
	v_mfma_f32_16x16x32_bf16 v[20:23], v[28:31], v[8:11], v[20:23]
	ds_read_b128 v[28:31], v168 offset:8896
	s_waitcnt lgkmcnt(1)
	v_mfma_f32_16x16x32_bf16 v[20:23], v[32:35], v[4:7], v[20:23]
	v_lshl_add_u64 v[32:33], v[42:43], 0, s[14:15]
	global_store_dwordx2 v[32:33], v[36:37], off offset:32 sc1
	s_waitcnt lgkmcnt(0)
	v_mfma_f32_16x16x32_bf16 v[20:23], v[28:31], v[0:3], v[20:23]
	v_lshlrev_b32_e32 v28, 16, v92
	v_and_b32_e32 v29, 0xffff0000, v92
	v_lshlrev_b32_e32 v30, 16, v93
	v_and_b32_e32 v31, 0xffff0000, v93
	s_nop 3
	v_fma_f32 v20, v24, v20, v112
	v_fma_f32 v21, v25, v21, v112
	v_mul_f32_e32 v20, v20, v28
	v_mul_f32_e32 v21, v21, v29
	v_cvt_pk_bf16_f32 v28, v20, v21
	v_fma_f32 v20, v26, v22, v112
	v_fma_f32 v21, v27, v23, v112
	v_mul_f32_e32 v20, v20, v30
	v_mul_f32_e32 v21, v21, v31
	v_cvt_pk_bf16_f32 v29, v20, v21
	ds_read_b128 v[20:23], v169
	ds_read_b128 v[24:27], v169 offset:64
	s_waitcnt lgkmcnt(1)
	v_mfma_f32_16x16x32_bf16 v[16:19], v[20:23], v[16:19], 0
	ds_read_b128 v[20:23], v169 offset:128
	global_store_dwordx2 v[32:33], v[28:29], off offset:64 sc1
	s_waitcnt lgkmcnt(1)
	v_mfma_f32_16x16x32_bf16 v[8:11], v[24:27], v[8:11], v[16:19]
	s_nop 3
	ds_read_b128 v[16:19], v169 offset:192
	s_waitcnt lgkmcnt(1)
	v_mfma_f32_16x16x32_bf16 v[4:7], v[20:23], v[4:7], v[8:11]
	s_waitcnt lgkmcnt(0)
	v_mfma_f32_16x16x32_bf16 v[0:3], v[16:19], v[0:3], v[4:7]
	s_nop 5
	v_lshlrev_b32_e32 v4, 16, v90
	v_and_b32_e32 v5, 0xffff0000, v90
	v_lshlrev_b32_e32 v6, 16, v91
	v_fma_f32 v0, v12, v0, v112
	v_fma_f32 v1, v13, v1, v112
	v_mul_f32_e32 v0, v0, v4
	v_mul_f32_e32 v1, v1, v5
	v_cvt_pk_bf16_f32 v0, v0, v1
	v_fma_f32 v1, v14, v2, v112
	v_and_b32_e32 v7, 0xffff0000, v91
	v_mul_f32_e32 v1, v1, v6
	v_fmac_f32_e32 v112, v15, v3
	v_mul_f32_e32 v2, v112, v7
	v_cvt_pk_bf16_f32 v1, v1, v2
	global_store_dwordx2 v[32:33], v[0:1], off offset:96 sc1
	s_waitcnt lgkmcnt(0)
	s_branch .LBB0_1014

.LBB0_1024:
	v_cmp_lt_i32_e32 vcc, v187, v183
	s_add_u32 s6, s62, 0x4800000
	s_addc_u32 s7, s63, 0
	v_cndmask_b32_e32 v2, v182, v187, vcc
	v_lshlrev_b32_e32 v4, 2, v2
	ds_bpermute_b32 v2, v4, v165
	v_cmp_lt_i32_e32 vcc, v184, v183
	v_lshlrev_b64 v[0:1], 11, v[162:163]
	v_lshl_add_u64 v[0:1], s[6:7], 0, v[0:1]
	v_cndmask_b32_e32 v3, v182, v184, vcc
	s_waitcnt lgkmcnt(0)
	v_add_f32_e32 v2, v165, v2
	v_lshlrev_b32_e32 v5, 2, v3
	ds_bpermute_b32 v3, v5, v2
	s_lshl_b32 s38, s38, 1
	v_lshl_add_u64 v[0:1], v[0:1], 0, s[38:39]
	v_mov_b32_e32 v159, v145
	v_lshl_add_u64 v[0:1], v[0:1], 0, v[158:159]
	s_waitcnt lgkmcnt(0)
	v_add_f32_e32 v2, v2, v3
	v_rcp_f32_e32 v6, v2
	v_readlane_b32 s82, v255, 6
	v_readlane_b32 s84, v255, 8
	v_readlane_b32 s92, v255, 10
	v_mul_f32_e32 v2, v84, v6
	v_mul_f32_e32 v3, v85, v6
	v_cvt_pk_bf16_f32 v2, v2, v3
	v_mul_f32_e32 v3, v86, v6
	v_mul_f32_e32 v7, v87, v6
	v_cvt_pk_bf16_f32 v3, v3, v7
	global_store_dwordx2 v[0:1], v[2:3], off sc1
	v_mul_f32_e32 v2, v80, v6
	v_mul_f32_e32 v3, v81, v6
	v_cvt_pk_bf16_f32 v2, v2, v3
	v_mul_f32_e32 v3, v82, v6
	v_mul_f32_e32 v7, v83, v6
	v_cvt_pk_bf16_f32 v3, v3, v7
	global_store_dwordx2 v[0:1], v[2:3], off offset:32 sc1
	v_mul_f32_e32 v2, v88, v6
	v_mul_f32_e32 v3, v89, v6
	v_cvt_pk_bf16_f32 v2, v2, v3
	v_mul_f32_e32 v3, v90, v6
	v_mul_f32_e32 v7, v91, v6
	v_cvt_pk_bf16_f32 v3, v3, v7
	global_store_dwordx2 v[0:1], v[2:3], off offset:64 sc1
	v_mul_f32_e32 v2, v92, v6
	v_mul_f32_e32 v3, v93, v6
	v_cvt_pk_bf16_f32 v2, v2, v3
	v_mul_f32_e32 v3, v94, v6
	v_mul_f32_e32 v6, v95, v6
	v_cvt_pk_bf16_f32 v3, v3, v6
	global_store_dwordx2 v[0:1], v[2:3], off offset:96 sc1
	ds_bpermute_b32 v2, v4, v164
	v_lshlrev_b64 v[0:1], 11, v[160:161]
	v_lshl_add_u64 v[0:1], s[6:7], 0, v[0:1]
	v_lshl_add_u64 v[0:1], v[0:1], 0, s[38:39]
	v_lshl_add_u64 v[0:1], v[0:1], 0, v[158:159]
	s_waitcnt lgkmcnt(0)
	v_add_f32_e32 v2, v164, v2
	ds_bpermute_b32 v3, v5, v2
	v_readlane_b32 s83, v255, 7
	v_readlane_b32 s85, v255, 9
	v_readlane_b32 s93, v255, 11
	s_movk_i32 s67, 0x1000
	s_waitcnt lgkmcnt(0)
	v_add_f32_e32 v2, v2, v3
	v_rcp_f32_e32 v4, v2
	s_movk_i32 s69, 0xfff
	s_mov_b32 s73, 0xff000000
	s_mov_b64 s[94:95], 0x1000
	v_mul_f32_e32 v2, v96, v4
	v_mul_f32_e32 v3, v97, v4
	v_cvt_pk_bf16_f32 v2, v2, v3
	v_mul_f32_e32 v3, v98, v4
	v_mul_f32_e32 v5, v99, v4
	v_cvt_pk_bf16_f32 v3, v3, v5
	global_store_dwordx2 v[0:1], v[2:3], off sc1
	v_mul_f32_e32 v2, v100, v4
	v_mul_f32_e32 v3, v101, v4
	v_cvt_pk_bf16_f32 v2, v2, v3
	v_mul_f32_e32 v3, v102, v4
	v_mul_f32_e32 v5, v103, v4
	v_cvt_pk_bf16_f32 v3, v3, v5
	global_store_dwordx2 v[0:1], v[2:3], off offset:32 sc1
	v_mul_f32_e32 v2, v104, v4
	v_mul_f32_e32 v3, v105, v4
	v_cvt_pk_bf16_f32 v2, v2, v3
	v_mul_f32_e32 v3, v106, v4
	v_mul_f32_e32 v5, v107, v4
	v_cvt_pk_bf16_f32 v3, v3, v5
	global_store_dwordx2 v[0:1], v[2:3], off offset:64 sc1
	v_mul_f32_e32 v2, v108, v4
	v_mul_f32_e32 v3, v109, v4
	v_cvt_pk_bf16_f32 v2, v2, v3
	v_mul_f32_e32 v3, v110, v4
	s_mov_b32 s74, 0xf7800000
	s_movk_i32 s75, 0x1fff
	s_mov_b32 s76, 0x10000
	s_mov_b32 s77, 0x18000
	s_mov_b32 s86, 0x8000
	s_mov_b32 s87, 0x40000
	s_mov_b32 s90, 0x48000
	s_mov_b32 s78, 0x50000
	s_mov_b32 s79, 0x58000
	v_mul_f32_e32 v4, v111, v4
	v_cvt_pk_bf16_f32 v3, v3, v4
	global_store_dwordx2 v[0:1], v[2:3], off offset:96 sc1

.LBB0_1165:
	s_ashr_i32 s25, s24, 31
	s_lshl_b64 s[24:25], s[24:25], 24
	v_lshl_add_u32 v140, s22, 8, v142
	s_add_u32 s24, s46, s24
	v_ashrrev_i32_e32 v141, 31, v140
	s_addc_u32 s25, s47, s25
	v_lshlrev_b64 v[140:141], 11, v[140:141]
	v_lshl_add_u64 v[140:141], s[24:25], 0, v[140:141]
	s_lshl_b32 s24, s51, 8
	s_ashr_i32 s25, s24, 31
	v_lshl_add_u64 v[140:141], s[24:25], 1, v[140:141]
	v_lshl_add_u64 v[140:141], v[140:141], 0, s[38:39]
	v_lshl_add_u64 v[140:141], v[140:141], 0, v[144:145]
	v_cvt_pk_bf16_f32 v124, v124, v125
	v_cvt_pk_bf16_f32 v125, v126, v127
	v_cvt_pk_bf16_f32 v126, v120, v121
	v_cvt_pk_bf16_f32 v127, v122, v123
	global_store_dwordx4 v[140:141], v[124:127], off sc1
	v_cvt_pk_bf16_f32 v112, v112, v113
	v_cvt_pk_bf16_f32 v113, v114, v115
	v_cvt_pk_bf16_f32 v114, v104, v105
	v_cvt_pk_bf16_f32 v115, v106, v107
	global_store_dwordx4 v[140:141], v[112:115], off offset:256 sc1
	v_cvt_pk_bf16_f32 v104, v116, v117
	v_cvt_pk_bf16_f32 v105, v118, v119
	v_cvt_pk_bf16_f32 v106, v108, v109
	v_add_co_u32_e32 v108, vcc, s86, v140
	v_cvt_pk_bf16_f32 v107, v110, v111
	s_nop 1
	v_addc_co_u32_e32 v109, vcc, 0, v141, vcc
	global_store_dwordx4 v[108:109], v[104:107], off sc1
	v_cvt_pk_bf16_f32 v96, v96, v97
	v_cvt_pk_bf16_f32 v97, v98, v99
	v_cvt_pk_bf16_f32 v98, v88, v89
	v_cvt_pk_bf16_f32 v99, v90, v91
	global_store_dwordx4 v[108:109], v[96:99], off offset:256 sc1
	v_cvt_pk_bf16_f32 v88, v100, v101
	v_cvt_pk_bf16_f32 v89, v102, v103
	v_cvt_pk_bf16_f32 v90, v92, v93
	v_add_co_u32_e32 v92, vcc, s76, v140
	v_cvt_pk_bf16_f32 v91, v94, v95
	s_nop 1
	v_addc_co_u32_e32 v93, vcc, 0, v141, vcc
	global_store_dwordx4 v[92:93], v[88:91], off sc1
	v_cvt_pk_bf16_f32 v80, v80, v81
	v_cvt_pk_bf16_f32 v81, v82, v83
	v_cvt_pk_bf16_f32 v82, v72, v73
	v_cvt_pk_bf16_f32 v83, v74, v75
	global_store_dwordx4 v[92:93], v[80:83], off offset:256 sc1
	v_cvt_pk_bf16_f32 v72, v84, v85
	v_cvt_pk_bf16_f32 v73, v86, v87
	v_cvt_pk_bf16_f32 v74, v76, v77
	v_add_co_u32_e32 v76, vcc, s77, v140
	v_cvt_pk_bf16_f32 v75, v78, v79
	s_nop 1
	v_addc_co_u32_e32 v77, vcc, 0, v141, vcc
	global_store_dwordx4 v[76:77], v[72:75], off sc1
	v_cvt_pk_bf16_f32 v68, v68, v69
	v_cvt_pk_bf16_f32 v69, v70, v71
	v_cvt_pk_bf16_f32 v70, v64, v65
	v_cvt_pk_bf16_f32 v71, v66, v67
	global_store_dwordx4 v[76:77], v[68:71], off offset:256 sc1
	v_cvt_pk_bf16_f32 v60, v60, v61
	v_cvt_pk_bf16_f32 v61, v62, v63
	v_cvt_pk_bf16_f32 v62, v56, v57
	v_add_co_u32_e32 v56, vcc, s87, v140
	v_cvt_pk_bf16_f32 v63, v58, v59
	s_nop 1
	v_addc_co_u32_e32 v57, vcc, 0, v141, vcc
	global_store_dwordx4 v[56:57], v[60:63], off sc1
	v_cvt_pk_bf16_f32 v48, v48, v49
	v_cvt_pk_bf16_f32 v49, v50, v51
	v_cvt_pk_bf16_f32 v50, v40, v41
	v_cvt_pk_bf16_f32 v51, v42, v43
	global_store_dwordx4 v[56:57], v[48:51], off offset:256 sc1
	v_cvt_pk_bf16_f32 v40, v52, v53
	v_cvt_pk_bf16_f32 v41, v54, v55
	v_cvt_pk_bf16_f32 v42, v44, v45
	v_add_co_u32_e32 v44, vcc, s90, v140
	v_cvt_pk_bf16_f32 v43, v46, v47
	s_nop 1
	v_addc_co_u32_e32 v45, vcc, 0, v141, vcc
	global_store_dwordx4 v[44:45], v[40:43], off sc1
	v_cvt_pk_bf16_f32 v32, v32, v33
	v_cvt_pk_bf16_f32 v33, v34, v35
	v_cvt_pk_bf16_f32 v34, v24, v25
	v_cvt_pk_bf16_f32 v35, v26, v27
	global_store_dwordx4 v[44:45], v[32:35], off offset:256 sc1
	v_cvt_pk_bf16_f32 v24, v36, v37
	v_cvt_pk_bf16_f32 v25, v38, v39
	v_cvt_pk_bf16_f32 v26, v28, v29
	v_add_co_u32_e32 v28, vcc, s78, v140
	v_cvt_pk_bf16_f32 v27, v30, v31
	s_nop 1
	v_addc_co_u32_e32 v29, vcc, 0, v141, vcc
	global_store_dwordx4 v[28:29], v[24:27], off sc1
	v_cvt_pk_bf16_f32 v16, v16, v17
	v_cvt_pk_bf16_f32 v17, v18, v19
	v_cvt_pk_bf16_f32 v18, v8, v9
	v_cvt_pk_bf16_f32 v19, v10, v11
	global_store_dwordx4 v[28:29], v[16:19], off offset:256 sc1
	v_cvt_pk_bf16_f32 v8, v20, v21
	v_cvt_pk_bf16_f32 v9, v22, v23
	v_cvt_pk_bf16_f32 v10, v12, v13
	v_add_co_u32_e32 v12, vcc, s79, v140
	v_cvt_pk_bf16_f32 v11, v14, v15
	s_nop 1
	v_addc_co_u32_e32 v13, vcc, 0, v141, vcc
	s_andn2_b64 vcc, exec, s[4:5]
	s_mov_b64 s[4:5], -1
	global_store_dwordx4 v[12:13], v[8:11], off sc1
	v_cvt_pk_bf16_f32 v4, v4, v5
	v_cvt_pk_bf16_f32 v5, v6, v7
	v_cvt_pk_bf16_f32 v6, v0, v1
	v_cvt_pk_bf16_f32 v7, v2, v3
	global_store_dwordx4 v[12:13], v[4:7], off offset:256 sc1
	s_cbranch_vccnz .LBB0_1154
	s_andn2_b64 vcc, exec, s[6:7]
	s_cbranch_vccnz .LBB0_1153
	s_barrier
	s_branch .LBB0_1153

.LBB0_1224:
	v_add_u32_e32 v0, 0xfffff000, v16
	v_ashrrev_i32_e32 v0, 10, v0
	v_add_u32_e32 v0, 1, v0
	v_cmp_lt_i32_e32 vcc, s69, v16
	v_add_u32_e32 v16, s82, v16
	s_nop 0
	v_cndmask_b32_e32 v17, 0, v0, vcc
	v_mul_hi_i32_i24_e32 v67, 0x9000, v17
	v_mul_i32_i24_e32 v66, 0x9000, v17
	v_add_co_u32_e32 v60, vcc, s73, v24
	v_lshl_add_u64 v[58:59], v[18:19], 0, v[66:67]
	s_nop 0
	v_addc_co_u32_e32 v61, vcc, -1, v25, vcc
	global_load_dwordx4 v[12:15], v[26:27], off
	global_load_dwordx4 v[8:11], v[26:27], off offset:1024
	global_load_dwordx4 v[4:7], v[26:27], off offset:2048
	global_load_dwordx4 v[0:3], v[26:27], off offset:3072
	global_load_dwordx2 v[114:115], v[60:61], off offset:-1536
	global_load_dwordx2 v[116:117], v[24:25], off offset:-1536
	global_load_dwordx4 v[34:37], v[58:59], off
	global_load_dwordx4 v[38:41], v[20:21], off
	global_load_dwordx2 v[118:119], v[60:61], off offset:-1024
	global_load_dwordx2 v[120:121], v[24:25], off offset:-1024
	global_load_dwordx4 v[42:45], v[58:59], off offset:1024
	global_load_dwordx4 v[46:49], v[20:21], off offset:1024
	global_load_dwordx2 v[122:123], v[60:61], off offset:-512
	global_load_dwordx2 v[124:125], v[24:25], off offset:-512
	global_load_dwordx4 v[50:53], v[58:59], off offset:2048
	global_load_dwordx4 v[54:57], v[20:21], off offset:2048
	global_load_dwordx2 v[126:127], v[60:61], off
	global_load_dwordx2 v[128:129], v[24:25], off
	s_nop 0
	global_load_dwordx4 v[58:61], v[58:59], off offset:3072
	s_nop 0
	global_load_dwordx4 v[62:65], v[20:21], off offset:3072
	v_lshl_add_u64 v[66:67], s[12:13], 0, v[66:67]
	v_lshl_add_u64 v[102:103], v[66:67], 0, v[144:145]
	global_load_dwordx4 v[66:69], v[102:103], off
	v_add_co_u32_e32 v70, vcc, s67, v102
	v_lshl_add_u64 v[106:107], v[102:103], 0, s[94:95]
	s_nop 0
	v_addc_co_u32_e32 v71, vcc, 0, v103, vcc
	global_load_dwordx4 v[70:73], v[70:71], off
	s_nop 0
	global_load_dwordx4 v[74:77], v[22:23], off
	global_load_dwordx4 v[78:81], v[102:103], off offset:1024
	global_load_dwordx4 v[82:85], v[106:107], off offset:1024
	global_load_dwordx4 v[86:89], v[22:23], off offset:1024
	global_load_dwordx4 v[90:93], v[102:103], off offset:2048
	global_load_dwordx4 v[94:97], v[106:107], off offset:2048
	global_load_dwordx4 v[98:101], v[22:23], off offset:2048
	s_nop 0
	global_load_dwordx4 v[102:105], v[102:103], off offset:3072
	s_nop 0
	global_load_dwordx4 v[106:109], v[106:107], off offset:3072
	s_nop 0
	global_load_dwordx4 v[110:113], v[22:23], off offset:3072
	s_waitcnt vmcnt(27)
	v_lshlrev_b32_e32 v130, 16, v114
	v_and_b32_e32 v131, 0xffff0000, v114
	s_waitcnt vmcnt(26)
	v_lshlrev_b32_e32 v132, 16, v116
	v_and_b32_e32 v133, 0xffff0000, v116
	v_lshlrev_b32_e32 v114, 16, v115
	v_and_b32_e32 v115, 0xffff0000, v115
	v_lshlrev_b32_e32 v116, 16, v117
	v_and_b32_e32 v117, 0xffff0000, v117
	v_pk_add_f32 v[130:131], v[130:131], v[132:133]
	v_pk_add_f32 v[114:115], v[114:115], v[116:117]
	v_mov_b32_e32 v132, v130
	v_pk_mov_b32 v[116:117], v[130:131], v[114:115] op_sel:[1,0]
	v_mov_b32_e32 v133, v115
	v_pk_mul_f32 v[116:117], v[116:117], v[116:117]
	s_waitcnt vmcnt(22)
	v_lshlrev_b32_e32 v134, 16, v120
	v_pk_fma_f32 v[116:117], v[132:133], v[132:133], v[116:117]
	v_lshlrev_b32_e32 v132, 16, v118
	v_and_b32_e32 v133, 0xffff0000, v118
	v_and_b32_e32 v135, 0xffff0000, v120
	v_lshlrev_b32_e32 v118, 16, v119
	v_and_b32_e32 v119, 0xffff0000, v119
	v_lshlrev_b32_e32 v120, 16, v121
	v_and_b32_e32 v121, 0xffff0000, v121
	v_pk_add_f32 v[132:133], v[132:133], v[134:135]
	v_pk_add_f32 v[118:119], v[118:119], v[120:121]
	v_mov_b32_e32 v134, v132
	v_pk_mov_b32 v[120:121], v[132:133], v[118:119] op_sel:[1,0]
	v_mov_b32_e32 v135, v119
	v_pk_mul_f32 v[120:121], v[120:121], v[120:121]
	s_waitcnt vmcnt(18)
	v_lshlrev_b32_e32 v136, 16, v124
	v_pk_fma_f32 v[120:121], v[134:135], v[134:135], v[120:121]
	v_lshlrev_b32_e32 v134, 16, v122
	v_and_b32_e32 v135, 0xffff0000, v122
	v_and_b32_e32 v137, 0xffff0000, v124
	v_lshlrev_b32_e32 v122, 16, v123
	v_and_b32_e32 v123, 0xffff0000, v123
	v_lshlrev_b32_e32 v124, 16, v125
	v_and_b32_e32 v125, 0xffff0000, v125
	v_pk_add_f32 v[134:135], v[134:135], v[136:137]
	v_pk_add_f32 v[122:123], v[122:123], v[124:125]
	s_waitcnt vmcnt(15)
	v_lshlrev_b32_e32 v138, 16, v126
	v_and_b32_e32 v139, 0xffff0000, v126
	s_waitcnt vmcnt(14)
	v_lshlrev_b32_e32 v140, 16, v128
	v_and_b32_e32 v141, 0xffff0000, v128
	v_lshlrev_b32_e32 v126, 16, v127
	v_and_b32_e32 v127, 0xffff0000, v127
	v_lshlrev_b32_e32 v128, 16, v129
	v_and_b32_e32 v129, 0xffff0000, v129
	v_mul_f32_e32 v124, v135, v135
	v_mul_f32_e32 v136, v123, v123
	v_pk_add_f32 v[138:139], v[138:139], v[140:141]
	v_pk_add_f32 v[126:127], v[126:127], v[128:129]
	v_pk_add_f32 v[116:117], v[116:117], v[116:117] op_sel:[0,1] op_sel_hi:[1,0]
	v_pk_add_f32 v[120:121], v[120:121], v[120:121] op_sel:[0,1] op_sel_hi:[1,0]
	v_pk_fma_f32 v[124:125], v[134:135], v[134:135], v[124:125] op_sel_hi:[1,1,0]
	v_pk_fma_f32 v[136:137], v[122:123], v[122:123], v[136:137] op_sel_hi:[1,1,0]
	v_pk_mul_f32 v[128:129], v[138:139], v[138:139]
	v_pk_mul_f32 v[140:141], v[126:127], v[126:127]
	v_mov_b32_e32 v117, v128
	v_mov_b32_e32 v121, v129
	v_mov_b32_e32 v125, v141
	v_mov_b32_e32 v137, v140
	v_pk_add_f32 v[116:117], v[116:117], v[120:121]
	v_pk_add_f32 v[120:121], v[124:125], v[136:137]
	s_nop 0
	v_pk_add_f32 v[116:117], v[116:117], v[120:121]
	s_nop 0
	v_add_f32_e32 v17, v116, v117
	ds_bpermute_b32 v116, v28, v17
	s_waitcnt lgkmcnt(0)
	v_add_f32_e32 v17, v17, v116
	ds_bpermute_b32 v116, v29, v17
	s_waitcnt lgkmcnt(0)
	v_add_f32_e32 v17, v17, v116
	ds_bpermute_b32 v116, v30, v17
	s_waitcnt lgkmcnt(0)
	v_add_f32_e32 v17, v17, v116
	ds_bpermute_b32 v116, v31, v17
	s_waitcnt lgkmcnt(0)
	v_add_f32_e32 v17, v17, v116
	ds_bpermute_b32 v116, v32, v17
	s_waitcnt lgkmcnt(0)
	v_add_f32_e32 v17, v17, v116
	ds_bpermute_b32 v116, v33, v17
	s_waitcnt lgkmcnt(0)
	v_add_f32_e32 v17, v17, v116
	v_fmamk_f32 v17, v17, 0x3a800000, v146
	v_cmp_gt_f32_e32 vcc, s72, v17
	v_mul_f32_e32 v116, 0x4b800000, v17
	s_nop 0
	v_cndmask_b32_e32 v17, v17, v116, vcc
	v_rsq_f32_e32 v17, v17
	s_nop 0
	v_mul_f32_e32 v116, 0x45800000, v17
	v_cndmask_b32_e32 v116, v17, v116, vcc
	v_pk_mul_f32 v[114:115], v[114:115], v[116:117] op_sel_hi:[1,0]
	v_pk_mul_f32 v[120:121], v[130:131], v[116:117] op_sel_hi:[1,0]
	v_pk_mul_f32 v[40:41], v[40:41], v[114:115]
	v_pk_mul_f32 v[38:39], v[38:39], v[120:121]
	v_pk_fma_f32 v[14:15], v[36:37], v[40:41], v[14:15]
	v_pk_fma_f32 v[12:13], v[34:35], v[38:39], v[12:13]
	v_pk_mul_f32 v[34:35], v[118:119], v[116:117] op_sel_hi:[1,0]
	v_pk_mul_f32 v[36:37], v[132:133], v[116:117] op_sel_hi:[1,0]
	v_pk_mul_f32 v[34:35], v[48:49], v[34:35]
	v_pk_mul_f32 v[36:37], v[46:47], v[36:37]
	v_pk_fma_f32 v[10:11], v[44:45], v[34:35], v[10:11]
	v_pk_fma_f32 v[8:9], v[42:43], v[36:37], v[8:9]
	v_pk_mul_f32 v[34:35], v[122:123], v[116:117] op_sel_hi:[1,0]
	v_pk_mul_f32 v[36:37], v[134:135], v[116:117] op_sel_hi:[1,0]
	v_pk_mul_f32 v[34:35], v[56:57], v[34:35]
	v_pk_mul_f32 v[38:39], v[54:55], v[36:37]
	v_pk_fma_f32 v[36:37], v[52:53], v[34:35], v[6:7]
	v_pk_fma_f32 v[34:35], v[50:51], v[38:39], v[4:5]
	v_pk_mul_f32 v[4:5], v[126:127], v[116:117] op_sel_hi:[1,0]
	v_pk_mul_f32 v[6:7], v[138:139], v[116:117] op_sel_hi:[1,0]
	s_waitcnt vmcnt(12)
	v_pk_mul_f32 v[4:5], v[64:65], v[4:5]
	v_pk_mul_f32 v[6:7], v[62:63], v[6:7]
	v_pk_fma_f32 v[40:41], v[60:61], v[4:5], v[2:3]
	v_pk_fma_f32 v[38:39], v[58:59], v[6:7], v[0:1]
	v_pk_mul_f32 v[0:1], v[14:15], v[14:15]
	v_pk_mul_f32 v[2:3], v[12:13], v[12:13]
	s_waitcnt vmcnt(10)
	v_pk_add_f32 v[42:43], v[70:71], 1.0 op_sel_hi:[1,0]
	v_pk_mov_b32 v[4:5], v[2:3], v[0:1] op_sel:[1,0]
	v_mov_b32_e32 v3, v1
	v_pk_add_f32 v[0:1], v[4:5], v[2:3]
	v_pk_mul_f32 v[2:3], v[10:11], v[10:11]
	v_pk_add_f32 v[0:1], v[0:1], v[0:1] op_sel_hi:[0,1]
	v_pk_mul_f32 v[4:5], v[8:9], v[8:9]
	v_mul_f32_e32 v0, v34, v34
	v_pk_mov_b32 v[6:7], v[4:5], v[2:3] op_sel:[1,0]
	v_mov_b32_e32 v5, v3
	v_pk_add_f32 v[2:3], v[6:7], v[4:5]
	v_pk_fma_f32 v[4:5], v[34:35], v[34:35], v[0:1] op_sel_hi:[1,1,0]
	v_mul_f32_e32 v0, v36, v36
	v_pk_add_f32 v[2:3], v[2:3], v[2:3] op_sel_hi:[0,1]
	v_pk_fma_f32 v[6:7], v[36:37], v[36:37], v[0:1] op_sel_hi:[1,1,0]
	v_mul_f32_e32 v4, v38, v38
	v_mul_f32_e32 v6, v39, v39
	v_mul_f32_e32 v0, v40, v40
	v_mul_f32_e32 v2, v41, v41
	v_pk_add_f32 v[4:5], v[4:5], v[6:7]
	v_pk_add_f32 v[0:1], v[0:1], v[2:3]
	s_waitcnt vmcnt(7)
	v_pk_add_f32 v[44:45], v[82:83], 1.0 op_sel_hi:[1,0]
	v_pk_add_f32 v[0:1], v[4:5], v[0:1]
	v_pk_add_f32 v[4:5], v[72:73], 1.0 op_sel_hi:[1,0]
	v_add_f32_e32 v0, v0, v1
	ds_bpermute_b32 v1, v28, v0
	s_waitcnt vmcnt(4)
	v_pk_add_f32 v[46:47], v[94:95], 1.0 op_sel_hi:[1,0]
	s_waitcnt lgkmcnt(0)
	v_add_f32_e32 v0, v0, v1
	ds_bpermute_b32 v1, v29, v0
	s_waitcnt lgkmcnt(0)
	v_add_f32_e32 v0, v0, v1
	ds_bpermute_b32 v1, v30, v0
	s_waitcnt lgkmcnt(0)
	v_add_f32_e32 v0, v0, v1
	ds_bpermute_b32 v1, v31, v0
	s_waitcnt lgkmcnt(0)
	v_add_f32_e32 v0, v0, v1
	ds_bpermute_b32 v1, v32, v0
	s_waitcnt lgkmcnt(0)
	v_add_f32_e32 v0, v0, v1
	ds_bpermute_b32 v1, v33, v0
	s_waitcnt lgkmcnt(0)
	v_add_f32_e32 v0, v0, v1
	v_fmamk_f32 v0, v0, 0x3a800000, v146
	v_cmp_gt_f32_e32 vcc, s72, v0
	v_mul_f32_e32 v1, 0x4b800000, v0
	s_nop 0
	v_cndmask_b32_e32 v0, v0, v1, vcc
	v_rsq_f32_e32 v0, v0
	s_nop 0
	v_mul_f32_e32 v1, 0x45800000, v0
	v_cndmask_b32_e32 v6, v0, v1, vcc
	v_pk_mul_f32 v[0:1], v[14:15], v[6:7] op_sel_hi:[1,0]
	v_pk_mul_f32 v[2:3], v[12:13], v[6:7] op_sel_hi:[1,0]
	v_pk_mul_f32 v[0:1], v[76:77], v[0:1]
	v_pk_mul_f32 v[2:3], v[74:75], v[2:3]
	v_pk_fma_f32 v[4:5], v[4:5], v[0:1], v[68:69]
	v_pk_fma_f32 v[0:1], v[42:43], v[2:3], v[66:67]
	v_pk_mul_f32 v[2:3], v[10:11], v[6:7] op_sel_hi:[1,0]
	v_cvt_pk_bf16_f32 v0, v0, v1
	v_cvt_pk_bf16_f32 v1, v4, v5
	v_pk_mul_f32 v[4:5], v[8:9], v[6:7] op_sel_hi:[1,0]
	v_pk_mul_f32 v[2:3], v[88:89], v[2:3]
	v_pk_mul_f32 v[4:5], v[86:87], v[4:5]
	v_pk_add_f32 v[42:43], v[84:85], 1.0 op_sel_hi:[1,0]
	s_nop 0
	v_pk_fma_f32 v[42:43], v[42:43], v[2:3], v[80:81]
	v_pk_fma_f32 v[2:3], v[44:45], v[4:5], v[78:79]
	v_pk_mul_f32 v[4:5], v[36:37], v[6:7] op_sel_hi:[1,0]
	v_cvt_pk_bf16_f32 v2, v2, v3
	v_cvt_pk_bf16_f32 v3, v42, v43
	v_pk_mul_f32 v[42:43], v[34:35], v[6:7] op_sel_hi:[1,0]
	s_waitcnt vmcnt(3)
	v_pk_mul_f32 v[4:5], v[100:101], v[4:5]
	v_pk_mul_f32 v[42:43], v[98:99], v[42:43]
	v_pk_add_f32 v[44:45], v[96:97], 1.0 op_sel_hi:[1,0]
	s_nop 0
	v_pk_fma_f32 v[44:45], v[44:45], v[4:5], v[92:93]
	v_pk_fma_f32 v[4:5], v[46:47], v[42:43], v[90:91]
	v_pk_mul_f32 v[42:43], v[40:41], v[6:7] op_sel_hi:[1,0]
	v_pk_mul_f32 v[6:7], v[38:39], v[6:7] op_sel_hi:[1,0]
	s_waitcnt vmcnt(1)
	v_pk_add_f32 v[46:47], v[106:107], 1.0 op_sel_hi:[1,0]
	s_waitcnt vmcnt(0)
	v_pk_mul_f32 v[6:7], v[110:111], v[6:7]
	v_cvt_pk_bf16_f32 v4, v4, v5
	v_cvt_pk_bf16_f32 v5, v44, v45
	v_pk_mul_f32 v[42:43], v[112:113], v[42:43]
	v_pk_add_f32 v[44:45], v[108:109], 1.0 op_sel_hi:[1,0]
	v_pk_fma_f32 v[6:7], v[46:47], v[6:7], v[102:103]
	v_pk_fma_f32 v[42:43], v[44:45], v[42:43], v[104:105]
	v_cvt_pk_bf16_f32 v6, v6, v7
	s_nop 0
	v_cvt_pk_bf16_f32 v7, v42, v43
	global_store_dwordx4 v[26:27], v[12:15], off sc1
	global_store_dwordx4 v[26:27], v[8:11], off offset:1024 sc1
	global_store_dwordx4 v[26:27], v[34:37], off offset:2048 sc1
	global_store_dwordx4 v[26:27], v[38:41], off offset:3072 sc1
	v_add_co_u32_e32 v8, vcc, s74, v24
	v_lshl_add_u64 v[26:27], v[26:27], 0, s[34:35]
	s_nop 0
	v_addc_co_u32_e32 v9, vcc, -1, v25, vcc
	v_cmp_lt_i32_e32 vcc, s75, v16
	v_lshl_add_u64 v[24:25], v[24:25], 0, s[84:85]
	s_or_b64 s[4:5], vcc, s[4:5]
	global_store_dwordx2 v[8:9], v[0:1], off offset:-1536 sc1
	global_store_dwordx2 v[8:9], v[2:3], off offset:-1024 sc1
	global_store_dwordx2 v[8:9], v[4:5], off offset:-512 sc1
	global_store_dwordx2 v[8:9], v[6:7], off sc1
	s_andn2_b64 exec, exec, s[4:5]
	s_cbranch_execnz .LBB0_1224
